# gdn chunk-scan consumer hand-scheduled: A-operand fragments streamed through 6 register slots with counted lgkmcnt, U init via identity MFMA, output writes overlapped; attention K/V fragment reads hoi
# speedup vs baseline: 1.0252x; 1.0252x over previous
;     __device__ __forceinline__ void operator()(const f32x4 (&acc)[2][2][4][2], const Unit& u, int wr, int wc, int fr, int fq) const {
;         const int row0 = u.pm * BM + wr * 64 + fr; const int col0 = u.pn * BM + wc * 32 + 4 * fq;
; #pragma unroll
;         for (int ai = 0; ai < 2; ++ai)
; #pragma unroll
;             for (int m = 0; m < 4; ++m) { float* rowp = out + (size_t)(row0 + ai * HALF + m * 16) * ldc + col0;
; #pragma unroll
;                 for (int bj = 0; bj < 2; ++bj)
; #pragma unroll
;                     for (int n = 0; n < 2; ++n) { f32x4* q = (f32x4*)(rowp + bj * HALF + n * 16); *q = *q + acc[ai][bj][m][n]; }
;                 asm volatile("" ::: "memory"); }
;     }
.LBB0_48:
	v_lshl_add_u32 v140, s46, 8, v1
	v_lshl_or_b32 v138, s85, 8, v150
	v_ashrrev_i32_e32 v141, 31, v140
	v_ashrrev_i32_e32 v139, 31, v138
	v_lshlrev_b64 v[142:143], 12, v[140:141]
	v_lshl_add_u64 v[184:185], s[66:67], 0, v[142:143]
	v_lshlrev_b64 v[142:143], 2, v[138:139]
	v_lshl_add_u64 v[138:139], v[184:185], 0, v[142:143]
	global_load_dwordx4 v[184:187], v[138:139], off
	s_mov_b32 s0, 0x80000
	s_mov_b64 s[2:3], 0x80000
	s_mov_b32 s62, 0xc000
	s_mov_b32 s63, 0x12000
	s_mov_b32 s86, 0x30000
	s_waitcnt vmcnt(0) lgkmcnt(0)
	v_pk_add_f32 v[128:129], v[128:129], v[186:187]
	v_pk_add_f32 v[126:127], v[126:127], v[184:185]
	global_store_dwordx4 v[138:139], v[126:129], off
	global_load_dwordx4 v[126:129], v[138:139], off offset:64
	s_waitcnt vmcnt(0) lgkmcnt(0)
	v_pk_add_f32 v[124:125], v[124:125], v[128:129]
	v_pk_add_f32 v[122:123], v[122:123], v[126:127]
	global_store_dwordx4 v[138:139], v[122:125], off offset:64
	global_load_dwordx4 v[122:125], v[138:139], off offset:512
	s_waitcnt vmcnt(0) lgkmcnt(0)
	v_pk_add_f32 v[120:121], v[120:121], v[124:125]
	v_pk_add_f32 v[118:119], v[118:119], v[122:123]
	global_store_dwordx4 v[138:139], v[118:121], off offset:512
	global_load_dwordx4 v[118:121], v[138:139], off offset:576
	s_waitcnt vmcnt(0) lgkmcnt(0)
	v_pk_add_f32 v[116:117], v[116:117], v[120:121]
	v_pk_add_f32 v[114:115], v[114:115], v[118:119]
	global_store_dwordx4 v[138:139], v[114:117], off offset:576
	s_nop 1
	v_or_b32_e32 v114, 16, v140
	v_ashrrev_i32_e32 v115, 31, v114
	v_lshlrev_b64 v[114:115], 12, v[114:115]
	v_lshl_add_u64 v[114:115], s[66:67], 0, v[114:115]
	v_lshl_add_u64 v[118:119], v[114:115], 0, v[142:143]
	global_load_dwordx4 v[114:117], v[118:119], off
	s_waitcnt vmcnt(0) lgkmcnt(0)
	v_pk_add_f32 v[112:113], v[112:113], v[116:117]
	v_pk_add_f32 v[110:111], v[110:111], v[114:115]
	global_store_dwordx4 v[118:119], v[110:113], off
	global_load_dwordx4 v[110:113], v[118:119], off offset:64
	s_waitcnt vmcnt(0) lgkmcnt(0)
	v_pk_add_f32 v[108:109], v[108:109], v[112:113]
	v_pk_add_f32 v[106:107], v[106:107], v[110:111]
	global_store_dwordx4 v[118:119], v[106:109], off offset:64
	global_load_dwordx4 v[106:109], v[118:119], off offset:512
	s_waitcnt vmcnt(0) lgkmcnt(0)
	v_pk_add_f32 v[104:105], v[104:105], v[108:109]
	v_pk_add_f32 v[102:103], v[102:103], v[106:107]
	global_store_dwordx4 v[118:119], v[102:105], off offset:512
	global_load_dwordx4 v[102:105], v[118:119], off offset:576
	s_waitcnt vmcnt(0) lgkmcnt(0)
	v_pk_add_f32 v[100:101], v[100:101], v[104:105]
	v_pk_add_f32 v[98:99], v[98:99], v[102:103]
	global_store_dwordx4 v[118:119], v[98:101], off offset:576
	s_nop 1
	v_or_b32_e32 v98, 32, v140
	v_ashrrev_i32_e32 v99, 31, v98
	v_lshlrev_b64 v[98:99], 12, v[98:99]
	v_lshl_add_u64 v[98:99], s[66:67], 0, v[98:99]
	v_lshl_add_u64 v[102:103], v[98:99], 0, v[142:143]
	global_load_dwordx4 v[98:101], v[102:103], off
	s_waitcnt vmcnt(0) lgkmcnt(0)
	v_pk_add_f32 v[96:97], v[96:97], v[100:101]
	v_pk_add_f32 v[94:95], v[94:95], v[98:99]
	global_store_dwordx4 v[102:103], v[94:97], off
	global_load_dwordx4 v[94:97], v[102:103], off offset:64
	s_waitcnt vmcnt(0) lgkmcnt(0)
	v_pk_add_f32 v[92:93], v[92:93], v[96:97]
	v_pk_add_f32 v[90:91], v[90:91], v[94:95]
	global_store_dwordx4 v[102:103], v[90:93], off offset:64
	global_load_dwordx4 v[90:93], v[102:103], off offset:512
	s_waitcnt vmcnt(0) lgkmcnt(0)
	v_pk_add_f32 v[88:89], v[88:89], v[92:93]
	v_pk_add_f32 v[86:87], v[86:87], v[90:91]
	global_store_dwordx4 v[102:103], v[86:89], off offset:512
	global_load_dwordx4 v[86:89], v[102:103], off offset:576
	s_waitcnt vmcnt(0) lgkmcnt(0)
	v_pk_add_f32 v[84:85], v[84:85], v[88:89]
	v_pk_add_f32 v[82:83], v[82:83], v[86:87]
	global_store_dwordx4 v[102:103], v[82:85], off offset:576
	s_nop 1
	v_or_b32_e32 v82, 48, v140
	v_ashrrev_i32_e32 v83, 31, v82
	v_lshlrev_b64 v[82:83], 12, v[82:83]
	v_lshl_add_u64 v[82:83], s[66:67], 0, v[82:83]
	v_lshl_add_u64 v[86:87], v[82:83], 0, v[142:143]
	global_load_dwordx4 v[82:85], v[86:87], off
	s_waitcnt vmcnt(0) lgkmcnt(0)
	v_pk_add_f32 v[80:81], v[80:81], v[84:85]
	v_pk_add_f32 v[78:79], v[78:79], v[82:83]
	global_store_dwordx4 v[86:87], v[78:81], off
	global_load_dwordx4 v[78:81], v[86:87], off offset:64
	s_waitcnt vmcnt(0) lgkmcnt(0)
	v_pk_add_f32 v[76:77], v[76:77], v[80:81]
	v_pk_add_f32 v[74:75], v[74:75], v[78:79]
	global_store_dwordx4 v[86:87], v[74:77], off offset:64
	global_load_dwordx4 v[74:77], v[86:87], off offset:512
	s_waitcnt vmcnt(0) lgkmcnt(0)
	v_pk_add_f32 v[72:73], v[72:73], v[76:77]
	v_pk_add_f32 v[70:71], v[70:71], v[74:75]
	global_store_dwordx4 v[86:87], v[70:73], off offset:512
	global_load_dwordx4 v[70:73], v[86:87], off offset:576
	s_waitcnt vmcnt(0) lgkmcnt(0)
;     __device__ __forceinline__ void operator()(const f32x4 (&acc)[2][2][4][2], const Unit& u, int wr, int wc, int fr, int fq) const {
;         const int row0 = u.pm * BM + wr * 64 + fr; const int col0 = u.pn * BM + wc * 32 + 4 * fq;
; #pragma unroll
;         for (int ai = 0; ai < 2; ++ai)
; #pragma unroll
;             for (int m = 0; m < 4; ++m) { float* rowp = out + (size_t)(row0 + ai * HALF + m * 16) * ldc + col0;
; #pragma unroll
;                 for (int bj = 0; bj < 2; ++bj)
; #pragma unroll
;                     for (int n = 0; n < 2; ++n) { f32x4* q = (f32x4*)(rowp + bj * HALF + n * 16); *q = *q + acc[ai][bj][m][n]; }
;                 asm volatile("" ::: "memory"); }
;     }
	v_pk_add_f32 v[68:69], v[68:69], v[72:73]
	v_pk_add_f32 v[66:67], v[66:67], v[70:71]
	global_store_dwordx4 v[86:87], v[66:69], off offset:576
	v_add_co_u32_e32 v72, vcc, s0, v138
	v_lshl_add_u64 v[70:71], v[138:139], 0, s[2:3]
	s_nop 0
	v_addc_co_u32_e32 v73, vcc, 0, v139, vcc
	global_load_dwordx4 v[66:69], v[72:73], off
	s_mov_b32 s0, 0x90000
	s_mov_b64 s[2:3], 0x90000
	s_waitcnt vmcnt(0) lgkmcnt(0)
	v_pk_add_f32 v[64:65], v[64:65], v[68:69]
	v_pk_add_f32 v[62:63], v[62:63], v[66:67]
	global_store_dwordx4 v[72:73], v[62:65], off
	global_load_dwordx4 v[62:65], v[70:71], off offset:64
	s_waitcnt vmcnt(0) lgkmcnt(0)
	v_pk_add_f32 v[60:61], v[60:61], v[64:65]
	v_pk_add_f32 v[58:59], v[58:59], v[62:63]
	global_store_dwordx4 v[70:71], v[58:61], off offset:64
	global_load_dwordx4 v[58:61], v[70:71], off offset:512
	s_waitcnt vmcnt(0) lgkmcnt(0)
	v_pk_add_f32 v[56:57], v[56:57], v[60:61]
	v_pk_add_f32 v[54:55], v[54:55], v[58:59]
	global_store_dwordx4 v[70:71], v[54:57], off offset:512
	global_load_dwordx4 v[54:57], v[70:71], off offset:576
	s_waitcnt vmcnt(0) lgkmcnt(0)
	v_pk_add_f32 v[52:53], v[52:53], v[56:57]
	v_pk_add_f32 v[50:51], v[50:51], v[54:55]
	global_store_dwordx4 v[70:71], v[50:53], off offset:576
	v_add_co_u32_e32 v56, vcc, s0, v138
	v_lshl_add_u64 v[54:55], v[138:139], 0, s[2:3]
	s_nop 0
	v_addc_co_u32_e32 v57, vcc, 0, v139, vcc
	global_load_dwordx4 v[50:53], v[56:57], off
	s_mov_b32 s0, 0xa0000
	s_mov_b64 s[2:3], 0xa0000
	s_waitcnt vmcnt(0) lgkmcnt(0)
	v_pk_add_f32 v[48:49], v[48:49], v[52:53]
	v_pk_add_f32 v[46:47], v[46:47], v[50:51]
	global_store_dwordx4 v[56:57], v[46:49], off
	global_load_dwordx4 v[46:49], v[54:55], off offset:64
	s_waitcnt vmcnt(0) lgkmcnt(0)
	v_pk_add_f32 v[44:45], v[44:45], v[48:49]
	v_pk_add_f32 v[42:43], v[42:43], v[46:47]
	global_store_dwordx4 v[54:55], v[42:45], off offset:64
	global_load_dwordx4 v[42:45], v[54:55], off offset:512
	s_waitcnt vmcnt(0) lgkmcnt(0)
	v_pk_add_f32 v[40:41], v[40:41], v[44:45]
	v_pk_add_f32 v[38:39], v[38:39], v[42:43]
	global_store_dwordx4 v[54:55], v[38:41], off offset:512
	global_load_dwordx4 v[38:41], v[54:55], off offset:576
	s_waitcnt vmcnt(0) lgkmcnt(0)
	v_pk_add_f32 v[36:37], v[36:37], v[40:41]
	v_pk_add_f32 v[34:35], v[34:35], v[38:39]
	global_store_dwordx4 v[54:55], v[34:37], off offset:576
	v_add_co_u32_e32 v40, vcc, s0, v138
	v_lshl_add_u64 v[38:39], v[138:139], 0, s[2:3]
	s_nop 0
	v_addc_co_u32_e32 v41, vcc, 0, v139, vcc
	global_load_dwordx4 v[34:37], v[40:41], off
	s_mov_b32 s0, 0xb0000
	s_mov_b64 s[2:3], 0xb0000
	s_waitcnt vmcnt(0) lgkmcnt(0)
	v_pk_add_f32 v[32:33], v[32:33], v[36:37]
	v_pk_add_f32 v[30:31], v[30:31], v[34:35]
	global_store_dwordx4 v[40:41], v[30:33], off
	global_load_dwordx4 v[30:33], v[38:39], off offset:64
	s_waitcnt vmcnt(0) lgkmcnt(0)
	v_pk_add_f32 v[28:29], v[28:29], v[32:33]
	v_pk_add_f32 v[26:27], v[26:27], v[30:31]
	global_store_dwordx4 v[38:39], v[26:29], off offset:64
	global_load_dwordx4 v[26:29], v[38:39], off offset:512
	s_waitcnt vmcnt(0) lgkmcnt(0)
	v_pk_add_f32 v[24:25], v[24:25], v[28:29]
	v_pk_add_f32 v[22:23], v[22:23], v[26:27]
	global_store_dwordx4 v[38:39], v[22:25], off offset:512
	global_load_dwordx4 v[22:25], v[38:39], off offset:576
	s_waitcnt vmcnt(0) lgkmcnt(0)
	v_pk_add_f32 v[20:21], v[20:21], v[24:25]
	v_pk_add_f32 v[18:19], v[18:19], v[22:23]
	global_store_dwordx4 v[38:39], v[18:21], off offset:576
	v_add_co_u32_e32 v24, vcc, s0, v138
	v_lshl_add_u64 v[22:23], v[138:139], 0, s[2:3]
	s_nop 0
	v_addc_co_u32_e32 v25, vcc, 0, v139, vcc
	global_load_dwordx4 v[18:21], v[24:25], off
	s_mov_b64 s[2:3], -1
	s_and_b64 vcc, exec, s[6:7]
	s_waitcnt vmcnt(0) lgkmcnt(0)
	v_pk_add_f32 v[16:17], v[16:17], v[20:21]
	v_pk_add_f32 v[14:15], v[14:15], v[18:19]
	global_store_dwordx4 v[24:25], v[14:17], off
	global_load_dwordx4 v[14:17], v[22:23], off offset:64
	s_waitcnt vmcnt(0) lgkmcnt(0)
	v_pk_add_f32 v[12:13], v[12:13], v[16:17]
	v_pk_add_f32 v[10:11], v[10:11], v[14:15]
	global_store_dwordx4 v[22:23], v[10:13], off offset:64
	global_load_dwordx4 v[10:13], v[22:23], off offset:512
	s_waitcnt vmcnt(0) lgkmcnt(0)
	v_pk_add_f32 v[8:9], v[8:9], v[12:13]
	v_pk_add_f32 v[6:7], v[6:7], v[10:11]
	global_store_dwordx4 v[22:23], v[6:9], off offset:512
	global_load_dwordx4 v[6:9], v[22:23], off offset:576
	s_waitcnt vmcnt(0) lgkmcnt(0)
	v_pk_add_f32 v[4:5], v[4:5], v[8:9]
	v_pk_add_f32 v[2:3], v[2:3], v[6:7]
	global_store_dwordx4 v[22:23], v[2:5], off offset:576
	s_cbranch_vccnz .LBB0_33
	s_andn2_b64 vcc, exec, s[12:13]
	s_cbranch_vccnz .LBB0_32
	s_barrier
	s_branch .LBB0_32

; __device__ __forceinline__ u32x4 pack8(const float* f) { u32x4 o; o.x = pk2(f[0], f[1]); o.y = pk2(f[2], f[3]); o.z = pk2(f[4], f[5]); o.w = pk2(f[6], f[7]); return o; }
; __device__ __forceinline__ float siluf_(float x) { return x * __builtin_amdgcn_rcpf(1.f + __expf(-x)); }
;     __device__ __forceinline__ void operator()(const f32x4 (&acc)[2][2][4][2], const Unit& u, int wr, int wc, int fr, int fq) const {
;         const int row0 = u.pm * BM + wr * 64 + fr; const int col0 = u.pn * HALF + wc * 32 + 8 * fq;
; #pragma unroll
;         for (int ai = 0; ai < 2; ++ai)
; #pragma unroll
;             for (int m = 0; m < 4; ++m) { bf16_t* rowp = O + (size_t)(row0 + ai * HALF + m * 16) * ldc + col0;
;                 float h[8];
; #pragma unroll
;                 for (int n = 0; n < 2; ++n)
; #pragma unroll
;                     for (int i = 0; i < 4; ++i) { const float g = acc[ai][0][m][n][i], up = acc[ai][1][m][n][i]; h[4 * n + i] = siluf_(g) * up; }
;                 *(u32x4*)rowp = pack8(h); }
;     }
.LBB0_67:
	v_mul_f32_e32 v142, 0xbfb8aa3b, v126
	v_exp_f32_e32 v142, v142
	v_mul_f32_e32 v143, 0xbfb8aa3b, v127
	v_exp_f32_e32 v143, v143
	v_mul_f32_e32 v169, 0xbfb8aa3b, v128
	v_add_f32_e32 v142, 1.0, v142
	v_rcp_f32_e32 v184, v142
	v_add_f32_e32 v142, 1.0, v143
	v_rcp_f32_e32 v185, v142
	v_mul_f32_e32 v174, 0xbfb8aa3b, v129
	v_exp_f32_e32 v169, v169
	v_exp_f32_e32 v174, v174
	v_pk_mul_f32 v[126:127], v[126:127], v[184:185]
	v_lshl_or_b32 v170, s46, 7, v165
	v_pk_mul_f32 v[118:119], v[126:127], v[118:119]
	v_add_f32_e32 v126, 1.0, v169
	v_add_f32_e32 v127, 1.0, v174
	v_mul_f32_e32 v169, 0xbfb8aa3b, v122
	v_rcp_f32_e32 v126, v126
	v_rcp_f32_e32 v127, v127
	v_exp_f32_e32 v169, v169
	v_mul_f32_e32 v174, 0xbfb8aa3b, v123
	v_exp_f32_e32 v174, v174
	v_pk_mul_f32 v[126:127], v[128:129], v[126:127]
	v_add_f32_e32 v128, 1.0, v169
	v_mul_f32_e32 v169, 0xbfb8aa3b, v124
	v_add_f32_e32 v129, 1.0, v174
	v_exp_f32_e32 v169, v169
	v_mul_f32_e32 v174, 0xbfb8aa3b, v125
	v_exp_f32_e32 v174, v174
	v_rcp_f32_e32 v128, v128
	v_add_f32_e32 v169, 1.0, v169
	v_rcp_f32_e32 v129, v129
	v_rcp_f32_e32 v184, v169
	v_add_f32_e32 v169, 1.0, v174
	v_rcp_f32_e32 v185, v169
	v_pk_mul_f32 v[122:123], v[122:123], v[128:129]
	v_pk_mul_f32 v[120:121], v[126:127], v[120:121]
	v_pk_mul_f32 v[122:123], v[122:123], v[114:115]
	v_pk_mul_f32 v[114:115], v[124:125], v[184:185]
	v_lshl_add_u32 v168, s40, 8, v1
	v_pk_mul_f32 v[124:125], v[114:115], v[116:117]
	v_cvt_pk_bf16_f32 v117, v120, v121
	v_mul_f32_e32 v120, 0xbfb8aa3b, v110
	v_mul_f32_e32 v121, 0xbfb8aa3b, v111
	v_exp_f32_e32 v120, v120
	v_exp_f32_e32 v121, v121
	v_ashrrev_i32_e32 v171, 31, v170
	v_mov_b64_e32 v[142:143], s[16:17]
	s_movk_i32 s19, 0x1600
	v_mad_i64_i32 v[186:187], s[2:3], v168, s19, v[142:143]
	v_lshlrev_b64 v[114:115], 1, v[170:171]
	v_lshl_add_u64 v[126:127], v[186:187], 0, v[114:115]
	v_cvt_pk_bf16_f32 v116, v118, v119
	v_cvt_pk_bf16_f32 v118, v122, v123
	v_cvt_pk_bf16_f32 v119, v124, v125
	global_store_dwordx4 v[126:127], v[116:119], off
	s_andn2_b64 vcc, exec, s[6:7]
	s_nop 0
	v_add_f32_e32 v116, 1.0, v120
	v_add_f32_e32 v117, 1.0, v121
	v_rcp_f32_e32 v116, v116
	v_rcp_f32_e32 v117, v117
	v_or_b32_e32 v118, 16, v168
	v_mad_i64_i32 v[118:119], s[2:3], v118, s19, v[142:143]
	v_pk_mul_f32 v[110:111], v[110:111], v[116:117]
	v_mul_f32_e32 v116, 0xbfb8aa3b, v112
	v_mul_f32_e32 v117, 0xbfb8aa3b, v113
	v_exp_f32_e32 v116, v116
	v_exp_f32_e32 v117, v117
	v_pk_mul_f32 v[102:103], v[110:111], v[102:103]
	v_add_f32_e32 v110, 1.0, v116
	v_add_f32_e32 v111, 1.0, v117
	v_mul_f32_e32 v116, 0xbfb8aa3b, v106
	v_mul_f32_e32 v117, 0xbfb8aa3b, v107
	v_rcp_f32_e32 v110, v110
	v_rcp_f32_e32 v111, v111
	v_exp_f32_e32 v116, v116
	v_exp_f32_e32 v117, v117
	v_pk_mul_f32 v[110:111], v[112:113], v[110:111]
	v_add_f32_e32 v112, 1.0, v116
	v_add_f32_e32 v113, 1.0, v117
	v_mul_f32_e32 v116, 0xbfb8aa3b, v108
	v_mul_f32_e32 v117, 0xbfb8aa3b, v109
	v_exp_f32_e32 v116, v116
	v_exp_f32_e32 v117, v117
	v_rcp_f32_e32 v112, v112
	v_rcp_f32_e32 v113, v113
	v_add_f32_e32 v116, 1.0, v116
	v_add_f32_e32 v117, 1.0, v117
	v_rcp_f32_e32 v116, v116
	v_rcp_f32_e32 v117, v117
	v_pk_mul_f32 v[106:107], v[106:107], v[112:113]
	v_pk_mul_f32 v[104:105], v[110:111], v[104:105]
	v_pk_mul_f32 v[106:107], v[106:107], v[98:99]
	v_pk_mul_f32 v[98:99], v[108:109], v[116:117]
	v_lshl_add_u64 v[110:111], v[118:119], 0, v[114:115]
	v_pk_mul_f32 v[108:109], v[98:99], v[100:101]
	v_cvt_pk_bf16_f32 v98, v102, v103
	v_mul_f32_e32 v102, 0xbfb8aa3b, v94
	v_mul_f32_e32 v103, 0xbfb8aa3b, v95
	v_exp_f32_e32 v102, v102
	v_exp_f32_e32 v103, v103
	v_cvt_pk_bf16_f32 v99, v104, v105
	v_cvt_pk_bf16_f32 v100, v106, v107
	v_cvt_pk_bf16_f32 v101, v108, v109
	global_store_dwordx4 v[110:111], v[98:101], off
	s_nop 1
	v_add_f32_e32 v98, 1.0, v102
	v_add_f32_e32 v99, 1.0, v103
	v_rcp_f32_e32 v98, v98
	v_rcp_f32_e32 v99, v99
	v_or_b32_e32 v100, 32, v168
	v_mad_i64_i32 v[100:101], s[2:3], v100, s19, v[142:143]
	v_pk_mul_f32 v[94:95], v[94:95], v[98:99]
	v_mul_f32_e32 v98, 0xbfb8aa3b, v96
	v_mul_f32_e32 v99, 0xbfb8aa3b, v97
	v_exp_f32_e32 v98, v98
	v_exp_f32_e32 v99, v99
	v_pk_mul_f32 v[86:87], v[94:95], v[86:87]
	v_add_f32_e32 v94, 1.0, v98
	v_add_f32_e32 v95, 1.0, v99
	v_mul_f32_e32 v98, 0xbfb8aa3b, v90
	v_mul_f32_e32 v99, 0xbfb8aa3b, v91
	v_rcp_f32_e32 v94, v94
	v_rcp_f32_e32 v95, v95
	v_exp_f32_e32 v98, v98
	v_exp_f32_e32 v99, v99
	v_pk_mul_f32 v[94:95], v[96:97], v[94:95]
	v_add_f32_e32 v96, 1.0, v98
	v_add_f32_e32 v97, 1.0, v99
	v_mul_f32_e32 v98, 0xbfb8aa3b, v92
	v_mul_f32_e32 v99, 0xbfb8aa3b, v93
	v_exp_f32_e32 v98, v98
	v_exp_f32_e32 v99, v99
	v_rcp_f32_e32 v96, v96
	v_rcp_f32_e32 v97, v97
	v_add_f32_e32 v98, 1.0, v98
	v_add_f32_e32 v99, 1.0, v99
	v_rcp_f32_e32 v98, v98
	v_rcp_f32_e32 v99, v99
	v_pk_mul_f32 v[90:91], v[90:91], v[96:97]
	v_pk_mul_f32 v[88:89], v[94:95], v[88:89]
	v_pk_mul_f32 v[90:91], v[90:91], v[82:83]
	v_pk_mul_f32 v[82:83], v[92:93], v[98:99]
	v_lshl_add_u64 v[94:95], v[100:101], 0, v[114:115]
	v_pk_mul_f32 v[92:93], v[82:83], v[84:85]
	v_cvt_pk_bf16_f32 v82, v86, v87
	v_mul_f32_e32 v86, 0xbfb8aa3b, v78
	v_mul_f32_e32 v87, 0xbfb8aa3b, v79
	v_exp_f32_e32 v86, v86
	v_exp_f32_e32 v87, v87
	v_cvt_pk_bf16_f32 v83, v88, v89
	v_cvt_pk_bf16_f32 v84, v90, v91
	v_cvt_pk_bf16_f32 v85, v92, v93
	global_store_dwordx4 v[94:95], v[82:85], off
	s_nop 1
	v_add_f32_e32 v82, 1.0, v86
	v_add_f32_e32 v83, 1.0, v87
	v_rcp_f32_e32 v82, v82
	v_rcp_f32_e32 v83, v83
	v_or_b32_e32 v84, 48, v168
	v_mad_i64_i32 v[84:85], s[2:3], v84, s19, v[142:143]
	v_pk_mul_f32 v[78:79], v[78:79], v[82:83]
	v_mul_f32_e32 v82, 0xbfb8aa3b, v80
	v_mul_f32_e32 v83, 0xbfb8aa3b, v81
	v_exp_f32_e32 v82, v82
; __device__ __forceinline__ u32x4 pack8(const float* f) { u32x4 o; o.x = pk2(f[0], f[1]); o.y = pk2(f[2], f[3]); o.z = pk2(f[4], f[5]); o.w = pk2(f[6], f[7]); return o; }
; __device__ __forceinline__ float siluf_(float x) { return x * __builtin_amdgcn_rcpf(1.f + __expf(-x)); }
;     __device__ __forceinline__ void operator()(const f32x4 (&acc)[2][2][4][2], const Unit& u, int wr, int wc, int fr, int fq) const {
;         const int row0 = u.pm * BM + wr * 64 + fr; const int col0 = u.pn * HALF + wc * 32 + 8 * fq;
; #pragma unroll
;         for (int ai = 0; ai < 2; ++ai)
; #pragma unroll
;             for (int m = 0; m < 4; ++m) { bf16_t* rowp = O + (size_t)(row0 + ai * HALF + m * 16) * ldc + col0;
;                 float h[8];
; #pragma unroll
;                 for (int n = 0; n < 2; ++n)
; #pragma unroll
;                     for (int i = 0; i < 4; ++i) { const float g = acc[ai][0][m][n][i], up = acc[ai][1][m][n][i]; h[4 * n + i] = siluf_(g) * up; }
;                 *(u32x4*)rowp = pack8(h); }
;     }
	v_exp_f32_e32 v83, v83
	v_pk_mul_f32 v[70:71], v[78:79], v[70:71]
	v_add_f32_e32 v78, 1.0, v82
	v_add_f32_e32 v79, 1.0, v83
	v_mul_f32_e32 v82, 0xbfb8aa3b, v74
	v_mul_f32_e32 v83, 0xbfb8aa3b, v75
	v_rcp_f32_e32 v78, v78
	v_rcp_f32_e32 v79, v79
	v_exp_f32_e32 v82, v82
	v_exp_f32_e32 v83, v83
	v_pk_mul_f32 v[78:79], v[80:81], v[78:79]
	v_add_f32_e32 v80, 1.0, v82
	v_add_f32_e32 v81, 1.0, v83
	v_mul_f32_e32 v82, 0xbfb8aa3b, v76
	v_mul_f32_e32 v83, 0xbfb8aa3b, v77
	v_exp_f32_e32 v82, v82
	v_exp_f32_e32 v83, v83
	v_rcp_f32_e32 v80, v80
	v_rcp_f32_e32 v81, v81
	v_add_f32_e32 v82, 1.0, v82
	v_add_f32_e32 v83, 1.0, v83
	v_rcp_f32_e32 v82, v82
	v_rcp_f32_e32 v83, v83
	v_pk_mul_f32 v[74:75], v[74:75], v[80:81]
	v_pk_mul_f32 v[72:73], v[78:79], v[72:73]
	v_pk_mul_f32 v[74:75], v[74:75], v[66:67]
	v_pk_mul_f32 v[66:67], v[76:77], v[82:83]
	v_lshl_add_u64 v[78:79], v[84:85], 0, v[114:115]
	v_pk_mul_f32 v[76:77], v[66:67], v[68:69]
	v_cvt_pk_bf16_f32 v66, v70, v71
	v_mul_f32_e32 v70, 0xbfb8aa3b, v62
	v_mul_f32_e32 v71, 0xbfb8aa3b, v63
	v_exp_f32_e32 v70, v70
	v_exp_f32_e32 v71, v71
	v_cvt_pk_bf16_f32 v67, v72, v73
	v_cvt_pk_bf16_f32 v68, v74, v75
	v_cvt_pk_bf16_f32 v69, v76, v77
	global_store_dwordx4 v[78:79], v[66:69], off
	s_nop 1
	v_add_f32_e32 v66, 1.0, v70
	v_add_f32_e32 v67, 1.0, v71
	v_rcp_f32_e32 v66, v66
	v_rcp_f32_e32 v67, v67
	v_add_u32_e32 v68, 0x80, v168
	v_mad_i64_i32 v[68:69], s[2:3], v68, s19, v[142:143]
	v_pk_mul_f32 v[62:63], v[62:63], v[66:67]
	v_mul_f32_e32 v66, 0xbfb8aa3b, v64
	v_mul_f32_e32 v67, 0xbfb8aa3b, v65
	v_exp_f32_e32 v66, v66
	v_exp_f32_e32 v67, v67
	v_pk_mul_f32 v[54:55], v[62:63], v[54:55]
	v_add_f32_e32 v62, 1.0, v66
	v_add_f32_e32 v63, 1.0, v67
	v_mul_f32_e32 v66, 0xbfb8aa3b, v58
	v_mul_f32_e32 v67, 0xbfb8aa3b, v59
	v_rcp_f32_e32 v62, v62
	v_rcp_f32_e32 v63, v63
	v_exp_f32_e32 v66, v66
	v_exp_f32_e32 v67, v67
	v_pk_mul_f32 v[62:63], v[64:65], v[62:63]
	v_add_f32_e32 v64, 1.0, v66
	v_add_f32_e32 v65, 1.0, v67
	v_mul_f32_e32 v66, 0xbfb8aa3b, v60
	v_mul_f32_e32 v67, 0xbfb8aa3b, v61
	v_exp_f32_e32 v66, v66
	v_exp_f32_e32 v67, v67
	v_rcp_f32_e32 v64, v64
	v_rcp_f32_e32 v65, v65
	v_add_f32_e32 v66, 1.0, v66
	v_add_f32_e32 v67, 1.0, v67
	v_rcp_f32_e32 v66, v66
	v_rcp_f32_e32 v67, v67
	v_pk_mul_f32 v[58:59], v[58:59], v[64:65]
	v_pk_mul_f32 v[56:57], v[62:63], v[56:57]
	v_pk_mul_f32 v[58:59], v[58:59], v[50:51]
	v_pk_mul_f32 v[50:51], v[60:61], v[66:67]
	v_lshl_add_u64 v[62:63], v[68:69], 0, v[114:115]
	v_pk_mul_f32 v[60:61], v[50:51], v[52:53]
	v_cvt_pk_bf16_f32 v50, v54, v55
	v_mul_f32_e32 v54, 0xbfb8aa3b, v46
	v_mul_f32_e32 v55, 0xbfb8aa3b, v47
	v_exp_f32_e32 v54, v54
	v_exp_f32_e32 v55, v55
	v_cvt_pk_bf16_f32 v51, v56, v57
	v_cvt_pk_bf16_f32 v52, v58, v59
	v_cvt_pk_bf16_f32 v53, v60, v61
	global_store_dwordx4 v[62:63], v[50:53], off
	s_nop 1
	v_add_f32_e32 v50, 1.0, v54
	v_add_f32_e32 v51, 1.0, v55
	v_rcp_f32_e32 v50, v50
	v_rcp_f32_e32 v51, v51
	v_add_u32_e32 v52, 0x90, v168
	v_mad_i64_i32 v[52:53], s[2:3], v52, s19, v[142:143]
	v_pk_mul_f32 v[46:47], v[46:47], v[50:51]
	v_mul_f32_e32 v50, 0xbfb8aa3b, v48
	v_mul_f32_e32 v51, 0xbfb8aa3b, v49
	v_exp_f32_e32 v50, v50
	v_exp_f32_e32 v51, v51
	v_pk_mul_f32 v[38:39], v[46:47], v[38:39]
	v_add_f32_e32 v46, 1.0, v50
	v_add_f32_e32 v47, 1.0, v51
	v_mul_f32_e32 v50, 0xbfb8aa3b, v42
	v_mul_f32_e32 v51, 0xbfb8aa3b, v43
	v_rcp_f32_e32 v46, v46
	v_rcp_f32_e32 v47, v47
	v_exp_f32_e32 v50, v50
	v_exp_f32_e32 v51, v51
	v_pk_mul_f32 v[46:47], v[48:49], v[46:47]
	v_add_f32_e32 v48, 1.0, v50
	v_add_f32_e32 v49, 1.0, v51
	v_mul_f32_e32 v50, 0xbfb8aa3b, v44
	v_mul_f32_e32 v51, 0xbfb8aa3b, v45
	v_exp_f32_e32 v50, v50
	v_exp_f32_e32 v51, v51
	v_rcp_f32_e32 v48, v48
	v_rcp_f32_e32 v49, v49
	v_add_f32_e32 v50, 1.0, v50
	v_add_f32_e32 v51, 1.0, v51
; __device__ __forceinline__ u32x4 pack8(const float* f) { u32x4 o; o.x = pk2(f[0], f[1]); o.y = pk2(f[2], f[3]); o.z = pk2(f[4], f[5]); o.w = pk2(f[6], f[7]); return o; }
; __device__ __forceinline__ float siluf_(float x) { return x * __builtin_amdgcn_rcpf(1.f + __expf(-x)); }
;     __device__ __forceinline__ void operator()(const f32x4 (&acc)[2][2][4][2], const Unit& u, int wr, int wc, int fr, int fq) const {
;         const int row0 = u.pm * BM + wr * 64 + fr; const int col0 = u.pn * HALF + wc * 32 + 8 * fq;
; #pragma unroll
;         for (int ai = 0; ai < 2; ++ai)
; #pragma unroll
;             for (int m = 0; m < 4; ++m) { bf16_t* rowp = O + (size_t)(row0 + ai * HALF + m * 16) * ldc + col0;
;                 float h[8];
; #pragma unroll
;                 for (int n = 0; n < 2; ++n)
; #pragma unroll
;                     for (int i = 0; i < 4; ++i) { const float g = acc[ai][0][m][n][i], up = acc[ai][1][m][n][i]; h[4 * n + i] = siluf_(g) * up; }
;                 *(u32x4*)rowp = pack8(h); }
;     }
	v_rcp_f32_e32 v50, v50
	v_rcp_f32_e32 v51, v51
	v_pk_mul_f32 v[42:43], v[42:43], v[48:49]
	v_pk_mul_f32 v[40:41], v[46:47], v[40:41]
	v_pk_mul_f32 v[42:43], v[42:43], v[34:35]
	v_pk_mul_f32 v[34:35], v[44:45], v[50:51]
	v_lshl_add_u64 v[46:47], v[52:53], 0, v[114:115]
	v_pk_mul_f32 v[44:45], v[34:35], v[36:37]
	v_cvt_pk_bf16_f32 v34, v38, v39
	v_mul_f32_e32 v38, 0xbfb8aa3b, v30
	v_mul_f32_e32 v39, 0xbfb8aa3b, v31
	v_exp_f32_e32 v38, v38
	v_exp_f32_e32 v39, v39
	v_cvt_pk_bf16_f32 v35, v40, v41
	v_cvt_pk_bf16_f32 v36, v42, v43
	v_cvt_pk_bf16_f32 v37, v44, v45
	global_store_dwordx4 v[46:47], v[34:37], off
	s_nop 1
	v_add_f32_e32 v34, 1.0, v38
	v_add_f32_e32 v35, 1.0, v39
	v_rcp_f32_e32 v34, v34
	v_rcp_f32_e32 v35, v35
	v_add_u32_e32 v36, 0xa0, v168
	v_mad_i64_i32 v[36:37], s[2:3], v36, s19, v[142:143]
	v_pk_mul_f32 v[30:31], v[30:31], v[34:35]
	v_mul_f32_e32 v34, 0xbfb8aa3b, v32
	v_mul_f32_e32 v35, 0xbfb8aa3b, v33
	v_exp_f32_e32 v34, v34
	v_exp_f32_e32 v35, v35
	v_pk_mul_f32 v[22:23], v[30:31], v[22:23]
	v_add_f32_e32 v30, 1.0, v34
	v_add_f32_e32 v31, 1.0, v35
	v_mul_f32_e32 v34, 0xbfb8aa3b, v26
	v_mul_f32_e32 v35, 0xbfb8aa3b, v27
	v_rcp_f32_e32 v30, v30
	v_rcp_f32_e32 v31, v31
	v_exp_f32_e32 v34, v34
	v_exp_f32_e32 v35, v35
	v_pk_mul_f32 v[30:31], v[32:33], v[30:31]
	v_add_f32_e32 v32, 1.0, v34
	v_add_f32_e32 v33, 1.0, v35
	v_mul_f32_e32 v34, 0xbfb8aa3b, v28
	v_mul_f32_e32 v35, 0xbfb8aa3b, v29
	v_exp_f32_e32 v34, v34
	v_exp_f32_e32 v35, v35
	v_rcp_f32_e32 v32, v32
	v_rcp_f32_e32 v33, v33
	v_add_f32_e32 v34, 1.0, v34
	v_add_f32_e32 v35, 1.0, v35
	v_rcp_f32_e32 v34, v34
	v_rcp_f32_e32 v35, v35
	v_pk_mul_f32 v[26:27], v[26:27], v[32:33]
	v_pk_mul_f32 v[24:25], v[30:31], v[24:25]
	v_pk_mul_f32 v[26:27], v[26:27], v[18:19]
	v_pk_mul_f32 v[18:19], v[28:29], v[34:35]
	v_lshl_add_u64 v[30:31], v[36:37], 0, v[114:115]
	v_pk_mul_f32 v[28:29], v[18:19], v[20:21]
	v_cvt_pk_bf16_f32 v18, v22, v23
	v_mul_f32_e32 v22, 0xbfb8aa3b, v14
	v_mul_f32_e32 v23, 0xbfb8aa3b, v15
	v_exp_f32_e32 v22, v22
	v_exp_f32_e32 v23, v23
	v_cvt_pk_bf16_f32 v19, v24, v25
	v_cvt_pk_bf16_f32 v20, v26, v27
	v_cvt_pk_bf16_f32 v21, v28, v29
	global_store_dwordx4 v[30:31], v[18:21], off
	s_nop 1
	v_add_f32_e32 v18, 1.0, v22
	v_add_f32_e32 v19, 1.0, v23
	v_rcp_f32_e32 v18, v18
	v_rcp_f32_e32 v19, v19
	v_add_u32_e32 v20, 0xb0, v168
	v_mad_i64_i32 v[20:21], s[2:3], v20, s19, v[142:143]
	v_pk_mul_f32 v[14:15], v[14:15], v[18:19]
	v_mul_f32_e32 v18, 0xbfb8aa3b, v16
	v_mul_f32_e32 v19, 0xbfb8aa3b, v17
	v_exp_f32_e32 v18, v18
	v_exp_f32_e32 v19, v19
	v_pk_mul_f32 v[6:7], v[14:15], v[6:7]
	s_mov_b64 s[2:3], -1
	v_add_f32_e32 v14, 1.0, v18
	v_add_f32_e32 v15, 1.0, v19
	v_mul_f32_e32 v18, 0xbfb8aa3b, v10
	v_mul_f32_e32 v19, 0xbfb8aa3b, v11
	v_rcp_f32_e32 v14, v14
	v_rcp_f32_e32 v15, v15
	v_exp_f32_e32 v18, v18
	v_exp_f32_e32 v19, v19
	v_pk_mul_f32 v[14:15], v[16:17], v[14:15]
	v_add_f32_e32 v16, 1.0, v18
	v_add_f32_e32 v17, 1.0, v19
	v_mul_f32_e32 v18, 0xbfb8aa3b, v12
	v_mul_f32_e32 v19, 0xbfb8aa3b, v13
	v_exp_f32_e32 v18, v18
	v_exp_f32_e32 v19, v19
	v_rcp_f32_e32 v16, v16
	v_rcp_f32_e32 v17, v17
	v_add_f32_e32 v18, 1.0, v18
	v_add_f32_e32 v19, 1.0, v19
	v_rcp_f32_e32 v18, v18
	v_rcp_f32_e32 v19, v19
	v_pk_mul_f32 v[10:11], v[10:11], v[16:17]
	v_pk_mul_f32 v[8:9], v[14:15], v[8:9]
	v_pk_mul_f32 v[10:11], v[10:11], v[2:3]
	v_pk_mul_f32 v[2:3], v[12:13], v[18:19]
	v_lshl_add_u64 v[14:15], v[20:21], 0, v[114:115]
	v_pk_mul_f32 v[12:13], v[2:3], v[4:5]
	v_cvt_pk_bf16_f32 v2, v6, v7
	v_cvt_pk_bf16_f32 v3, v8, v9
	v_cvt_pk_bf16_f32 v4, v10, v11
	v_cvt_pk_bf16_f32 v5, v12, v13
	global_store_dwordx4 v[14:15], v[2:5], off
	s_cbranch_vccnz .LBB0_60
	s_andn2_b64 vcc, exec, s[12:13]
	s_cbranch_vccnz .LBB0_59
	s_barrier
	s_branch .LBB0_59

; __device__ __forceinline__ unsigned pk2(float lo, float hi) { f32x2 v = {lo, hi}; bf16x2_t b = __builtin_convertvector(v, bf16x2_t); return __builtin_bit_cast(unsigned, b); }
; __device__ __forceinline__ float wave_sum_dpp(float v) { v = half32_sum(v); auto r = __builtin_amdgcn_permlane32_swap(asu(v), asu(v), false, false); return asf(r[0]) + asf(r[1]); }
; __device__ __forceinline__ void rms_rows(const Ctx& c, const float* x, const float* gain, bf16_t* out, float* xcopy) {
;     ...
;     for (int m = c.gw; m < M_; m += c.ngw) {
;         const f32x4* xr = (const f32x4*)(x + (size_t)m * D_) + c.lane;
;         f32x4 v[4]; float s = 0.f;
; #pragma unroll
;         for (int j = 0; j < 4; ++j) { v[j] = xr[64 * j]; s += (v[j].x * v[j].x + v[j].y * v[j].y) + (v[j].z * v[j].z + v[j].w * v[j].w); }
;         if (xcopy) { f32x4* xc = (f32x4*)(xcopy + (size_t)m * D_) + c.lane;
; #pragma unroll
;             for (int j = 0; j < 4; ++j) xc[64 * j] = v[j]; }
;         const float r = rsqrtf(wave_sum_dpp(s) * (1.f / D_) + 1e-6f);
;         u32x2* o8 = (u32x2*)(out + (size_t)m * D_) + c.lane;
; #pragma unroll
;         for (int j = 0; j < 4; ++j) { u32x2 w; w.x = pk2(v[j].x * r * gv[j].x, v[j].y * r * gv[j].y); w.y = pk2(v[j].z * r * gv[j].z, v[j].w * r * gv[j].w); o8[64 * j] = w; }
;     }
.LBB0_76:
	global_load_dwordx4 v[22:25], v[20:21], off
	s_add_i32 s10, s10, s30
	s_cmpk_gt_i32 s10, 0x7fff
	s_waitcnt vmcnt(0) lgkmcnt(0)
	v_mul_f32_e32 v1, v23, v23
	v_mul_f32_e32 v26, v25, v25
	v_fmac_f32_e32 v1, v22, v22
	v_fmac_f32_e32 v26, v24, v24
	v_add_f32_e32 v1, v1, v26
	global_load_dwordx4 v[26:29], v[20:21], off offset:1024
	s_waitcnt vmcnt(0) lgkmcnt(0)
	v_mul_f32_e32 v30, v27, v27
	v_mul_f32_e32 v31, v29, v29
	v_fmac_f32_e32 v30, v26, v26
	v_fmac_f32_e32 v31, v28, v28
	v_add_f32_e32 v30, v30, v31
	v_add_f32_e32 v1, v1, v30
	global_load_dwordx4 v[30:33], v[20:21], off offset:2048
	s_waitcnt vmcnt(0) lgkmcnt(0)
	v_mul_f32_e32 v34, v31, v31
	v_mul_f32_e32 v35, v33, v33
	v_fmac_f32_e32 v34, v30, v30
	v_fmac_f32_e32 v35, v32, v32
	v_add_f32_e32 v34, v34, v35
	v_add_f32_e32 v1, v1, v34
	global_load_dwordx4 v[34:37], v[20:21], off offset:3072
	v_lshl_add_u64 v[20:21], v[20:21], 0, s[6:7]
	s_waitcnt vmcnt(0) lgkmcnt(0)
	v_mul_f32_e32 v38, v35, v35
	v_mul_f32_e32 v39, v37, v37
	v_fmac_f32_e32 v38, v34, v34
	v_fmac_f32_e32 v39, v36, v36
	v_add_f32_e32 v38, v38, v39
	v_add_f32_e32 v1, v1, v38
	s_nop 1
	v_add_f32_dpp v1, v1, v1 row_ror:8 row_mask:0xf bank_mask:0xf bound_ctrl:1
	s_nop 1
	v_add_f32_dpp v1, v1, v1 row_ror:4 row_mask:0xf bank_mask:0xf bound_ctrl:1
	s_nop 1
	v_add_f32_dpp v1, v1, v1 row_ror:2 row_mask:0xf bank_mask:0xf bound_ctrl:1
	s_nop 1
	v_add_f32_dpp v1, v1, v1 row_ror:1 row_mask:0xf bank_mask:0xf bound_ctrl:1
	v_mov_b32_e32 v38, v1
	s_nop 1
	v_permlane16_swap_b32_e32 v1, v38
	v_add_f32_e32 v1, v1, v38
	v_mov_b32_e32 v38, v1
	s_nop 1
	v_permlane32_swap_b32_e32 v1, v38
	v_add_f32_e32 v1, v1, v38
	v_fmamk_f32 v1, v1, 0x3a800000, v148
	v_cmp_gt_f32_e32 vcc, s33, v1
	v_mul_f32_e32 v38, 0x4b800000, v1
	s_nop 0
	v_cndmask_b32_e32 v1, v1, v38, vcc
	v_rsq_f32_e32 v1, v1
	s_nop 0
	v_mul_f32_e32 v38, 0x45800000, v1
	v_cndmask_b32_e32 v38, v1, v38, vcc
	v_pk_mul_f32 v[22:23], v[22:23], v[38:39] op_sel_hi:[1,0]
	v_pk_mul_f32 v[24:25], v[24:25], v[38:39] op_sel_hi:[1,0]
	v_pk_mul_f32 v[22:23], v[14:15], v[22:23]
	v_pk_mul_f32 v[24:25], v[16:17], v[24:25]
	v_cvt_pk_bf16_f32 v22, v22, v23
	v_cvt_pk_bf16_f32 v23, v24, v25
	global_store_dwordx2 v[18:19], v[22:23], off
	v_pk_mul_f32 v[22:23], v[26:27], v[38:39] op_sel_hi:[1,0]
	v_pk_mul_f32 v[24:25], v[28:29], v[38:39] op_sel_hi:[1,0]
	v_pk_mul_f32 v[22:23], v[10:11], v[22:23]
	v_pk_mul_f32 v[24:25], v[12:13], v[24:25]
	v_cvt_pk_bf16_f32 v22, v22, v23
	v_cvt_pk_bf16_f32 v23, v24, v25
	global_store_dwordx2 v[18:19], v[22:23], off offset:512
	v_pk_mul_f32 v[22:23], v[30:31], v[38:39] op_sel_hi:[1,0]
	v_pk_mul_f32 v[24:25], v[32:33], v[38:39] op_sel_hi:[1,0]
	v_pk_mul_f32 v[22:23], v[6:7], v[22:23]
	v_pk_mul_f32 v[24:25], v[8:9], v[24:25]
	v_cvt_pk_bf16_f32 v22, v22, v23
	v_cvt_pk_bf16_f32 v23, v24, v25
	global_store_dwordx2 v[18:19], v[22:23], off offset:1024
	v_pk_mul_f32 v[22:23], v[34:35], v[38:39] op_sel_hi:[1,0]
	v_pk_mul_f32 v[24:25], v[36:37], v[38:39] op_sel_hi:[1,0]
	v_pk_mul_f32 v[22:23], v[2:3], v[22:23]
	v_pk_mul_f32 v[24:25], v[4:5], v[24:25]
	v_cvt_pk_bf16_f32 v22, v22, v23
	v_cvt_pk_bf16_f32 v23, v24, v25
	global_store_dwordx2 v[18:19], v[22:23], off offset:1536
	v_lshl_add_u64 v[18:19], v[18:19], 0, s[2:3]
	s_cbranch_scc0 .LBB0_76

; __device__ __forceinline__ void rwkv_load_chunk(RwkvRegs& R, int n, int pw, int b, int col, const bf16_t* RKV, const bf16_t* LO, const bf16_t* Y) {
; #pragma unroll
;     for (int i = 0; i < 8; ++i) { const int tt = pw + 4 * i, m = b * T_ + 32 * n + tt; const bf16_t* zr = RKV + (size_t)m * RKV_LD; const bf16_t* lo = LO + (size_t)m * 2048;
;         R.vr[i] = zr[col]; R.vx[i] = zr[512 + col]; R.vv[i] = zr[1024 + col]; R.ve[i] = lo[col]; R.va[i] = lo[512 + col]; R.vk[i] = Y[(size_t)m * D_ + col]; }
; }
; __device__ __forceinline__ void rwkv_scan(const Ctx& c, const Params& p, int o, int nblk) {
;     ...
;         if (producer) {
;             const int pw = c.wave - 4;
;             RwkvRegs R;
;             rwkv_load_chunk(R, 0, pw, b, col, RKV, LO, Y); rwkv_write_chunk(L, R, 0, pw, c.lane);
;             rwkv_load_chunk(R, 1, pw, b, col, RKV, LO, Y);
.LBB0_96:
	s_and_b64 vcc, exec, s[2:3]
	s_cbranch_vccz .LBB0_89
	s_and_b32 s2, s48, 0xffffe000
	v_readlane_b32 s0, v255, 46
	s_add_i32 s59, s0, s2
	s_lshl_b32 s2, s49, 4
	s_lshl_b32 s58, s49, 8
	s_and_b32 s2, s2, 0x1c0
	s_and_b32 s36, s58, 0xffffe000
	v_add_u32_e32 v2, s2, v164
	s_add_i32 s2, s36, s20
	s_ashr_i32 s3, s2, 31
	s_mul_i32 s39, s2, 0xc00
	s_mul_hi_i32 s11, s2, 0xc00
	s_add_u32 s10, s16, s39
	s_addc_u32 s11, s17, s11
	s_lshl_b64 s[18:19], s[2:3], 12
	v_ashrrev_i32_e32 v3, 31, v2
	s_add_u32 s18, s12, s18
	v_lshlrev_b64 v[2:3], 1, v[2:3]
	s_addc_u32 s19, s13, s19
	s_waitcnt vmcnt(0) lgkmcnt(0)
	v_lshl_add_u64 v[48:49], s[18:19], 0, v[2:3]
	s_add_i32 s18, s36, s0
	v_lshl_add_u64 v[4:5], s[74:75], 0, v[2:3]
	v_lshl_add_u64 v[46:47], s[10:11], 0, v[2:3]
	s_lshl_b64 s[10:11], s[2:3], 11
	s_ashr_i32 s19, s18, 31
	s_mul_i32 s3, s18, 0xc00
	v_lshl_add_u64 v[50:51], v[4:5], 0, s[10:11]
	s_mul_hi_i32 s11, s18, 0xc00
	s_add_u32 s10, s16, s3
	s_addc_u32 s11, s17, s11
	s_lshl_b64 s[62:63], s[18:19], 12
	s_add_u32 s62, s12, s62
	s_addc_u32 s63, s13, s63
	v_lshl_add_u64 v[36:37], s[10:11], 0, v[2:3]
	s_lshl_b64 s[10:11], s[18:19], 11
	global_load_ushort v59, v[46:47], off
	v_lshl_add_u64 v[52:53], v[4:5], 0, s[10:11]
	s_add_i32 s10, s2, 8
	s_ashr_i32 s11, s10, 31
	s_add_i32 s36, s39, 0x6000
	v_lshl_add_u64 v[42:43], s[62:63], 0, v[2:3]
	s_mul_hi_i32 s19, s10, 0xc00
	s_add_u32 s62, s16, s36
	s_addc_u32 s63, s17, s19
	s_lshl_b64 s[72:73], s[10:11], 12
	s_add_u32 s72, s12, s72
	s_addc_u32 s73, s13, s73
	s_lshl_b64 s[10:11], s[10:11], 11
	v_lshl_add_u64 v[44:45], v[4:5], 0, s[10:11]
	s_add_i32 s10, s2, 12
	s_ashr_i32 s11, s10, 31
	s_add_i32 s36, s39, 0x9000
	v_lshl_add_u64 v[32:33], s[62:63], 0, v[2:3]
	s_mul_hi_i32 s19, s10, 0xc00
	s_add_u32 s62, s16, s36
	v_lshl_add_u64 v[40:41], s[72:73], 0, v[2:3]
	s_addc_u32 s63, s17, s19
	s_lshl_b64 s[72:73], s[10:11], 12
	s_add_u32 s72, s12, s72
	s_addc_u32 s73, s13, s73
	s_lshl_b64 s[10:11], s[10:11], 11
	v_lshl_add_u64 v[38:39], v[4:5], 0, s[10:11]
	s_add_i32 s10, s2, 16
	s_ashr_i32 s11, s10, 31
	s_add_i32 s36, s39, 0xc000
	v_lshl_add_u64 v[26:27], s[62:63], 0, v[2:3]
	s_mul_hi_i32 s19, s10, 0xc00
	s_add_u32 s62, s16, s36
	v_lshl_add_u64 v[34:35], s[72:73], 0, v[2:3]
	s_addc_u32 s63, s17, s19
	s_lshl_b64 s[72:73], s[10:11], 12
	s_add_u32 s72, s12, s72
	s_addc_u32 s73, s13, s73
	s_lshl_b64 s[10:11], s[10:11], 11
	v_lshl_add_u64 v[30:31], v[4:5], 0, s[10:11]
	s_add_i32 s10, s2, 20
	s_ashr_i32 s11, s10, 31
	s_add_i32 s36, s39, 0xf000
	v_lshl_add_u64 v[20:21], s[62:63], 0, v[2:3]
	s_mul_hi_i32 s19, s10, 0xc00
	s_add_u32 s62, s16, s36
	v_lshl_add_u64 v[28:29], s[72:73], 0, v[2:3]
	s_addc_u32 s63, s17, s19
	s_lshl_b64 s[72:73], s[10:11], 12
	s_add_u32 s72, s12, s72
	s_addc_u32 s73, s13, s73
	s_lshl_b64 s[10:11], s[10:11], 11
	v_lshl_add_u64 v[24:25], v[4:5], 0, s[10:11]
	s_add_i32 s10, s2, 24
	s_ashr_i32 s11, s10, 31
	s_add_i32 s36, s39, 0x12000
	v_lshl_add_u64 v[14:15], s[62:63], 0, v[2:3]
	s_mul_hi_i32 s19, s10, 0xc00
	s_add_u32 s62, s16, s36
	v_lshl_add_u64 v[22:23], s[72:73], 0, v[2:3]
	s_addc_u32 s63, s17, s19
	s_lshl_b64 s[72:73], s[10:11], 12
	s_add_u32 s72, s12, s72
	s_addc_u32 s73, s13, s73
	s_lshl_b64 s[10:11], s[10:11], 11
	v_lshl_add_u64 v[18:19], v[4:5], 0, s[10:11]
	s_add_i32 s10, s2, 28
	s_ashr_i32 s11, s10, 31
	s_add_i32 s39, s39, 0x15000
	v_lshl_add_u64 v[8:9], s[62:63], 0, v[2:3]
	s_mul_hi_i32 s2, s10, 0xc00
	s_add_u32 s62, s16, s39
	v_lshl_add_u64 v[16:17], s[72:73], 0, v[2:3]
	s_addc_u32 s63, s17, s2
	s_lshl_b64 s[72:73], s[10:11], 12
	s_add_u32 s72, s12, s72
	s_addc_u32 s73, s13, s73
	s_lshl_b64 s[10:11], s[10:11], 11
	v_lshl_add_u64 v[6:7], s[62:63], 0, v[2:3]
	v_lshl_add_u64 v[10:11], s[72:73], 0, v[2:3]
	v_lshl_add_u64 v[12:13], v[4:5], 0, s[10:11]
	global_load_ushort v60, v[48:49], off
	global_load_ushort v61, v[46:47], off offset:1024
	s_nop 0
	global_load_ushort v50, v[50:51], off
	s_nop 0
	global_load_ushort v48, v[48:49], off offset:1024
	s_nop 0
	global_load_ushort v46, v[46:47], off offset:2048
	s_nop 0
	global_load_ushort v47, v[36:37], off
	global_load_ushort v49, v[42:43], off
	global_load_ushort v51, v[36:37], off offset:1024
	s_nop 0
	global_load_ushort v52, v[52:53], off
	s_nop 0
	global_load_ushort v42, v[42:43], off offset:1024
	s_nop 0
	global_load_ushort v36, v[36:37], off offset:2048
	s_nop 0
	global_load_ushort v37, v[32:33], off
	global_load_ushort v43, v[40:41], off
	global_load_ushort v53, v[32:33], off offset:1024
	s_nop 0
	global_load_ushort v44, v[44:45], off
	s_nop 0
	global_load_ushort v40, v[40:41], off offset:1024
	s_nop 0
	global_load_ushort v32, v[32:33], off offset:2048
	s_nop 0
	global_load_ushort v33, v[26:27], off
	global_load_ushort v41, v[34:35], off
	global_load_ushort v45, v[26:27], off offset:1024
	s_nop 0
	global_load_ushort v38, v[38:39], off
	s_nop 0
	global_load_ushort v34, v[34:35], off offset:1024
	s_nop 0
	global_load_ushort v26, v[26:27], off offset:2048
	s_nop 0
	global_load_ushort v27, v[20:21], off
	global_load_ushort v35, v[28:29], off
	global_load_ushort v39, v[20:21], off offset:1024
	s_nop 0
	global_load_ushort v30, v[30:31], off
	s_nop 0
	global_load_ushort v28, v[28:29], off offset:1024
	s_nop 0
	global_load_ushort v20, v[20:21], off offset:2048
	s_nop 0
	global_load_ushort v21, v[14:15], off
	global_load_ushort v29, v[22:23], off
	global_load_ushort v31, v[14:15], off offset:1024
	s_nop 0
	global_load_ushort v24, v[24:25], off
	s_nop 0
	global_load_ushort v22, v[22:23], off offset:1024
	s_nop 0
	global_load_ushort v14, v[14:15], off offset:2048
	s_nop 0
	global_load_ushort v15, v[8:9], off
	global_load_ushort v23, v[16:17], off
	global_load_ushort v25, v[8:9], off offset:1024
	s_nop 0
	global_load_ushort v18, v[18:19], off
	s_nop 0
	global_load_ushort v16, v[16:17], off offset:1024
	s_nop 0
	global_load_ushort v8, v[8:9], off offset:2048
	s_nop 0
	global_load_ushort v9, v[6:7], off
	global_load_ushort v17, v[10:11], off
	global_load_ushort v19, v[6:7], off offset:1024
	s_nop 0
	global_load_ushort v12, v[12:13], off
	s_nop 0
	global_load_ushort v10, v[10:11], off offset:1024
	s_nop 0
	global_load_ushort v6, v[6:7], off offset:2048
	s_waitcnt vmcnt(0) lgkmcnt(0)
; #define LAS __attribute__((address_space(3)))
; __device__ __forceinline__ float bf2f(bf16_t b) { return asf((unsigned)b << 16); }
; __device__ __forceinline__ void rwkv_load_chunk(RwkvRegs& R, int n, int pw, int b, int col, const bf16_t* RKV, const bf16_t* LO, const bf16_t* Y) {
; #pragma unroll
;     for (int i = 0; i < 8; ++i) { const int tt = pw + 4 * i, m = b * T_ + 32 * n + tt; const bf16_t* zr = RKV + (size_t)m * RKV_LD; const bf16_t* lo = LO + (size_t)m * 2048;
;         R.vr[i] = zr[col]; R.vx[i] = zr[512 + col]; R.vv[i] = zr[1024 + col]; R.ve[i] = lo[col]; R.va[i] = lo[512 + col]; R.vk[i] = Y[(size_t)m * D_ + col]; }
; }
; __device__ __forceinline__ void rwkv_write_chunk(LAS float* L, const RwkvRegs& R, int n, int pw, int lane) {
;     LAS float* st = L + (n & 1) * 12288;
; #pragma unroll
;     for (int i = 0; i < 8; ++i) { const int tt = pw + 4 * i; LAS float* q = st + tt * 64 + lane;
;         q[0] = bf2f(R.vr[i]); q[2048] = __expf(-bf2f(R.ve[i])); q[4096] = bf2f(R.vx[i]); q[6144] = bf2f(R.vk[i]); q[8192] = bf2f(R.va[i]); q[10240] = bf2f(R.vv[i]); }
; }
	v_lshlrev_b32_e32 v59, 16, v59
	s_add_i32 s10, s18, 28
	s_ashr_i32 s11, s10, 31
	s_add_i32 s19, s3, 0x15000
	s_mul_hi_i32 s2, s10, 0xc00
	s_add_u32 s62, s16, s19
	s_addc_u32 s63, s17, s2
	s_lshl_b64 s[72:73], s[10:11], 12
	s_add_u32 s72, s12, s72
	s_addc_u32 s73, s13, s73
	s_lshl_b64 s[10:11], s[10:11], 11
	s_add_i32 s19, s3, 0x18000
	s_movk_i32 s46, 0xf800
	v_lshlrev_b32_e32 v7, 16, v60
	v_mul_f32_e32 v7, 0xbfb8aa3b, v7
	v_exp_f32_e32 v7, v7
	v_lshlrev_b32_e32 v11, 16, v61
	v_lshlrev_b32_e32 v13, 16, v50
	v_lshlrev_b32_e32 v47, 16, v47
	ds_write2st64_b32 v56, v59, v47 offset1:4
	v_lshlrev_b32_e32 v47, 16, v49
	v_mul_f32_e32 v47, 0xbfb8aa3b, v47
	v_exp_f32_e32 v47, v47
	v_lshlrev_b32_e32 v48, 16, v48
	v_lshlrev_b32_e32 v46, 16, v46
	ds_write2st64_b32 v56, v7, v47 offset0:32 offset1:36
	v_lshlrev_b32_e32 v7, 16, v51
	ds_write2st64_b32 v56, v11, v7 offset0:64 offset1:68
	v_lshlrev_b32_e32 v7, 16, v52
	ds_write2st64_b32 v56, v13, v7 offset0:96 offset1:100
	v_lshlrev_b32_e32 v7, 16, v42
	ds_write2st64_b32 v56, v48, v7 offset0:128 offset1:132
	v_lshlrev_b32_e32 v7, 16, v36
	ds_write2st64_b32 v56, v46, v7 offset0:160 offset1:164
	v_lshlrev_b32_e32 v7, 16, v37
	v_lshlrev_b32_e32 v33, 16, v33
	v_lshlrev_b32_e32 v11, 16, v43
	ds_write2st64_b32 v56, v7, v33 offset0:8 offset1:12
	v_lshlrev_b32_e32 v7, 16, v41
	v_mul_f32_e32 v11, 0xbfb8aa3b, v11
	v_mul_f32_e32 v7, 0xbfb8aa3b, v7
	v_exp_f32_e32 v11, v11
	v_exp_f32_e32 v7, v7
	v_lshlrev_b32_e32 v13, 16, v53
	v_lshlrev_b32_e32 v36, 16, v44
	v_lshlrev_b32_e32 v37, 16, v40
	ds_write2st64_b32 v56, v11, v7 offset0:40 offset1:44
	v_lshlrev_b32_e32 v7, 16, v45
	ds_write2st64_b32 v56, v13, v7 offset0:72 offset1:76
	v_lshlrev_b32_e32 v7, 16, v38
	ds_write2st64_b32 v56, v36, v7 offset0:104 offset1:108
	v_lshlrev_b32_e32 v7, 16, v34
	v_lshlrev_b32_e32 v32, 16, v32
	ds_write2st64_b32 v56, v37, v7 offset0:136 offset1:140
	v_lshlrev_b32_e32 v7, 16, v26
	ds_write2st64_b32 v56, v32, v7 offset0:168 offset1:172
	v_lshlrev_b32_e32 v7, 16, v27
	v_lshlrev_b32_e32 v21, 16, v21
	v_lshlrev_b32_e32 v11, 16, v35
	ds_write2st64_b32 v56, v7, v21 offset0:16 offset1:20
	v_lshlrev_b32_e32 v7, 16, v29
	v_mul_f32_e32 v11, 0xbfb8aa3b, v11
	v_mul_f32_e32 v7, 0xbfb8aa3b, v7
	v_exp_f32_e32 v11, v11
	v_exp_f32_e32 v7, v7
	v_lshlrev_b32_e32 v13, 16, v39
	v_lshlrev_b32_e32 v26, 16, v30
	v_lshlrev_b32_e32 v27, 16, v28
	ds_write2st64_b32 v56, v11, v7 offset0:48 offset1:52
	v_lshlrev_b32_e32 v7, 16, v31
	ds_write2st64_b32 v56, v13, v7 offset0:80 offset1:84
	v_lshlrev_b32_e32 v7, 16, v24
	ds_write2st64_b32 v56, v26, v7 offset0:112 offset1:116
	v_lshlrev_b32_e32 v7, 16, v22
	v_lshlrev_b32_e32 v20, 16, v20
	ds_write2st64_b32 v56, v27, v7 offset0:144 offset1:148
	v_lshlrev_b32_e32 v7, 16, v14
	ds_write2st64_b32 v56, v20, v7 offset0:176 offset1:180
	v_lshlrev_b32_e32 v7, 16, v15
	v_lshlrev_b32_e32 v9, 16, v9
	v_lshlrev_b32_e32 v11, 16, v23
	ds_write2st64_b32 v56, v7, v9 offset0:24 offset1:28
	v_lshlrev_b32_e32 v7, 16, v17
	v_mul_f32_e32 v11, 0xbfb8aa3b, v11
	v_mul_f32_e32 v7, 0xbfb8aa3b, v7
	v_exp_f32_e32 v11, v11
	v_exp_f32_e32 v7, v7
	v_lshlrev_b32_e32 v13, 16, v25
	v_lshlrev_b32_e32 v14, 16, v18
	v_lshlrev_b32_e32 v15, 16, v16
	ds_write2st64_b32 v56, v11, v7 offset0:56 offset1:60
	v_lshlrev_b32_e32 v7, 16, v19
	ds_write2st64_b32 v56, v13, v7 offset0:88 offset1:92
	v_lshlrev_b32_e32 v7, 16, v12
	v_lshlrev_b32_e32 v8, 16, v8
	ds_write2st64_b32 v56, v14, v7 offset0:120 offset1:124
	v_lshlrev_b32_e32 v7, 16, v10
	v_lshlrev_b32_e32 v6, 16, v6
	ds_write2st64_b32 v56, v15, v7 offset0:152 offset1:156
	ds_write2st64_b32 v56, v8, v6 offset0:184 offset1:188
	v_lshl_add_u64 v[6:7], s[62:63], 0, v[2:3]
	global_load_ushort v10, v[6:7], off
	global_load_ushort v11, v[6:7], off offset:1024
	global_load_ushort v12, v[6:7], off offset:2048
	v_lshl_add_u64 v[6:7], s[72:73], 0, v[2:3]
	global_load_ushort v13, v[6:7], off
	global_load_ushort v14, v[6:7], off offset:1024
	v_lshl_add_u64 v[6:7], v[4:5], 0, s[10:11]
	s_add_i32 s10, s18, 32
	s_ashr_i32 s11, s10, 31
	s_mul_hi_i32 s2, s10, 0xc00
	s_add_u32 s62, s16, s19
	s_addc_u32 s63, s17, s2
	s_lshl_b64 s[72:73], s[10:11], 12
	s_add_u32 s72, s12, s72
	global_load_ushort v15, v[6:7], off
	s_addc_u32 s73, s13, s73
	v_lshl_add_u64 v[6:7], s[62:63], 0, v[2:3]
	global_load_ushort v16, v[6:7], off
	global_load_ushort v17, v[6:7], off offset:1024
	global_load_ushort v18, v[6:7], off offset:2048
; __device__ __forceinline__ void rwkv_load_chunk(RwkvRegs& R, int n, int pw, int b, int col, const bf16_t* RKV, const bf16_t* LO, const bf16_t* Y) {
; #pragma unroll
;     for (int i = 0; i < 8; ++i) { const int tt = pw + 4 * i, m = b * T_ + 32 * n + tt; const bf16_t* zr = RKV + (size_t)m * RKV_LD; const bf16_t* lo = LO + (size_t)m * 2048;
;         R.vr[i] = zr[col]; R.vx[i] = zr[512 + col]; R.vv[i] = zr[1024 + col]; R.ve[i] = lo[col]; R.va[i] = lo[512 + col]; R.vk[i] = Y[(size_t)m * D_ + col]; }
; }
	v_lshl_add_u64 v[6:7], s[72:73], 0, v[2:3]
	s_lshl_b64 s[10:11], s[10:11], 11
	global_load_ushort v19, v[6:7], off
	global_load_ushort v20, v[6:7], off offset:1024
	v_lshl_add_u64 v[6:7], v[4:5], 0, s[10:11]
	s_add_i32 s10, s18, 36
	s_ashr_i32 s11, s10, 31
	s_add_i32 s19, s3, 0x1b000
	s_mul_hi_i32 s2, s10, 0xc00
	s_add_u32 s62, s16, s19
	s_addc_u32 s63, s17, s2
	s_lshl_b64 s[72:73], s[10:11], 12
	s_add_u32 s72, s12, s72
	global_load_ushort v21, v[6:7], off
	s_addc_u32 s73, s13, s73
	v_lshl_add_u64 v[6:7], s[62:63], 0, v[2:3]
	global_load_ushort v22, v[6:7], off
	global_load_ushort v23, v[6:7], off offset:1024
	global_load_ushort v24, v[6:7], off offset:2048
	v_lshl_add_u64 v[6:7], s[72:73], 0, v[2:3]
	s_lshl_b64 s[10:11], s[10:11], 11
	global_load_ushort v25, v[6:7], off
	global_load_ushort v26, v[6:7], off offset:1024
	v_lshl_add_u64 v[6:7], v[4:5], 0, s[10:11]
	s_add_i32 s10, s18, 40
	s_ashr_i32 s11, s10, 31
	s_add_i32 s19, s3, 0x1e000
	s_mul_hi_i32 s2, s10, 0xc00
	s_add_u32 s62, s16, s19
	s_addc_u32 s63, s17, s2
	s_lshl_b64 s[72:73], s[10:11], 12
	s_add_u32 s72, s12, s72
	global_load_ushort v27, v[6:7], off
	s_addc_u32 s73, s13, s73
	v_lshl_add_u64 v[6:7], s[62:63], 0, v[2:3]
	global_load_ushort v28, v[6:7], off
	global_load_ushort v29, v[6:7], off offset:1024
	global_load_ushort v30, v[6:7], off offset:2048
	v_lshl_add_u64 v[6:7], s[72:73], 0, v[2:3]
	s_lshl_b64 s[10:11], s[10:11], 11
	global_load_ushort v31, v[6:7], off
	global_load_ushort v32, v[6:7], off offset:1024
	v_lshl_add_u64 v[6:7], v[4:5], 0, s[10:11]
	s_add_i32 s10, s18, 44
	s_ashr_i32 s11, s10, 31
	s_add_i32 s19, s3, 0x21000
	s_mul_hi_i32 s2, s10, 0xc00
	s_add_u32 s62, s16, s19
	s_addc_u32 s63, s17, s2
	s_lshl_b64 s[72:73], s[10:11], 12
	s_add_u32 s72, s12, s72
	global_load_ushort v33, v[6:7], off
	s_addc_u32 s73, s13, s73
	v_lshl_add_u64 v[6:7], s[62:63], 0, v[2:3]
	global_load_ushort v34, v[6:7], off
	global_load_ushort v35, v[6:7], off offset:1024
	global_load_ushort v36, v[6:7], off offset:2048
	v_lshl_add_u64 v[6:7], s[72:73], 0, v[2:3]
	s_lshl_b64 s[10:11], s[10:11], 11
	global_load_ushort v37, v[6:7], off
	global_load_ushort v38, v[6:7], off offset:1024
	v_lshl_add_u64 v[6:7], v[4:5], 0, s[10:11]
	s_add_i32 s10, s18, 48
	s_ashr_i32 s11, s10, 31
	s_add_i32 s19, s3, 0x24000
	s_mul_hi_i32 s2, s10, 0xc00
	s_add_u32 s62, s16, s19
	s_addc_u32 s63, s17, s2
	s_lshl_b64 s[72:73], s[10:11], 12
	s_add_u32 s72, s12, s72
	global_load_ushort v39, v[6:7], off
	s_addc_u32 s73, s13, s73
	v_lshl_add_u64 v[6:7], s[62:63], 0, v[2:3]
	global_load_ushort v40, v[6:7], off
	global_load_ushort v41, v[6:7], off offset:1024
	global_load_ushort v42, v[6:7], off offset:2048
	v_lshl_add_u64 v[6:7], s[72:73], 0, v[2:3]
	s_lshl_b64 s[10:11], s[10:11], 11
	global_load_ushort v43, v[6:7], off
	global_load_ushort v44, v[6:7], off offset:1024
	v_lshl_add_u64 v[6:7], v[4:5], 0, s[10:11]
	s_add_i32 s10, s18, 52
	s_ashr_i32 s11, s10, 31
	s_add_i32 s19, s3, 0x27000
	s_mul_hi_i32 s2, s10, 0xc00
	s_add_u32 s62, s16, s19
	s_addc_u32 s63, s17, s2
	s_lshl_b64 s[72:73], s[10:11], 12
	s_add_u32 s72, s12, s72
	global_load_ushort v45, v[6:7], off
	s_addc_u32 s73, s13, s73
	v_lshl_add_u64 v[6:7], s[62:63], 0, v[2:3]
	global_load_ushort v46, v[6:7], off
	global_load_ushort v47, v[6:7], off offset:1024
	global_load_ushort v48, v[6:7], off offset:2048
	v_lshl_add_u64 v[6:7], s[72:73], 0, v[2:3]
	s_lshl_b64 s[10:11], s[10:11], 11
	global_load_ushort v49, v[6:7], off
	global_load_ushort v50, v[6:7], off offset:1024
	v_lshl_add_u64 v[6:7], v[4:5], 0, s[10:11]
	s_add_i32 s10, s18, 56
	s_ashr_i32 s11, s10, 31
	s_add_i32 s3, s3, 0x2a000
	s_mul_hi_i32 s18, s10, 0xc00
	s_add_u32 s2, s16, s3
	s_addc_u32 s3, s17, s18
	s_lshl_b64 s[18:19], s[10:11], 12
	s_add_u32 s18, s12, s18
	global_load_ushort v51, v[6:7], off
	s_addc_u32 s19, s13, s19
	v_lshl_add_u64 v[6:7], s[2:3], 0, v[2:3]
	global_load_ushort v52, v[6:7], off
	global_load_ushort v53, v[6:7], off offset:1024
	global_load_ushort v59, v[6:7], off offset:2048
	v_lshl_add_u64 v[6:7], s[18:19], 0, v[2:3]
	s_lshl_b64 s[2:3], s[10:11], 11
	global_load_ushort v60, v[6:7], off
	global_load_ushort v61, v[6:7], off offset:1024
	v_lshl_add_u64 v[6:7], v[4:5], 0, s[2:3]
	global_load_ushort v62, v[6:7], off
	v_lshl_add_u64 v[6:7], s[16:17], 0, v[2:3]
	v_lshl_add_u64 v[8:9], s[12:13], 0, v[2:3]
	s_mov_b32 s72, 0
	s_mov_b32 s2, 0
	s_branch .LBB0_99

; #define LDS_BARRIER() do { asm volatile("s_waitcnt lgkmcnt(0)" ::: "memory"); __builtin_amdgcn_s_barrier(); asm volatile("" ::: "memory"); } while (0)
; __device__ __forceinline__ void rwkv_load_chunk(RwkvRegs& R, int n, int pw, int b, int col, const bf16_t* RKV, const bf16_t* LO, const bf16_t* Y) {
; #pragma unroll
;     for (int i = 0; i < 8; ++i) { const int tt = pw + 4 * i, m = b * T_ + 32 * n + tt; const bf16_t* zr = RKV + (size_t)m * RKV_LD; const bf16_t* lo = LO + (size_t)m * 2048;
;         R.vr[i] = zr[col]; R.vx[i] = zr[512 + col]; R.vv[i] = zr[1024 + col]; R.ve[i] = lo[col]; R.va[i] = lo[512 + col]; R.vk[i] = Y[(size_t)m * D_ + col]; }
; }
; __device__ __forceinline__ void rwkv_scan(const Ctx& c, const Params& p, int o, int nblk) {
;     ...
;             for (int n = 0; n < 256; ++n) {
;                 LDS_BARRIER();
;                 if (n + 1 < 256) rwkv_write_chunk(L, R, n + 1, pw, c.lane);
;                 if (n + 2 < 256) rwkv_load_chunk(R, n + 2, pw, b, col, RKV, LO, Y);
;                 if (n >= 1) rwkv_store_chunk(L, n - 1, pw, c.lane, b, col, (bf16_t*)LO, half);
.LBB0_101:
	s_cmpk_gt_u32 s2, 0xfd
	s_cbranch_scc1 .LBB0_103
	s_add_i32 s11, s59, s72
	s_add_i32 s2, s11, 60
	s_ashr_i32 s3, s2, 31
	s_lshl_b64 s[18:19], s[2:3], 12
	s_waitcnt vmcnt(0) lgkmcnt(0)
	v_mad_i64_i32 v[12:13], s[62:63], s2, v172, v[6:7]
	s_lshl_b64 s[2:3], s[2:3], 11
	v_lshl_add_u64 v[16:17], v[4:5], 0, s[2:3]
	s_add_i32 s2, s11, 64
	s_ashr_i32 s3, s2, 31
	v_lshl_add_u64 v[14:15], v[8:9], 0, s[18:19]
	s_lshl_b64 s[18:19], s[2:3], 12
	v_mad_i64_i32 v[18:19], s[62:63], s2, v172, v[6:7]
	s_lshl_b64 s[2:3], s[2:3], 11
	v_lshl_add_u64 v[22:23], v[4:5], 0, s[2:3]
	s_add_i32 s2, s11, 0x44
	s_ashr_i32 s3, s2, 31
	v_lshl_add_u64 v[20:21], v[8:9], 0, s[18:19]
	s_lshl_b64 s[18:19], s[2:3], 12
	v_mad_i64_i32 v[24:25], s[62:63], s2, v172, v[6:7]
	s_lshl_b64 s[2:3], s[2:3], 11
	v_lshl_add_u64 v[28:29], v[4:5], 0, s[2:3]
	s_add_i32 s2, s11, 0x48
	s_ashr_i32 s3, s2, 31
	v_lshl_add_u64 v[26:27], v[8:9], 0, s[18:19]
	s_lshl_b64 s[18:19], s[2:3], 12
	v_mad_i64_i32 v[30:31], s[62:63], s2, v172, v[6:7]
	s_lshl_b64 s[2:3], s[2:3], 11
	v_lshl_add_u64 v[34:35], v[4:5], 0, s[2:3]
	s_add_i32 s2, s11, 0x4c
	s_ashr_i32 s3, s2, 31
	v_lshl_add_u64 v[32:33], v[8:9], 0, s[18:19]
	s_lshl_b64 s[18:19], s[2:3], 12
	v_mad_i64_i32 v[36:37], s[62:63], s2, v172, v[6:7]
	s_lshl_b64 s[2:3], s[2:3], 11
	v_lshl_add_u64 v[40:41], v[4:5], 0, s[2:3]
	s_add_i32 s2, s11, 0x50
	s_ashr_i32 s3, s2, 31
	v_lshl_add_u64 v[38:39], v[8:9], 0, s[18:19]
	s_lshl_b64 s[18:19], s[2:3], 12
	v_mad_i64_i32 v[42:43], s[62:63], s2, v172, v[6:7]
	s_lshl_b64 s[2:3], s[2:3], 11
	v_lshl_add_u64 v[46:47], v[4:5], 0, s[2:3]
	s_add_i32 s2, s11, 0x54
	s_ashr_i32 s3, s2, 31
	v_lshl_add_u64 v[44:45], v[8:9], 0, s[18:19]
	s_lshl_b64 s[18:19], s[2:3], 12
	v_mad_i64_i32 v[48:49], s[62:63], s2, v172, v[6:7]
	s_lshl_b64 s[2:3], s[2:3], 11
	v_lshl_add_u64 v[52:53], v[4:5], 0, s[2:3]
	s_add_i32 s2, s11, 0x58
	s_ashr_i32 s3, s2, 31
	v_lshl_add_u64 v[50:51], v[8:9], 0, s[18:19]
	s_lshl_b64 s[18:19], s[2:3], 12
	v_mad_i64_i32 v[60:61], s[62:63], s2, v172, v[6:7]
	v_lshl_add_u64 v[62:63], v[8:9], 0, s[18:19]
	s_lshl_b64 s[2:3], s[2:3], 11
	global_load_ushort v10, v[12:13], off
	global_load_ushort v11, v[12:13], off offset:1024
	s_nop 0
	global_load_ushort v12, v[12:13], off offset:2048
	s_nop 0
	global_load_ushort v13, v[14:15], off
	s_nop 0
	global_load_ushort v14, v[14:15], off offset:1024
	s_nop 0
	global_load_ushort v15, v[16:17], off
	s_nop 0
	global_load_ushort v16, v[18:19], off
	global_load_ushort v17, v[18:19], off offset:1024
	s_nop 0
	global_load_ushort v18, v[18:19], off offset:2048
	s_nop 0
	global_load_ushort v19, v[20:21], off
	s_nop 0
	global_load_ushort v20, v[20:21], off offset:1024
	s_nop 0
	global_load_ushort v21, v[22:23], off
	s_nop 0
	global_load_ushort v22, v[24:25], off
	global_load_ushort v23, v[24:25], off offset:1024
	s_nop 0
	global_load_ushort v24, v[24:25], off offset:2048
	s_nop 0
	global_load_ushort v25, v[26:27], off
	s_nop 0
	global_load_ushort v26, v[26:27], off offset:1024
	s_nop 0
	global_load_ushort v27, v[28:29], off
	s_nop 0
	global_load_ushort v28, v[30:31], off
	global_load_ushort v29, v[30:31], off offset:1024
	s_nop 0
	global_load_ushort v30, v[30:31], off offset:2048
	s_nop 0
	global_load_ushort v31, v[32:33], off
	s_nop 0
	global_load_ushort v32, v[32:33], off offset:1024
	s_nop 0
	global_load_ushort v33, v[34:35], off
	s_nop 0
	global_load_ushort v34, v[36:37], off
	global_load_ushort v35, v[36:37], off offset:1024
	s_nop 0
	global_load_ushort v36, v[36:37], off offset:2048
	s_nop 0
	global_load_ushort v37, v[38:39], off
	s_nop 0
	global_load_ushort v38, v[38:39], off offset:1024
	s_nop 0
	global_load_ushort v39, v[40:41], off
	s_nop 0
	global_load_ushort v40, v[42:43], off
	global_load_ushort v41, v[42:43], off offset:1024
	s_nop 0
	global_load_ushort v42, v[42:43], off offset:2048
	s_nop 0
	global_load_ushort v43, v[44:45], off
	s_nop 0
	global_load_ushort v44, v[44:45], off offset:1024
	s_nop 0
	global_load_ushort v45, v[46:47], off
	s_nop 0
	global_load_ushort v46, v[48:49], off
	global_load_ushort v47, v[48:49], off offset:1024
	s_nop 0
	global_load_ushort v48, v[48:49], off offset:2048
	s_nop 0
	global_load_ushort v49, v[50:51], off
	s_nop 0
	global_load_ushort v50, v[50:51], off offset:1024
	s_nop 0
	global_load_ushort v51, v[52:53], off
	s_nop 0
	global_load_ushort v52, v[60:61], off
	global_load_ushort v53, v[60:61], off offset:1024
	global_load_ushort v59, v[60:61], off offset:2048
	s_nop 0
	global_load_ushort v60, v[62:63], off
	global_load_ushort v61, v[62:63], off offset:1024
	v_lshl_add_u64 v[62:63], v[4:5], 0, s[2:3]
	global_load_ushort v62, v[62:63], off
; #define LAS __attribute__((address_space(3)))
; __device__ __forceinline__ bf16_t f2bf(float f) { return (bf16_t)(pk2(f, 0.f) & 0xffffu); }
; #define LDS_BARRIER() do { asm volatile("s_waitcnt lgkmcnt(0)" ::: "memory"); __builtin_amdgcn_s_barrier(); asm volatile("" ::: "memory"); } while (0)
; __device__ __forceinline__ void rwkv_store_chunk(const LAS float* L, int n, int pw, int lane, int b, int col, bf16_t* YR, int half) {
;     const LAS float* sY = L + 24576 + (n & 1) * 2048;
; #pragma unroll
;     for (int i = 0; i < 8; ++i) { const int tt = pw + 4 * i, m = b * T_ + 32 * n + tt; if ((lane >> 4) == half) YR[(size_t)m * 2048 + 1536 + col] = f2bf(sY[tt * 64 + lane]); }
; }
; __device__ __forceinline__ void rwkv_scan(const Ctx& c, const Params& p, int o, int nblk) {
;     ...
;                 if (n >= 1) rwkv_store_chunk(L, n - 1, pw, c.lane, b, col, (bf16_t*)LO, half);
;             }
;             LDS_BARRIER();
;             rwkv_store_chunk(L, 255, pw, c.lane, b, col, (bf16_t*)LO, half);
.LBB0_103:
	s_cmp_lg_u32 s72, 0
	s_cselect_b64 s[2:3], -1, 0
	s_and_b64 s[18:19], s[2:3], s[8:9]
	s_and_saveexec_b64 s[2:3], s[18:19]
	s_cbranch_execz .LBB0_98
	s_and_b32 s11, s46, 0x800
	v_lshl_add_u32 v63, s11, 2, v57
	v_add_u32_e32 v64, s21, v63
	ds_read_b32 v64, v64
	s_add_i32 s11, s59, s72
	s_sub_i32 s18, s11, 36
	s_ashr_i32 s19, s18, 31
	s_lshl_b64 s[18:19], s[18:19], 12
	s_waitcnt lgkmcnt(0)
	v_cvt_pk_bf16_f32 v66, v64, s0
	v_lshl_add_u64 v[64:65], v[8:9], 0, s[18:19]
	global_store_short v[64:65], v66, off offset:3072
	v_add_u32_e32 v64, s24, v63
	ds_read_b32 v64, v64
	s_sub_i32 s18, s11, 32
	s_ashr_i32 s19, s18, 31
	s_lshl_b64 s[18:19], s[18:19], 12
	s_waitcnt lgkmcnt(0)
	v_cvt_pk_bf16_f32 v66, v64, s0
	v_lshl_add_u64 v[64:65], v[8:9], 0, s[18:19]
	global_store_short v[64:65], v66, off offset:3072
	v_add_u32_e32 v64, s26, v63
	ds_read_b32 v64, v64
	s_sub_i32 s18, s11, 28
	s_ashr_i32 s19, s18, 31
	s_lshl_b64 s[18:19], s[18:19], 12
	s_waitcnt lgkmcnt(0)
	v_cvt_pk_bf16_f32 v66, v64, s0
	v_lshl_add_u64 v[64:65], v[8:9], 0, s[18:19]
	global_store_short v[64:65], v66, off offset:3072
	v_add_u32_e32 v64, s29, v63
	ds_read_b32 v64, v64
	s_sub_i32 s18, s11, 24
	s_ashr_i32 s19, s18, 31
	s_lshl_b64 s[18:19], s[18:19], 12
	s_waitcnt lgkmcnt(0)
	v_cvt_pk_bf16_f32 v66, v64, s0
	v_lshl_add_u64 v[64:65], v[8:9], 0, s[18:19]
	global_store_short v[64:65], v66, off offset:3072
	v_add_u32_e32 v64, s34, v63
	ds_read_b32 v64, v64
	s_sub_i32 s18, s11, 20
	s_ashr_i32 s19, s18, 31
	s_lshl_b64 s[18:19], s[18:19], 12
	s_waitcnt lgkmcnt(0)
	v_cvt_pk_bf16_f32 v66, v64, s0
	v_lshl_add_u64 v[64:65], v[8:9], 0, s[18:19]
	global_store_short v[64:65], v66, off offset:3072
	v_add_u32_e32 v64, s40, v63
	ds_read_b32 v64, v64
	s_add_i32 s18, s11, -16
	s_ashr_i32 s19, s18, 31
	s_lshl_b64 s[18:19], s[18:19], 12
	s_waitcnt lgkmcnt(0)
	v_cvt_pk_bf16_f32 v66, v64, s0
	v_lshl_add_u64 v[64:65], v[8:9], 0, s[18:19]
	global_store_short v[64:65], v66, off offset:3072
	v_add_u32_e32 v64, s42, v63
	ds_read_b32 v64, v64
	s_add_i32 s18, s11, -12
	v_add_u32_e32 v63, s45, v63
	s_ashr_i32 s19, s18, 31
	ds_read_b32 v63, v63
	s_lshl_b64 s[18:19], s[18:19], 12
	s_waitcnt lgkmcnt(0)
	v_cvt_pk_bf16_f32 v66, v64, s0
	v_lshl_add_u64 v[64:65], v[8:9], 0, s[18:19]
	s_add_i32 s18, s11, -8
	s_ashr_i32 s19, s18, 31
	s_lshl_b64 s[18:19], s[18:19], 12
	global_store_short v[64:65], v66, off offset:3072
	v_cvt_pk_bf16_f32 v63, v63, s0
	v_lshl_add_u64 v[64:65], v[8:9], 0, s[18:19]
	global_store_short v[64:65], v63, off offset:3072
	s_branch .LBB0_98
.LBB0_105:
	s_waitcnt lgkmcnt(0)
	s_barrier
	s_and_saveexec_b64 s[2:3], s[8:9]
	s_cbranch_execz .LBB0_88
	s_or_b32 s10, s58, 0x1fe0
	v_add_u32_e32 v4, s21, v58
	s_add_i32 s18, s10, s20
	ds_read_b32 v4, v4
	s_ashr_i32 s19, s18, 31
	s_lshl_b64 s[18:19], s[18:19], 12
	s_add_u32 s18, s12, s18
	s_addc_u32 s19, s13, s19
	s_waitcnt lgkmcnt(0)
	v_cvt_pk_bf16_f32 v6, v4, s0
	v_lshl_add_u64 v[4:5], s[18:19], 0, v[2:3]
	global_store_short v[4:5], v6, off offset:3072
	v_readlane_b32 s0, v255, 46
	v_add_u32_e32 v4, s24, v58
	s_add_i32 s18, s10, s0
	ds_read_b32 v4, v4
	s_ashr_i32 s19, s18, 31
	s_lshl_b64 s[18:19], s[18:19], 12
	s_add_u32 s18, s12, s18
	s_addc_u32 s19, s13, s19
	s_waitcnt lgkmcnt(0)
	v_cvt_pk_bf16_f32 v6, v4, s0
	v_lshl_add_u64 v[4:5], s[18:19], 0, v[2:3]
	global_store_short v[4:5], v6, off offset:3072
	v_add_u32_e32 v4, s26, v58
	s_add_i32 s18, s10, s25
	ds_read_b32 v4, v4
	s_ashr_i32 s19, s18, 31
	s_lshl_b64 s[18:19], s[18:19], 12
	s_add_u32 s18, s12, s18
	s_addc_u32 s19, s13, s19
	s_waitcnt lgkmcnt(0)
	v_cvt_pk_bf16_f32 v6, v4, s0
	v_lshl_add_u64 v[4:5], s[18:19], 0, v[2:3]
	global_store_short v[4:5], v6, off offset:3072
	v_add_u32_e32 v4, s29, v58
	s_add_i32 s18, s10, s27
	ds_read_b32 v4, v4
	s_ashr_i32 s19, s18, 31
	s_lshl_b64 s[18:19], s[18:19], 12
	s_add_u32 s18, s12, s18
	s_addc_u32 s19, s13, s19
	s_waitcnt lgkmcnt(0)
	v_cvt_pk_bf16_f32 v6, v4, s0
	v_lshl_add_u64 v[4:5], s[18:19], 0, v[2:3]
	global_store_short v[4:5], v6, off offset:3072
	v_add_u32_e32 v4, s34, v58
	s_add_i32 s18, s10, s31
	ds_read_b32 v4, v4
	s_ashr_i32 s19, s18, 31
	s_lshl_b64 s[18:19], s[18:19], 12
	s_add_u32 s18, s12, s18
	s_addc_u32 s19, s13, s19
	s_waitcnt lgkmcnt(0)
	v_cvt_pk_bf16_f32 v6, v4, s0
	v_lshl_add_u64 v[4:5], s[18:19], 0, v[2:3]
	global_store_short v[4:5], v6, off offset:3072
	v_add_u32_e32 v4, s40, v58
	s_add_i32 s18, s10, s35
	ds_read_b32 v4, v4
	s_ashr_i32 s19, s18, 31
	s_lshl_b64 s[18:19], s[18:19], 12
	s_add_u32 s18, s12, s18
	s_addc_u32 s19, s13, s19
	s_waitcnt lgkmcnt(0)
	v_cvt_pk_bf16_f32 v6, v4, s0
	v_lshl_add_u64 v[4:5], s[18:19], 0, v[2:3]
	global_store_short v[4:5], v6, off offset:3072
	v_add_u32_e32 v4, s42, v58
	s_add_i32 s18, s10, s41
	ds_read_b32 v4, v4
	s_ashr_i32 s19, s18, 31
	s_lshl_b64 s[18:19], s[18:19], 12
	s_add_u32 s18, s12, s18
	s_addc_u32 s19, s13, s19
	s_waitcnt lgkmcnt(0)
	v_cvt_pk_bf16_f32 v6, v4, s0
	v_lshl_add_u64 v[4:5], s[18:19], 0, v[2:3]
	global_store_short v[4:5], v6, off offset:3072
	v_add_u32_e32 v4, s45, v58
	s_add_i32 s18, s10, s44
	ds_read_b32 v4, v4
	s_ashr_i32 s19, s18, 31
	s_lshl_b64 s[10:11], s[18:19], 12
	s_add_u32 s10, s12, s10
	s_addc_u32 s11, s13, s11
	s_waitcnt lgkmcnt(0)
	v_cvt_pk_bf16_f32 v4, v4, s0
	v_lshl_add_u64 v[2:3], s[10:11], 0, v[2:3]
	global_store_short v[2:3], v4, off offset:3072
	s_branch .LBB0_88

; __device__ __forceinline__ bf16_t f2bf(float f) { return (bf16_t)(pk2(f, 0.f) & 0xffffu); }
; __device__ __forceinline__ int crow(int r, int hi) { return (r & 3) + 8 * (r >> 2) + 4 * hi; }
; __device__ __forceinline__ void attn_phase(const Ctx& c, const Params& p, int o, int first, int cidx) {
;     ...
;         float l; { auto rr = __builtin_amdgcn_permlane32_swap(asu(lrun), asu(lrun), false, false); l = asf(rr[0]) + asf(rr[1]); }
;         const float inv = 1.f / l;
;         bf16_t* yo = Y + (size_t)(b * T_ + qs + l31) * D_ + 512 + h * 64;
; #pragma unroll
;         for (int r = 0; r < 16; ++r) { yo[crow(r, hh)] = f2bf(o0[r] * inv); yo[32 + crow(r, hh)] = f2bf(o1[r] * inv); }
.LBB0_110:
	v_mov_b32_e32 v1, v136
	s_nop 1
	v_permlane32_swap_b32_e32 v136, v1
	v_add_f32_e32 v1, v136, v1
	v_div_scale_f32 v34, s[2:3], v1, v1, 1.0
	v_rcp_f32_e32 v35, v34
	s_lshl_b32 s42, s25, 7
	s_mov_b64 s[2:3], 0x2100400
	v_fma_f32 v36, -v34, v35, 1.0
	v_fmac_f32_e32 v35, v36, v35
	v_div_scale_f32 v36, vcc, 1.0, v1, 1.0
	v_mul_f32_e32 v37, v36, v35
	v_fma_f32 v38, -v34, v37, v36
	v_fmac_f32_e32 v37, v38, v35
	v_fma_f32 v34, -v34, v37, v36
	v_div_fmas_f32 v34, v34, v35, v37
	v_div_fixup_f32 v1, v34, v1, 1.0
	v_lshlrev_b64 v[34:35], 11, v[116:117]
	v_lshl_add_u64 v[34:35], s[22:23], 0, v[34:35]
	v_lshl_add_u64 v[34:35], v[34:35], 0, s[42:43]
	v_mul_f32_e32 v18, v18, v1
	v_lshl_add_u64 v[34:35], v[112:113], 1, v[34:35]
	v_mul_f32_e32 v38, v2, v1
	v_mul_f32_e32 v2, v19, v1
	v_mul_f32_e32 v39, v3, v1
	v_mul_f32_e32 v3, v20, v1
	v_mul_f32_e32 v19, v21, v1
	v_cvt_pk_bf16_f32 v2, v18, v2
	v_add_co_u32_e32 v18, vcc, s36, v34
	v_cvt_pk_bf16_f32 v3, v3, v19
	s_nop 0
	v_addc_co_u32_e32 v19, vcc, 0, v35, vcc
	v_mul_f32_e32 v4, v4, v1
	global_store_dwordx2 v[18:19], v[2:3], off offset:1024
	v_mul_f32_e32 v2, v5, v1
	v_lshl_add_u64 v[36:37], v[34:35], 0, s[2:3]
	v_cvt_pk_bf16_f32 v3, v4, v2
	v_cvt_pk_bf16_f32 v2, v38, v39
	global_store_dwordx2 v[36:37], v[2:3], off offset:64
	v_mul_f32_e32 v2, v22, v1
	v_mul_f32_e32 v4, v6, v1
	v_mul_f32_e32 v5, v23, v1
	v_mul_f32_e32 v6, v7, v1
	v_mul_f32_e32 v3, v24, v1
	v_mul_f32_e32 v7, v8, v1
	v_mul_f32_e32 v8, v25, v1
	v_cvt_pk_bf16_f32 v3, v3, v8
	v_cvt_pk_bf16_f32 v2, v2, v5
	global_store_dwordx2 v[36:37], v[2:3], off offset:16
	v_mul_f32_e32 v2, v9, v1
	v_cvt_pk_bf16_f32 v3, v7, v2
	v_cvt_pk_bf16_f32 v2, v4, v6
	global_store_dwordx2 v[36:37], v[2:3], off offset:80
	v_mul_f32_e32 v2, v26, v1
	v_mul_f32_e32 v5, v27, v1
	v_mul_f32_e32 v3, v28, v1
	v_mul_f32_e32 v8, v29, v1
	v_cvt_pk_bf16_f32 v3, v3, v8
	v_cvt_pk_bf16_f32 v2, v2, v5
	v_mul_f32_e32 v4, v10, v1
	v_mul_f32_e32 v6, v11, v1
	v_mul_f32_e32 v7, v12, v1
	global_store_dwordx2 v[36:37], v[2:3], off offset:32
	v_mul_f32_e32 v2, v13, v1
	v_cvt_pk_bf16_f32 v3, v7, v2
	v_cvt_pk_bf16_f32 v2, v4, v6
	global_store_dwordx2 v[36:37], v[2:3], off offset:96
	v_mul_f32_e32 v2, v30, v1
	v_mul_f32_e32 v5, v31, v1
	v_mul_f32_e32 v3, v32, v1
	v_mul_f32_e32 v8, v33, v1
	v_mul_f32_e32 v4, v14, v1
	v_mul_f32_e32 v6, v15, v1
	v_mul_f32_e32 v7, v16, v1
	v_cvt_pk_bf16_f32 v3, v3, v8
	v_cvt_pk_bf16_f32 v2, v2, v5
	v_mul_f32_e32 v1, v17, v1
	global_store_dwordx2 v[36:37], v[2:3], off offset:48
	v_cvt_pk_bf16_f32 v3, v7, v1
	v_cvt_pk_bf16_f32 v2, v4, v6
	s_mov_b64 s[2:3], 0
	global_store_dwordx2 v[36:37], v[2:3], off offset:112

; #define LAS __attribute__((address_space(3)))
; __device__ __forceinline__ void attn_phase(const Ctx& c, const Params& p, int o, int first, int cidx) {
;     ...
;         if (c.tid == 0) sU[0] = atomicAdd(cnt, 1u);
;         __syncthreads();
;         const unsigned uu = sU[0];
;         __syncthreads();
;         if (uu >= 1024u) break;
;         const int bh = uu & 31, b = bh >> 3, h = bh & 7; const int qblk = 31 - (int)(uu >> 5); const int q0 = qblk * 256, qs = q0 + 32 * c.wave;
;         bf16x8 qf[6]; { const bf16_t* qp = QH + (size_t)(b * T_ + qs + l31) * 768 + h * 96 + 8 * hh;
; #pragma unroll
;             for (int ks = 0; ks < 6; ++ks) qf[ks] = *(const bf16x8*)(qp + 16 * ks); }
;         f32x16 o0 = {}, o1 = {}; float mrun = -INFINITY, lrun = 0.f;
;         const int ntile = 4 * (qblk + 1);
;         const bf16_t* kg = KH + (size_t)(b * T_) * 768 + h * 96; const bf16_t* vg = VT + (size_t)bh * 64 * T_;
;         u32x4 rk0, rk1 = {}, rv;
;         rk0 = *(const u32x4*)(kg + (size_t)k0row * 768 + 8 * k0ch); if (k1on) rk1 = *(const u32x4*)(kg + (size_t)k1row * 768 + 8 * k1ch); rv = *(const u32x4*)(vg + (size_t)vrow * T_ + 8 * vch);
;         *(LAS u32x4*)(sK + k0row * 104 + 8 * k0ch) = rk0; if (k1on) *(LAS u32x4*)(sK + k1row * 104 + 8 * k1ch) = rk1; *(LAS u32x4*)(sVt + vrow * 72 + 8 * vch) = rv;
;         __syncthreads();
;         for (int kt = 0; kt < ntile; ++kt) { const int kv0 = kt * 64; const int buf = kt & 1;
;             if (kt + 1 < ntile) { const int kn = kv0 + 64;
;                 rk0 = *(const u32x4*)(kg + (size_t)(kn + k0row) * 768 + 8 * k0ch); if (k1on) rk1 = *(const u32x4*)(kg + (size_t)(kn + k1row) * 768 + 8 * k1ch); rv = *(const u32x4*)(vg + (size_t)vrow * T_ + kn + 8 * vch); }
.LBB0_114:
	s_or_b64 exec, exec, s[2:3]
	v_mov_b32_e32 v1, s80
	s_waitcnt vmcnt(0) lgkmcnt(0)
	s_barrier
	ds_read_b32 v1, v1 offset:45056
	s_mov_b64 s[2:3], -1
	s_waitcnt lgkmcnt(0)
	s_barrier
	v_cmp_lt_u32_e32 vcc, s0, v1
	v_readfirstlane_b32 s11, v1
	s_cbranch_vccnz .LBB0_111
	s_lshr_b32 s10, s11, 5
	s_lshl_b32 s2, s10, 8
	s_sub_i32 s29, s24, s2
	s_lshl_b32 s2, s11, 10
	s_add_i32 s26, s29, 0x1f00
	s_and_b32 s18, s2, 0x6000
	s_add_i32 s2, s26, s18
	s_and_b32 s25, s11, 7
	v_or_b32_e32 v116, s2, v124
	v_mov_b64_e32 v[2:3], s[12:13]
	v_mad_i64_i32 v[2:3], s[2:3], v116, s50, v[2:3]
	s_mul_i32 s42, s25, 0xc0
	s_mulk_i32 s18, 0x600
	v_lshl_add_u64 v[2:3], v[2:3], 0, s[42:43]
	s_add_u32 s2, s20, s18
	v_lshl_add_u64 v[2:3], v[102:103], 1, v[2:3]
	s_addc_u32 s3, s21, 0
	global_load_dwordx4 v[66:69], v[2:3], off
	global_load_dwordx4 v[70:73], v[2:3], off offset:32
	global_load_dwordx4 v[74:77], v[2:3], off offset:64
	global_load_dwordx4 v[78:81], v[2:3], off offset:96
	global_load_dwordx4 v[82:85], v[2:3], off offset:128
	global_load_dwordx4 v[86:89], v[2:3], off offset:160
	s_add_u32 s2, s2, s42
	s_addc_u32 s3, s3, 0
	v_lshl_add_u64 v[2:3], s[2:3], 0, v[104:105]
	v_lshl_add_u64 v[2:3], v[106:107], 1, v[2:3]
	global_load_dwordx4 v[90:93], v[2:3], off
	v_mov_b32_e32 v2, v0
	v_mov_b32_e32 v3, v0
	v_mov_b32_e32 v1, v0
	v_mov_b64_e32 v[96:97], v[2:3]
	v_mov_b64_e32 v[94:95], v[0:1]
	s_and_saveexec_b64 s[18:19], s[6:7]
	s_cbranch_execz .LBB0_117
	v_lshl_add_u64 v[2:3], s[2:3], 0, v[108:109]
	v_lshl_add_u64 v[2:3], v[110:111], 1, v[2:3]
	global_load_dwordx4 v[94:97], v[2:3], off
.LBB0_117:
	s_or_b64 exec, exec, s[18:19]
	s_lshl_b32 s11, s11, 20
	s_and_b32 s42, s11, 0x1f00000
	v_lshl_add_u64 v[118:119], v[114:115], 0, s[42:43]
	global_load_dwordx4 v[98:101], v[118:119], off
	s_waitcnt vmcnt(0) lgkmcnt(0)
	ds_write_b128 v126, v[90:93]
	s_and_saveexec_b64 s[18:19], s[6:7]
	ds_write_b128 v134, v[94:97]
	s_or_b64 exec, exec, s[18:19]
	v_mov_b32_e32 v14, v0
	v_mov_b32_e32 v15, v0
	v_mov_b32_e32 v1, v0
	v_mov_b32_e32 v2, v0
	v_mov_b32_e32 v3, v0
	v_mov_b32_e32 v4, v0
	v_mov_b32_e32 v5, v0
	v_mov_b32_e32 v6, v0
	v_mov_b32_e32 v7, v0
	v_mov_b32_e32 v8, v0
	v_mov_b32_e32 v9, v0
	v_mov_b32_e32 v10, v0
	v_mov_b32_e32 v11, v0
	v_mov_b32_e32 v12, v0
	v_mov_b32_e32 v13, v0
	v_mov_b64_e32 v[32:33], v[14:15]
	s_lshl_b32 s10, s10, 2
	s_mov_b32 s42, 0
	v_mov_b64_e32 v[30:31], v[12:13]
	v_mov_b64_e32 v[28:29], v[10:11]
	v_mov_b64_e32 v[26:27], v[8:9]
	v_mov_b64_e32 v[24:25], v[6:7]
	v_mov_b64_e32 v[22:23], v[4:5]
	v_mov_b64_e32 v[20:21], v[2:3]
	v_mov_b64_e32 v[18:19], v[0:1]
	v_mov_b64_e32 v[16:17], v[14:15]
	v_ashrrev_i32_e32 v117, 31, v116
	s_sub_i32 s27, 0x80, s10
	v_lshl_add_u64 v[120:121], v[106:107], 1, s[2:3]
	v_lshl_add_u64 v[122:123], v[110:111], 1, s[2:3]
	s_addk_i32 s29, 0x1f1f
	v_or_b32_e32 v135, s26, v124
	v_mov_b32_e32 v136, 0
	v_mov_b32_e32 v137, 0xff800000
	v_mov_b64_e32 v[14:15], v[12:13]
	v_mov_b64_e32 v[12:13], v[10:11]
	v_mov_b64_e32 v[10:11], v[8:9]
	v_mov_b64_e32 v[8:9], v[6:7]
	v_mov_b64_e32 v[6:7], v[4:5]
	v_mov_b64_e32 v[4:5], v[2:3]
	v_mov_b64_e32 v[2:3], v[0:1]
	s_mov_b32 s10, s42
	ds_write_b128 v129, v[98:101] offset:26624
	s_waitcnt lgkmcnt(0)
	s_barrier
.LBB0_120:
	s_add_i32 s31, s10, 1
	s_cmp_lt_u32 s31, s27
	s_cselect_b64 s[2:3], -1, 0
	s_cmp_ge_u32 s31, s27
	s_cbranch_scc1 .LBB0_124
	v_add_u32_e32 v1, s42, v133
	v_mad_i64_i32 v[34:35], s[18:19], v1, s50, v[120:121]
	s_waitcnt vmcnt(0)
	global_load_dwordx4 v[90:93], v[34:35], off
	s_and_saveexec_b64 s[18:19], s[6:7]
	s_cbranch_execz .LBB0_123
	v_add_u32_e32 v1, s42, v132
	v_mad_i64_i32 v[34:35], s[34:35], v1, s50, v[122:123]
	global_load_dwordx4 v[94:97], v[34:35], off
.LBB0_123:
	s_or_b64 exec, exec, s[18:19]
	v_lshl_add_u64 v[34:35], s[42:43], 1, v[118:119]
	global_load_dwordx4 v[98:101], v[34:35], off offset:128
; #define LAS __attribute__((address_space(3)))
; __device__ __forceinline__ int crow(int r, int hi) { return (r & 3) + 8 * (r >> 2) + 4 * hi; }
; #define PV_STEP(OACC, mm, ktt, ss, PF) do { OACC = __builtin_amdgcn_mfma_f32_32x32x16_bf16(ldA_perm(vb + (mm) * 32 * 72 + 32 * (ktt) + 16 * (ss)), PF, OACC, 0, 0, 0); } while (0)
; __device__ __forceinline__ void attn_phase(const Ctx& c, const Params& p, int o, int first, int cidx) {
;     ...
;             if (kv0 <= qs + 31) {
;                 const LAS bf16_t* kb = sK + buf * 6656 + l31 * 104 + 8 * hh; const LAS bf16_t* vb = sVt + buf * 4608 + l31 * 72 + 4 * hh;
;                 f32x16 p0 = {}, p1 = {};
; #pragma unroll
;                 for (int ks = 0; ks < 6; ++ks) { const bf16x8 k0 = *(const LAS bf16x8*)(kb + 16 * ks); const bf16x8 k1 = *(const LAS bf16x8*)(kb + 32 * 104 + 16 * ks);
;                     p0 = __builtin_amdgcn_mfma_f32_32x32x16_bf16(k0, qf[ks], p0, 0, 0, 0); p1 = __builtin_amdgcn_mfma_f32_32x32x16_bf16(k1, qf[ks], p1, 0, 0, 0); }
;                 if (kv0 + 63 > qs) { const int q = qs + l31;
; #pragma unroll
;                     for (int r = 0; r < 16; ++r) { const int kv = kv0 + crow(r, hh); if (kv > q) p0[r] = -INFINITY; if (kv + 32 > q) p1[r] = -INFINITY; } }
;     ...
;                 PV_STEP(o0, 0, 0, 0, pf00); PV_STEP(o0, 0, 0, 1, pf01); PV_STEP(o0, 0, 1, 0, pf10); PV_STEP(o0, 0, 1, 1, pf11);
;                 PV_STEP(o1, 1, 0, 0, pf00); PV_STEP(o1, 1, 0, 1, pf01); PV_STEP(o1, 1, 1, 0, pf10); PV_STEP(o1, 1, 1, 1, pf11);
.LBB0_124:
	s_and_b32 s18, s10, 1
	s_cmp_gt_i32 s42, s29
	s_cbranch_scc1 .LBB0_130
	s_mul_i32 s10, s18, 0x3400
	s_mul_i32 s11, s18, 0x2400
	v_add_u32_e32 v1, s10, v130
	v_add_u32_e32 v142, s11, v131
	ds_read_b128 v[200:203], v1
	ds_read_b128 v[204:207], v1 offset:6656
	ds_read_b128 v[208:211], v1 offset:32
	ds_read_b128 v[212:215], v1 offset:6688
	ds_read_b128 v[216:219], v1 offset:64
	ds_read_b128 v[220:223], v1 offset:6720
	ds_read_b128 v[224:227], v1 offset:96
	ds_read_b128 v[228:231], v1 offset:6752
	ds_read_b128 v[232:235], v1 offset:128
	ds_read_b128 v[236:239], v1 offset:6784
	ds_read_b128 v[240:243], v1 offset:160
	ds_read_b128 v[244:247], v1 offset:6816
	v_add_u32_e32 v143, 0x7a00, v142
	v_add_u32_e32 v142, 0x6800, v142
	s_add_i32 s10, s42, 63
	s_cmp_le_i32 s10, s26
	s_waitcnt lgkmcnt(10)
	v_mfma_f32_32x32x16_bf16 v[50:65], v[200:203], v[66:69], 0
	v_mfma_f32_32x32x16_bf16 v[34:49], v[204:207], v[66:69], 0
	ds_read2_b64 v[200:203], v142 offset1:2
	ds_read2_b64 v[204:207], v142 offset0:4 offset1:6
	s_waitcnt lgkmcnt(10)
	v_mfma_f32_32x32x16_bf16 v[50:65], v[208:211], v[70:73], v[50:65]
	v_mfma_f32_32x32x16_bf16 v[34:49], v[212:215], v[70:73], v[34:49]
	ds_read2_b64 v[208:211], v142 offset0:8 offset1:10
	ds_read2_b64 v[212:215], v142 offset0:12 offset1:14
	s_waitcnt lgkmcnt(10)
	v_mfma_f32_32x32x16_bf16 v[50:65], v[216:219], v[74:77], v[50:65]
	v_mfma_f32_32x32x16_bf16 v[34:49], v[220:223], v[74:77], v[34:49]
	ds_read2_b64 v[216:219], v143 offset1:2
	ds_read2_b64 v[220:223], v143 offset0:4 offset1:6
	s_waitcnt lgkmcnt(10)
	v_mfma_f32_32x32x16_bf16 v[50:65], v[224:227], v[78:81], v[50:65]
	v_mfma_f32_32x32x16_bf16 v[34:49], v[228:231], v[78:81], v[34:49]
	ds_read2_b64 v[224:227], v143 offset0:8 offset1:10
	ds_read2_b64 v[228:231], v143 offset0:12 offset1:14
	s_waitcnt lgkmcnt(10)
	v_mfma_f32_32x32x16_bf16 v[50:65], v[232:235], v[82:85], v[50:65]
	v_mfma_f32_32x32x16_bf16 v[34:49], v[236:239], v[82:85], v[34:49]
	s_waitcnt lgkmcnt(8)
	v_mfma_f32_32x32x16_bf16 v[50:65], v[240:243], v[86:89], v[50:65]
	v_mfma_f32_32x32x16_bf16 v[34:49], v[244:247], v[86:89], v[34:49]
	s_cbranch_scc1 .LBB0_127
	v_add_u32_e32 v1, s42, v112
	v_add_u32_e32 v138, 32, v1
	v_cmp_le_i32_e32 vcc, v138, v135
	v_add_u32_e32 v138, 33, v1
	s_nop 6
	v_cndmask_b32_e32 v34, v173, v34, vcc
	v_cmp_lt_i32_e32 vcc, v1, v135
	s_nop 1
	v_cndmask_b32_e32 v51, v173, v51, vcc
	v_cmp_le_i32_e32 vcc, v1, v135
	s_nop 1
	v_cndmask_b32_e32 v50, v173, v50, vcc
	v_cmp_le_i32_e32 vcc, v138, v135
	v_add_u32_e32 v138, 2, v1
	s_nop 0
	v_cndmask_b32_e32 v35, v173, v35, vcc
	v_cmp_le_i32_e32 vcc, v138, v135
	v_add_u32_e32 v138, 34, v1
	s_nop 0
	v_cndmask_b32_e32 v52, v173, v52, vcc
	v_cmp_le_i32_e32 vcc, v138, v135
	v_add_u32_e32 v138, 3, v1
	s_nop 0
	v_cndmask_b32_e32 v36, v173, v36, vcc
	v_cmp_le_i32_e32 vcc, v138, v135
	v_add_u32_e32 v138, 35, v1
	s_nop 0
	v_cndmask_b32_e32 v53, v173, v53, vcc
	v_cmp_le_i32_e32 vcc, v138, v135
	v_add_u32_e32 v138, 8, v1
	s_nop 0
	v_cndmask_b32_e32 v37, v173, v37, vcc
	v_cmp_le_i32_e32 vcc, v138, v135
	v_add_u32_e32 v138, 40, v1
	s_nop 0
	v_cndmask_b32_e32 v54, v173, v54, vcc
	v_cmp_le_i32_e32 vcc, v138, v135
	v_add_u32_e32 v138, 9, v1
	s_nop 0
	v_cndmask_b32_e32 v38, v173, v38, vcc
	v_cmp_le_i32_e32 vcc, v138, v135
	v_add_u32_e32 v138, 41, v1
	s_nop 0
	v_cndmask_b32_e32 v55, v173, v55, vcc
	v_cmp_le_i32_e32 vcc, v138, v135
	v_add_u32_e32 v138, 10, v1
	s_nop 0
	v_cndmask_b32_e32 v39, v173, v39, vcc
	v_cmp_le_i32_e32 vcc, v138, v135
	v_add_u32_e32 v138, 42, v1
	s_nop 0
	v_cndmask_b32_e32 v56, v173, v56, vcc
	v_cmp_le_i32_e32 vcc, v138, v135
	v_add_u32_e32 v138, 11, v1
	s_nop 0
	v_cndmask_b32_e32 v40, v173, v40, vcc
	v_cmp_le_i32_e32 vcc, v138, v135
	v_add_u32_e32 v138, 43, v1
	s_nop 0
	v_cndmask_b32_e32 v57, v173, v57, vcc
	v_cmp_le_i32_e32 vcc, v138, v135
	v_add_u32_e32 v138, 16, v1
	s_nop 0
	v_cndmask_b32_e32 v41, v173, v41, vcc
	v_cmp_le_i32_e32 vcc, v138, v135
	v_add_u32_e32 v138, 48, v1
	s_nop 0
	v_cndmask_b32_e32 v58, v173, v58, vcc
	v_cmp_le_i32_e32 vcc, v138, v135
	v_add_u32_e32 v138, 17, v1
	s_nop 0
	v_cndmask_b32_e32 v42, v173, v42, vcc
	v_cmp_le_i32_e32 vcc, v138, v135
	v_add_u32_e32 v138, 49, v1
	s_nop 0
	v_cndmask_b32_e32 v59, v173, v59, vcc
	v_cmp_le_i32_e32 vcc, v138, v135
	v_add_u32_e32 v138, 18, v1
	s_nop 0
	v_cndmask_b32_e32 v43, v173, v43, vcc
	v_cmp_le_i32_e32 vcc, v138, v135
	v_add_u32_e32 v138, 50, v1
	s_nop 0
	v_cndmask_b32_e32 v60, v173, v60, vcc
	v_cmp_le_i32_e32 vcc, v138, v135
	v_add_u32_e32 v138, 19, v1
	s_nop 0
	v_cndmask_b32_e32 v44, v173, v44, vcc
	v_cmp_le_i32_e32 vcc, v138, v135
	v_add_u32_e32 v138, 51, v1
	s_nop 0
	v_cndmask_b32_e32 v61, v173, v61, vcc
	v_cmp_le_i32_e32 vcc, v138, v135
	v_add_u32_e32 v138, 24, v1
	s_nop 0
	v_cndmask_b32_e32 v45, v173, v45, vcc
	v_cmp_le_i32_e32 vcc, v138, v135
	v_add_u32_e32 v138, 56, v1
	s_nop 0
	v_cndmask_b32_e32 v62, v173, v62, vcc
	v_cmp_le_i32_e32 vcc, v138, v135
	v_add_u32_e32 v138, 25, v1
	s_nop 0
	v_cndmask_b32_e32 v46, v173, v46, vcc
	v_cmp_le_i32_e32 vcc, v138, v135
	v_add_u32_e32 v138, 57, v1
	s_nop 0
	v_cndmask_b32_e32 v63, v173, v63, vcc
	v_cmp_le_i32_e32 vcc, v138, v135
	v_add_u32_e32 v138, 26, v1
	s_nop 0
	v_cndmask_b32_e32 v47, v173, v47, vcc
	v_cmp_le_i32_e32 vcc, v138, v135
	v_add_u32_e32 v138, 58, v1
	s_nop 0
	v_cndmask_b32_e32 v64, v173, v64, vcc
	v_cmp_le_i32_e32 vcc, v138, v135
	v_add_u32_e32 v138, 27, v1
	v_add_u32_e32 v1, 59, v1
	v_cndmask_b32_e32 v48, v173, v48, vcc
	v_cmp_le_i32_e32 vcc, v138, v135
	s_nop 1
	v_cndmask_b32_e32 v65, v173, v65, vcc
	v_cmp_le_i32_e32 vcc, v1, v135
	s_nop 1
	v_cndmask_b32_e32 v49, v173, v49, vcc

; #define PV_STEP(OACC, mm, ktt, ss, PF) do { OACC = __builtin_amdgcn_mfma_f32_32x32x16_bf16(ldA_perm(vb + (mm) * 32 * 72 + 32 * (ktt) + 16 * (ss)), PF, OACC, 0, 0, 0); } while (0)
; __device__ __forceinline__ void attn_phase(const Ctx& c, const Params& p, int o, int first, int cidx) {
;     ...
;                 float mxa = fmaxf(fmaxf(p0[0], p1[0]), p0[1]), mxb = fmaxf(fmaxf(p1[1], p0[2]), p1[2]);
; #pragma unroll
;                 for (int r = 3; r < 15; r += 2) { mxa = fmaxf(fmaxf(mxa, p0[r]), p1[r]); mxb = fmaxf(fmaxf(mxb, p0[r + 1]), p1[r + 1]); }
;                 float mx = fmaxf(fmaxf(mxa, mxb), fmaxf(p0[15], p1[15]));
;                 { auto rr = __builtin_amdgcn_permlane32_swap(asu(mx), asu(mx), false, false); mx = fmaxf(asf(rr[0]), asf(rr[1])); }
;                 const float mnew = fmaxf(mrun, mx);
;                 if (__any(mnew > mrun)) { const float alpha = __builtin_amdgcn_exp2f(mrun - mnew); lrun *= alpha; o0 = o0 * alpha; o1 = o1 * alpha; }
;                 mrun = mnew;
;                 f32x16 e0, e1;
; #pragma unroll
;                 for (int r = 0; r < 16; ++r) { e0[r] = __builtin_amdgcn_exp2f(p0[r] - mnew); e1[r] = __builtin_amdgcn_exp2f(p1[r] - mnew); }
;                 p0 = e0; p1 = e1;
;                 { const f32x16 t = e0 + e1; lrun += ((t[0] + t[1]) + (t[2] + t[3])) + ((t[4] + t[5]) + (t[6] + t[7])) + ((t[8] + t[9]) + (t[10] + t[11])) + ((t[12] + t[13]) + (t[14] + t[15])); }
;                 const bf16x8 pf00 = pkfrag(p0, 0), pf01 = pkfrag(p0, 1), pf10 = pkfrag(p1, 0), pf11 = pkfrag(p1, 1);
;     ...
;                 PV_STEP(o0, 0, 0, 0, pf00); PV_STEP(o0, 0, 0, 1, pf01); PV_STEP(o0, 0, 1, 0, pf10); PV_STEP(o0, 0, 1, 1, pf11);
;                 PV_STEP(o1, 1, 0, 0, pf00); PV_STEP(o1, 1, 0, 1, pf01); PV_STEP(o1, 1, 1, 0, pf10); PV_STEP(o1, 1, 1, 1, pf11);
.LBB0_129:
	v_sub_f32_e32 v38, v38, v1
	v_exp_f32_e32 v138, v38
	v_sub_f32_e32 v38, v55, v1
	v_exp_f32_e32 v55, v38
	v_sub_f32_e32 v38, v39, v1
	v_sub_f32_e32 v39, v40, v1
	v_sub_f32_e32 v40, v41, v1
	v_sub_f32_e32 v41, v42, v1
	v_sub_f32_e32 v42, v43, v1
	v_exp_f32_e32 v139, v38
	v_sub_f32_e32 v38, v56, v1
	v_exp_f32_e32 v56, v39
	v_sub_f32_e32 v39, v57, v1
	v_exp_f32_e32 v57, v40
	v_sub_f32_e32 v40, v58, v1
	v_exp_f32_e32 v58, v41
	v_sub_f32_e32 v41, v59, v1
	v_exp_f32_e32 v59, v42
	v_sub_f32_e32 v42, v60, v1
	v_exp_f32_e32 v60, v42
	v_sub_f32_e32 v42, v44, v1
	v_exp_f32_e32 v140, v42
	v_sub_f32_e32 v42, v61, v1
	v_exp_f32_e32 v61, v42
	v_sub_f32_e32 v42, v45, v1
	v_exp_f32_e32 v141, v42
	v_sub_f32_e32 v42, v62, v1
	v_exp_f32_e32 v44, v42
	v_sub_f32_e32 v42, v46, v1
	v_exp_f32_e32 v62, v42
	v_sub_f32_e32 v42, v63, v1
	v_sub_f32_e32 v50, v50, v1
	v_sub_f32_e32 v34, v34, v1
	v_sub_f32_e32 v51, v51, v1
	v_sub_f32_e32 v35, v35, v1
	v_sub_f32_e32 v52, v52, v1
	v_sub_f32_e32 v36, v36, v1
	v_sub_f32_e32 v53, v53, v1
	v_sub_f32_e32 v37, v37, v1
	v_exp_f32_e32 v45, v42
	v_sub_f32_e32 v42, v47, v1
	v_exp_f32_e32 v50, v50
	v_exp_f32_e32 v34, v34
	v_exp_f32_e32 v51, v51
	v_exp_f32_e32 v35, v35
	v_exp_f32_e32 v52, v52
	v_exp_f32_e32 v36, v36
	v_exp_f32_e32 v53, v53
	v_exp_f32_e32 v37, v37
	v_sub_f32_e32 v54, v54, v1
	v_exp_f32_e32 v63, v42
	v_sub_f32_e32 v42, v64, v1
	v_exp_f32_e32 v54, v54
	v_exp_f32_e32 v38, v38
	v_exp_f32_e32 v39, v39
	v_exp_f32_e32 v64, v42
	v_sub_f32_e32 v42, v48, v1
	v_exp_f32_e32 v142, v42
	v_sub_f32_e32 v42, v65, v1
	v_exp_f32_e32 v65, v42
	v_sub_f32_e32 v42, v49, v1
	v_exp_f32_e32 v40, v40
	v_exp_f32_e32 v41, v41
	v_exp_f32_e32 v143, v42
	v_pk_add_f32 v[184:185], v[52:53], v[36:37]
	v_pk_add_f32 v[186:187], v[50:51], v[34:35]
	v_pk_add_f32 v[170:171], v[38:39], v[56:57]
	v_pk_add_f32 v[174:175], v[54:55], v[138:139]
	v_pk_mov_b32 v[188:189], v[186:187], v[184:185] op_sel:[1,0]
	v_mov_b32_e32 v187, v185
	v_pk_add_f32 v[184:185], v[188:189], v[186:187]
	v_pk_mov_b32 v[186:187], v[174:175], v[170:171] op_sel:[1,0]
	v_mov_b32_e32 v175, v171
	v_pk_add_f32 v[170:171], v[186:187], v[174:175]
	v_pk_add_f32 v[42:43], v[64:65], v[142:143]
	v_pk_add_f32 v[46:47], v[44:45], v[62:63]
	v_pk_add_f32 v[48:49], v[60:61], v[140:141]
	v_pk_add_f32 v[168:169], v[40:41], v[58:59]
	v_pk_add_f32 v[184:185], v[184:185], v[184:185] op_sel_hi:[0,1]
	v_pk_add_f32 v[170:171], v[170:171], v[170:171] op_sel_hi:[0,1]
	v_add_f32_e32 v169, v168, v169
	v_add_f32_e32 v49, v48, v49
	v_mov_b32_e32 v168, v46
	v_mov_b32_e32 v48, v47
	v_mov_b32_e32 v184, v42
	v_mov_b32_e32 v170, v43
	s_mul_i32 s10, s18, 0x2400
	v_pk_add_f32 v[46:47], v[168:169], v[48:49]
	v_pk_add_f32 v[42:43], v[184:185], v[170:171]
	v_cvt_pk_bf16_f32 v49, v38, v39
	v_pk_add_f32 v[42:43], v[46:47], v[42:43]
	v_cvt_pk_bf16_f32 v38, v34, v35
	v_cvt_pk_bf16_f32 v34, v58, v59
	v_add_u32_e32 v58, s10, v131
	v_add_f32_e32 v42, v42, v43
	v_add_u32_e32 v59, 0x6800, v58
	v_add_f32_e32 v136, v42, v136
	v_cvt_pk_bf16_f32 v46, v50, v51
	v_cvt_pk_bf16_f32 v47, v52, v53
	v_cvt_pk_bf16_f32 v48, v54, v55
	v_cvt_pk_bf16_f32 v42, v40, v41
	v_cvt_pk_bf16_f32 v41, v56, v57
	s_waitcnt lgkmcnt(0)
	v_mfma_f32_32x32x16_bf16 v[18:33], v[200:203], v[46:49], v[18:33]
	v_cvt_pk_bf16_f32 v43, v60, v61
	v_cvt_pk_bf16_f32 v44, v44, v45
	v_cvt_pk_bf16_f32 v45, v64, v65
	v_cvt_pk_bf16_f32 v39, v36, v37
	v_cvt_pk_bf16_f32 v40, v138, v139
	v_cvt_pk_bf16_f32 v35, v140, v141
	v_cvt_pk_bf16_f32 v36, v62, v63
	v_cvt_pk_bf16_f32 v37, v142, v143
	v_mfma_f32_32x32x16_bf16 v[2:17], v[216:219], v[46:49], v[2:17]
	v_mfma_f32_32x32x16_bf16 v[18:33], v[204:207], v[42:45], v[18:33]
	v_mfma_f32_32x32x16_bf16 v[2:17], v[220:223], v[42:45], v[2:17]
	v_mfma_f32_32x32x16_bf16 v[18:33], v[208:211], v[38:41], v[18:33]
	v_mfma_f32_32x32x16_bf16 v[2:17], v[224:227], v[38:41], v[2:17]
	v_mfma_f32_32x32x16_bf16 v[18:33], v[212:215], v[34:37], v[18:33]
	v_mfma_f32_32x32x16_bf16 v[2:17], v[228:231], v[34:37], v[2:17]
	s_andn2_b64 vcc, exec, s[2:3]
	s_cbranch_vccz .LBB0_131
	s_branch .LBB0_134

; __device__ __forceinline__ void rwkv_prep(const Ctx& c, const Params& p, int o) {
;     ...
;     for (int item = c.gw; item < 2048; item += c.ngw) { const int rg = item >> 1, hf = item & 1, m0 = 32 * rg; const bool seq0 = (rg & 255) == 0;
;         int ln_ = c.lane; asm volatile("" : "+v"(ln_));
;         const int h = 4 * hf + (ln_ >> 4), c4 = h * 64 + 4 * (ln_ & 15);
;         const f32x4 mur = *(const f32x4*)(mu + c4), muk = *(const f32x4*)(mu + 512 + c4), muv = *(const f32x4*)(mu + 1024 + c4), w0c = *(const f32x4*)(w0 + c4), a0c = *(const f32x4*)(a0 + c4);
;         const f32x4 kkc = *(const f32x4*)(k_k + c4), kac = *(const f32x4*)(k_a + c4), v0c = *(const f32x4*)(v0p + c4), rkc = *(const f32x4*)(r_k + c4);
;         u32x2 cr, ck, cv, pr, pk, pv, wl, al, vl = {}, vf = {};
;         { const bf16_t* zr = RKV + (size_t)(m0 + 31) * RKV_LD + c4; cr = *(const u32x2*)zr; ck = *(const u32x2*)(zr + 512); cv = *(const u32x2*)(zr + 1024);
;           const bf16_t* zq = zr - RKV_LD; pr = *(const u32x2*)zq; pk = *(const u32x2*)(zq + 512); pv = *(const u32x2*)(zq + 1024);
;           const bf16_t* lo = LO + (size_t)(m0 + 31) * 2048 + c4; wl = *(const u32x2*)lo; al = *(const u32x2*)(lo + 512); if (o) { vl = *(const u32x2*)(lo + 1536); vf = *(const u32x2*)(VF + (size_t)(m0 + 31) * 512 + c4); } }
.LBB0_141:
	s_ashr_i32 s10, s42, 1
	v_mov_b32_e32 v2, v164
	s_lshl_b32 s6, s42, 2
	s_lshl_b32 s86, s10, 5
	s_and_b32 s6, s6, 4
	v_ashrrev_i32_e32 v1, 4, v2
	s_waitcnt vmcnt(0)
	v_and_b32_e32 v39, 15, v2
	v_add_u32_e32 v38, s6, v1
	v_lshlrev_b32_e32 v54, 2, v39
	s_or_b32 s8, s86, 31
	v_lshl_or_b32 v40, v38, 6, v54
	s_ashr_i32 s9, s8, 31
	s_mul_i32 s6, s8, 0xc00
	v_ashrrev_i32_e32 v41, 31, v40
	s_mul_hi_i32 s7, s8, 0xc00
	s_add_u32 s6, s16, s6
	s_addc_u32 s7, s17, s7
	v_lshlrev_b64 v[46:47], 1, v[40:41]
	v_lshl_add_u64 v[42:43], s[6:7], 0, v[46:47]
	s_movk_i32 s6, 0xf400
	v_lshlrev_b64 v[34:35], 2, v[40:41]
	v_add_co_u32_e32 v44, vcc, s6, v42
	v_lshl_add_u64 v[6:7], s[2:3], 0, v[34:35]
	v_lshl_add_u64 v[10:11], s[92:93], 0, v[34:35]
	v_lshl_add_u64 v[14:15], s[26:27], 0, v[34:35]
	v_lshl_add_u64 v[18:19], s[40:41], 0, v[34:35]
	v_lshl_add_u64 v[22:23], s[44:45], 0, v[34:35]
	v_lshl_add_u64 v[26:27], s[80:81], 0, v[34:35]
	v_lshl_add_u64 v[30:31], s[84:85], 0, v[34:35]
	v_lshl_add_u64 v[34:35], s[82:83], 0, v[34:35]
	v_addc_co_u32_e32 v45, vcc, -1, v43, vcc
	s_movk_i32 s6, 0xf800
	global_load_dwordx4 v[2:5], v[6:7], off
	s_nop 0
	global_load_dwordx4 v[6:9], v[6:7], off offset:2048
	v_readlane_b32 s12, v255, 24
	global_load_dwordx4 v[10:13], v[10:11], off
	v_readlane_b32 s13, v255, 25
	global_load_dwordx4 v[14:17], v[14:15], off
	s_waitcnt lgkmcnt(0)
	v_mov_b32_e32 v76, 0
	global_load_dwordx4 v[18:21], v[18:19], off
	v_mov_b32_e32 v77, 0
	global_load_dwordx4 v[22:25], v[22:23], off
	v_mov_b32_e32 v78, 0
	global_load_dwordx4 v[26:29], v[26:27], off
	v_mov_b32_e32 v79, 0
	global_load_dwordx4 v[30:33], v[30:31], off
	s_nop 0
	global_load_dwordx4 v[34:37], v[34:35], off
	s_nop 0
	global_load_dwordx2 v[90:91], v[42:43], off
	global_load_dwordx2 v[88:89], v[42:43], off offset:1024
	global_load_dwordx2 v[80:81], v[42:43], off offset:2048
	global_load_dwordx2 v[66:67], v[44:45], off
	v_add_co_u32_e32 v44, vcc, s6, v42
	s_movk_i32 s6, 0xfc00
	s_nop 0
	v_addc_co_u32_e32 v45, vcc, -1, v43, vcc
	v_add_co_u32_e32 v42, vcc, s6, v42
	s_lshl_b64 s[6:7], s[8:9], 12
	s_add_u32 s6, s14, s6
	v_addc_co_u32_e32 v43, vcc, -1, v43, vcc
	s_addc_u32 s7, s15, s7
	global_load_dwordx2 v[68:69], v[44:45], off
	global_load_dwordx2 v[70:71], v[42:43], off
	v_lshl_add_u64 v[42:43], s[6:7], 0, v[46:47]
	global_load_dwordx2 v[56:57], v[42:43], off
	global_load_dwordx2 v[74:75], v[42:43], off offset:1024
	v_cndmask_b32_e64 v44, 0, 1, s[12:13]
	v_cmp_ne_u32_e64 s[6:7], 1, v44
	s_andn2_b64 vcc, exec, s[12:13]
	s_cbranch_vccnz .LBB0_143
	s_lshl_b64 s[8:9], s[8:9], 10
	s_add_u32 s8, s18, s8
	s_addc_u32 s9, s19, s9
	v_lshl_add_u64 v[40:41], v[40:41], 1, s[8:9]
	global_load_dwordx2 v[78:79], v[42:43], off offset:3072
	global_load_dwordx2 v[76:77], v[40:41], off

; __device__ __forceinline__ void rwkv_prep(const Ctx& c, const Params& p, int o) {
;     ...
;             if (tt >= 2) { const bf16_t* zq = RKV + (size_t)(m - 2) * RKV_LD + c4; qr = *(const u32x2*)zq; qk = *(const u32x2*)(zq + 512); qv = *(const u32x2*)(zq + 1024); }
;             else if (tt == 1 && !seq0) { const bf16_t* zq = BND + (size_t)rg * 1536 + c4; qr = *(const u32x2*)zq; qk = *(const u32x2*)(zq + 512); qv = *(const u32x2*)(zq + 1024); }
;             if (tt >= 1) { const bf16_t* ln = LO + (size_t)(m - 1) * 2048 + c4; nwl = *(const u32x2*)ln; nal = *(const u32x2*)(ln + 512); if (o) { nvl = *(const u32x2*)(ln + 1536); nvf = *(const u32x2*)(VF + (size_t)(m - 1) * 512 + c4); } }
;             const bool has_prev = (tt > 0) || !seq0;
.LBB0_145:
	s_add_i32 s11, s34, 31
	s_cmp_lt_u32 s11, 2
	s_mov_b64 s[12:13], -1
	s_cbranch_scc0 .LBB0_148
	s_cmpk_lg_i32 s34, 0xffe2
	s_cselect_b64 s[12:13], -1, 0
	s_or_b64 s[12:13], s[72:73], s[12:13]
	s_and_b64 vcc, exec, s[12:13]
	s_cbranch_vccnz .LBB0_176
	global_load_dwordx2 v[62:63], v[48:49], off
	global_load_dwordx2 v[60:61], v[48:49], off offset:1024
	global_load_dwordx2 v[58:59], v[48:49], off offset:2048
	s_mov_b64 s[12:13], 0

; __device__ __forceinline__ void rwkv_prep(const Ctx& c, const Params& p, int o) {
;     ...
;             u32x2 qr = {}, qk = {}, qv = {}, nwl = {}, nal = {}, nvl = {}, nvf = {};
;             if (tt >= 2) { const bf16_t* zq = RKV + (size_t)(m - 2) * RKV_LD + c4; qr = *(const u32x2*)zq; qk = *(const u32x2*)(zq + 512); qv = *(const u32x2*)(zq + 1024); }
;             else if (tt == 1 && !seq0) { const bf16_t* zq = BND + (size_t)rg * 1536 + c4; qr = *(const u32x2*)zq; qk = *(const u32x2*)(zq + 512); qv = *(const u32x2*)(zq + 1024); }
;             if (tt >= 1) { const bf16_t* ln = LO + (size_t)(m - 1) * 2048 + c4; nwl = *(const u32x2*)ln; nal = *(const u32x2*)(ln + 512); if (o) { nvl = *(const u32x2*)(ln + 1536); nvf = *(const u32x2*)(VF + (size_t)(m - 1) * 512 + c4); } }
.LBB0_149:
	s_add_i32 s11, s86, s34
	s_add_i32 s11, s11, 29
	v_mad_i64_i32 v[26:27], s[12:13], s11, v172, v[40:41]
	s_waitcnt vmcnt(0) lgkmcnt(0)
	global_load_dwordx2 v[62:63], v[26:27], off
	global_load_dwordx2 v[60:61], v[26:27], off offset:1024
	global_load_dwordx2 v[58:59], v[26:27], off offset:2048
.LBB0_150:
	v_lshl_add_u64 v[26:27], s[96:97], 0, v[54:55]
	v_add_co_u32_e32 v38, vcc, 0x1491e000, v26
	v_mov_b32_e32 v84, 0
	s_nop 0
	v_addc_co_u32_e32 v39, vcc, 0, v27, vcc
	global_load_dwordx2 v[64:65], v[38:39], off
	global_load_dwordx2 v[82:83], v[38:39], off offset:1024
	s_and_b64 vcc, exec, s[6:7]
	v_lshl_add_u64 v[72:73], s[48:49], 0, v[54:55]
	v_mov_b32_e32 v85, 0
	v_mov_b32_e32 v86, 0
	v_mov_b32_e32 v87, 0
	s_cbranch_vccnz .LBB0_152
	v_add_co_u32_e32 v26, vcc, 0x1491e000, v26
	s_nop 1
	v_addc_co_u32_e32 v27, vcc, 0, v27, vcc
	global_load_dwordx2 v[84:85], v[26:27], off offset:3072
	v_add_co_u32_e32 v26, vcc, 0x6107000, v72
	s_nop 1
	v_addc_co_u32_e32 v27, vcc, 0, v73, vcc
	global_load_dwordx2 v[86:87], v[26:27], off offset:2048

; __device__ __forceinline__ float sigmoidf_(float x) { return __builtin_amdgcn_rcpf(1.f + __expf(-x)); }
; __device__ __forceinline__ float sum16_dpp(float v) { v += dppf<0xB1>(v); v += dppf<0x4E>(v); v += dppf<0x141>(v); v += dppf<0x140>(v); return v; }
; __device__ __forceinline__ u32x2 pack4(const float* f) { u32x2 o; o.x = pk2(f[0], f[1]); o.y = pk2(f[2], f[3]); return o; }
; __device__ __forceinline__ void rwkv_prep(const Ctx& c, const Params& p, int o) {
;     ...
;                 if (o) v = v + (fvf[j] - v) * sigmoidf_(v0c[j] + fvl[j]);
;                 v_[j] = v; bs += r_[j] * kx_[j] * rkc[j]; }
;             ss = sum16_dpp(ss); bs = sum16_dpp(bs);
;             const float rn = rsqrtf(ss + 1e-6f); float kk_[4];
; #pragma unroll
;             for (int j = 0; j < 4; ++j) { kk_[j] = kq_[j] * rn; ka_[j] = kk_[j] * a_[j]; }
;             if (o == 0) *(u32x2*)(VF + (size_t)m * 512 + c4) = pack4(v_);
;             bf16_t* zr = RKV + (size_t)m * RKV_LD + c4; *(u32x2*)zr = pack4(r_); *(u32x2*)(zr + 512) = pack4(kx_); *(u32x2*)(zr + 1024) = pack4(v_);
;             bf16_t* lo = LO + (size_t)m * 2048 + c4; *(u32x2*)lo = pack4(ew_); *(u32x2*)(lo + 512) = pack4(ka_); *(u32x2*)(Y + (size_t)m * D_ + c4) = pack4(kk_);
;             if ((ln_ & 15) == 0) BON[(size_t)m * 8 + h] = bs;
.LBB0_156:
	s_andn2_b64 vcc, exec, s[58:59]
	s_cbranch_vccnz .LBB0_158
	s_add_u32 s11, s86, s34
	s_addc_u32 s13, s87, s35
	s_add_u32 s12, s11, 31
	v_add_co_u32_e32 v104, vcc, 0x6107000, v72
	s_addc_u32 s13, s13, 0
	s_nop 0
	v_addc_co_u32_e32 v105, vcc, 0, v73, vcc
	global_store_dwordx2 v[104:105], v[38:39], off offset:3072
.LBB0_158:
	v_lshlrev_b32_e32 v104, 16, v57
	v_and_b32_e32 v57, 0xffff0000, v57
	v_add_f32_e32 v57, v17, v57
	v_mul_f32_e32 v57, 0xbfb8aa3b, v57
	v_exp_f32_e32 v57, v57
	v_and_b32_e32 v103, 0xffff0000, v56
	v_lshlrev_b32_e32 v56, 16, v56
	v_add_f32_e32 v103, v15, v103
	v_add_f32_e32 v57, 1.0, v57
	v_rcp_f32_e32 v105, v57
	v_add_f32_e32 v57, v89, v102
	v_add_f32_e32 v57, 0x358637bd, v57
	v_mul_f32_e32 v89, 0x4b800000, v57
	v_cmp_gt_f32_e32 vcc, s33, v57
	v_add_f32_e32 v104, v16, v104
	v_add_f32_e32 v56, v14, v56
	v_cndmask_b32_e32 v57, v57, v89, vcc
	v_rsq_f32_e32 v57, v57
	v_mul_f32_e32 v103, 0xbfb8aa3b, v103
	v_mul_f32_e32 v104, 0xbfb8aa3b, v104
	v_mul_f32_e32 v56, 0xbfb8aa3b, v56
	v_exp_f32_e32 v103, v103
	v_exp_f32_e32 v104, v104
	v_exp_f32_e32 v89, v56
	v_mul_f32_e32 v56, 0x45800000, v57
	v_cndmask_b32_e32 v56, v57, v56, vcc
	v_add_f32_e32 v103, 1.0, v103
	v_add_f32_e32 v104, 1.0, v104
	v_pk_mul_f32 v[70:71], v[70:71], v[56:57] op_sel_hi:[1,0]
	v_add_f32_e32 v57, 1.0, v89
	v_rcp_f32_e32 v103, v103
	v_rcp_f32_e32 v104, v104
	v_rcp_f32_e32 v89, v57
	v_pk_mul_f32 v[56:57], v[92:93], v[56:57] op_sel_hi:[1,0]
	v_mad_u64_u32 v[92:93], s[58:59], s12, v172, v[40:41]
	s_mul_i32 s11, s13, 0xc00
	s_mov_b32 s0, 0x3f1b4598
	v_add_u32_e32 v93, s11, v93
	v_cvt_pk_bf16_f32 v100, v1, v100
	v_cvt_pk_bf16_f32 v101, v101, v91
	v_mul_f32_e32 v103, 0x3f1b4598, v103
	v_pk_mul_f32 v[104:105], v[104:105], s[0:1] op_sel_hi:[1,0]
	v_pk_mul_f32 v[68:69], v[68:69], v[70:71]
	v_pk_mul_f32 v[76:77], v[76:77], v[56:57]
	v_mul_f32_e32 v89, 0x3f1b4598, v89
	global_store_dwordx2 v[92:93], v[100:101], off
	v_cvt_pk_bf16_f32 v100, v66, v74
	v_cvt_pk_bf16_f32 v101, v78, v79
	s_lshl_b64 s[58:59], s[12:13], 12
	global_store_dwordx2 v[92:93], v[100:101], off offset:1024
	global_store_dwordx2 v[92:93], v[38:39], off offset:2048
	v_lshl_add_u64 v[38:39], v[42:43], 0, s[58:59]
	v_cvt_pk_bf16_f32 v78, v89, v103
	v_cvt_pk_bf16_f32 v79, v104, v105
	v_cvt_pk_bf16_f32 v68, v68, v69
	v_cvt_pk_bf16_f32 v69, v76, v77
	s_lshl_b64 s[58:59], s[12:13], 11
	global_store_dwordx2 v[38:39], v[78:79], off
	global_store_dwordx2 v[38:39], v[68:69], off offset:1024
	v_cvt_pk_bf16_f32 v38, v70, v71
	v_cvt_pk_bf16_f32 v39, v56, v57
	v_lshl_add_u64 v[56:57], v[46:47], 0, s[58:59]
	global_store_dwordx2 v[56:57], v[38:39], off
	s_and_saveexec_b64 s[58:59], s[8:9]
	s_cbranch_execz .LBB0_160
	s_lshl_b64 s[12:13], s[12:13], 5
	v_add_f32_e32 v1, v67, v75
	v_lshl_add_u64 v[38:39], v[50:51], 0, s[12:13]
	global_store_dword v[38:39], v1, off

; __device__ __forceinline__ void rwkv_prep(const Ctx& c, const Params& p, int o) {
;     ...
;             u32x2 qr = {}, qk = {}, qv = {}, nwl = {}, nal = {}, nvl = {}, nvf = {};
;             if (tt >= 2) { const bf16_t* zq = RKV + (size_t)(m - 2) * RKV_LD + c4; qr = *(const u32x2*)zq; qk = *(const u32x2*)(zq + 512); qv = *(const u32x2*)(zq + 1024); }
;             else if (tt == 1 && !seq0) { const bf16_t* zq = BND + (size_t)rg * 1536 + c4; qr = *(const u32x2*)zq; qk = *(const u32x2*)(zq + 512); qv = *(const u32x2*)(zq + 1024); }
;             if (tt >= 1) { const bf16_t* ln = LO + (size_t)(m - 1) * 2048 + c4; nwl = *(const u32x2*)ln; nal = *(const u32x2*)(ln + 512); if (o) { nvl = *(const u32x2*)(ln + 1536); nvf = *(const u32x2*)(VF + (size_t)(m - 1) * 512 + c4); } }
.LBB0_162:
	s_andn2_b64 vcc, exec, s[12:13]
	s_cbranch_vccnz .LBB0_165
	s_add_i32 s12, s86, s34
	s_add_i32 s12, s12, 28
	v_mad_i64_i32 v[38:39], s[12:13], s12, v172, v[40:41]
	global_load_dwordx2 v[66:67], v[38:39], off
	global_load_dwordx2 v[68:69], v[38:39], off offset:1024
	global_load_dwordx2 v[70:71], v[38:39], off offset:2048
	s_cmpk_eq_i32 s34, 0xffe2
	s_cbranch_scc0 .LBB0_166

; __device__ __forceinline__ void rwkv_prep(const Ctx& c, const Params& p, int o) {
;     ...
;             if (tt >= 1) { const bf16_t* ln = LO + (size_t)(m - 1) * 2048 + c4; nwl = *(const u32x2*)ln; nal = *(const u32x2*)(ln + 512); if (o) { nvl = *(const u32x2*)(ln + 1536); nvf = *(const u32x2*)(VF + (size_t)(m - 1) * 512 + c4); } }
.LBB0_166:
	s_add_i32 s12, s86, s34
	s_add_i32 s12, s12, 29
	s_ashr_i32 s13, s12, 31
	s_lshl_b64 s[58:59], s[12:13], 12
	v_lshl_add_u64 v[38:39], v[42:43], 0, s[58:59]
	global_load_dwordx2 v[56:57], v[38:39], off
	global_load_dwordx2 v[74:75], v[38:39], off offset:1024
	v_mov_b32_e32 v77, 0
	s_and_b64 vcc, exec, s[6:7]
	v_mov_b32_e32 v76, 0
	v_mov_b32_e32 v79, 0
	v_mov_b32_e32 v78, 0
	s_cbranch_vccnz .LBB0_168
	s_lshl_b64 s[12:13], s[12:13], 10
	v_lshl_add_u64 v[76:77], v[44:45], 0, s[12:13]
	global_load_dwordx2 v[78:79], v[38:39], off offset:3072
	s_nop 0
	global_load_dwordx2 v[76:77], v[76:77], off

; __device__ __forceinline__ float sigmoidf_(float x) { return __builtin_amdgcn_rcpf(1.f + __expf(-x)); }
; __device__ __forceinline__ float sum16_dpp(float v) { v += dppf<0xB1>(v); v += dppf<0x4E>(v); v += dppf<0x141>(v); v += dppf<0x140>(v); return v; }
; __device__ __forceinline__ u32x2 pack4(const float* f) { u32x2 o; o.x = pk2(f[0], f[1]); o.y = pk2(f[2], f[3]); return o; }
; __device__ __forceinline__ void rwkv_prep(const Ctx& c, const Params& p, int o) {
;     ...
;                 ew_[j] = 0.6065306597126334f * sigmoidf_(w0c[j] + fwl[j]);
;                 a_[j] = sigmoidf_(a0c[j] + fal[j]);
;                 kq_[j] = kr * kkc[j]; ss += kq_[j] * kq_[j];
;                 kx_[j] = kr * (1.f + (a_[j] - 1.f) * kac[j]);
;                 if (o) v = v + (fvf[j] - v) * sigmoidf_(v0c[j] + fvl[j]);
;                 v_[j] = v; bs += r_[j] * kx_[j] * rkc[j]; }
;             ss = sum16_dpp(ss); bs = sum16_dpp(bs);
;             const float rn = rsqrtf(ss + 1e-6f); float kk_[4];
; #pragma unroll
;             for (int j = 0; j < 4; ++j) { kk_[j] = kq_[j] * rn; ka_[j] = kk_[j] * a_[j]; }
;             if (o == 0) *(u32x2*)(VF + (size_t)m * 512 + c4) = pack4(v_);
;             bf16_t* zr = RKV + (size_t)m * RKV_LD + c4; *(u32x2*)zr = pack4(r_); *(u32x2*)(zr + 512) = pack4(kx_); *(u32x2*)(zr + 1024) = pack4(v_);
;             bf16_t* lo = LO + (size_t)m * 2048 + c4; *(u32x2*)lo = pack4(ew_); *(u32x2*)(lo + 512) = pack4(ka_); *(u32x2*)(Y + (size_t)m * D_ + c4) = pack4(kk_);
;             if ((ln_ & 15) == 0) BON[(size_t)m * 8 + h] = bs;
;             cr = pr; ck = pk; cv = pv; pr = qr; pk = qk; pv = qv; wl = nwl; al = nal; vl = nvl; vf = nvf; } }
.LBB0_172:
	s_andn2_b64 vcc, exec, s[58:59]
	s_cbranch_vccnz .LBB0_174
	s_add_u32 s11, s86, s34
	s_addc_u32 s13, s87, s35
	s_add_u32 s12, s11, 30
	v_add_co_u32_e32 v72, vcc, 0x6107000, v72
	s_addc_u32 s13, s13, 0
	s_nop 0
	v_addc_co_u32_e32 v73, vcc, 0, v73, vcc
	global_store_dwordx2 v[72:73], v[26:27], off offset:2048
.LBB0_174:
	v_and_b32_e32 v72, 0xffff0000, v64
	v_lshlrev_b32_e32 v73, 16, v65
	v_and_b32_e32 v65, 0xffff0000, v65
	v_add_f32_e32 v72, v15, v72
	v_add_f32_e32 v65, v17, v65
	v_mul_f32_e32 v72, 0xbfb8aa3b, v72
	v_add_f32_e32 v73, v16, v73
	v_mul_f32_e32 v65, 0xbfb8aa3b, v65
	v_exp_f32_e32 v72, v72
	v_mul_f32_e32 v73, 0xbfb8aa3b, v73
	v_exp_f32_e32 v65, v65
	v_exp_f32_e32 v73, v73
	v_add_f32_e32 v72, 1.0, v72
	v_rcp_f32_e32 v93, v72
	v_add_f32_e32 v65, 1.0, v65
	v_add_f32_e32 v72, 1.0, v73
	v_rcp_f32_e32 v73, v65
	v_add_f32_e32 v65, v87, v92
	v_add_f32_e32 v65, 0x358637bd, v65
	v_mul_f32_e32 v87, 0x4b800000, v65
	v_cmp_gt_f32_e32 vcc, s33, v65
	v_lshlrev_b32_e32 v64, 16, v64
	v_add_f32_e32 v64, v14, v64
	v_cndmask_b32_e32 v65, v65, v87, vcc
	v_rsq_f32_e32 v65, v65
	v_mul_f32_e32 v64, 0xbfb8aa3b, v64
	v_exp_f32_e32 v87, v64
	v_rcp_f32_e32 v72, v72
	v_mul_f32_e32 v64, 0x45800000, v65
	v_cndmask_b32_e32 v64, v65, v64, vcc
	v_pk_mul_f32 v[84:85], v[84:85], v[64:65] op_sel_hi:[1,0]
	v_add_f32_e32 v65, 1.0, v87
	v_rcp_f32_e32 v87, v65
	v_pk_mul_f32 v[64:65], v[90:91], v[64:65] op_sel_hi:[1,0]
	v_mad_u64_u32 v[90:91], s[58:59], s12, v172, v[40:41]
	s_mul_i32 s11, s13, 0xc00
	v_mul_f32_e32 v98, 0x3f1b4598, v93
	v_pk_mul_f32 v[72:73], v[72:73], s[0:1] op_sel_hi:[1,0]
	v_pk_mul_f32 v[82:83], v[82:83], v[84:85]
	v_pk_mul_f32 v[88:89], v[88:89], v[64:65]
	v_mul_f32_e32 v99, 0x3f1b4598, v87
	v_add_u32_e32 v91, s11, v91
	v_cvt_pk_bf16_f32 v92, v94, v95
	v_cvt_pk_bf16_f32 v93, v96, v97
	v_cvt_pk_bf16_f32 v86, v38, v86
	v_cvt_pk_bf16_f32 v87, v80, v81
	s_lshl_b64 s[58:59], s[12:13], 12
	global_store_dwordx2 v[90:91], v[92:93], off
	global_store_dwordx2 v[90:91], v[86:87], off offset:1024
	global_store_dwordx2 v[90:91], v[26:27], off offset:2048
	v_lshl_add_u64 v[26:27], v[42:43], 0, s[58:59]
	v_cvt_pk_bf16_f32 v80, v99, v98
	v_cvt_pk_bf16_f32 v81, v72, v73
	v_cvt_pk_bf16_f32 v72, v82, v83
	v_cvt_pk_bf16_f32 v73, v88, v89
	s_lshl_b64 s[58:59], s[12:13], 11
	global_store_dwordx2 v[26:27], v[80:81], off
	global_store_dwordx2 v[26:27], v[72:73], off offset:1024
	v_cvt_pk_bf16_f32 v26, v84, v85
	v_cvt_pk_bf16_f32 v27, v64, v65
	v_lshl_add_u64 v[64:65], v[46:47], 0, s[58:59]
	global_store_dwordx2 v[64:65], v[26:27], off
	s_and_saveexec_b64 s[58:59], s[8:9]
	s_cbranch_execz .LBB0_144
	s_lshl_b64 s[12:13], s[12:13], 5
	v_add_f32_e32 v1, v1, v39
	v_lshl_add_u64 v[26:27], v[50:51], 0, s[12:13]
	global_store_dword v[26:27], v1, off
	s_branch .LBB0_144

; __device__ __forceinline__ unsigned pk2(float lo, float hi) { f32x2 v = {lo, hi}; bf16x2_t b = __builtin_convertvector(v, bf16x2_t); return __builtin_bit_cast(unsigned, b); }
; __device__ __forceinline__ u32x4 pack8(const float* f) { u32x4 o; o.x = pk2(f[0], f[1]); o.y = pk2(f[2], f[3]); o.z = pk2(f[4], f[5]); o.w = pk2(f[6], f[7]); return o; }
; __device__ __forceinline__ float sum8_dpp(float v) { v += dppf<0xB1>(v); v += dppf<0x4E>(v); v += dppf<0x141>(v); return v; }
; __device__ __forceinline__ void mla_prep(const Ctx& c, const Params& p, int o) {
;     ...
;         for (int q = 0; q < 8; ++q) { const int tt = c.wave * 8 + q, m = m0 + tt; const float rsq = RS[2 * m], rskv = RS[2 * m + 1];
;             float sn_, cs_; { const float rev = (float)pos[m] * invr; const float fr = rev - floorf(rev); sn_ = __builtin_amdgcn_sinf(fr); cs_ = __builtin_amdgcn_cosf(fr); }
;             float cs[2], sn[2];
; #pragma unroll
;             for (int j = 0; j < 2; ++j) { cs[j] = __shfl(cs_, 2 * sub + j); sn[j] = __shfl(sn_, 2 * sub + j); }
;             { bf16_t* qp = QR + (size_t)m * 768 + head * 96; float v[8]; unpack8(*(const u32x4*)(qp + 8 * sub), v);
;               const unsigned r1 = *(const unsigned*)(qp + 64 + 2 * sub), r2 = *(const unsigned*)(qp + 80 + 2 * sub);
;               float x1[2] = {asf(r1 << 16) * rsq, asf(r1 & 0xffff0000u) * rsq}, x2[2] = {asf(r2 << 16) * rsq, asf(r2 & 0xffff0000u) * rsq};
;               float ss = x1[0] * x1[0] + x1[1] * x1[1] + x2[0] * x2[0] + x2[1] * x2[1];
; #pragma unroll
;               for (int i = 0; i < 8; ++i) { v[i] *= rsq; ss += v[i] * v[i]; }
;               const float rn = rsqrtf(sum8_dpp(ss) * (1.f / 96.f) + 1e-6f) ;
; #pragma unroll
;               for (int i = 0; i < 8; ++i) v[i] = v[i] * rn * gqn[i] * QSCALE;
;               float o1[2], o2[2];
; #pragma unroll
;               for (int j = 0; j < 2; ++j) { const float a = x1[j] * rn * gq1[j], bq = x2[j] * rn * gq2[j]; o1[j] = (a * cs[j] - bq * sn[j]) * QSCALE; o2[j] = (bq * cs[j] + a * sn[j]) * QSCALE; }
;               *(u32x4*)(qp + 8 * sub) = pack8(v); *(unsigned*)(qp + 64 + 2 * sub) = pk2(o1[0], o1[1]); *(unsigned*)(qp + 80 + 2 * sub) = pk2(o2[0], o2[1]); }
;             { const bf16_t* kp = KVR + (size_t)m * 1024 + head * 128; float v[8]; unpack8(*(const u32x4*)(kp + 8 * sub), v);
.LBB0_182:
	s_add_i32 s14, s18, s25
	s_ashr_i32 s15, s14, 31
	s_lshl_b64 s[2:3], s[14:15], 2
	s_add_u32 s2, s12, s2
	s_addc_u32 s3, s13, s3
	s_ashr_i32 s7, s6, 31
	v_mov_b64_e32 v[18:19], s[2:3]
	s_lshl_b64 s[2:3], s[6:7], 2
	s_add_u32 s2, s4, s2
	s_addc_u32 s3, s5, s3
	global_load_dword v20, v0, s[2:3]
	v_mov_b32_e32 v41, v0
	v_mov_b32_e32 v43, v0
	global_load_dwordx2 v[18:19], v[18:19], off
	s_add_i32 s10, s14, 2
	s_ashr_i32 s11, s10, 31
	s_lshl_b64 s[10:11], s[10:11], 2
	s_waitcnt vmcnt(0)
	v_cvt_f32_i32_e32 v20, v20
	v_mul_f32_e32 v21, v1, v20
	v_floor_f32_e32 v21, v21
	v_fma_f32 v20, v1, v20, -v21
	v_sin_f32_e32 v21, v20
	v_cos_f32_e32 v20, v20
	ds_bpermute_b32 v56, v60, v21
	ds_bpermute_b32 v52, v60, v20
	ds_bpermute_b32 v53, v61, v20
	ds_bpermute_b32 v57, v61, v21
	v_mad_i64_i32 v[20:21], s[8:9], s6, v177, v[30:31]
	v_lshl_add_u64 v[48:49], v[20:21], 0, v[40:41]
	v_lshl_add_u64 v[20:21], v[20:21], 0, v[42:43]
	global_load_dwordx4 v[44:47], v[48:49], off
	global_load_dword v51, v[20:21], off offset:128
	global_load_dword v55, v[20:21], off offset:160
	s_lshl_b64 s[8:9], s[6:7], 11
	s_waitcnt vmcnt(0) lgkmcnt(0)
	v_lshlrev_b32_e32 v50, 16, v51
	v_and_b32_e32 v51, 0xffff0000, v51
	v_lshlrev_b32_e32 v54, 16, v55
	v_and_b32_e32 v55, 0xffff0000, v55
	v_pk_mul_f32 v[50:51], v[18:19], v[50:51] op_sel_hi:[0,1]
	v_pk_mul_f32 v[54:55], v[18:19], v[54:55] op_sel_hi:[0,1]
	v_pk_mul_f32 v[74:75], v[50:51], v[50:51]
	v_lshlrev_b32_e32 v72, 16, v44
	v_and_b32_e32 v73, 0xffff0000, v44
	v_pk_mul_f32 v[76:77], v[54:55], v[54:55]
	v_add_f32_e32 v74, v74, v75
	v_lshlrev_b32_e32 v68, 16, v45
	v_and_b32_e32 v69, 0xffff0000, v45
	v_pk_mul_f32 v[44:45], v[18:19], v[72:73] op_sel_hi:[0,1]
	v_add_f32_e32 v74, v74, v76
	v_pk_mul_f32 v[72:73], v[44:45], v[44:45]
	v_add_f32_e32 v74, v77, v74
	v_pk_mul_f32 v[68:69], v[18:19], v[68:69] op_sel_hi:[0,1]
	v_add_f32_e32 v72, v72, v74
	v_lshlrev_b32_e32 v66, 16, v46
	v_and_b32_e32 v67, 0xffff0000, v46
	v_pk_mul_f32 v[70:71], v[68:69], v[68:69]
	v_add_f32_e32 v72, v73, v72
	v_lshlrev_b32_e32 v58, 16, v47
	v_and_b32_e32 v59, 0xffff0000, v47
	v_pk_mul_f32 v[46:47], v[18:19], v[66:67] op_sel_hi:[0,1]
	v_add_f32_e32 v70, v70, v72
	v_pk_mul_f32 v[66:67], v[46:47], v[46:47]
	v_add_f32_e32 v70, v71, v70
	v_pk_mul_f32 v[58:59], v[18:19], v[58:59] op_sel_hi:[0,1]
	v_add_f32_e32 v66, v66, v70
	v_pk_mul_f32 v[64:65], v[58:59], v[58:59]
	v_add_f32_e32 v66, v67, v66
	v_add_f32_e32 v64, v64, v66
	v_add_f32_e32 v64, v65, v64
	s_nop 1
	v_add_f32_dpp v64, v64, v64 quad_perm:[1,0,3,2] row_mask:0xf bank_mask:0xf bound_ctrl:1
	s_nop 1
	v_add_f32_dpp v64, v64, v64 quad_perm:[2,3,0,1] row_mask:0xf bank_mask:0xf bound_ctrl:1
	s_nop 1
	v_add_f32_dpp v64, v64, v64 row_half_mirror row_mask:0xf bank_mask:0xf bound_ctrl:1
	v_fmamk_f32 v64, v64, 0x3c2aaaab, v148
	v_cmp_gt_f32_e32 vcc, s33, v64
	v_mul_f32_e32 v65, 0x4b800000, v64
	s_nop 0
	v_cndmask_b32_e32 v64, v64, v65, vcc
	v_rsq_f32_e32 v64, v64
	s_nop 0
	v_mul_f32_e32 v65, 0x45800000, v64
	v_cndmask_b32_e32 v64, v64, v65, vcc
	v_pk_mul_f32 v[54:55], v[54:55], v[64:65] op_sel_hi:[1,0]
	v_pk_mul_f32 v[44:45], v[44:45], v[64:65] op_sel_hi:[1,0]
	v_pk_mul_f32 v[66:67], v[68:69], v[64:65] op_sel_hi:[1,0]
	v_pk_mul_f32 v[46:47], v[46:47], v[64:65] op_sel_hi:[1,0]
	v_pk_mul_f32 v[58:59], v[58:59], v[64:65] op_sel_hi:[1,0]
	v_pk_mul_f32 v[54:55], v[24:25], v[54:55]
	v_pk_mul_f32 v[50:51], v[50:51], v[64:65] op_sel_hi:[1,0]
	v_pk_mul_f32 v[44:45], v[6:7], v[44:45]
	v_pk_mul_f32 v[66:67], v[8:9], v[66:67]
	v_pk_mul_f32 v[46:47], v[2:3], v[46:47]
	v_pk_mul_f32 v[58:59], v[4:5], v[58:59]
	v_pk_mul_f32 v[50:51], v[22:23], v[50:51]
	v_pk_mul_f32 v[64:65], v[54:55], v[56:57]
	v_pk_mul_f32 v[44:45], v[44:45], s[70:71] op_sel_hi:[1,0]
	v_pk_mul_f32 v[66:67], v[66:67], s[70:71] op_sel_hi:[1,0]
	v_pk_mul_f32 v[46:47], v[46:47], s[70:71] op_sel_hi:[1,0]
	v_pk_mul_f32 v[58:59], v[58:59], s[70:71] op_sel_hi:[1,0]
	v_pk_fma_f32 v[64:65], v[50:51], v[52:53], v[64:65] neg_lo:[0,0,1] neg_hi:[0,0,1]
	v_pk_mul_f32 v[54:55], v[54:55], v[52:53]
	v_pk_mul_f32 v[64:65], v[64:65], s[70:71] op_sel_hi:[1,0]
	v_pk_fma_f32 v[50:51], v[50:51], v[56:57], v[54:55]
	v_cvt_pk_bf16_f32 v44, v44, v45
	v_cvt_pk_bf16_f32 v45, v66, v67
	v_cvt_pk_bf16_f32 v46, v46, v47
	v_cvt_pk_bf16_f32 v47, v58, v59
	v_pk_mul_f32 v[50:51], v[50:51], s[70:71] op_sel_hi:[1,0]
	global_store_dwordx4 v[48:49], v[44:47], off
	s_nop 1
	v_cvt_pk_bf16_f32 v44, v64, v65
	global_store_dword v[20:21], v44, off offset:128
	v_cvt_pk_bf16_f32 v44, v50, v51
	global_store_dword v[20:21], v44, off offset:160
	v_lshl_add_u64 v[20:21], v[36:37], 0, s[8:9]
	s_lshl_b64 s[8:9], s[6:7], 6
	v_lshl_add_u64 v[48:49], v[38:39], 0, s[8:9]
	global_load_dwordx4 v[44:47], v[20:21], off
	global_load_dword v50, v[48:49], off
	s_nop 0
	global_load_dword v48, v[48:49], off offset:32
	s_waitcnt vmcnt(0) lgkmcnt(0)
; __device__ __forceinline__ unsigned pk2(float lo, float hi) { f32x2 v = {lo, hi}; bf16x2_t b = __builtin_convertvector(v, bf16x2_t); return __builtin_bit_cast(unsigned, b); }
; __device__ __forceinline__ bf16_t f2bf(float f) { return (bf16_t)(pk2(f, 0.f) & 0xffffu); }
; __device__ __forceinline__ u32x4 pack8(const float* f) { u32x4 o; o.x = pk2(f[0], f[1]); o.y = pk2(f[2], f[3]); o.z = pk2(f[4], f[5]); o.w = pk2(f[6], f[7]); return o; }
; __device__ __forceinline__ float sum8_dpp(float v) { v += dppf<0xB1>(v); v += dppf<0x4E>(v); v += dppf<0x141>(v); return v; }
; __device__ __forceinline__ void mla_prep(const Ctx& c, const Params& p, int o) {
;     ...
;             { const bf16_t* kp = KVR + (size_t)m * 1024 + head * 128; float v[8]; unpack8(*(const u32x4*)(kp + 8 * sub), v);
;               const unsigned r1 = *(const unsigned*)(KR + (size_t)m * 32 + 2 * sub), r2 = *(const unsigned*)(KR + (size_t)m * 32 + 16 + 2 * sub);
;               float x1[2] = {asf(r1 << 16), asf(r1 & 0xffff0000u)}, x2[2] = {asf(r2 << 16), asf(r2 & 0xffff0000u)};
;               float ss = x1[0] * x1[0] + x1[1] * x1[1] + x2[0] * x2[0] + x2[1] * x2[1];
; #pragma unroll
;               for (int i = 0; i < 8; ++i) { v[i] *= rskv; ss += v[i] * v[i]; }
;               const float rn = rsqrtf(sum8_dpp(ss) * (1.f / 96.f) + 1e-6f);
; #pragma unroll
;               for (int i = 0; i < 8; ++i) v[i] = v[i] * rn * gkn[i];
;               float o1[2], o2[2];
; #pragma unroll
;               for (int j = 0; j < 2; ++j) { const float a = x1[j] * rn * gk1[j], bq = x2[j] * rn * gk2[j]; o1[j] = a * cs[j] - bq * sn[j]; o2[j] = bq * cs[j] + a * sn[j]; }
;               bf16_t* ko = KH + (size_t)m * 768 + head * 96;
;               *(u32x4*)(ko + 8 * sub) = pack8(v); *(unsigned*)(ko + 64 + 2 * sub) = pk2(o1[0], o1[1]); *(unsigned*)(ko + 80 + 2 * sub) = pk2(o2[0], o2[1]);
;               float vv[8]; unpack8(*(const u32x4*)(kp + 64 + 8 * sub), vv);
; #pragma unroll
;               for (int i = 0; i < 8; ++i) sVT[(head * 64 + 8 * sub + i) * 72 + tt] = f2bf(vv[i] * rskv); } }
	v_lshlrev_b32_e32 v54, 16, v50
	v_and_b32_e32 v55, 0xffff0000, v50
	v_lshlrev_b32_e32 v58, 16, v48
	v_and_b32_e32 v59, 0xffff0000, v48
	v_lshlrev_b32_e32 v48, 16, v47
	v_and_b32_e32 v49, 0xffff0000, v47
	v_lshlrev_b32_e32 v64, 16, v46
	v_and_b32_e32 v65, 0xffff0000, v46
	v_lshlrev_b32_e32 v66, 16, v45
	v_and_b32_e32 v67, 0xffff0000, v45
	v_lshlrev_b32_e32 v70, 16, v44
	v_and_b32_e32 v71, 0xffff0000, v44
	v_pk_mul_f32 v[72:73], v[54:55], v[54:55]
	v_pk_mul_f32 v[50:51], v[18:19], v[48:49] op_sel:[1,0]
	v_pk_mul_f32 v[64:65], v[18:19], v[64:65] op_sel:[1,0]
	v_pk_mul_f32 v[66:67], v[18:19], v[66:67] op_sel:[1,0]
	v_pk_mul_f32 v[44:45], v[18:19], v[70:71] op_sel:[1,0]
	v_pk_mul_f32 v[74:75], v[58:59], v[58:59]
	v_add_f32_e32 v18, v72, v73
	v_add_f32_e32 v18, v18, v74
	v_pk_mul_f32 v[70:71], v[44:45], v[44:45]
	v_add_f32_e32 v18, v75, v18
	v_add_f32_e32 v18, v70, v18
	v_pk_mul_f32 v[68:69], v[66:67], v[66:67]
	v_add_f32_e32 v18, v71, v18
	v_add_f32_e32 v18, v68, v18
	v_pk_mul_f32 v[46:47], v[64:65], v[64:65]
	v_add_f32_e32 v18, v69, v18
	v_add_f32_e32 v18, v46, v18
	v_pk_mul_f32 v[48:49], v[50:51], v[50:51]
	v_add_f32_e32 v18, v47, v18
	v_add_f32_e32 v18, v48, v18
	v_add_f32_e32 v18, v49, v18
	s_nop 1
	v_add_f32_dpp v18, v18, v18 quad_perm:[1,0,3,2] row_mask:0xf bank_mask:0xf bound_ctrl:1
	s_nop 1
	v_add_f32_dpp v18, v18, v18 quad_perm:[2,3,0,1] row_mask:0xf bank_mask:0xf bound_ctrl:1
	s_nop 1
	v_add_f32_dpp v18, v18, v18 row_half_mirror row_mask:0xf bank_mask:0xf bound_ctrl:1
	v_fmamk_f32 v18, v18, 0x3c2aaaab, v148
	v_cmp_gt_f32_e32 vcc, s33, v18
	v_mul_f32_e32 v46, 0x4b800000, v18
	s_nop 0
	v_cndmask_b32_e32 v18, v18, v46, vcc
	v_rsq_f32_e32 v18, v18
	s_nop 0
	v_mul_f32_e32 v46, 0x45800000, v18
	v_cndmask_b32_e32 v18, v18, v46, vcc
	v_pk_mul_f32 v[58:59], v[18:19], v[58:59] op_sel_hi:[0,1]
	v_pk_mul_f32 v[58:59], v[28:29], v[58:59]
	v_pk_mul_f32 v[54:55], v[18:19], v[54:55] op_sel_hi:[0,1]
	v_pk_mul_f32 v[48:49], v[64:65], v[18:19] op_sel_hi:[1,0]
	v_pk_mul_f32 v[64:65], v[26:27], v[54:55]
	v_pk_mul_f32 v[54:55], v[58:59], v[56:57]
	v_pk_mul_f32 v[44:45], v[44:45], v[18:19] op_sel_hi:[1,0]
	v_pk_mul_f32 v[46:47], v[66:67], v[18:19] op_sel_hi:[1,0]
	v_pk_mul_f32 v[50:51], v[50:51], v[18:19] op_sel_hi:[1,0]
	v_pk_fma_f32 v[54:55], v[64:65], v[52:53], v[54:55] neg_lo:[0,0,1] neg_hi:[0,0,1]
	v_pk_mul_f32 v[52:53], v[58:59], v[52:53]
	v_pk_mul_f32 v[44:45], v[14:15], v[44:45]
	v_pk_mul_f32 v[46:47], v[16:17], v[46:47]
	v_pk_mul_f32 v[48:49], v[10:11], v[48:49]
	v_pk_mul_f32 v[50:51], v[12:13], v[50:51]
	v_pk_fma_f32 v[52:53], v[64:65], v[56:57], v[52:53]
	v_mad_i64_i32 v[56:57], s[8:9], s6, v177, v[32:33]
	v_cvt_pk_bf16_f32 v44, v44, v45
	v_cvt_pk_bf16_f32 v45, v46, v47
	v_cvt_pk_bf16_f32 v46, v48, v49
	v_cvt_pk_bf16_f32 v47, v50, v51
	v_lshl_add_u64 v[48:49], v[56:57], 0, v[40:41]
	global_store_dwordx4 v[48:49], v[44:47], off
	v_cvt_pk_bf16_f32 v18, v54, v55
	v_add_u32_e32 v64, s25, v62
	v_lshl_add_u64 v[44:45], v[56:57], 0, v[42:43]
	global_store_dword v[44:45], v18, off offset:128
	v_cvt_pk_bf16_f32 v18, v52, v53
	global_store_dword v[44:45], v18, off offset:160
	global_load_dwordx4 v[44:47], v[20:21], off offset:128
	s_add_i32 s8, s6, 1
	s_add_u32 s10, s12, s10
	s_addc_u32 s11, s13, s11
	s_ashr_i32 s9, s8, 31
	s_add_i32 s25, s25, 4
	s_add_i32 s6, s6, 2
	s_waitcnt vmcnt(0) lgkmcnt(0)
	v_lshlrev_b32_e32 v18, 16, v44
	v_mul_f32_e32 v18, v19, v18
	v_and_b32_e32 v20, 0xffff0000, v44
	v_cvt_pk_bf16_f32 v18, v18, s0
	ds_write_b16 v64, v18
	v_mul_f32_e32 v18, v19, v20
	v_lshlrev_b32_e32 v21, 16, v45
	v_cvt_pk_bf16_f32 v18, v18, s0
	ds_write_b16 v64, v18 offset:144
	v_mul_f32_e32 v18, v19, v21
	v_and_b32_e32 v44, 0xffff0000, v45
	v_cvt_pk_bf16_f32 v18, v18, s0
	ds_write_b16 v64, v18 offset:288
	v_mul_f32_e32 v18, v19, v44
	v_lshlrev_b32_e32 v45, 16, v46
	v_cvt_pk_bf16_f32 v18, v18, s0
	ds_write_b16 v64, v18 offset:432
	v_mul_f32_e32 v18, v19, v45
	v_and_b32_e32 v46, 0xffff0000, v46
	v_cvt_pk_bf16_f32 v18, v18, s0
	ds_write_b16 v64, v18 offset:576
	v_mul_f32_e32 v18, v19, v46
	v_lshlrev_b32_e32 v48, 16, v47
	v_cvt_pk_bf16_f32 v18, v18, s0
	ds_write_b16 v64, v18 offset:720
	v_mul_f32_e32 v18, v19, v48
	v_and_b32_e32 v47, 0xffff0000, v47
	v_cvt_pk_bf16_f32 v18, v18, s0
	ds_write_b16 v64, v18 offset:864
	v_mul_f32_e32 v18, v19, v47
	v_cvt_pk_bf16_f32 v18, v18, s0
	ds_write_b16 v64, v18 offset:1008
	v_mov_b64_e32 v[18:19], s[10:11]
	global_load_dwordx2 v[44:45], v[18:19], off
	s_nop 0
	global_load_dword v18, v0, s[2:3] offset:4
	v_mad_i64_i32 v[46:47], s[2:3], s8, v177, v[30:31]
	v_lshl_add_u64 v[52:53], v[46:47], 0, v[40:41]
	v_lshl_add_u64 v[46:47], v[46:47], 0, v[42:43]
	s_lshl_b64 s[2:3], s[8:9], 11
	s_waitcnt vmcnt(0)
	v_cvt_f32_i32_e32 v18, v18
	v_mul_f32_e32 v19, v1, v18
	v_floor_f32_e32 v19, v19
	v_fma_f32 v18, v1, v18, -v19
	v_sin_f32_e32 v19, v18
	v_cos_f32_e32 v18, v18
	ds_bpermute_b32 v48, v60, v19
	ds_bpermute_b32 v50, v60, v18
	ds_bpermute_b32 v51, v61, v18
	ds_bpermute_b32 v49, v61, v19
	global_load_dwordx4 v[18:21], v[52:53], off
	global_load_dword v55, v[46:47], off offset:128
	global_load_dword v57, v[46:47], off offset:160
	s_waitcnt vmcnt(0) lgkmcnt(0)
; __device__ __forceinline__ unsigned pk2(float lo, float hi) { f32x2 v = {lo, hi}; bf16x2_t b = __builtin_convertvector(v, bf16x2_t); return __builtin_bit_cast(unsigned, b); }
; __device__ __forceinline__ u32x4 pack8(const float* f) { u32x4 o; o.x = pk2(f[0], f[1]); o.y = pk2(f[2], f[3]); o.z = pk2(f[4], f[5]); o.w = pk2(f[6], f[7]); return o; }
; __device__ __forceinline__ float sum8_dpp(float v) { v += dppf<0xB1>(v); v += dppf<0x4E>(v); v += dppf<0x141>(v); return v; }
; __device__ __forceinline__ void mla_prep(const Ctx& c, const Params& p, int o) {
;     ...
;             { bf16_t* qp = QR + (size_t)m * 768 + head * 96; float v[8]; unpack8(*(const u32x4*)(qp + 8 * sub), v);
;               const unsigned r1 = *(const unsigned*)(qp + 64 + 2 * sub), r2 = *(const unsigned*)(qp + 80 + 2 * sub);
;               float x1[2] = {asf(r1 << 16) * rsq, asf(r1 & 0xffff0000u) * rsq}, x2[2] = {asf(r2 << 16) * rsq, asf(r2 & 0xffff0000u) * rsq};
;               float ss = x1[0] * x1[0] + x1[1] * x1[1] + x2[0] * x2[0] + x2[1] * x2[1];
; #pragma unroll
;               for (int i = 0; i < 8; ++i) { v[i] *= rsq; ss += v[i] * v[i]; }
;               const float rn = rsqrtf(sum8_dpp(ss) * (1.f / 96.f) + 1e-6f) ;
; #pragma unroll
;               for (int i = 0; i < 8; ++i) v[i] = v[i] * rn * gqn[i] * QSCALE;
;               float o1[2], o2[2];
; #pragma unroll
;               for (int j = 0; j < 2; ++j) { const float a = x1[j] * rn * gq1[j], bq = x2[j] * rn * gq2[j]; o1[j] = (a * cs[j] - bq * sn[j]) * QSCALE; o2[j] = (bq * cs[j] + a * sn[j]) * QSCALE; }
;               *(u32x4*)(qp + 8 * sub) = pack8(v); *(unsigned*)(qp + 64 + 2 * sub) = pk2(o1[0], o1[1]); *(unsigned*)(qp + 80 + 2 * sub) = pk2(o2[0], o2[1]); }
;             { const bf16_t* kp = KVR + (size_t)m * 1024 + head * 128; float v[8]; unpack8(*(const u32x4*)(kp + 8 * sub), v);
	v_lshlrev_b32_e32 v54, 16, v55
	v_and_b32_e32 v55, 0xffff0000, v55
	v_lshlrev_b32_e32 v56, 16, v57
	v_and_b32_e32 v57, 0xffff0000, v57
	v_pk_mul_f32 v[54:55], v[44:45], v[54:55] op_sel_hi:[0,1]
	v_lshlrev_b32_e32 v58, 16, v21
	v_and_b32_e32 v59, 0xffff0000, v21
	v_lshlrev_b32_e32 v68, 16, v20
	v_and_b32_e32 v69, 0xffff0000, v20
	v_lshlrev_b32_e32 v70, 16, v19
	v_and_b32_e32 v71, 0xffff0000, v19
	v_lshlrev_b32_e32 v74, 16, v18
	v_and_b32_e32 v75, 0xffff0000, v18
	v_pk_mul_f32 v[56:57], v[44:45], v[56:57] op_sel_hi:[0,1]
	v_pk_mul_f32 v[76:77], v[54:55], v[54:55]
	v_pk_mul_f32 v[58:59], v[44:45], v[58:59] op_sel_hi:[0,1]
	v_pk_mul_f32 v[20:21], v[44:45], v[68:69] op_sel_hi:[0,1]
	v_pk_mul_f32 v[70:71], v[44:45], v[70:71] op_sel_hi:[0,1]
	v_pk_mul_f32 v[18:19], v[44:45], v[74:75] op_sel_hi:[0,1]
	v_pk_mul_f32 v[78:79], v[56:57], v[56:57]
	v_add_f32_e32 v44, v76, v77
	v_add_f32_e32 v44, v44, v78
	v_pk_mul_f32 v[74:75], v[18:19], v[18:19]
	v_add_f32_e32 v44, v79, v44
	v_add_f32_e32 v44, v74, v44
	v_pk_mul_f32 v[72:73], v[70:71], v[70:71]
	v_add_f32_e32 v44, v75, v44
	v_add_f32_e32 v44, v72, v44
	v_pk_mul_f32 v[68:69], v[20:21], v[20:21]
	v_add_f32_e32 v44, v73, v44
	v_add_f32_e32 v44, v68, v44
	v_pk_mul_f32 v[66:67], v[58:59], v[58:59]
	v_add_f32_e32 v44, v69, v44
	v_add_f32_e32 v44, v66, v44
	v_add_f32_e32 v44, v67, v44
	s_nop 1
	v_add_f32_dpp v44, v44, v44 quad_perm:[1,0,3,2] row_mask:0xf bank_mask:0xf bound_ctrl:1
	s_nop 1
	v_add_f32_dpp v44, v44, v44 quad_perm:[2,3,0,1] row_mask:0xf bank_mask:0xf bound_ctrl:1
	s_nop 1
	v_add_f32_dpp v44, v44, v44 row_half_mirror row_mask:0xf bank_mask:0xf bound_ctrl:1
	v_fmamk_f32 v44, v44, 0x3c2aaaab, v148
	v_cmp_gt_f32_e32 vcc, s33, v44
	v_mul_f32_e32 v65, 0x4b800000, v44
	s_nop 0
	v_cndmask_b32_e32 v44, v44, v65, vcc
	v_rsq_f32_e32 v44, v44
	s_nop 0
	v_mul_f32_e32 v65, 0x45800000, v44
	v_cndmask_b32_e32 v44, v44, v65, vcc
	v_pk_mul_f32 v[56:57], v[56:57], v[44:45] op_sel_hi:[1,0]
	v_pk_mul_f32 v[18:19], v[18:19], v[44:45] op_sel_hi:[1,0]
	v_pk_mul_f32 v[66:67], v[70:71], v[44:45] op_sel_hi:[1,0]
	v_pk_mul_f32 v[20:21], v[20:21], v[44:45] op_sel_hi:[1,0]
	v_pk_mul_f32 v[58:59], v[58:59], v[44:45] op_sel_hi:[1,0]
	v_pk_mul_f32 v[56:57], v[24:25], v[56:57]
	v_pk_mul_f32 v[54:55], v[54:55], v[44:45] op_sel_hi:[1,0]
	v_pk_mul_f32 v[18:19], v[6:7], v[18:19]
	v_pk_mul_f32 v[66:67], v[8:9], v[66:67]
	v_pk_mul_f32 v[20:21], v[2:3], v[20:21]
	v_pk_mul_f32 v[58:59], v[4:5], v[58:59]
	v_pk_mul_f32 v[54:55], v[22:23], v[54:55]
	v_pk_mul_f32 v[68:69], v[56:57], v[48:49]
	v_pk_mul_f32 v[18:19], v[18:19], s[70:71] op_sel_hi:[1,0]
	v_pk_mul_f32 v[66:67], v[66:67], s[70:71] op_sel_hi:[1,0]
	v_pk_mul_f32 v[20:21], v[20:21], s[70:71] op_sel_hi:[1,0]
	v_pk_mul_f32 v[58:59], v[58:59], s[70:71] op_sel_hi:[1,0]
	v_pk_fma_f32 v[68:69], v[54:55], v[50:51], v[68:69] neg_lo:[0,0,1] neg_hi:[0,0,1]
	v_pk_mul_f32 v[56:57], v[56:57], v[50:51]
	v_pk_mul_f32 v[68:69], v[68:69], s[70:71] op_sel_hi:[1,0]
	v_pk_fma_f32 v[54:55], v[54:55], v[48:49], v[56:57]
	v_cvt_pk_bf16_f32 v18, v18, v19
	v_cvt_pk_bf16_f32 v19, v66, v67
	v_cvt_pk_bf16_f32 v20, v20, v21
	v_cvt_pk_bf16_f32 v21, v58, v59
	v_pk_mul_f32 v[54:55], v[54:55], s[70:71] op_sel_hi:[1,0]
	global_store_dwordx4 v[52:53], v[18:21], off
	s_nop 1
	v_cvt_pk_bf16_f32 v18, v68, v69
	global_store_dword v[46:47], v18, off offset:128
	v_cvt_pk_bf16_f32 v18, v54, v55
	global_store_dword v[46:47], v18, off offset:160
	v_lshl_add_u64 v[46:47], v[36:37], 0, s[2:3]
	s_lshl_b64 s[2:3], s[8:9], 6
	v_lshl_add_u64 v[52:53], v[38:39], 0, s[2:3]
	global_load_dwordx4 v[18:21], v[46:47], off
	global_load_dword v44, v[52:53], off
	s_nop 0
	global_load_dword v52, v[52:53], off offset:32
	s_cmp_eq_u32 s25, 16
	s_waitcnt vmcnt(0) lgkmcnt(0)
; #define LAS __attribute__((address_space(3)))
; __device__ __forceinline__ unsigned pk2(float lo, float hi) { f32x2 v = {lo, hi}; bf16x2_t b = __builtin_convertvector(v, bf16x2_t); return __builtin_bit_cast(unsigned, b); }
; __device__ __forceinline__ bf16_t f2bf(float f) { return (bf16_t)(pk2(f, 0.f) & 0xffffu); }
; __device__ __forceinline__ u32x4 pack8(const float* f) { u32x4 o; o.x = pk2(f[0], f[1]); o.y = pk2(f[2], f[3]); o.z = pk2(f[4], f[5]); o.w = pk2(f[6], f[7]); return o; }
; __device__ __forceinline__ void mla_prep(const Ctx& c, const Params& p, int o) {
;     ...
;             { const bf16_t* kp = KVR + (size_t)m * 1024 + head * 128; float v[8]; unpack8(*(const u32x4*)(kp + 8 * sub), v);
;               const unsigned r1 = *(const unsigned*)(KR + (size_t)m * 32 + 2 * sub), r2 = *(const unsigned*)(KR + (size_t)m * 32 + 16 + 2 * sub);
;               float x1[2] = {asf(r1 << 16), asf(r1 & 0xffff0000u)}, x2[2] = {asf(r2 << 16), asf(r2 & 0xffff0000u)};
;               float ss = x1[0] * x1[0] + x1[1] * x1[1] + x2[0] * x2[0] + x2[1] * x2[1];
; #pragma unroll
;               for (int i = 0; i < 8; ++i) { v[i] *= rskv; ss += v[i] * v[i]; }
;               const float rn = rsqrtf(sum8_dpp(ss) * (1.f / 96.f) + 1e-6f);
; #pragma unroll
;               for (int i = 0; i < 8; ++i) v[i] = v[i] * rn * gkn[i];
;               float o1[2], o2[2];
; #pragma unroll
;               for (int j = 0; j < 2; ++j) { const float a = x1[j] * rn * gk1[j], bq = x2[j] * rn * gk2[j]; o1[j] = a * cs[j] - bq * sn[j]; o2[j] = bq * cs[j] + a * sn[j]; }
;               bf16_t* ko = KH + (size_t)m * 768 + head * 96;
;               *(u32x4*)(ko + 8 * sub) = pack8(v); *(unsigned*)(ko + 64 + 2 * sub) = pk2(o1[0], o1[1]); *(unsigned*)(ko + 80 + 2 * sub) = pk2(o2[0], o2[1]);
;               float vv[8]; unpack8(*(const u32x4*)(kp + 64 + 8 * sub), vv);
; #pragma unroll
;               for (int i = 0; i < 8; ++i) sVT[(head * 64 + 8 * sub + i) * 72 + tt] = f2bf(vv[i] * rskv); } }
;         __syncthreads();
;         { const int row = c.tid; const int b = m0 / T_, t0 = m0 & (T_ - 1); bf16_t* dst = VT + ((size_t)(b * 8) * 64 + row) * T_ + t0;
; #pragma unroll
;           for (int i = 0; i < 8; ++i) *(u32x4*)(dst + 8 * i) = *(const LAS u32x4*)(sVT + row * 72 + 8 * i); }
;         __syncthreads();
	v_lshlrev_b32_e32 v66, 16, v44
	v_and_b32_e32 v67, 0xffff0000, v44
	v_lshlrev_b32_e32 v68, 16, v52
	v_and_b32_e32 v69, 0xffff0000, v52
	v_lshlrev_b32_e32 v52, 16, v21
	v_and_b32_e32 v53, 0xffff0000, v21
	v_mov_b32_e32 v44, v45
	v_lshlrev_b32_e32 v54, 16, v20
	v_and_b32_e32 v55, 0xffff0000, v20
	v_lshlrev_b32_e32 v56, 16, v19
	v_and_b32_e32 v57, 0xffff0000, v19
	v_lshlrev_b32_e32 v72, 16, v18
	v_and_b32_e32 v73, 0xffff0000, v18
	v_pk_mul_f32 v[74:75], v[66:67], v[66:67]
	v_pk_mul_f32 v[58:59], v[44:45], v[52:53] op_sel_hi:[0,1]
	v_pk_mul_f32 v[20:21], v[44:45], v[54:55] op_sel_hi:[0,1]
	v_pk_mul_f32 v[56:57], v[44:45], v[56:57] op_sel_hi:[0,1]
	v_pk_mul_f32 v[18:19], v[44:45], v[72:73] op_sel_hi:[0,1]
	v_pk_mul_f32 v[76:77], v[68:69], v[68:69]
	v_add_f32_e32 v44, v74, v75
	v_add_f32_e32 v44, v44, v76
	v_pk_mul_f32 v[72:73], v[18:19], v[18:19]
	v_add_f32_e32 v44, v77, v44
	v_add_f32_e32 v44, v72, v44
	v_pk_mul_f32 v[70:71], v[56:57], v[56:57]
	v_add_f32_e32 v44, v73, v44
	v_add_f32_e32 v44, v70, v44
	v_pk_mul_f32 v[54:55], v[20:21], v[20:21]
	v_add_f32_e32 v44, v71, v44
	v_add_f32_e32 v44, v54, v44
	v_pk_mul_f32 v[52:53], v[58:59], v[58:59]
	v_add_f32_e32 v44, v55, v44
	v_add_f32_e32 v44, v52, v44
	v_add_f32_e32 v44, v53, v44
	s_nop 1
	v_add_f32_dpp v44, v44, v44 quad_perm:[1,0,3,2] row_mask:0xf bank_mask:0xf bound_ctrl:1
	s_nop 1
	v_add_f32_dpp v44, v44, v44 quad_perm:[2,3,0,1] row_mask:0xf bank_mask:0xf bound_ctrl:1
	s_nop 1
	v_add_f32_dpp v44, v44, v44 row_half_mirror row_mask:0xf bank_mask:0xf bound_ctrl:1
	v_fmamk_f32 v44, v44, 0x3c2aaaab, v148
	v_cmp_gt_f32_e32 vcc, s33, v44
	v_mul_f32_e32 v52, 0x4b800000, v44
	s_nop 0
	v_cndmask_b32_e32 v44, v44, v52, vcc
	v_rsq_f32_e32 v44, v44
	s_nop 0
	v_mul_f32_e32 v52, 0x45800000, v44
	v_cndmask_b32_e32 v44, v44, v52, vcc
	v_pk_mul_f32 v[18:19], v[18:19], v[44:45] op_sel_hi:[1,0]
	s_nop 0
	v_pk_mul_f32 v[52:53], v[14:15], v[18:19]
	v_pk_mul_f32 v[18:19], v[56:57], v[44:45] op_sel_hi:[1,0]
	s_nop 0
	v_pk_mul_f32 v[54:55], v[16:17], v[18:19]
	v_pk_mul_f32 v[18:19], v[20:21], v[44:45] op_sel_hi:[1,0]
	v_pk_mul_f32 v[20:21], v[44:45], v[66:67] op_sel_hi:[0,1]
	v_pk_mul_f32 v[56:57], v[10:11], v[18:19]
	v_pk_mul_f32 v[18:19], v[58:59], v[44:45] op_sel_hi:[1,0]
	v_pk_mul_f32 v[66:67], v[26:27], v[20:21]
	v_pk_mul_f32 v[58:59], v[12:13], v[18:19]
	v_pk_mul_f32 v[18:19], v[44:45], v[68:69] op_sel_hi:[0,1]
	v_pk_mul_f32 v[18:19], v[28:29], v[18:19]
	s_nop 0
	v_pk_mul_f32 v[20:21], v[18:19], v[48:49]
	v_pk_mul_f32 v[18:19], v[18:19], v[50:51]
	v_pk_fma_f32 v[20:21], v[66:67], v[50:51], v[20:21] neg_lo:[0,0,1] neg_hi:[0,0,1]
	v_pk_fma_f32 v[18:19], v[66:67], v[48:49], v[18:19]
	v_mad_i64_i32 v[66:67], s[2:3], s8, v177, v[32:33]
	v_cvt_pk_bf16_f32 v48, v52, v53
	v_cvt_pk_bf16_f32 v49, v54, v55
	v_cvt_pk_bf16_f32 v50, v56, v57
	v_cvt_pk_bf16_f32 v51, v58, v59
	v_lshl_add_u64 v[52:53], v[66:67], 0, v[40:41]
	v_cvt_pk_bf16_f32 v41, v20, v21
	v_lshl_add_u64 v[20:21], v[66:67], 0, v[42:43]
	v_cvt_pk_bf16_f32 v18, v18, v19
	global_store_dwordx4 v[52:53], v[48:51], off
	global_store_dword v[20:21], v41, off offset:128
	global_store_dword v[20:21], v18, off offset:160
	global_load_dwordx4 v[18:21], v[46:47], off offset:128
	s_waitcnt vmcnt(0) lgkmcnt(0)
	v_lshlrev_b32_e32 v41, 16, v18
	v_and_b32_e32 v18, 0xffff0000, v18
	v_mul_f32_e32 v18, v45, v18
	v_lshlrev_b32_e32 v43, 16, v19
	v_cvt_pk_bf16_f32 v18, v18, s0
	ds_write_b16 v64, v18 offset:146
	v_mul_f32_e32 v18, v45, v43
	v_and_b32_e32 v19, 0xffff0000, v19
	v_cvt_pk_bf16_f32 v18, v18, s0
	ds_write_b16 v64, v18 offset:290
	v_mul_f32_e32 v18, v45, v19
	v_lshlrev_b32_e32 v44, 16, v20
	v_cvt_pk_bf16_f32 v18, v18, s0
	ds_write_b16 v64, v18 offset:434
	v_mul_f32_e32 v18, v45, v44
	v_and_b32_e32 v20, 0xffff0000, v20
	v_cvt_pk_bf16_f32 v18, v18, s0
	ds_write_b16 v64, v18 offset:578
	v_mul_f32_e32 v18, v45, v20
	v_lshlrev_b32_e32 v46, 16, v21
	v_cvt_pk_bf16_f32 v18, v18, s0
	ds_write_b16 v64, v18 offset:722
	v_mul_f32_e32 v18, v45, v46
	v_and_b32_e32 v21, 0xffff0000, v21
	v_cvt_pk_bf16_f32 v18, v18, s0
	v_mul_f32_e32 v41, v45, v41
	ds_write_b16 v64, v18 offset:866
	v_mul_f32_e32 v18, v45, v21
	v_cvt_pk_bf16_f32 v41, v41, s0
	v_cvt_pk_bf16_f32 v18, v18, s0
	ds_write_b16 v64, v41 offset:2
	ds_write_b16 v64, v18 offset:1010
	s_cbranch_scc0 .LBB0_182
	s_ashr_i32 s2, s24, 31
	s_lshr_b32 s2, s2, 25
	s_add_i32 s2, s24, s2
	s_ashr_i32 s2, s2, 7
	s_lshl_b32 s2, s2, 3
	s_ashr_i32 s3, s2, 31
	s_lshl_b64 s[2:3], s[2:3], 20
	v_lshl_add_u64 v[18:19], v[34:35], 0, s[2:3]
	s_lshl_b32 s2, s24, 7
	s_and_b32 s42, s2, 0x3f80
	s_waitcnt lgkmcnt(0)
	s_barrier
	v_lshl_add_u64 v[44:45], v[18:19], 0, s[42:43]
	ds_read_b128 v[18:21], v63
	s_add_i32 s24, s24, s38
	s_add_i32 s18, s18, s19
	s_add_i32 s20, s20, s21
	s_cmpk_gt_i32 s24, 0x1ff
	s_waitcnt lgkmcnt(0)
	global_store_dwordx4 v[44:45], v[18:21], off
	ds_read_b128 v[18:21], v63 offset:16
	s_waitcnt lgkmcnt(0)
	global_store_dwordx4 v[44:45], v[18:21], off offset:16
	ds_read_b128 v[18:21], v63 offset:32
	s_waitcnt lgkmcnt(0)
	global_store_dwordx4 v[44:45], v[18:21], off offset:32
	ds_read_b128 v[18:21], v63 offset:48
	s_waitcnt lgkmcnt(0)
	global_store_dwordx4 v[44:45], v[18:21], off offset:48
	ds_read_b128 v[18:21], v63 offset:64
	s_waitcnt lgkmcnt(0)
	global_store_dwordx4 v[44:45], v[18:21], off offset:64
	ds_read_b128 v[18:21], v63 offset:80
	s_waitcnt lgkmcnt(0)
	global_store_dwordx4 v[44:45], v[18:21], off offset:80
	ds_read_b128 v[18:21], v63 offset:96
	s_waitcnt lgkmcnt(0)
	global_store_dwordx4 v[44:45], v[18:21], off offset:96
	ds_read_b128 v[18:21], v63 offset:112
	s_waitcnt lgkmcnt(0)
	global_store_dwordx4 v[44:45], v[18:21], off offset:112
	s_waitcnt lgkmcnt(0)
	s_barrier
	s_cbranch_scc0 .LBB0_181

; __device__ __forceinline__ unsigned pk2(float lo, float hi) { f32x2 v = {lo, hi}; bf16x2_t b = __builtin_convertvector(v, bf16x2_t); return __builtin_bit_cast(unsigned, b); }
;     __device__ __forceinline__ void operator()(const f32x4 (&acc)[2][2][4][2], const Unit& u, int wr, int wc, int fr, int fq) const {
;         const int row0 = u.pm * BM + wr * 64 + fr; const int col0 = u.pn * BM + wc * 32 + 8 * fq;
; #pragma unroll
;         for (int ai = 0; ai < 2; ++ai)
; #pragma unroll
;             for (int m = 0; m < 4; ++m) { bf16_t* rowp = O + (size_t)(row0 + ai * HALF + m * 16) * ldc + col0;
; #pragma unroll
;                 for (int bj = 0; bj < 2; ++bj) { if (col0 + bj * HALF < ncols) { const f32x4 v0 = acc[ai][bj][m][0], v1 = acc[ai][bj][m][1];
;                     u32x4 w; w.x = pk2(v0[0], v0[1]); w.y = pk2(v0[2], v0[3]); w.z = pk2(v1[0], v1[1]); w.w = pk2(v1[2], v1[3]);
;                     *(u32x4*)(rowp + bj * HALF) = w; } } }
;     }
.LBB0_206:
	v_lshl_add_u32 v168, s96, 8, v1
	v_ashrrev_i32_e32 v169, 31, v168
	v_lshl_or_b32 v142, s95, 8, v165
	v_lshlrev_b64 v[170:171], 12, v[168:169]
	v_ashrrev_i32_e32 v143, 31, v142
	v_lshl_add_u64 v[170:171], s[10:11], 0, v[170:171]
	v_lshl_add_u64 v[170:171], v[142:143], 1, v[170:171]
	v_cmp_gt_i32_e32 vcc, s0, v142
	s_and_saveexec_b64 s[2:3], vcc
	s_cbranch_execz .LBB0_208
	v_cvt_pk_bf16_f32 v126, v126, v127
	v_cvt_pk_bf16_f32 v127, v128, v129
	v_cvt_pk_bf16_f32 v128, v122, v123
	v_cvt_pk_bf16_f32 v129, v124, v125
	global_store_dwordx4 v[170:171], v[126:129], off
.LBB0_208:
	s_or_b64 exec, exec, s[2:3]
	v_or_b32_e32 v122, 0x80, v142
	v_cmp_gt_i32_e64 s[6:7], s0, v122
	s_and_saveexec_b64 s[2:3], s[6:7]
	s_cbranch_execz .LBB0_210
	v_cvt_pk_bf16_f32 v114, v114, v115
	v_cvt_pk_bf16_f32 v115, v116, v117
	v_cvt_pk_bf16_f32 v116, v106, v107
	v_cvt_pk_bf16_f32 v117, v108, v109
	global_store_dwordx4 v[170:171], v[114:117], off offset:256
.LBB0_210:
	s_or_b64 exec, exec, s[2:3]
	v_or_b32_e32 v106, 16, v168
	v_ashrrev_i32_e32 v107, 31, v106
	v_lshlrev_b64 v[106:107], 12, v[106:107]
	v_lshl_add_u64 v[106:107], s[10:11], 0, v[106:107]
	v_lshl_add_u64 v[106:107], v[142:143], 1, v[106:107]
	s_and_saveexec_b64 s[2:3], vcc
	s_cbranch_execz .LBB0_212
	v_cvt_pk_bf16_f32 v108, v118, v119
	v_cvt_pk_bf16_f32 v109, v120, v121
	v_cvt_pk_bf16_f32 v110, v110, v111
	v_cvt_pk_bf16_f32 v111, v112, v113
	global_store_dwordx4 v[106:107], v[108:111], off
.LBB0_212:
	s_or_b64 exec, exec, s[2:3]
	s_and_saveexec_b64 s[2:3], s[6:7]
	s_cbranch_execz .LBB0_214
	v_cvt_pk_bf16_f32 v98, v98, v99
	v_cvt_pk_bf16_f32 v99, v100, v101
	v_cvt_pk_bf16_f32 v100, v90, v91
	v_cvt_pk_bf16_f32 v101, v92, v93
	global_store_dwordx4 v[106:107], v[98:101], off offset:256
.LBB0_214:
	s_or_b64 exec, exec, s[2:3]
	v_or_b32_e32 v90, 32, v168
	v_ashrrev_i32_e32 v91, 31, v90
	v_lshlrev_b64 v[90:91], 12, v[90:91]
	v_lshl_add_u64 v[90:91], s[10:11], 0, v[90:91]
	v_lshl_add_u64 v[90:91], v[142:143], 1, v[90:91]
	s_and_saveexec_b64 s[2:3], vcc
	s_cbranch_execz .LBB0_216
	v_cvt_pk_bf16_f32 v92, v102, v103
	v_cvt_pk_bf16_f32 v93, v104, v105
	v_cvt_pk_bf16_f32 v94, v94, v95
	v_cvt_pk_bf16_f32 v95, v96, v97
	global_store_dwordx4 v[90:91], v[92:95], off
.LBB0_216:
	s_or_b64 exec, exec, s[2:3]
	s_and_saveexec_b64 s[2:3], s[6:7]
	s_cbranch_execz .LBB0_218
	v_cvt_pk_bf16_f32 v82, v82, v83
	v_cvt_pk_bf16_f32 v83, v84, v85
	v_cvt_pk_bf16_f32 v84, v74, v75
	v_cvt_pk_bf16_f32 v85, v76, v77
	global_store_dwordx4 v[90:91], v[82:85], off offset:256
.LBB0_218:
	s_or_b64 exec, exec, s[2:3]
	v_or_b32_e32 v74, 48, v168
	v_ashrrev_i32_e32 v75, 31, v74
	v_lshlrev_b64 v[74:75], 12, v[74:75]
	v_lshl_add_u64 v[74:75], s[10:11], 0, v[74:75]
	v_lshl_add_u64 v[74:75], v[142:143], 1, v[74:75]
	s_and_saveexec_b64 s[2:3], vcc
	s_cbranch_execz .LBB0_220
	v_cvt_pk_bf16_f32 v76, v86, v87
	v_cvt_pk_bf16_f32 v77, v88, v89
	v_cvt_pk_bf16_f32 v78, v78, v79
	v_cvt_pk_bf16_f32 v79, v80, v81
	global_store_dwordx4 v[74:75], v[76:79], off
.LBB0_220:
	s_or_b64 exec, exec, s[2:3]
	s_and_saveexec_b64 s[2:3], s[6:7]
	s_cbranch_execz .LBB0_222
	v_cvt_pk_bf16_f32 v70, v70, v71
	v_cvt_pk_bf16_f32 v71, v72, v73
	v_cvt_pk_bf16_f32 v72, v66, v67
	v_cvt_pk_bf16_f32 v73, v68, v69
	global_store_dwordx4 v[74:75], v[70:73], off offset:256
.LBB0_222:
	s_or_b64 exec, exec, s[2:3]
	v_lshlrev_b64 v[66:67], 12, v[168:169]
	v_lshl_add_u64 v[66:67], s[10:11], 0, v[66:67]
	v_lshl_add_u64 v[66:67], v[142:143], 1, v[66:67]
	s_mov_b64 s[2:3], 0x80000
	v_lshl_add_u64 v[66:67], v[66:67], 0, s[2:3]
	s_and_saveexec_b64 s[2:3], vcc
	s_cbranch_execz .LBB0_224
	v_cvt_pk_bf16_f32 v62, v62, v63
	v_cvt_pk_bf16_f32 v63, v64, v65
	v_cvt_pk_bf16_f32 v64, v58, v59
	v_cvt_pk_bf16_f32 v65, v60, v61
	global_store_dwordx4 v[66:67], v[62:65], off
.LBB0_224:
	s_or_b64 exec, exec, s[2:3]
	s_and_saveexec_b64 s[2:3], s[6:7]
	s_cbranch_execz .LBB0_226
	v_cvt_pk_bf16_f32 v50, v50, v51
	v_cvt_pk_bf16_f32 v51, v52, v53
	v_cvt_pk_bf16_f32 v52, v42, v43
	v_cvt_pk_bf16_f32 v53, v44, v45
	global_store_dwordx4 v[66:67], v[50:53], off offset:256
.LBB0_226:
	s_or_b64 exec, exec, s[2:3]
	v_lshlrev_b64 v[42:43], 12, v[168:169]
	v_lshl_add_u64 v[42:43], s[10:11], 0, v[42:43]
	v_lshl_add_u64 v[42:43], v[142:143], 1, v[42:43]
	s_mov_b64 s[2:3], 0x90000
	v_lshl_add_u64 v[42:43], v[42:43], 0, s[2:3]
	s_and_saveexec_b64 s[2:3], vcc
	s_cbranch_execz .LBB0_228
	v_cvt_pk_bf16_f32 v44, v54, v55
	v_cvt_pk_bf16_f32 v45, v56, v57
	v_cvt_pk_bf16_f32 v46, v46, v47
	v_cvt_pk_bf16_f32 v47, v48, v49
	global_store_dwordx4 v[42:43], v[44:47], off
.LBB0_228:
	s_or_b64 exec, exec, s[2:3]
	s_and_saveexec_b64 s[2:3], s[6:7]
	s_cbranch_execz .LBB0_230
	v_cvt_pk_bf16_f32 v34, v34, v35
	v_cvt_pk_bf16_f32 v35, v36, v37
	v_cvt_pk_bf16_f32 v36, v26, v27
	v_cvt_pk_bf16_f32 v37, v28, v29
	global_store_dwordx4 v[42:43], v[34:37], off offset:256
.LBB0_230:
	s_or_b64 exec, exec, s[2:3]
	v_lshlrev_b64 v[26:27], 12, v[168:169]
	v_lshl_add_u64 v[26:27], s[10:11], 0, v[26:27]
	v_lshl_add_u64 v[26:27], v[142:143], 1, v[26:27]
	s_mov_b64 s[2:3], 0xa0000
	v_lshl_add_u64 v[26:27], v[26:27], 0, s[2:3]
	s_and_saveexec_b64 s[2:3], vcc
	s_cbranch_execz .LBB0_232
	v_cvt_pk_bf16_f32 v28, v38, v39
	v_cvt_pk_bf16_f32 v29, v40, v41
	v_cvt_pk_bf16_f32 v30, v30, v31
	v_cvt_pk_bf16_f32 v31, v32, v33
	global_store_dwordx4 v[26:27], v[28:31], off
.LBB0_232:
	s_or_b64 exec, exec, s[2:3]
	s_and_saveexec_b64 s[2:3], s[6:7]
	s_cbranch_execz .LBB0_234
	v_cvt_pk_bf16_f32 v18, v18, v19
	v_cvt_pk_bf16_f32 v19, v20, v21
	v_cvt_pk_bf16_f32 v20, v10, v11
	v_cvt_pk_bf16_f32 v21, v12, v13
	global_store_dwordx4 v[26:27], v[18:21], off offset:256
.LBB0_234:
	s_or_b64 exec, exec, s[2:3]
	v_lshlrev_b64 v[10:11], 12, v[168:169]
	v_lshl_add_u64 v[10:11], s[10:11], 0, v[10:11]
	v_lshl_add_u64 v[10:11], v[142:143], 1, v[10:11]
	s_mov_b64 s[2:3], 0xb0000
	v_lshl_add_u64 v[10:11], v[10:11], 0, s[2:3]
	s_and_saveexec_b64 s[2:3], vcc
	s_cbranch_execz .LBB0_237
	v_cvt_pk_bf16_f32 v12, v22, v23
	v_cvt_pk_bf16_f32 v13, v24, v25
	v_cvt_pk_bf16_f32 v14, v14, v15
	v_cvt_pk_bf16_f32 v15, v16, v17
	global_store_dwordx4 v[10:11], v[12:15], off
	s_or_b64 exec, exec, s[2:3]
	s_and_saveexec_b64 s[2:3], s[6:7]
	s_cbranch_execnz .LBB0_238

; __device__ __forceinline__ unsigned pk2(float lo, float hi) { f32x2 v = {lo, hi}; bf16x2_t b = __builtin_convertvector(v, bf16x2_t); return __builtin_bit_cast(unsigned, b); }
;     __device__ __forceinline__ void operator()(const f32x4 (&acc)[2][2][4][2], const Unit& u, int wr, int wc, int fr, int fq) const {
;         const int row0 = u.pm * BM + wr * 64 + fr; const int col0 = u.pn * BM + wc * 32 + 8 * fq;
; #pragma unroll
;         for (int ai = 0; ai < 2; ++ai)
; #pragma unroll
;             for (int m = 0; m < 4; ++m) { bf16_t* rowp = O + (size_t)(row0 + ai * HALF + m * 16) * ldc + col0;
; #pragma unroll
;                 for (int bj = 0; bj < 2; ++bj) { if (col0 + bj * HALF < ncols) { const f32x4 v0 = acc[ai][bj][m][0], v1 = acc[ai][bj][m][1];
;                     u32x4 w; w.x = pk2(v0[0], v0[1]); w.y = pk2(v0[2], v0[3]); w.z = pk2(v1[0], v1[1]); w.w = pk2(v1[2], v1[3]);
;                     *(u32x4*)(rowp + bj * HALF) = w; } } }
;     }
.LBB0_238:
	v_cvt_pk_bf16_f32 v6, v6, v7
	v_cvt_pk_bf16_f32 v7, v8, v9
	v_cvt_pk_bf16_f32 v8, v2, v3
	v_cvt_pk_bf16_f32 v9, v4, v5
	global_store_dwordx4 v[10:11], v[6:9], off offset:256
	s_or_b64 exec, exec, s[2:3]
	s_and_b64 vcc, exec, s[4:5]
	s_mov_b64 s[2:3], -1
	s_cbranch_vccnz .LBB0_195

; __device__ __forceinline__ unsigned pk2(float lo, float hi) { f32x2 v = {lo, hi}; bf16x2_t b = __builtin_convertvector(v, bf16x2_t); return __builtin_bit_cast(unsigned, b); }
;     __device__ __forceinline__ void operator()(const f32x4 (&acc)[2][2][4][2], const Unit& u, int wr, int wc, int fr, int fq) const {
;         const int row0 = u.pm * BM + wr * 64 + fr; const int col0 = u.pn * BM + wc * 32 + 8 * fq;
; #pragma unroll
;         for (int ai = 0; ai < 2; ++ai)
; #pragma unroll
;             for (int m = 0; m < 4; ++m) { bf16_t* rowp = O + (size_t)(row0 + ai * HALF + m * 16) * ldc + col0;
; #pragma unroll
;                 for (int bj = 0; bj < 2; ++bj) { if (col0 + bj * HALF < ncols) { const f32x4 v0 = acc[ai][bj][m][0], v1 = acc[ai][bj][m][1];
;                     u32x4 w; w.x = pk2(v0[0], v0[1]); w.y = pk2(v0[2], v0[3]); w.z = pk2(v1[0], v1[1]); w.w = pk2(v1[2], v1[3]);
;                     *(u32x4*)(rowp + bj * HALF) = w; } } }
;     }
.LBB0_258:
	v_lshl_add_u32 v171, s92, 8, v150
	v_lshl_or_b32 v142, s20, 8, v167
	v_mov_b64_e32 v[168:169], s[10:11]
	v_ashrrev_i32_e32 v143, 31, v142
	v_mad_i64_i32 v[168:169], s[2:3], v171, s50, v[168:169]
	v_lshl_add_u64 v[168:169], v[142:143], 1, v[168:169]
	v_cmp_gt_i32_e32 vcc, s0, v142
	s_and_saveexec_b64 s[2:3], vcc
	s_cbranch_execz .LBB0_260
	v_cvt_pk_bf16_f32 v126, v126, v127
	v_cvt_pk_bf16_f32 v127, v128, v129
	v_cvt_pk_bf16_f32 v128, v122, v123
	v_cvt_pk_bf16_f32 v129, v124, v125
	global_store_dwordx4 v[168:169], v[126:129], off
.LBB0_260:
	s_or_b64 exec, exec, s[2:3]
	v_or_b32_e32 v122, 0x80, v142
	v_cmp_gt_i32_e64 s[6:7], s0, v122
	s_and_saveexec_b64 s[2:3], s[6:7]
	s_cbranch_execz .LBB0_262
	v_cvt_pk_bf16_f32 v114, v114, v115
	v_cvt_pk_bf16_f32 v115, v116, v117
	v_cvt_pk_bf16_f32 v116, v106, v107
	v_cvt_pk_bf16_f32 v117, v108, v109
	global_store_dwordx4 v[168:169], v[114:117], off offset:256
.LBB0_262:
	s_or_b64 exec, exec, s[2:3]
	v_or_b32_e32 v108, 16, v171
	v_mov_b64_e32 v[106:107], s[10:11]
	v_mad_i64_i32 v[106:107], s[2:3], v108, s50, v[106:107]
	v_lshl_add_u64 v[106:107], v[142:143], 1, v[106:107]
	s_and_saveexec_b64 s[2:3], vcc
	s_cbranch_execz .LBB0_264
	v_cvt_pk_bf16_f32 v108, v118, v119
	v_cvt_pk_bf16_f32 v109, v120, v121
	v_cvt_pk_bf16_f32 v110, v110, v111
	v_cvt_pk_bf16_f32 v111, v112, v113
	global_store_dwordx4 v[106:107], v[108:111], off

; __device__ __forceinline__ unsigned pk2(float lo, float hi) { f32x2 v = {lo, hi}; bf16x2_t b = __builtin_convertvector(v, bf16x2_t); return __builtin_bit_cast(unsigned, b); }
;     __device__ __forceinline__ void operator()(const f32x4 (&acc)[2][2][4][2], const Unit& u, int wr, int wc, int fr, int fq) const {
;         const int row0 = u.pm * BM + wr * 64 + fr; const int col0 = u.pn * BM + wc * 32 + 8 * fq;
; #pragma unroll
;         for (int ai = 0; ai < 2; ++ai)
; #pragma unroll
;             for (int m = 0; m < 4; ++m) { bf16_t* rowp = O + (size_t)(row0 + ai * HALF + m * 16) * ldc + col0;
; #pragma unroll
;                 for (int bj = 0; bj < 2; ++bj) { if (col0 + bj * HALF < ncols) { const f32x4 v0 = acc[ai][bj][m][0], v1 = acc[ai][bj][m][1];
;                     u32x4 w; w.x = pk2(v0[0], v0[1]); w.y = pk2(v0[2], v0[3]); w.z = pk2(v1[0], v1[1]); w.w = pk2(v1[2], v1[3]);
;                     *(u32x4*)(rowp + bj * HALF) = w; } } }
;     }
.LBB0_266:
	s_or_b64 exec, exec, s[2:3]
	v_or_b32_e32 v92, 32, v171
	v_mov_b64_e32 v[90:91], s[10:11]
	v_mad_i64_i32 v[90:91], s[2:3], v92, s50, v[90:91]
	v_lshl_add_u64 v[90:91], v[142:143], 1, v[90:91]
	s_and_saveexec_b64 s[2:3], vcc
	s_cbranch_execz .LBB0_268
	v_cvt_pk_bf16_f32 v92, v102, v103
	v_cvt_pk_bf16_f32 v93, v104, v105
	v_cvt_pk_bf16_f32 v94, v94, v95
	v_cvt_pk_bf16_f32 v95, v96, v97
	global_store_dwordx4 v[90:91], v[92:95], off

; __device__ __forceinline__ unsigned pk2(float lo, float hi) { f32x2 v = {lo, hi}; bf16x2_t b = __builtin_convertvector(v, bf16x2_t); return __builtin_bit_cast(unsigned, b); }
;     __device__ __forceinline__ void operator()(const f32x4 (&acc)[2][2][4][2], const Unit& u, int wr, int wc, int fr, int fq) const {
;         const int row0 = u.pm * BM + wr * 64 + fr; const int col0 = u.pn * BM + wc * 32 + 8 * fq;
; #pragma unroll
;         for (int ai = 0; ai < 2; ++ai)
; #pragma unroll
;             for (int m = 0; m < 4; ++m) { bf16_t* rowp = O + (size_t)(row0 + ai * HALF + m * 16) * ldc + col0;
; #pragma unroll
;                 for (int bj = 0; bj < 2; ++bj) { if (col0 + bj * HALF < ncols) { const f32x4 v0 = acc[ai][bj][m][0], v1 = acc[ai][bj][m][1];
;                     u32x4 w; w.x = pk2(v0[0], v0[1]); w.y = pk2(v0[2], v0[3]); w.z = pk2(v1[0], v1[1]); w.w = pk2(v1[2], v1[3]);
;                     *(u32x4*)(rowp + bj * HALF) = w; } } }
;     }
.LBB0_270:
	s_or_b64 exec, exec, s[2:3]
	v_or_b32_e32 v76, 48, v171
	v_mov_b64_e32 v[74:75], s[10:11]
	v_mad_i64_i32 v[74:75], s[2:3], v76, s50, v[74:75]
	v_lshl_add_u64 v[74:75], v[142:143], 1, v[74:75]
	s_and_saveexec_b64 s[2:3], vcc
	s_cbranch_execz .LBB0_272
	v_cvt_pk_bf16_f32 v76, v86, v87
	v_cvt_pk_bf16_f32 v77, v88, v89
	v_cvt_pk_bf16_f32 v78, v78, v79
	v_cvt_pk_bf16_f32 v79, v80, v81
	global_store_dwordx4 v[74:75], v[76:79], off

; __device__ __forceinline__ unsigned pk2(float lo, float hi) { f32x2 v = {lo, hi}; bf16x2_t b = __builtin_convertvector(v, bf16x2_t); return __builtin_bit_cast(unsigned, b); }
;     __device__ __forceinline__ void operator()(const f32x4 (&acc)[2][2][4][2], const Unit& u, int wr, int wc, int fr, int fq) const {
;     ...
;             for (int m = 0; m < 4; ++m) { bf16_t* rowp = O + (size_t)(row0 + ai * HALF + m * 16) * ldc + col0;
; #pragma unroll
;                 for (int bj = 0; bj < 2; ++bj) { if (col0 + bj * HALF < ncols) { const f32x4 v0 = acc[ai][bj][m][0], v1 = acc[ai][bj][m][1];
;                     u32x4 w; w.x = pk2(v0[0], v0[1]); w.y = pk2(v0[2], v0[3]); w.z = pk2(v1[0], v1[1]); w.w = pk2(v1[2], v1[3]);
;                     *(u32x4*)(rowp + bj * HALF) = w; } } }
.LBB0_274:
	s_or_b64 exec, exec, s[2:3]
	v_add_u32_e32 v68, 0x80, v171
	v_mov_b64_e32 v[66:67], s[10:11]
	v_mad_i64_i32 v[66:67], s[2:3], v68, s50, v[66:67]
	v_lshl_add_u64 v[66:67], v[142:143], 1, v[66:67]
	s_and_saveexec_b64 s[2:3], vcc
	s_cbranch_execz .LBB0_276
	v_cvt_pk_bf16_f32 v62, v62, v63
	v_cvt_pk_bf16_f32 v63, v64, v65
	v_cvt_pk_bf16_f32 v64, v58, v59
	v_cvt_pk_bf16_f32 v65, v60, v61
	global_store_dwordx4 v[66:67], v[62:65], off

; __device__ __forceinline__ unsigned pk2(float lo, float hi) { f32x2 v = {lo, hi}; bf16x2_t b = __builtin_convertvector(v, bf16x2_t); return __builtin_bit_cast(unsigned, b); }
;     __device__ __forceinline__ void operator()(const f32x4 (&acc)[2][2][4][2], const Unit& u, int wr, int wc, int fr, int fq) const {
;     ...
;             for (int m = 0; m < 4; ++m) { bf16_t* rowp = O + (size_t)(row0 + ai * HALF + m * 16) * ldc + col0;
; #pragma unroll
;                 for (int bj = 0; bj < 2; ++bj) { if (col0 + bj * HALF < ncols) { const f32x4 v0 = acc[ai][bj][m][0], v1 = acc[ai][bj][m][1];
;                     u32x4 w; w.x = pk2(v0[0], v0[1]); w.y = pk2(v0[2], v0[3]); w.z = pk2(v1[0], v1[1]); w.w = pk2(v1[2], v1[3]);
;                     *(u32x4*)(rowp + bj * HALF) = w; } } }
.LBB0_278:
	s_or_b64 exec, exec, s[2:3]
	v_add_u32_e32 v44, 0x90, v171
	v_mov_b64_e32 v[42:43], s[10:11]
	v_mad_i64_i32 v[42:43], s[2:3], v44, s50, v[42:43]
	v_lshl_add_u64 v[42:43], v[142:143], 1, v[42:43]
	s_and_saveexec_b64 s[2:3], vcc
	s_cbranch_execz .LBB0_280
	v_cvt_pk_bf16_f32 v44, v54, v55
	v_cvt_pk_bf16_f32 v45, v56, v57
	v_cvt_pk_bf16_f32 v46, v46, v47
	v_cvt_pk_bf16_f32 v47, v48, v49
	global_store_dwordx4 v[42:43], v[44:47], off

; __device__ __forceinline__ unsigned pk2(float lo, float hi) { f32x2 v = {lo, hi}; bf16x2_t b = __builtin_convertvector(v, bf16x2_t); return __builtin_bit_cast(unsigned, b); }
;     __device__ __forceinline__ void operator()(const f32x4 (&acc)[2][2][4][2], const Unit& u, int wr, int wc, int fr, int fq) const {
;     ...
;             for (int m = 0; m < 4; ++m) { bf16_t* rowp = O + (size_t)(row0 + ai * HALF + m * 16) * ldc + col0;
; #pragma unroll
;                 for (int bj = 0; bj < 2; ++bj) { if (col0 + bj * HALF < ncols) { const f32x4 v0 = acc[ai][bj][m][0], v1 = acc[ai][bj][m][1];
;                     u32x4 w; w.x = pk2(v0[0], v0[1]); w.y = pk2(v0[2], v0[3]); w.z = pk2(v1[0], v1[1]); w.w = pk2(v1[2], v1[3]);
;                     *(u32x4*)(rowp + bj * HALF) = w; } } }
.LBB0_282:
	s_or_b64 exec, exec, s[2:3]
	v_add_u32_e32 v28, 0xa0, v171
	v_mov_b64_e32 v[26:27], s[10:11]
	v_mad_i64_i32 v[26:27], s[2:3], v28, s50, v[26:27]
	v_lshl_add_u64 v[26:27], v[142:143], 1, v[26:27]
	s_and_saveexec_b64 s[2:3], vcc
	s_cbranch_execz .LBB0_284
	v_cvt_pk_bf16_f32 v28, v38, v39
	v_cvt_pk_bf16_f32 v29, v40, v41
	v_cvt_pk_bf16_f32 v30, v30, v31
	v_cvt_pk_bf16_f32 v31, v32, v33
	global_store_dwordx4 v[26:27], v[28:31], off

; __device__ __forceinline__ unsigned pk2(float lo, float hi) { f32x2 v = {lo, hi}; bf16x2_t b = __builtin_convertvector(v, bf16x2_t); return __builtin_bit_cast(unsigned, b); }
;     __device__ __forceinline__ void operator()(const f32x4 (&acc)[2][2][4][2], const Unit& u, int wr, int wc, int fr, int fq) const {
;     ...
;             for (int m = 0; m < 4; ++m) { bf16_t* rowp = O + (size_t)(row0 + ai * HALF + m * 16) * ldc + col0;
; #pragma unroll
;                 for (int bj = 0; bj < 2; ++bj) { if (col0 + bj * HALF < ncols) { const f32x4 v0 = acc[ai][bj][m][0], v1 = acc[ai][bj][m][1];
;                     u32x4 w; w.x = pk2(v0[0], v0[1]); w.y = pk2(v0[2], v0[3]); w.z = pk2(v1[0], v1[1]); w.w = pk2(v1[2], v1[3]);
;                     *(u32x4*)(rowp + bj * HALF) = w; } } }
.LBB0_286:
	s_or_b64 exec, exec, s[2:3]
	v_add_u32_e32 v12, 0xb0, v171
	v_mov_b64_e32 v[10:11], s[10:11]
	v_mad_i64_i32 v[10:11], s[2:3], v12, s50, v[10:11]
	v_lshl_add_u64 v[10:11], v[142:143], 1, v[10:11]
	s_and_saveexec_b64 s[2:3], vcc
	s_cbranch_execz .LBB0_289
	v_cvt_pk_bf16_f32 v12, v22, v23
	v_cvt_pk_bf16_f32 v13, v24, v25
	v_cvt_pk_bf16_f32 v14, v14, v15
	v_cvt_pk_bf16_f32 v15, v16, v17
	global_store_dwordx4 v[10:11], v[12:15], off
	s_or_b64 exec, exec, s[2:3]
	s_and_saveexec_b64 s[2:3], s[6:7]
	s_cbranch_execnz .LBB0_290

; __device__ __forceinline__ unsigned pk2(float lo, float hi) { f32x2 v = {lo, hi}; bf16x2_t b = __builtin_convertvector(v, bf16x2_t); return __builtin_bit_cast(unsigned, b); }
;     __device__ __forceinline__ void operator()(const f32x4 (&acc)[2][2][4][2], const Unit& u, int wr, int wc, int fr, int fq) const {
;         const int row0 = u.pm * BM + wr * 64 + fr; const int col0 = u.pn * BM + wc * 32 + 8 * fq;
; #pragma unroll
;         for (int ai = 0; ai < 2; ++ai)
; #pragma unroll
;             for (int m = 0; m < 4; ++m) { bf16_t* rowp = O + (size_t)(row0 + ai * HALF + m * 16) * ldc + col0;
; #pragma unroll
;                 for (int bj = 0; bj < 2; ++bj) { if (col0 + bj * HALF < ncols) { const f32x4 v0 = acc[ai][bj][m][0], v1 = acc[ai][bj][m][1];
;                     u32x4 w; w.x = pk2(v0[0], v0[1]); w.y = pk2(v0[2], v0[3]); w.z = pk2(v1[0], v1[1]); w.w = pk2(v1[2], v1[3]);
;                     *(u32x4*)(rowp + bj * HALF) = w; } } }
;     }
.LBB0_310:
	v_lshl_add_u32 v140, s9, 8, v150
	v_ashrrev_i32_e32 v141, 31, v140
	v_lshl_or_b32 v138, s18, 8, v165
	v_lshlrev_b64 v[142:143], 11, v[140:141]
	v_ashrrev_i32_e32 v139, 31, v138
	v_lshl_add_u64 v[142:143], s[74:75], 0, v[142:143]
	s_movk_i32 s0, 0x400
	v_lshl_add_u64 v[142:143], v[138:139], 1, v[142:143]
	v_cmp_gt_i32_e32 vcc, s0, v138
	s_and_saveexec_b64 s[2:3], vcc
	s_cbranch_execz .LBB0_312
	v_cvt_pk_bf16_f32 v126, v126, v127
	v_cvt_pk_bf16_f32 v127, v128, v129
	v_cvt_pk_bf16_f32 v128, v122, v123
	v_cvt_pk_bf16_f32 v129, v124, v125
	global_store_dwordx4 v[142:143], v[126:129], off
.LBB0_312:
	s_or_b64 exec, exec, s[2:3]
	v_or_b32_e32 v122, 0x80, v138
	v_cmp_gt_i32_e64 s[6:7], s0, v122
	s_and_saveexec_b64 s[2:3], s[6:7]
	s_cbranch_execz .LBB0_314
	v_cvt_pk_bf16_f32 v118, v118, v119
	v_cvt_pk_bf16_f32 v119, v120, v121
	v_cvt_pk_bf16_f32 v120, v110, v111
	v_cvt_pk_bf16_f32 v121, v112, v113
	global_store_dwordx4 v[142:143], v[118:121], off offset:256
.LBB0_314:
	s_or_b64 exec, exec, s[2:3]
	v_or_b32_e32 v110, 16, v140
	v_ashrrev_i32_e32 v111, 31, v110
	v_lshlrev_b64 v[110:111], 11, v[110:111]
	v_lshl_add_u64 v[110:111], s[74:75], 0, v[110:111]
	v_lshl_add_u64 v[110:111], v[138:139], 1, v[110:111]
	s_and_saveexec_b64 s[2:3], vcc
	v_readlane_b32 s80, v255, 41
	s_cbranch_execz .LBB0_316
	v_cvt_pk_bf16_f32 v112, v114, v115
	v_cvt_pk_bf16_f32 v113, v116, v117
	v_cvt_pk_bf16_f32 v114, v106, v107
	v_cvt_pk_bf16_f32 v115, v108, v109
	global_store_dwordx4 v[110:111], v[112:115], off
.LBB0_316:
	s_or_b64 exec, exec, s[2:3]
	s_and_saveexec_b64 s[2:3], s[6:7]
	s_cbranch_execz .LBB0_318
	v_cvt_pk_bf16_f32 v98, v98, v99
	v_cvt_pk_bf16_f32 v99, v100, v101
	v_cvt_pk_bf16_f32 v100, v90, v91
	v_cvt_pk_bf16_f32 v101, v92, v93
	global_store_dwordx4 v[110:111], v[98:101], off offset:256
.LBB0_318:
	s_or_b64 exec, exec, s[2:3]
	v_or_b32_e32 v90, 32, v140
	v_ashrrev_i32_e32 v91, 31, v90
	v_lshlrev_b64 v[90:91], 11, v[90:91]
	v_lshl_add_u64 v[90:91], s[74:75], 0, v[90:91]
	v_lshl_add_u64 v[90:91], v[138:139], 1, v[90:91]
	s_and_saveexec_b64 s[2:3], vcc
	s_cbranch_execz .LBB0_320
	v_cvt_pk_bf16_f32 v92, v102, v103
	v_cvt_pk_bf16_f32 v93, v104, v105
	v_cvt_pk_bf16_f32 v94, v94, v95
	v_cvt_pk_bf16_f32 v95, v96, v97
	global_store_dwordx4 v[90:91], v[92:95], off

; __device__ __forceinline__ unsigned pk2(float lo, float hi) { f32x2 v = {lo, hi}; bf16x2_t b = __builtin_convertvector(v, bf16x2_t); return __builtin_bit_cast(unsigned, b); }
;     __device__ __forceinline__ void operator()(const f32x4 (&acc)[2][2][4][2], const Unit& u, int wr, int wc, int fr, int fq) const {
;     ...
;             for (int m = 0; m < 4; ++m) { bf16_t* rowp = O + (size_t)(row0 + ai * HALF + m * 16) * ldc + col0;
; #pragma unroll
;                 for (int bj = 0; bj < 2; ++bj) { if (col0 + bj * HALF < ncols) { const f32x4 v0 = acc[ai][bj][m][0], v1 = acc[ai][bj][m][1];
;                     u32x4 w; w.x = pk2(v0[0], v0[1]); w.y = pk2(v0[2], v0[3]); w.z = pk2(v1[0], v1[1]); w.w = pk2(v1[2], v1[3]);
;                     *(u32x4*)(rowp + bj * HALF) = w; } } }
.LBB0_322:
	s_or_b64 exec, exec, s[2:3]
	v_or_b32_e32 v74, 48, v140
	v_ashrrev_i32_e32 v75, 31, v74
	v_lshlrev_b64 v[74:75], 11, v[74:75]
	v_lshl_add_u64 v[74:75], s[74:75], 0, v[74:75]
	v_lshl_add_u64 v[74:75], v[138:139], 1, v[74:75]
	s_and_saveexec_b64 s[2:3], vcc
	s_cbranch_execz .LBB0_324
	v_cvt_pk_bf16_f32 v76, v86, v87
	v_cvt_pk_bf16_f32 v77, v88, v89
	v_cvt_pk_bf16_f32 v78, v78, v79
	v_cvt_pk_bf16_f32 v79, v80, v81
	global_store_dwordx4 v[74:75], v[76:79], off

; __device__ __forceinline__ unsigned pk2(float lo, float hi) { f32x2 v = {lo, hi}; bf16x2_t b = __builtin_convertvector(v, bf16x2_t); return __builtin_bit_cast(unsigned, b); }
;     __device__ __forceinline__ void operator()(const f32x4 (&acc)[2][2][4][2], const Unit& u, int wr, int wc, int fr, int fq) const {
;     ...
;             for (int m = 0; m < 4; ++m) { bf16_t* rowp = O + (size_t)(row0 + ai * HALF + m * 16) * ldc + col0;
; #pragma unroll
;                 for (int bj = 0; bj < 2; ++bj) { if (col0 + bj * HALF < ncols) { const f32x4 v0 = acc[ai][bj][m][0], v1 = acc[ai][bj][m][1];
;                     u32x4 w; w.x = pk2(v0[0], v0[1]); w.y = pk2(v0[2], v0[3]); w.z = pk2(v1[0], v1[1]); w.w = pk2(v1[2], v1[3]);
;                     *(u32x4*)(rowp + bj * HALF) = w; } } }
.LBB0_326:
	s_or_b64 exec, exec, s[2:3]
	v_lshlrev_b64 v[66:67], 11, v[140:141]
	v_lshl_add_u64 v[66:67], s[74:75], 0, v[66:67]
	v_lshl_add_u64 v[66:67], v[138:139], 1, v[66:67]
	s_mov_b64 s[2:3], 0x40000
	v_lshl_add_u64 v[66:67], v[66:67], 0, s[2:3]
	s_and_saveexec_b64 s[2:3], vcc
	s_cbranch_execz .LBB0_328
	v_cvt_pk_bf16_f32 v62, v62, v63
	v_cvt_pk_bf16_f32 v63, v64, v65
	v_cvt_pk_bf16_f32 v64, v58, v59
	v_cvt_pk_bf16_f32 v65, v60, v61
	global_store_dwordx4 v[66:67], v[62:65], off

; __device__ __forceinline__ unsigned pk2(float lo, float hi) { f32x2 v = {lo, hi}; bf16x2_t b = __builtin_convertvector(v, bf16x2_t); return __builtin_bit_cast(unsigned, b); }
;     __device__ __forceinline__ void operator()(const f32x4 (&acc)[2][2][4][2], const Unit& u, int wr, int wc, int fr, int fq) const {
;     ...
;             for (int m = 0; m < 4; ++m) { bf16_t* rowp = O + (size_t)(row0 + ai * HALF + m * 16) * ldc + col0;
; #pragma unroll
;                 for (int bj = 0; bj < 2; ++bj) { if (col0 + bj * HALF < ncols) { const f32x4 v0 = acc[ai][bj][m][0], v1 = acc[ai][bj][m][1];
;                     u32x4 w; w.x = pk2(v0[0], v0[1]); w.y = pk2(v0[2], v0[3]); w.z = pk2(v1[0], v1[1]); w.w = pk2(v1[2], v1[3]);
;                     *(u32x4*)(rowp + bj * HALF) = w; } } }
.LBB0_330:
	s_or_b64 exec, exec, s[2:3]
	v_lshlrev_b64 v[42:43], 11, v[140:141]
	v_lshl_add_u64 v[42:43], s[74:75], 0, v[42:43]
	v_lshl_add_u64 v[42:43], v[138:139], 1, v[42:43]
	s_mov_b64 s[2:3], 0x48000
	v_lshl_add_u64 v[42:43], v[42:43], 0, s[2:3]
	s_and_saveexec_b64 s[2:3], vcc
	s_cbranch_execz .LBB0_332
	v_cvt_pk_bf16_f32 v44, v54, v55
	v_cvt_pk_bf16_f32 v45, v56, v57
	v_cvt_pk_bf16_f32 v46, v46, v47
	v_cvt_pk_bf16_f32 v47, v48, v49
	global_store_dwordx4 v[42:43], v[44:47], off

; __device__ __forceinline__ unsigned pk2(float lo, float hi) { f32x2 v = {lo, hi}; bf16x2_t b = __builtin_convertvector(v, bf16x2_t); return __builtin_bit_cast(unsigned, b); }
;     __device__ __forceinline__ void operator()(const f32x4 (&acc)[2][2][4][2], const Unit& u, int wr, int wc, int fr, int fq) const {
;     ...
;             for (int m = 0; m < 4; ++m) { bf16_t* rowp = O + (size_t)(row0 + ai * HALF + m * 16) * ldc + col0;
; #pragma unroll
;                 for (int bj = 0; bj < 2; ++bj) { if (col0 + bj * HALF < ncols) { const f32x4 v0 = acc[ai][bj][m][0], v1 = acc[ai][bj][m][1];
;                     u32x4 w; w.x = pk2(v0[0], v0[1]); w.y = pk2(v0[2], v0[3]); w.z = pk2(v1[0], v1[1]); w.w = pk2(v1[2], v1[3]);
;                     *(u32x4*)(rowp + bj * HALF) = w; } } }
.LBB0_334:
	s_or_b64 exec, exec, s[2:3]
	v_lshlrev_b64 v[26:27], 11, v[140:141]
	v_lshl_add_u64 v[26:27], s[74:75], 0, v[26:27]
	v_lshl_add_u64 v[26:27], v[138:139], 1, v[26:27]
	s_mov_b64 s[2:3], 0x50000
	v_lshl_add_u64 v[26:27], v[26:27], 0, s[2:3]
	s_and_saveexec_b64 s[2:3], vcc
	s_cbranch_execz .LBB0_336
	v_cvt_pk_bf16_f32 v28, v38, v39
	v_cvt_pk_bf16_f32 v29, v40, v41
	v_cvt_pk_bf16_f32 v30, v30, v31
	v_cvt_pk_bf16_f32 v31, v32, v33
	global_store_dwordx4 v[26:27], v[28:31], off

; __device__ __forceinline__ unsigned pk2(float lo, float hi) { f32x2 v = {lo, hi}; bf16x2_t b = __builtin_convertvector(v, bf16x2_t); return __builtin_bit_cast(unsigned, b); }
;     __device__ __forceinline__ void operator()(const f32x4 (&acc)[2][2][4][2], const Unit& u, int wr, int wc, int fr, int fq) const {
;     ...
;             for (int m = 0; m < 4; ++m) { bf16_t* rowp = O + (size_t)(row0 + ai * HALF + m * 16) * ldc + col0;
; #pragma unroll
;                 for (int bj = 0; bj < 2; ++bj) { if (col0 + bj * HALF < ncols) { const f32x4 v0 = acc[ai][bj][m][0], v1 = acc[ai][bj][m][1];
;                     u32x4 w; w.x = pk2(v0[0], v0[1]); w.y = pk2(v0[2], v0[3]); w.z = pk2(v1[0], v1[1]); w.w = pk2(v1[2], v1[3]);
;                     *(u32x4*)(rowp + bj * HALF) = w; } } }
.LBB0_338:
	s_or_b64 exec, exec, s[2:3]
	v_lshlrev_b64 v[10:11], 11, v[140:141]
	v_lshl_add_u64 v[10:11], s[74:75], 0, v[10:11]
	v_lshl_add_u64 v[10:11], v[138:139], 1, v[10:11]
	s_mov_b64 s[2:3], 0x58000
	v_lshl_add_u64 v[10:11], v[10:11], 0, s[2:3]
	s_and_saveexec_b64 s[2:3], vcc
	s_cbranch_execz .LBB0_341
	v_cvt_pk_bf16_f32 v12, v22, v23
	v_cvt_pk_bf16_f32 v13, v24, v25
	v_cvt_pk_bf16_f32 v14, v14, v15
	v_cvt_pk_bf16_f32 v15, v16, v17
	global_store_dwordx4 v[10:11], v[12:15], off
	s_or_b64 exec, exec, s[2:3]
	s_and_saveexec_b64 s[2:3], s[6:7]
	s_cbranch_execnz .LBB0_342

; __device__ __forceinline__ void odd_prep_a(const Ctx& c, const Params& p, int o) {
;     const bf16_t* Z2 = (const bf16_t*)(c.ws + WS_Z2); bf16_t* LA = (bf16_t*)(c.ws + WS_LA); bf16_t* KR = (bf16_t*)(c.ws + WS_KR); float* RS = (float*)(c.ws + WS_RS);
;     const float* mu = p.in[c.zo + 14] + (size_t)o * 1792; const float* vmu = o ? p.in[c.zo + 26] + (size_t)(o - 1) * 32 : p.in[c.zo + 26];
;     if (c.bid == 0 && c.tid == 0) { unsigned* ctl = (unsigned*)(c.ws + WS_CTL); ctl[64 * o] = 0u; ctl[64 * o + 16] = 0u; }
.LBB0_347:
	s_and_b64 vcc, exec, s[2:3]
	s_cbranch_vccz .LBB0_485
	v_readlane_b32 s0, v255, 26
	v_readlane_b32 s1, v255, 27
	s_lshl_b64 s[2:3], s[0:1], 3
	v_readlane_b32 s0, v255, 15
	v_readlane_b32 s1, v255, 16
	s_add_u32 s2, s0, s2
	s_addc_u32 s3, s1, s3
	s_load_dwordx2 s[4:5], s[2:3], 0x70
	s_nop 0
	s_load_dwordx2 s[2:3], s[2:3], 0xd0
	v_or_b32_e32 v1, s94, v166
	v_cmp_eq_u32_e32 vcc, 0, v1
	s_and_saveexec_b64 s[6:7], vcc
	s_cbranch_execz .LBB0_350
	v_readlane_b32 s0, v255, 39
	s_lshl_b32 s42, s0, 6
	s_lshl_b64 s[8:9], s[42:43], 2
	s_add_u32 s8, s22, s8
	s_addc_u32 s9, s23, s9
	v_mov_b64_e32 v[2:3], s[8:9]
	v_readlane_b32 s1, v255, 40
	global_store_dword v[2:3], v0, off
	global_store_dword v[2:3], v0, off offset:64

; __device__ __forceinline__ float sigmoidf_(float x) { return __builtin_amdgcn_rcpf(1.f + __expf(-x)); }
; __device__ __forceinline__ void odd_prep_a(const Ctx& c, const Params& p, int o) {
;     ...
;     for (int m = c.gw; m < M_; m += c.ngw) { const int t = m & (T_ - 1); const bf16_t* zr = Z2 + (size_t)m * Z2_LD;
;         if (grp < 48) { float out[8];
; #pragma unroll
;             for (int i = 0; i < 8; ++i) out[i] = 0.f;
;             if (kind < 3 || (kind == 3 && o > 0)) { float cu[8], pv[8]; unpack8(*(const u32x4*)(zr + zc), cu);
;                 if (t > 0) unpack8(*(const u32x4*)(zr + zc - Z2_LD), pv); else {
; #pragma unroll
;                     for (int i = 0; i < 8; ++i) pv[i] = 0.f; }
; #pragma unroll
;                 for (int i = 0; i < 8; ++i) { const float x = cu[i] + mv[i] * (pv[i] - cu[i]); out[i] = (kind == 0) ? (2.f * sigmoidf_(2.f * x) - 1.f) : (kind == 2 ? sigmoidf_(x) : x); } }
.LBB0_401:
	s_and_saveexec_b64 s[10:11], s[4:5]
	s_cbranch_execz .LBB0_472
	v_mov_b32_e32 v5, 0
	v_mov_b32_e32 v30, 0
	v_mov_b32_e32 v4, 0
	v_mov_b32_e32 v32, 0
	v_mov_b32_e32 v3, 0
	v_mov_b32_e32 v29, 0
	v_mov_b32_e32 v2, 0
	v_mov_b32_e32 v18, 0
	s_and_saveexec_b64 s[26:27], s[2:3]
	s_cbranch_execz .LBB0_471
	v_lshl_add_u64 v[18:19], s[22:23], 0, v[14:15]
	v_add_co_u32_e32 v2, vcc, 0xe100000, v18
	s_and_b32 s12, s29, 0x1fff
	s_nop 0
	v_addc_co_u32_e32 v3, vcc, 0, v19, vcc
	global_load_dwordx4 v[2:5], v[2:3], off
	s_cmp_eq_u32 s12, 0
	s_cbranch_scc1 .LBB0_405
	v_add_co_u32_e32 v18, vcc, 0xe0ff000, v18
	s_nop 1
	v_addc_co_u32_e32 v19, vcc, 0, v19, vcc
	global_load_dwordx4 v[36:39], v[18:19], off offset:1536
	s_waitcnt vmcnt(0) lgkmcnt(0)
	v_lshlrev_b32_e32 v34, 16, v36
	v_and_b32_e32 v29, 0xffff0000, v36
	v_lshlrev_b32_e32 v33, 16, v37
	v_and_b32_e32 v32, 0xffff0000, v37
	v_lshlrev_b32_e32 v31, 16, v38
	v_and_b32_e32 v30, 0xffff0000, v38
	v_lshlrev_b32_e32 v28, 16, v39
	v_and_b32_e32 v19, 0xffff0000, v39
	s_branch .LBB0_406

; __device__ __forceinline__ u32x4 pack8(const float* f) { u32x4 o; o.x = pk2(f[0], f[1]); o.y = pk2(f[2], f[3]); o.z = pk2(f[4], f[5]); o.w = pk2(f[6], f[7]); return o; }
; __device__ __forceinline__ float sigmoidf_(float x) { return __builtin_amdgcn_rcpf(1.f + __expf(-x)); }
; __device__ __forceinline__ float wave_sum_dpp(float v) { v = half32_sum(v); auto r = __builtin_amdgcn_permlane32_swap(asu(v), asu(v), false, false); return asf(r[0]) + asf(r[1]); }
; __device__ __forceinline__ void odd_prep_a(const Ctx& c, const Params& p, int o) {
;     ...
;             if (kind < 3 || (kind == 3 && o > 0)) { float cu[8], pv[8]; unpack8(*(const u32x4*)(zr + zc), cu);
;                 if (t > 0) unpack8(*(const u32x4*)(zr + zc - Z2_LD), pv); else {
; #pragma unroll
;                     for (int i = 0; i < 8; ++i) pv[i] = 0.f; }
; #pragma unroll
;                 for (int i = 0; i < 8; ++i) { const float x = cu[i] + mv[i] * (pv[i] - cu[i]); out[i] = (kind == 0) ? (2.f * sigmoidf_(2.f * x) - 1.f) : (kind == 2 ? sigmoidf_(x) : x); } }
;             *(u32x4*)(LA + (size_t)m * 384 + 8 * grp) = pack8(out); }
;         if (c.lane < 32) KR[(size_t)m * 32 + c.lane] = zr[1024 + c.lane];
;         float f[8]; unpack8(*(const u32x4*)(zr + 256 + 8 * c.lane), f); float s1 = 0.f;
; #pragma unroll
;         for (int i = 0; i < 8; ++i) s1 += f[i] * f[i];
;         const u32x2 kvv = *(const u32x2*)(zr + 768 + 4 * c.lane);
;         const float k0 = asf(kvv.x << 16), k1 = asf(kvv.x & 0xffff0000u), k2 = asf(kvv.y << 16), k3 = asf(kvv.y & 0xffff0000u);
;         float s2 = (k0 * k0 + k1 * k1) + (k2 * k2 + k3 * k3);
;         s1 = wave_sum_dpp(s1); s2 = wave_sum_dpp(s2);
;         if (c.lane == 0) { RS[2 * m] = rsqrtf(s1 * (1.f / 512.f) + 1e-6f); RS[2 * m + 1] = rsqrtf(s2 * (1.f / 256.f) + 1e-6f); } }
.LBB0_471:
	s_or_b64 exec, exec, s[26:27]
	v_cvt_pk_bf16_f32 v2, v18, v2
	v_cvt_pk_bf16_f32 v3, v29, v3
	v_cvt_pk_bf16_f32 v4, v32, v4
	v_cvt_pk_bf16_f32 v5, v30, v5
	v_lshl_add_u64 v[18:19], s[22:23], 0, v[6:7]
	global_store_dwordx4 v[18:19], v[2:5], off
.LBB0_472:
	s_or_b64 exec, exec, s[10:11]
	s_and_saveexec_b64 s[10:11], s[6:7]
	s_cbranch_execz .LBB0_474
	v_lshl_add_u64 v[2:3], s[22:23], 0, v[16:17]
	global_load_ushort v4, v[2:3], off
	v_lshl_add_u64 v[2:3], s[22:23], 0, v[8:9]
	s_waitcnt vmcnt(0) lgkmcnt(0)
	global_store_short v[2:3], v4, off
.LBB0_474:
	s_or_b64 exec, exec, s[10:11]
	v_lshl_add_u64 v[2:3], s[22:23], 0, v[12:13]
	global_load_dwordx4 v[2:5], v[2:3], off
	s_waitcnt vmcnt(0) lgkmcnt(0)
	v_lshlrev_b32_e32 v18, 16, v2
	v_and_b32_e32 v2, 0xffff0000, v2
	v_mul_f32_e32 v30, v2, v2
	v_lshlrev_b32_e32 v19, 16, v3
	v_fmac_f32_e32 v30, v18, v18
	v_and_b32_e32 v3, 0xffff0000, v3
	v_fmac_f32_e32 v30, v19, v19
	v_fmac_f32_e32 v30, v3, v3
	v_lshl_add_u64 v[2:3], s[22:23], 0, v[10:11]
	global_load_dwordx2 v[2:3], v[2:3], off
	v_lshlrev_b32_e32 v28, 16, v4
	v_and_b32_e32 v4, 0xffff0000, v4
	v_fmac_f32_e32 v30, v28, v28
	v_lshlrev_b32_e32 v29, 16, v5
	v_fmac_f32_e32 v30, v4, v4
	v_and_b32_e32 v5, 0xffff0000, v5
	v_fmac_f32_e32 v30, v29, v29
	v_fmac_f32_e32 v30, v5, v5
	s_waitcnt vmcnt(0) lgkmcnt(0)
	v_lshlrev_b32_e32 v4, 16, v2
	v_and_b32_e32 v2, 0xffff0000, v2
	v_lshlrev_b32_e32 v5, 16, v3
	v_and_b32_e32 v3, 0xffff0000, v3
	v_mul_f32_e32 v2, v2, v2
	v_mul_f32_e32 v3, v3, v3
	v_fmac_f32_e32 v2, v4, v4
	v_fmac_f32_e32 v3, v5, v5
	v_add_f32_e32 v3, v2, v3
	v_add_f32_dpp v2, v30, v30 row_ror:8 row_mask:0xf bank_mask:0xf bound_ctrl:1
	s_nop 0
	v_add_f32_dpp v3, v3, v3 row_ror:8 row_mask:0xf bank_mask:0xf bound_ctrl:1
	v_add_f32_dpp v2, v2, v2 row_ror:4 row_mask:0xf bank_mask:0xf bound_ctrl:1
	s_nop 0
	v_add_f32_dpp v3, v3, v3 row_ror:4 row_mask:0xf bank_mask:0xf bound_ctrl:1
	v_add_f32_dpp v2, v2, v2 row_ror:2 row_mask:0xf bank_mask:0xf bound_ctrl:1
	s_nop 0
	v_add_f32_dpp v3, v3, v3 row_ror:2 row_mask:0xf bank_mask:0xf bound_ctrl:1
	v_add_f32_dpp v2, v2, v2 row_ror:1 row_mask:0xf bank_mask:0xf bound_ctrl:1
	v_mov_b32_e32 v4, v2
	v_add_f32_dpp v3, v3, v3 row_ror:1 row_mask:0xf bank_mask:0xf bound_ctrl:1
	v_mov_b32_e32 v5, v3
	v_permlane16_swap_b32_e32 v2, v4
	s_nop 0
	v_permlane16_swap_b32_e32 v3, v5
	v_add_f32_e32 v2, v2, v4
	v_add_f32_e32 v3, v3, v5
	v_mov_b32_e32 v4, v2
	v_mov_b32_e32 v5, v3
	s_nop 0
	v_permlane32_swap_b32_e32 v2, v4
	v_permlane32_swap_b32_e32 v3, v5
	s_and_saveexec_b64 s[12:13], s[8:9]
	s_cbranch_execz .LBB0_400
	s_ashr_i32 s15, s14, 31
	s_lshl_b64 s[10:11], s[14:15], 2
	s_add_u32 s26, s39, s10
	s_addc_u32 s27, s40, s11
	s_mov_b32 s10, 0x3b000000
	v_pk_add_f32 v[2:3], v[2:3], v[4:5]
	s_mov_b32 s11, 0x3b800000
	v_pk_fma_f32 v[2:3], v[2:3], s[10:11], v[148:149] op_sel_hi:[1,1,0]
	s_mov_b32 s34, 0x45800000
	v_mul_f32_e32 v4, 0x4b800000, v2
	v_cmp_gt_f32_e64 s[10:11], s33, v2
	v_cmp_gt_f32_e32 vcc, s33, v3
	s_nop 0
	v_cndmask_b32_e64 v2, v2, v4, s[10:11]
	v_mul_f32_e32 v4, 0x4b800000, v3
	v_cndmask_b32_e32 v3, v3, v4, vcc
	v_rsq_f32_e32 v2, v2
	v_rsq_f32_e32 v3, v3
	s_nop 0
	v_pk_mul_f32 v[4:5], v[2:3], s[34:35] op_sel_hi:[1,0]
	s_nop 0
	v_cndmask_b32_e32 v3, v3, v5, vcc
	v_cndmask_b32_e64 v2, v2, v4, s[10:11]
	v_mov_b64_e32 v[4:5], s[26:27]
	global_store_dwordx2 v[4:5], v[2:3], off
	s_branch .LBB0_400

; __device__ __forceinline__ void rwkv_bnd_copy(const Ctx& c, const Params& p) {
;     const bf16_t* RKV = (const bf16_t*)(c.ws + WS_RKV); bf16_t* BND = (bf16_t*)(c.ws + WS_BND);
;     const int NT = c.G * 512, total = 1024 * 192;
;     for (int it = c.bid * 512 + c.tid; it < total; it += NT) { const int rg = it / 192, c8 = (it % 192) * 8;
;         if ((rg & 255) == 0) continue;
;         *(u32x4*)(BND + (size_t)rg * 1536 + c8) = *(const u32x4*)(RKV + (size_t)(32 * rg - 1) * RKV_LD + c8); }
; }
.LBB0_482:
	s_mov_b32 s0, 0x2aaaaaab
	v_mul_hi_i32 v3, v1, s0
	v_lshrrev_b32_e32 v4, 31, v3
	v_ashrrev_i32_e32 v3, 5, v3
	v_add_u32_e32 v3, v3, v4
	v_cmp_ne_u32_sdwa s[12:13], v3, v0 src0_sel:BYTE_0 src1_sel:DWORD
	s_and_saveexec_b64 s[8:9], s[12:13]
	s_cbranch_execz .LBB0_481
	s_movk_i32 s12, 0xfa00
	v_mad_u64_u32 v[4:5], s[12:13], v3, s12, v[2:3]
	v_lshl_add_u32 v5, v3, 5, -1
	v_mov_b64_e32 v[6:7], s[16:17]
	s_movk_i32 s0, 0xc00
	v_mad_i64_i32 v[6:7], s[12:13], v5, s0, v[6:7]
	v_ashrrev_i32_e32 v5, 31, v4
	v_lshlrev_b64 v[8:9], 1, v[4:5]
	v_lshl_add_u64 v[4:5], v[6:7], 0, v[8:9]
	global_load_dwordx4 v[4:7], v[4:5], off
	v_mov_b64_e32 v[10:11], s[4:5]
	v_mad_i64_i32 v[10:11], s[12:13], v3, s0, v[10:11]
	v_lshl_add_u64 v[8:9], v[10:11], 0, v[8:9]
	s_waitcnt vmcnt(0) lgkmcnt(0)
	global_store_dwordx4 v[8:9], v[4:7], off
	s_branch .LBB0_481

; __device__ __forceinline__ u32x4 pack8(const float* f) { u32x4 o; o.x = pk2(f[0], f[1]); o.y = pk2(f[2], f[3]); o.z = pk2(f[4], f[5]); o.w = pk2(f[6], f[7]); return o; }
; __device__ __forceinline__ float sum8_dpp(float v) { v += dppf<0xB1>(v); v += dppf<0x4E>(v); v += dppf<0x141>(v); return v; }
; __device__ __forceinline__ void rwkv_post(const Ctx& c, const Params& p, int o) {
;     const bf16_t* RKV = (const bf16_t*)(c.ws + WS_RKV); const bf16_t* LO = (const bf16_t*)(c.ws + WS_LO); bf16_t* Y = (bf16_t*)(c.ws + WS_AB);
;     const float* lnw = p.in[c.zo + 23] + (size_t)o * 512; const float* lnb = p.in[c.zo + 24] + (size_t)o * 512; const float* BON = (const float*)(c.ws + WS_LA);
;     const int h = c.lane >> 3, c8 = h * 64 + 8 * (c.lane & 7);
;     float lw[8], lb[8];
; #pragma unroll
;     for (int i = 0; i < 8; ++i) { lw[i] = lnw[c8 + i]; lb[i] = lnb[c8 + i]; }
;     for (int m = c.gw; m < M_; m += c.ngw) { const bf16_t* lo = LO + (size_t)m * 2048;
;         float y[8], v[8], g[8]; unpack8(*(const u32x4*)(lo + 1536 + c8), y); unpack8(*(const u32x4*)(RKV + (size_t)m * RKV_LD + 1024 + c8), v); unpack8(*(const u32x4*)(lo + 1024 + c8), g);
;         const float bon = BON[(size_t)m * 8 + h];
;         float s1 = 0.f;
; #pragma unroll
;         for (int i = 0; i < 8; ++i) s1 += y[i];
;         const float mean = sum8_dpp(s1) * (1.f / 64.f); float s2 = 0.f;
; #pragma unroll
;         for (int i = 0; i < 8; ++i) { y[i] -= mean; s2 += y[i] * y[i]; }
;         const float rs = rsqrtf(sum8_dpp(s2) * (1.f / 64.f) + 64e-5f); float out[8];
; #pragma unroll
;         for (int i = 0; i < 8; ++i) out[i] = (y[i] * rs * lw[i] + lb[i] + bon * v[i]) * g[i];
;         *(u32x4*)(Y + (size_t)m * D_ + c8) = pack8(out); }
; }
.LBB0_491:
	global_load_dwordx4 v[28:31], v[24:25], off
	global_load_dwordx4 v[32:35], v[22:23], off
	v_add_co_u32_e32 v36, vcc, 0xfffffc00, v24
	global_load_dword v26, v[20:21], off
	s_nop 0
	v_addc_co_u32_e32 v37, vcc, -1, v25, vcc
	global_load_dwordx4 v[36:39], v[36:37], off
	v_mov_b32_e32 v27, 0x3a27c5ac
	s_add_i32 s10, s10, s30
	v_lshl_add_u64 v[20:21], v[20:21], 0, s[4:5]
	v_lshl_add_u64 v[22:23], v[22:23], 0, s[6:7]
	s_cmpk_gt_i32 s10, 0x7fff
	v_lshl_add_u64 v[24:25], v[24:25], 0, s[8:9]
	s_waitcnt vmcnt(0) lgkmcnt(0)
	v_lshlrev_b32_e32 v48, 16, v28
	v_and_b32_e32 v49, 0xffff0000, v28
	v_add_f32_e32 v1, 0, v48
	v_lshlrev_b32_e32 v40, 16, v31
	v_and_b32_e32 v41, 0xffff0000, v31
	v_lshlrev_b32_e32 v44, 16, v30
	v_and_b32_e32 v45, 0xffff0000, v30
	v_lshlrev_b32_e32 v30, 16, v34
	v_and_b32_e32 v31, 0xffff0000, v34
	v_lshlrev_b32_e32 v34, 16, v29
	v_add_f32_e32 v1, v1, v49
	v_lshlrev_b32_e32 v42, 16, v35
	v_and_b32_e32 v43, 0xffff0000, v35
	v_and_b32_e32 v35, 0xffff0000, v29
	v_add_f32_e32 v1, v1, v34
	v_add_f32_e32 v1, v1, v35
	v_add_f32_e32 v1, v1, v44
	v_add_f32_e32 v1, v1, v45
	v_add_f32_e32 v1, v1, v40
	v_add_f32_e32 v1, v1, v41
	v_lshlrev_b32_e32 v52, 16, v36
	v_and_b32_e32 v53, 0xffff0000, v36
	v_add_f32_dpp v1, v1, v1 quad_perm:[1,0,3,2] row_mask:0xf bank_mask:0xf bound_ctrl:1
	v_lshlrev_b32_e32 v46, 16, v33
	v_and_b32_e32 v47, 0xffff0000, v33
	v_add_f32_dpp v1, v1, v1 quad_perm:[2,3,0,1] row_mask:0xf bank_mask:0xf bound_ctrl:1
	v_lshlrev_b32_e32 v28, 16, v32
	v_and_b32_e32 v29, 0xffff0000, v32
	v_add_f32_dpp v1, v1, v1 row_half_mirror row_mask:0xf bank_mask:0xf bound_ctrl:1
	v_mul_f32_e32 v36, 0x3c800000, v1
	v_pk_add_f32 v[48:49], v[48:49], v[36:37] op_sel_hi:[1,0] neg_lo:[0,1] neg_hi:[0,1]
	v_lshlrev_b32_e32 v32, 16, v39
	v_and_b32_e32 v33, 0xffff0000, v39
	v_lshlrev_b32_e32 v50, 16, v38
	v_and_b32_e32 v51, 0xffff0000, v38
	v_lshlrev_b32_e32 v38, 16, v37
	v_and_b32_e32 v39, 0xffff0000, v37
	v_pk_add_f32 v[34:35], v[34:35], v[36:37] op_sel_hi:[1,0] neg_lo:[0,1] neg_hi:[0,1]
	v_pk_add_f32 v[44:45], v[44:45], v[36:37] op_sel_hi:[1,0] neg_lo:[0,1] neg_hi:[0,1]
	v_pk_add_f32 v[36:37], v[40:41], v[36:37] op_sel_hi:[1,0] neg_lo:[0,1] neg_hi:[0,1]
	v_pk_mul_f32 v[40:41], v[48:49], v[48:49]
	v_pk_mul_f32 v[54:55], v[34:35], v[34:35]
	v_add_f32_e32 v1, v40, v41
	v_add_f32_e32 v1, v54, v1
	v_pk_mul_f32 v[56:57], v[44:45], v[44:45]
	v_add_f32_e32 v1, v55, v1
	v_add_f32_e32 v1, v56, v1
	v_pk_mul_f32 v[58:59], v[36:37], v[36:37]
	v_add_f32_e32 v1, v57, v1
	v_add_f32_e32 v1, v58, v1
	v_add_f32_e32 v1, v59, v1
	s_nop 1
	v_add_f32_dpp v1, v1, v1 quad_perm:[1,0,3,2] row_mask:0xf bank_mask:0xf bound_ctrl:1
	s_nop 1
	v_add_f32_dpp v1, v1, v1 quad_perm:[2,3,0,1] row_mask:0xf bank_mask:0xf bound_ctrl:1
	s_nop 1
	v_add_f32_dpp v1, v1, v1 row_half_mirror row_mask:0xf bank_mask:0xf bound_ctrl:1
	v_fmamk_f32 v1, v1, 0x3c800000, v27
	v_mul_f32_e32 v27, 0x4b800000, v1
	v_cmp_gt_f32_e32 vcc, s33, v1
	s_nop 1
	v_cndmask_b32_e32 v1, v1, v27, vcc
	v_rsq_f32_e32 v1, v1
	s_nop 0
	v_mul_f32_e32 v27, 0x45800000, v1
	v_cndmask_b32_e32 v40, v1, v27, vcc
	v_pk_mul_f32 v[48:49], v[48:49], v[40:41] op_sel_hi:[1,0]
	v_pk_mul_f32 v[34:35], v[34:35], v[40:41] op_sel_hi:[1,0]
	v_pk_mul_f32 v[44:45], v[44:45], v[40:41] op_sel_hi:[1,0]
	v_pk_mul_f32 v[36:37], v[36:37], v[40:41] op_sel_hi:[1,0]
	v_pk_fma_f32 v[40:41], v[6:7], v[48:49], v[14:15]
	v_pk_fma_f32 v[34:35], v[8:9], v[34:35], v[16:17]
	v_pk_fma_f32 v[44:45], v[2:3], v[44:45], v[10:11]
	v_pk_fma_f32 v[36:37], v[4:5], v[36:37], v[12:13]
	v_pk_fma_f32 v[28:29], v[26:27], v[28:29], v[40:41] op_sel_hi:[0,1,1]
	v_pk_fma_f32 v[34:35], v[26:27], v[46:47], v[34:35] op_sel_hi:[0,1,1]
	v_pk_fma_f32 v[30:31], v[26:27], v[30:31], v[44:45] op_sel_hi:[0,1,1]
	v_pk_fma_f32 v[26:27], v[26:27], v[42:43], v[36:37] op_sel_hi:[0,1,1]
	v_pk_mul_f32 v[28:29], v[28:29], v[52:53]
	v_pk_mul_f32 v[34:35], v[34:35], v[38:39]
	v_pk_mul_f32 v[30:31], v[30:31], v[50:51]
	v_pk_mul_f32 v[32:33], v[26:27], v[32:33]
	v_cvt_pk_bf16_f32 v26, v28, v29
	v_cvt_pk_bf16_f32 v27, v34, v35
	v_cvt_pk_bf16_f32 v28, v30, v31
	v_cvt_pk_bf16_f32 v29, v32, v33
	global_store_dwordx4 v[18:19], v[26:29], off
	v_lshl_add_u64 v[18:19], v[18:19], 0, s[2:3]
	s_cbranch_scc0 .LBB0_491

; __device__ __forceinline__ unsigned pk2(float lo, float hi) { f32x2 v = {lo, hi}; bf16x2_t b = __builtin_convertvector(v, bf16x2_t); return __builtin_bit_cast(unsigned, b); }
;     __device__ __forceinline__ void operator()(const f32x4 (&acc)[2][2][4][2], const Unit& u, int wr, int wc, int fr, int fq) const {
;         const int row0 = u.pm * BM + wr * 64 + fr; const int col0 = u.pn * BM + wc * 32 + 8 * fq;
; #pragma unroll
;         for (int bj = 0; bj < 2; ++bj) { const int cg = col0 + bj * HALF; if (cg < ncols) { bf16_t* base = (cg < split) ? O1 + cg : O2 + (cg - split); const int ld = (cg < split) ? ld1 : ld2;
; #pragma unroll
;             for (int ai = 0; ai < 2; ++ai)
; #pragma unroll
;                 for (int m = 0; m < 4; ++m) { const f32x4 v0 = acc[ai][bj][m][0], v1 = acc[ai][bj][m][1];
;                     u32x4 w; w.x = pk2(v0[0], v0[1]); w.y = pk2(v0[2], v0[3]); w.z = pk2(v1[0], v1[1]); w.w = pk2(v1[2], v1[3]);
;                     *(u32x4*)(base + (size_t)(row0 + ai * HALF + m * 16) * ld) = w; } } }
;     }
.LBB0_506:
	v_lshl_add_u32 v186, s14, 8, v1
	v_lshl_or_b32 v142, s85, 8, v165
	s_movk_i32 s0, 0xb00
	v_cmp_gt_i32_e32 vcc, s0, v142
	v_ashrrev_i32_e32 v143, 31, v142
	v_or_b32_e32 v185, 16, v186
	v_or_b32_e32 v184, 32, v186
	v_or_b32_e32 v183, 48, v186
	v_add_u32_e32 v171, 0x80, v186
	v_add_u32_e32 v170, 0x90, v186
	v_add_u32_e32 v169, 0xa0, v186
	v_add_u32_e32 v168, 0xb0, v186
	s_and_saveexec_b64 s[2:3], vcc
	s_mov_b32 s62, 0xc000
	s_mov_b32 s63, 0x12000
	s_mov_b32 s86, 0x30000
	s_cbranch_execz .LBB0_508
	v_lshlrev_b64 v[188:189], 1, v[142:143]
	s_movk_i32 s26, 0xf400
	v_lshl_add_u64 v[190:191], s[16:17], 0, v[188:189]
	v_lshl_add_u64 v[188:189], s[8:9], 0, v[188:189]
	s_mov_b32 s27, -1
	v_cmp_gt_i32_e32 vcc, s50, v142
	v_lshl_add_u64 v[188:189], v[188:189], 0, s[26:27]
	v_cvt_pk_bf16_f32 v126, v126, v127
	v_cndmask_b32_e32 v174, v179, v177, vcc
	v_cndmask_b32_e32 v189, v189, v191, vcc
	v_cndmask_b32_e32 v188, v188, v190, vcc
	v_cvt_pk_bf16_f32 v127, v128, v129
	v_cvt_pk_bf16_f32 v128, v122, v123
	v_mad_i64_i32 v[122:123], s[26:27], v174, v186, 0
	v_cvt_pk_bf16_f32 v118, v118, v119
	v_cvt_pk_bf16_f32 v119, v120, v121
	v_cvt_pk_bf16_f32 v120, v114, v115
	v_mad_i64_i32 v[114:115], s[26:27], v174, v185, 0
	v_cvt_pk_bf16_f32 v110, v110, v111
	v_cvt_pk_bf16_f32 v111, v112, v113
	v_cvt_pk_bf16_f32 v112, v106, v107
	v_mad_i64_i32 v[106:107], s[26:27], v174, v184, 0
	v_cvt_pk_bf16_f32 v102, v102, v103
	v_cvt_pk_bf16_f32 v103, v104, v105
	v_cvt_pk_bf16_f32 v104, v98, v99
	v_mad_i64_i32 v[98:99], s[26:27], v174, v183, 0
	v_cvt_pk_bf16_f32 v94, v94, v95
	v_cvt_pk_bf16_f32 v95, v96, v97
	v_cvt_pk_bf16_f32 v96, v90, v91
	v_mad_i64_i32 v[90:91], s[26:27], v174, v171, 0
	v_cvt_pk_bf16_f32 v86, v86, v87
	v_cvt_pk_bf16_f32 v87, v88, v89
	v_cvt_pk_bf16_f32 v88, v82, v83
	v_mad_i64_i32 v[82:83], s[26:27], v174, v170, 0
	v_cvt_pk_bf16_f32 v78, v78, v79
	v_cvt_pk_bf16_f32 v79, v80, v81
	v_cvt_pk_bf16_f32 v80, v74, v75
	v_mad_i64_i32 v[74:75], s[26:27], v174, v169, 0
	v_cvt_pk_bf16_f32 v62, v62, v63
	v_cvt_pk_bf16_f32 v63, v64, v65
	v_cvt_pk_bf16_f32 v64, v58, v59
	v_mad_i64_i32 v[58:59], s[26:27], v174, v168, 0
	v_cvt_pk_bf16_f32 v129, v124, v125
	v_lshl_add_u64 v[122:123], v[122:123], 1, v[188:189]
	v_cvt_pk_bf16_f32 v121, v116, v117
	v_lshl_add_u64 v[114:115], v[114:115], 1, v[188:189]
	v_cvt_pk_bf16_f32 v113, v108, v109
	v_lshl_add_u64 v[106:107], v[106:107], 1, v[188:189]
	v_cvt_pk_bf16_f32 v105, v100, v101
	v_lshl_add_u64 v[98:99], v[98:99], 1, v[188:189]
	v_cvt_pk_bf16_f32 v97, v92, v93
	v_lshl_add_u64 v[90:91], v[90:91], 1, v[188:189]
	v_cvt_pk_bf16_f32 v89, v84, v85
	v_lshl_add_u64 v[82:83], v[82:83], 1, v[188:189]
	v_cvt_pk_bf16_f32 v81, v76, v77
	v_lshl_add_u64 v[74:75], v[74:75], 1, v[188:189]
	v_cvt_pk_bf16_f32 v65, v60, v61
	v_lshl_add_u64 v[58:59], v[58:59], 1, v[188:189]
	global_store_dwordx4 v[122:123], v[126:129], off
	global_store_dwordx4 v[114:115], v[118:121], off
	global_store_dwordx4 v[106:107], v[110:113], off
	global_store_dwordx4 v[98:99], v[102:105], off
	global_store_dwordx4 v[90:91], v[94:97], off
	global_store_dwordx4 v[82:83], v[86:89], off
	global_store_dwordx4 v[74:75], v[78:81], off
	global_store_dwordx4 v[58:59], v[62:65], off
.LBB0_508:
	s_or_b64 exec, exec, s[2:3]
	v_or_b32_e32 v58, 0x80, v142
	v_cmp_gt_i32_e32 vcc, s0, v58
	s_and_saveexec_b64 s[2:3], vcc
	s_cbranch_execz .LBB0_510
	s_movk_i32 s26, 0xf500
	v_cmp_gt_i32_e32 vcc, s50, v58
	v_ashrrev_i32_e32 v59, 31, v58
	v_lshl_add_u64 v[60:61], v[142:143], 1, s[8:9]
	s_mov_b32 s27, -1
	v_lshl_add_u64 v[58:59], v[58:59], 1, s[16:17]
	v_lshl_add_u64 v[60:61], v[60:61], 0, s[26:27]
	v_cndmask_b32_e32 v74, v179, v177, vcc
	v_cndmask_b32_e32 v63, v61, v59, vcc
	v_cndmask_b32_e32 v62, v60, v58, vcc
	v_mad_i64_i32 v[64:65], s[26:27], v74, v186, 0
	v_cvt_pk_bf16_f32 v54, v54, v55
	v_cvt_pk_bf16_f32 v55, v56, v57
	v_cvt_pk_bf16_f32 v56, v50, v51
	v_mad_i64_i32 v[50:51], s[26:27], v74, v185, 0
	v_cvt_pk_bf16_f32 v46, v46, v47
	v_cvt_pk_bf16_f32 v47, v48, v49
	v_cvt_pk_bf16_f32 v48, v42, v43
	v_mad_i64_i32 v[42:43], s[26:27], v74, v184, 0
	v_cvt_pk_bf16_f32 v38, v38, v39
	v_cvt_pk_bf16_f32 v39, v40, v41
	v_cvt_pk_bf16_f32 v40, v34, v35
	v_mad_i64_i32 v[34:35], s[26:27], v74, v183, 0
	v_cvt_pk_bf16_f32 v30, v30, v31
	v_cvt_pk_bf16_f32 v31, v32, v33
	v_cvt_pk_bf16_f32 v32, v26, v27
	v_mad_i64_i32 v[26:27], s[26:27], v74, v171, 0
	v_cvt_pk_bf16_f32 v22, v22, v23
	v_cvt_pk_bf16_f32 v23, v24, v25
	v_cvt_pk_bf16_f32 v24, v18, v19
	v_mad_i64_i32 v[18:19], s[26:27], v74, v170, 0
	v_cvt_pk_bf16_f32 v14, v14, v15
	v_cvt_pk_bf16_f32 v15, v16, v17
	v_cvt_pk_bf16_f32 v16, v10, v11
	v_mad_i64_i32 v[10:11], s[26:27], v74, v169, 0
	v_cvt_pk_bf16_f32 v6, v6, v7
	v_cvt_pk_bf16_f32 v7, v8, v9
	v_cvt_pk_bf16_f32 v8, v2, v3
	v_mad_i64_i32 v[2:3], s[26:27], v74, v168, 0
	v_cvt_pk_bf16_f32 v58, v70, v71
	v_cvt_pk_bf16_f32 v59, v72, v73
	v_cvt_pk_bf16_f32 v60, v66, v67
	v_cvt_pk_bf16_f32 v61, v68, v69
	v_lshl_add_u64 v[64:65], v[64:65], 1, v[62:63]
	v_cvt_pk_bf16_f32 v57, v52, v53
	v_lshl_add_u64 v[50:51], v[50:51], 1, v[62:63]
	v_cvt_pk_bf16_f32 v49, v44, v45
	v_lshl_add_u64 v[42:43], v[42:43], 1, v[62:63]
	v_cvt_pk_bf16_f32 v41, v36, v37
	v_lshl_add_u64 v[34:35], v[34:35], 1, v[62:63]
	v_cvt_pk_bf16_f32 v33, v28, v29
	v_lshl_add_u64 v[26:27], v[26:27], 1, v[62:63]
	v_cvt_pk_bf16_f32 v25, v20, v21
	v_lshl_add_u64 v[18:19], v[18:19], 1, v[62:63]
	v_cvt_pk_bf16_f32 v17, v12, v13
	v_lshl_add_u64 v[10:11], v[10:11], 1, v[62:63]
	v_cvt_pk_bf16_f32 v9, v4, v5
	v_lshl_add_u64 v[2:3], v[2:3], 1, v[62:63]
	global_store_dwordx4 v[64:65], v[58:61], off
	global_store_dwordx4 v[50:51], v[54:57], off
	global_store_dwordx4 v[42:43], v[46:49], off
	global_store_dwordx4 v[34:35], v[38:41], off
	global_store_dwordx4 v[26:27], v[30:33], off
	global_store_dwordx4 v[18:19], v[22:25], off
	global_store_dwordx4 v[10:11], v[14:17], off
	global_store_dwordx4 v[2:3], v[6:9], off

; __device__ __forceinline__ float bf2f(bf16_t b) { return asf((unsigned)b << 16); }
; __device__ __forceinline__ int crow(int r, int hi) { return (r & 3) + 8 * (r >> 2) + 4 * hi; }
; #define LDS_BARRIER() do { asm volatile("s_waitcnt lgkmcnt(0)" ::: "memory"); __builtin_amdgcn_s_barrier(); asm volatile("" ::: "memory"); } while (0)
; __device__ __forceinline__ void gdn_scan(const Ctx& c, const Params& p, int e) {
;     ...
;             f32x16 S[4];
; #pragma unroll
;             for (int i = 0; i < 4; ++i) S[i] = (f32x16){};
;             float gtn = GC[(size_t)bh * 128];
;             for (int n = 0; n < 128; ++n) {
;                 LDS_BARRIER();
;                 if (c.wave < 2) {
;                 const float gt = gtn; if (n + 1 < 128) gtn = GC[(size_t)bh * 128 + n + 1];
;                 f32x16 av[2];
; #pragma unroll
;                 for (int tc = 0; tc < 2; ++tc)
; #pragma unroll
;                     for (int r = 0; r < 16; ++r) av[tc][r] = bf2f(UT[(32 * tc + crow(r, hh)) * 136 + e0 + l31]);
.LBB0_522:
	s_lshl_b32 s2, s31, 6
	s_ashr_i32 s20, s31, 1
	s_and_b32 s34, s2, 64
	s_mov_b64 s[2:3], -1
	s_and_b64 vcc, exec, s[10:11]
	s_cbranch_vccz .LBB0_530
	s_ashr_i32 s21, s20, 31
	s_lshl_b64 s[2:3], s[20:21], 9
	s_add_u32 s4, s14, s2
	s_addc_u32 s5, s15, s3
	v_mov_b64_e32 v[2:3], s[4:5]
	global_load_dword v150, v[2:3], off
	s_waitcnt vmcnt(0) lgkmcnt(0)
	v_mov_b32_e32 v14, v0
	v_mov_b32_e32 v15, v0
	s_add_u32 s2, s27, s2
	v_mov_b32_e32 v1, v0
	v_mov_b32_e32 v2, v0
	v_mov_b32_e32 v3, v0
	v_mov_b32_e32 v4, v0
	v_mov_b32_e32 v5, v0
	v_mov_b32_e32 v6, v0
	v_mov_b32_e32 v7, v0
	v_mov_b32_e32 v8, v0
	v_mov_b32_e32 v9, v0
	v_mov_b32_e32 v10, v0
	v_mov_b32_e32 v11, v0
	v_mov_b32_e32 v12, v0
	v_mov_b32_e32 v13, v0
	v_mov_b64_e32 v[30:31], v[14:15]
	v_mov_b64_e32 v[46:47], v[14:15]
	v_mov_b64_e32 v[62:63], v[14:15]
	v_mov_b64_e32 v[78:79], v[14:15]
	v_lshl_add_u32 v198, s34, 1, v194
	s_addc_u32 s3, s29, s3
	s_mov_b32 s21, 0
	v_mov_b64_e32 v[28:29], v[12:13]
	v_mov_b64_e32 v[26:27], v[10:11]
	v_mov_b64_e32 v[24:25], v[8:9]
	v_mov_b64_e32 v[22:23], v[6:7]
	v_mov_b64_e32 v[20:21], v[4:5]
	v_mov_b64_e32 v[18:19], v[2:3]
	v_mov_b64_e32 v[16:17], v[0:1]
	v_mov_b64_e32 v[44:45], v[12:13]
	v_mov_b64_e32 v[42:43], v[10:11]
	v_mov_b64_e32 v[40:41], v[8:9]
	v_mov_b64_e32 v[38:39], v[6:7]
	v_mov_b64_e32 v[36:37], v[4:5]
	v_mov_b64_e32 v[34:35], v[2:3]
	v_mov_b64_e32 v[32:33], v[0:1]
	v_mov_b64_e32 v[60:61], v[12:13]
	v_mov_b64_e32 v[58:59], v[10:11]
	v_mov_b64_e32 v[56:57], v[8:9]
	v_mov_b64_e32 v[54:55], v[6:7]
	v_mov_b64_e32 v[52:53], v[4:5]
	v_mov_b64_e32 v[50:51], v[2:3]
	v_mov_b64_e32 v[48:49], v[0:1]
	v_mov_b64_e32 v[76:77], v[12:13]
	v_mov_b64_e32 v[74:75], v[10:11]
	v_mov_b64_e32 v[72:73], v[8:9]
	v_mov_b64_e32 v[70:71], v[6:7]
	v_mov_b64_e32 v[68:69], v[4:5]
	v_mov_b64_e32 v[66:67], v[2:3]
	v_mov_b64_e32 v[64:65], v[0:1]
	v_and_b32_e32 v1, 31, v164
	v_lshrrev_b32_e32 v14, 5, v164
	v_lshlrev_b32_e32 v14, 2, v14
	v_sub_u32_e32 v1, v1, v14
	v_mov_b32_e32 v15, 0x3f80
	v_mov_b32_e32 v2, 0x3f800000
	v_subrev_u32_e32 v14, 0, v1
	v_cmp_eq_u32_e32 vcc, 0, v14
	s_nop 1
	v_cndmask_b32_e32 v6, 0, v15, vcc
	v_cmp_eq_u32_e32 vcc, 1, v14
	s_nop 1
	v_cndmask_b32_e32 v6, v6, v2, vcc
	v_subrev_u32_e32 v14, 2, v1
	v_cmp_eq_u32_e32 vcc, 0, v14
	s_nop 1
	v_cndmask_b32_e32 v7, 0, v15, vcc
	v_cmp_eq_u32_e32 vcc, 1, v14
	s_nop 1
	v_cndmask_b32_e32 v7, v7, v2, vcc
	v_subrev_u32_e32 v14, 8, v1
	v_cmp_eq_u32_e32 vcc, 0, v14
	s_nop 1
	v_cndmask_b32_e32 v8, 0, v15, vcc
	v_cmp_eq_u32_e32 vcc, 1, v14
	s_nop 1
	v_cndmask_b32_e32 v8, v8, v2, vcc
	v_subrev_u32_e32 v14, 10, v1
	v_cmp_eq_u32_e32 vcc, 0, v14
	s_nop 1
	v_cndmask_b32_e32 v9, 0, v15, vcc
	v_cmp_eq_u32_e32 vcc, 1, v14
	s_nop 1
	v_cndmask_b32_e32 v9, v9, v2, vcc
	v_subrev_u32_e32 v14, 16, v1
	v_cmp_eq_u32_e32 vcc, 0, v14
	s_nop 1
	v_cndmask_b32_e32 v10, 0, v15, vcc
	v_cmp_eq_u32_e32 vcc, 1, v14
	s_nop 1
	v_cndmask_b32_e32 v10, v10, v2, vcc
	v_subrev_u32_e32 v14, 18, v1
	v_cmp_eq_u32_e32 vcc, 0, v14
	s_nop 1
	v_cndmask_b32_e32 v11, 0, v15, vcc
	v_cmp_eq_u32_e32 vcc, 1, v14
	s_nop 1
	v_cndmask_b32_e32 v11, v11, v2, vcc
	v_subrev_u32_e32 v14, 24, v1
	v_cmp_eq_u32_e32 vcc, 0, v14
	s_nop 1
	v_cndmask_b32_e32 v12, 0, v15, vcc
	v_cmp_eq_u32_e32 vcc, 1, v14
	s_nop 1
	v_cndmask_b32_e32 v12, v12, v2, vcc
	v_subrev_u32_e32 v14, 26, v1
	v_cmp_eq_u32_e32 vcc, 0, v14
	s_nop 1
	v_cndmask_b32_e32 v13, 0, v15, vcc
	v_cmp_eq_u32_e32 vcc, 1, v14
	s_nop 1
	v_cndmask_b32_e32 v13, v13, v2, vcc
	v_and_b32_e32 v1, 31, v164
	v_lshlrev_b32_e32 v1, 1, v1
	v_add_u32_e32 v14, v186, v198
	v_sub_u32_e32 v14, v14, v1
	v_subrev_u32_e32 v14, s80, v14
	v_add_u32_e32 v14, 0x8800, v14
	v_add_u32_e32 v15, 0x2200, v14
	s_branch .LBB0_525

; __device__ __forceinline__ float bf2f(bf16_t b) { return asf((unsigned)b << 16); }
; __device__ __forceinline__ int crow(int r, int hi) { return (r & 3) + 8 * (r >> 2) + 4 * hi; }
; __device__ __forceinline__ bf16x8 ldA_perm(const LAS bf16_t* p) { s16x4 a = *(const LAS s16x4*)p; s16x4 b = *(const LAS s16x4*)(p + 8); return (bf16x8){a[0], a[1], a[2], a[3], b[0], b[1], b[2], b[3]}; }
; #define LDS_BARRIER() do { asm volatile("s_waitcnt lgkmcnt(0)" ::: "memory"); __builtin_amdgcn_s_barrier(); asm volatile("" ::: "memory"); } while (0)
; #define GDN_LDF_WQ(F, td_) do { _Pragma("unroll") for (int tc = 0; tc < 2; ++tc) _Pragma("unroll") for (int s_ = 0; s_ < 2; ++s_) { const int ko_ = 32 * (td_) + 16 * s_ + 4 * hh; \
;                     F[tc * 2 + s_] = ldA_perm(WNs + (32 * tc + l31) * 136 + ko_); F[4 + tc * 2 + s_] = ldA_perm(QD + (32 * tc + l31) * 136 + ko_); } } while (0)
; __device__ __forceinline__ void gdn_scan(const Ctx& c, const Params& p, int e) {
;     ...
;             for (int n = 0; n < 128; ++n) {
;                 LDS_BARRIER();
;                 if (c.wave < 2) {
;                 const float gt = gtn; if (n + 1 < 128) gtn = GC[(size_t)bh * 128 + n + 1];
;                 f32x16 av[2];
; #pragma unroll
;                 for (int tc = 0; tc < 2; ++tc)
; #pragma unroll
;                     for (int r = 0; r < 16; ++r) av[tc][r] = bf2f(UT[(32 * tc + crow(r, hh)) * 136 + e0 + l31]);
;                 f32x16 ao[2] = {(f32x16){}, (f32x16){}};
;                 bf16x8 fa[8], fb[8];
;     ...
;                 GDN_LDF_WQ(fa, 0);
;                 GDN_LDF_WQ(fb, 1); GDN_MMA_WQ(fa, 0);
;                 GDN_LDF_WQ(fa, 2); GDN_MMA_WQ(fb, 1);
;                 GDN_LDF_WQ(fb, 3); GDN_MMA_WQ(fa, 2);
; #pragma unroll
;                 for (int tc = 0; tc < 2; ++tc)
; #pragma unroll
;                     for (int ts = 0; ts < 2; ++ts)
; #pragma unroll
;                         for (int s_ = 0; s_ < 2; ++s_) fa[tc * 4 + ts * 2 + s_] = ldA_perm(QK + (32 * tc + l31) * 72 + 32 * ts + 16 * s_ + 4 * hh);
;                 GDN_MMA_WQ(fb, 3);
.LBB0_525:
	s_waitcnt lgkmcnt(0)
	s_barrier
	v_cndmask_b32_e64 v1, 0, 1, s[12:13]
	v_cmp_ne_u32_e64 s[4:5], 1, v1
	s_andn2_b64 vcc, exec, s[12:13]
	s_cbranch_vccnz .LBB0_524
	v_mov_b64_e32 v[252:253], s[2:3]
	v_add_u32_e32 v174, 0x4000, v186
	v_add_u32_e32 v175, 0x4000, v187
	global_load_dword v253, v[252:253], off
	v_add_u32_e32 v1, v168, v188
	ds_read2_b64 v[232:235], v14 offset0:0 offset1:2
	ds_read2_b64 v[236:239], v15 offset0:0 offset1:2
	ds_read2_b64 v[240:243], v14 offset0:4 offset1:6
	ds_read2_b64 v[244:247], v15 offset0:4 offset1:6
	ds_read2_b64 v[248:251], v174 offset0:128 offset1:130
	ds_read2_b64 v[2:5], v186 offset0:0 offset1:2
	v_add_u32_e32 v252, 0x1000, v1
	s_bitcmp1_b32 s21, 0
	s_cselect_b32 s35, 0x2400, 0
	v_cvt_pk_bf16_f32 v200, v64, v65
	v_cvt_pk_bf16_f32 v201, v66, v67
	v_cvt_pk_bf16_f32 v202, v68, v69
	v_cvt_pk_bf16_f32 v203, v70, v71
	v_cvt_pk_bf16_f32 v204, v72, v73
	v_cvt_pk_bf16_f32 v205, v74, v75
	v_cvt_pk_bf16_f32 v206, v76, v77
	v_cvt_pk_bf16_f32 v207, v78, v79
	s_waitcnt lgkmcnt(5)
	v_mfma_f32_32x32x16_bf16 v[80:95], v[232:235], v[6:9], 0
	ds_read2_b64 v[232:235], v175 offset0:128 offset1:130
	s_waitcnt lgkmcnt(5)
	v_mfma_f32_32x32x16_bf16 v[112:127], v[236:239], v[6:9], 0
	ds_read2_b64 v[236:239], v187 offset0:0 offset1:2
	s_waitcnt lgkmcnt(5)
	v_mfma_f32_32x32x16_bf16 v[80:95], v[240:243], v[10:13], v[80:95]
	ds_read2_b64 v[240:243], v174 offset0:132 offset1:134
	s_waitcnt lgkmcnt(5)
	v_mfma_f32_32x32x16_bf16 v[112:127], v[244:247], v[10:13], v[112:127]
	ds_read2_b64 v[244:247], v186 offset0:4 offset1:6
	s_waitcnt lgkmcnt(5)
	v_mfma_f32_32x32x16_bf16 v[80:95], v[248:251], v[200:203], v[80:95]
	ds_read2_b64 v[248:251], v175 offset0:132 offset1:134
	v_cvt_pk_bf16_f32 v208, v48, v49
	v_cvt_pk_bf16_f32 v209, v50, v51
	s_waitcnt lgkmcnt(5)
	v_mfma_f32_32x32x16_bf16 v[96:111], v[2:5], v[200:203], 0
	ds_read2_b64 v[2:5], v187 offset0:4 offset1:6
	v_cvt_pk_bf16_f32 v210, v52, v53
	v_cvt_pk_bf16_f32 v211, v54, v55
	s_waitcnt lgkmcnt(5)
	v_mfma_f32_32x32x16_bf16 v[112:127], v[232:235], v[200:203], v[112:127]
	ds_read2_b64 v[232:235], v174 offset0:136 offset1:138
	v_cvt_pk_bf16_f32 v212, v56, v57
	v_cvt_pk_bf16_f32 v213, v58, v59
	s_waitcnt lgkmcnt(5)
	v_mfma_f32_32x32x16_bf16 v[128:143], v[236:239], v[200:203], 0
	ds_read2_b64 v[236:239], v186 offset0:8 offset1:10
	v_cvt_pk_bf16_f32 v214, v60, v61
	v_cvt_pk_bf16_f32 v215, v62, v63
	s_waitcnt lgkmcnt(5)
	v_mfma_f32_32x32x16_bf16 v[80:95], v[240:243], v[204:207], v[80:95]
	ds_read2_b64 v[240:243], v175 offset0:136 offset1:138
	v_cvt_pk_bf16_f32 v216, v32, v33
	v_cvt_pk_bf16_f32 v217, v34, v35
	s_waitcnt lgkmcnt(5)
	v_mfma_f32_32x32x16_bf16 v[96:111], v[244:247], v[204:207], v[96:111]
	ds_read2_b64 v[244:247], v187 offset0:8 offset1:10
	v_cvt_pk_bf16_f32 v218, v36, v37
	v_cvt_pk_bf16_f32 v219, v38, v39
	s_waitcnt lgkmcnt(5)
	v_mfma_f32_32x32x16_bf16 v[112:127], v[248:251], v[204:207], v[112:127]
	ds_read2_b64 v[248:251], v174 offset0:140 offset1:142
	v_cvt_pk_bf16_f32 v220, v40, v41
	v_cvt_pk_bf16_f32 v221, v42, v43
	s_waitcnt lgkmcnt(5)
	v_mfma_f32_32x32x16_bf16 v[128:143], v[2:5], v[204:207], v[128:143]
	ds_read2_b64 v[2:5], v186 offset0:12 offset1:14
	v_cvt_pk_bf16_f32 v222, v44, v45
	v_cvt_pk_bf16_f32 v223, v46, v47
	s_waitcnt lgkmcnt(5)
	v_mfma_f32_32x32x16_bf16 v[80:95], v[232:235], v[208:211], v[80:95]
	ds_read2_b64 v[232:235], v175 offset0:140 offset1:142
	v_cvt_pk_bf16_f32 v224, v16, v17
	v_cvt_pk_bf16_f32 v225, v18, v19
	s_waitcnt lgkmcnt(5)
	v_mfma_f32_32x32x16_bf16 v[96:111], v[236:239], v[208:211], v[96:111]
	ds_read2_b64 v[236:239], v187 offset0:12 offset1:14
	v_cvt_pk_bf16_f32 v226, v20, v21
	v_cvt_pk_bf16_f32 v227, v22, v23
	s_waitcnt lgkmcnt(5)
	v_mfma_f32_32x32x16_bf16 v[112:127], v[240:243], v[208:211], v[112:127]
	ds_read2_b64 v[240:243], v174 offset0:144 offset1:146
	v_cvt_pk_bf16_f32 v228, v24, v25
	v_cvt_pk_bf16_f32 v229, v26, v27
	s_waitcnt lgkmcnt(5)
	v_mfma_f32_32x32x16_bf16 v[128:143], v[244:247], v[208:211], v[128:143]
	ds_read2_b64 v[244:247], v186 offset0:16 offset1:18
	v_cvt_pk_bf16_f32 v230, v28, v29
	v_cvt_pk_bf16_f32 v231, v30, v31
	s_waitcnt lgkmcnt(5)
	v_mfma_f32_32x32x16_bf16 v[80:95], v[248:251], v[212:215], v[80:95]
	ds_read2_b64 v[248:251], v175 offset0:144 offset1:146
	v_pk_mul_f32 v[64:65], v[64:65], v[150:151] op_sel_hi:[1,0]
	v_pk_mul_f32 v[66:67], v[66:67], v[150:151] op_sel_hi:[1,0]
	s_waitcnt lgkmcnt(5)
	v_mfma_f32_32x32x16_bf16 v[96:111], v[2:5], v[212:215], v[96:111]
	ds_read2_b64 v[2:5], v187 offset0:16 offset1:18
	v_pk_mul_f32 v[68:69], v[68:69], v[150:151] op_sel_hi:[1,0]
	v_pk_mul_f32 v[70:71], v[70:71], v[150:151] op_sel_hi:[1,0]
	s_waitcnt lgkmcnt(5)
	v_mfma_f32_32x32x16_bf16 v[112:127], v[232:235], v[212:215], v[112:127]
	ds_read2_b64 v[232:235], v174 offset0:148 offset1:150
	v_pk_mul_f32 v[72:73], v[72:73], v[150:151] op_sel_hi:[1,0]
	v_pk_mul_f32 v[74:75], v[74:75], v[150:151] op_sel_hi:[1,0]
	s_waitcnt lgkmcnt(5)
	v_mfma_f32_32x32x16_bf16 v[128:143], v[236:239], v[212:215], v[128:143]
	ds_read2_b64 v[236:239], v186 offset0:20 offset1:22
	v_pk_mul_f32 v[76:77], v[76:77], v[150:151] op_sel_hi:[1,0]
	v_pk_mul_f32 v[78:79], v[78:79], v[150:151] op_sel_hi:[1,0]
	s_waitcnt lgkmcnt(5)
	v_mfma_f32_32x32x16_bf16 v[80:95], v[240:243], v[216:219], v[80:95]
	ds_read2_b64 v[240:243], v175 offset0:148 offset1:150
	v_pk_mul_f32 v[48:49], v[48:49], v[150:151] op_sel_hi:[1,0]
	v_pk_mul_f32 v[50:51], v[50:51], v[150:151] op_sel_hi:[1,0]
	s_waitcnt lgkmcnt(5)
	v_mfma_f32_32x32x16_bf16 v[96:111], v[244:247], v[216:219], v[96:111]
	ds_read2_b64 v[244:247], v187 offset0:20 offset1:22
	v_pk_mul_f32 v[52:53], v[52:53], v[150:151] op_sel_hi:[1,0]
	v_pk_mul_f32 v[54:55], v[54:55], v[150:151] op_sel_hi:[1,0]
	s_waitcnt lgkmcnt(5)
; #define LAS __attribute__((address_space(3)))
; __device__ __forceinline__ bf16_t f2bf(float f) { return (bf16_t)(pk2(f, 0.f) & 0xffffu); }
; __device__ __forceinline__ int crow(int r, int hi) { return (r & 3) + 8 * (r >> 2) + 4 * hi; }
; __device__ __forceinline__ bf16x8 ldA_perm(const LAS bf16_t* p) { s16x4 a = *(const LAS s16x4*)p; s16x4 b = *(const LAS s16x4*)(p + 8); return (bf16x8){a[0], a[1], a[2], a[3], b[0], b[1], b[2], b[3]}; }
; #define GDN_LDF_WQ(F, td_) do { _Pragma("unroll") for (int tc = 0; tc < 2; ++tc) _Pragma("unroll") for (int s_ = 0; s_ < 2; ++s_) { const int ko_ = 32 * (td_) + 16 * s_ + 4 * hh; \
;                     F[tc * 2 + s_] = ldA_perm(WNs + (32 * tc + l31) * 136 + ko_); F[4 + tc * 2 + s_] = ldA_perm(QD + (32 * tc + l31) * 136 + ko_); } } while (0)
; __device__ __forceinline__ void gdn_scan(const Ctx& c, const Params& p, int e) {
;     ...
;                 GDN_LDF_WQ(fa, 0);
;                 GDN_LDF_WQ(fb, 1); GDN_MMA_WQ(fa, 0);
;                 GDN_LDF_WQ(fa, 2); GDN_MMA_WQ(fb, 1);
;                 GDN_LDF_WQ(fb, 3); GDN_MMA_WQ(fa, 2);
; #pragma unroll
;                 for (int tc = 0; tc < 2; ++tc)
; #pragma unroll
;                     for (int ts = 0; ts < 2; ++ts)
; #pragma unroll
;                         for (int s_ = 0; s_ < 2; ++s_) fa[tc * 4 + ts * 2 + s_] = ldA_perm(QK + (32 * tc + l31) * 72 + 32 * ts + 16 * s_ + 4 * hh);
;                 GDN_MMA_WQ(fb, 3);
;     ...
;                 bf16x8 Vb[2][2];
; #pragma unroll
;                 for (int tc = 0; tc < 2; ++tc) { Vb[tc][0] = pkfrag(av[tc], 0); Vb[tc][1] = pkfrag(av[tc], 1); }
;     ...
;                 GDN_LDF_K(fb, 0);
; #pragma unroll
;                 for (int ts = 0; ts < 2; ++ts)
; #pragma unroll
;                     for (int s_ = 0; s_ < 2; ++s_)
; #pragma unroll
;                         for (int tc = 0; tc < 2; ++tc) ao[tc] = __builtin_amdgcn_mfma_f32_32x32x16_bf16(fa[tc * 4 + ts * 2 + s_], Vb[ts][s_], ao[tc], 0, 0, 0);
;                 GDN_LDF_K(fa, 1); GDN_MMA_K(fb, 0);
;                 GDN_MMA_K(fa, 1);
;     ...
;                 LAS bf16_t* ob = OTb + (n & 1) * 4608;
; #pragma unroll
;                 for (int tc = 0; tc < 2; ++tc)
; #pragma unroll
;                     for (int r = 0; r < 16; ++r) ob[(32 * tc + crow(r, hh)) * 72 + 32 * (c.wave & 1) + l31] = f2bf(ao[tc][r]);
	v_mfma_f32_32x32x16_bf16 v[112:127], v[248:251], v[216:219], v[112:127]
	ds_read2_b64 v[248:251], v174 offset0:152 offset1:154
	v_pk_mul_f32 v[56:57], v[56:57], v[150:151] op_sel_hi:[1,0]
	v_pk_mul_f32 v[58:59], v[58:59], v[150:151] op_sel_hi:[1,0]
	s_waitcnt lgkmcnt(5)
	v_mfma_f32_32x32x16_bf16 v[128:143], v[2:5], v[216:219], v[128:143]
	ds_read2_b64 v[2:5], v175 offset0:152 offset1:154
	v_pk_mul_f32 v[60:61], v[60:61], v[150:151] op_sel_hi:[1,0]
	v_pk_mul_f32 v[62:63], v[62:63], v[150:151] op_sel_hi:[1,0]
	s_waitcnt lgkmcnt(5)
	v_mfma_f32_32x32x16_bf16 v[80:95], v[232:235], v[220:223], v[80:95]
	ds_read2_b64 v[232:235], v174 offset0:156 offset1:158
	v_pk_mul_f32 v[32:33], v[32:33], v[150:151] op_sel_hi:[1,0]
	v_pk_mul_f32 v[34:35], v[34:35], v[150:151] op_sel_hi:[1,0]
	s_waitcnt lgkmcnt(5)
	v_mfma_f32_32x32x16_bf16 v[96:111], v[236:239], v[220:223], v[96:111]
	ds_read2_b64 v[236:239], v175 offset0:156 offset1:158
	v_pk_mul_f32 v[36:37], v[36:37], v[150:151] op_sel_hi:[1,0]
	v_pk_mul_f32 v[38:39], v[38:39], v[150:151] op_sel_hi:[1,0]
	s_waitcnt lgkmcnt(5)
	v_mfma_f32_32x32x16_bf16 v[112:127], v[240:243], v[220:223], v[112:127]
	ds_read2_b64 v[240:243], v186 offset0:24 offset1:26
	v_pk_mul_f32 v[40:41], v[40:41], v[150:151] op_sel_hi:[1,0]
	v_pk_mul_f32 v[42:43], v[42:43], v[150:151] op_sel_hi:[1,0]
	s_waitcnt lgkmcnt(5)
	v_mfma_f32_32x32x16_bf16 v[128:143], v[244:247], v[220:223], v[128:143]
	ds_read2_b64 v[244:247], v187 offset0:24 offset1:26
	v_pk_mul_f32 v[44:45], v[44:45], v[150:151] op_sel_hi:[1,0]
	v_pk_mul_f32 v[46:47], v[46:47], v[150:151] op_sel_hi:[1,0]
	s_waitcnt lgkmcnt(5)
	v_mfma_f32_32x32x16_bf16 v[80:95], v[248:251], v[224:227], v[80:95]
	ds_read2_b64 v[248:251], v186 offset0:28 offset1:30
	v_pk_mul_f32 v[16:17], v[16:17], v[150:151] op_sel_hi:[1,0]
	v_pk_mul_f32 v[18:19], v[18:19], v[150:151] op_sel_hi:[1,0]
	s_waitcnt lgkmcnt(5)
	v_mfma_f32_32x32x16_bf16 v[112:127], v[2:5], v[224:227], v[112:127]
	ds_read2_b64 v[2:5], v187 offset0:28 offset1:30
	v_pk_mul_f32 v[20:21], v[20:21], v[150:151] op_sel_hi:[1,0]
	v_pk_mul_f32 v[22:23], v[22:23], v[150:151] op_sel_hi:[1,0]
	s_waitcnt lgkmcnt(5)
	v_mfma_f32_32x32x16_bf16 v[80:95], v[232:235], v[228:231], v[80:95]
	ds_read2_b64 v[232:235], v1 offset0:0 offset1:2
	v_pk_mul_f32 v[24:25], v[24:25], v[150:151] op_sel_hi:[1,0]
	v_pk_mul_f32 v[26:27], v[26:27], v[150:151] op_sel_hi:[1,0]
	s_waitcnt lgkmcnt(5)
	v_mfma_f32_32x32x16_bf16 v[112:127], v[236:239], v[228:231], v[112:127]
	ds_read2_b64 v[236:239], v252 offset0:64 offset1:66
	v_pk_mul_f32 v[28:29], v[28:29], v[150:151] op_sel_hi:[1,0]
	v_pk_mul_f32 v[30:31], v[30:31], v[150:151] op_sel_hi:[1,0]
	s_waitcnt lgkmcnt(5)
	v_mfma_f32_32x32x16_bf16 v[96:111], v[240:243], v[224:227], v[96:111]
	ds_read2_b64 v[240:243], v1 offset0:4 offset1:6
	s_waitcnt lgkmcnt(5)
	v_mfma_f32_32x32x16_bf16 v[128:143], v[244:247], v[224:227], v[128:143]
	ds_read2_b64 v[244:247], v252 offset0:68 offset1:70
	s_waitcnt lgkmcnt(5)
	v_mfma_f32_32x32x16_bf16 v[96:111], v[248:251], v[228:231], v[96:111]
	ds_read2_b64 v[248:251], v1 offset0:8 offset1:10
	s_waitcnt lgkmcnt(5)
	v_mfma_f32_32x32x16_bf16 v[128:143], v[2:5], v[228:231], v[128:143]
	ds_read2_b64 v[2:5], v252 offset0:72 offset1:74
	s_waitcnt vmcnt(0)
	v_mov_b32_e32 v150, v253
	s_nop 3
	v_cvt_pk_bf16_f32 v80, v80, v81
	v_cvt_pk_bf16_f32 v81, v82, v83
	v_cvt_pk_bf16_f32 v82, v84, v85
	v_cvt_pk_bf16_f32 v83, v86, v87
	v_cvt_pk_bf16_f32 v84, v88, v89
	v_cvt_pk_bf16_f32 v85, v90, v91
	v_cvt_pk_bf16_f32 v86, v92, v93
	v_cvt_pk_bf16_f32 v87, v94, v95
	v_cvt_pk_bf16_f32 v112, v112, v113
	v_cvt_pk_bf16_f32 v113, v114, v115
	v_cvt_pk_bf16_f32 v114, v116, v117
	v_cvt_pk_bf16_f32 v115, v118, v119
	v_cvt_pk_bf16_f32 v116, v120, v121
	v_cvt_pk_bf16_f32 v117, v122, v123
	v_cvt_pk_bf16_f32 v118, v124, v125
	v_cvt_pk_bf16_f32 v119, v126, v127
	v_add_u32_e32 v174, v169, v188
	v_add_u32_e32 v174, 0xcc00, v174
	v_add_u32_e32 v175, 0x1200, v174
	v_add_u32_e32 v253, 0x1200, v175
	s_waitcnt lgkmcnt(5)
	v_mfma_f32_32x32x16_bf16 v[96:111], v[232:235], v[80:83], v[96:111]
	ds_read2_b64 v[232:235], v1 offset0:12 offset1:14
	s_waitcnt lgkmcnt(5)
	v_mfma_f32_32x32x16_bf16 v[128:143], v[236:239], v[80:83], v[128:143]
	ds_read2_b64 v[236:239], v252 offset0:76 offset1:78
	v_add_u32_e32 v252, 0x1200, v253
	s_waitcnt lgkmcnt(5)
	v_mfma_f32_32x32x16_bf16 v[96:111], v[240:243], v[84:87], v[96:111]
	ds_read2_b64 v[240:243], v174 offset0:0 offset1:2
	s_waitcnt lgkmcnt(5)
	v_mfma_f32_32x32x16_bf16 v[128:143], v[244:247], v[84:87], v[128:143]
	ds_read2_b64 v[244:247], v175 offset0:0 offset1:2
	s_waitcnt lgkmcnt(5)
	v_mfma_f32_32x32x16_bf16 v[96:111], v[248:251], v[112:115], v[96:111]
	ds_read2_b64 v[248:251], v253 offset0:0 offset1:2
	s_waitcnt lgkmcnt(5)
	v_mfma_f32_32x32x16_bf16 v[128:143], v[2:5], v[112:115], v[128:143]
	ds_read2_b64 v[2:5], v252 offset0:0 offset1:2
	s_waitcnt lgkmcnt(5)
	v_mfma_f32_32x32x16_bf16 v[96:111], v[232:235], v[116:119], v[96:111]
	ds_read2_b64 v[232:235], v174 offset0:4 offset1:6
	s_waitcnt lgkmcnt(5)
	v_mfma_f32_32x32x16_bf16 v[128:143], v[236:239], v[116:119], v[128:143]
	ds_read2_b64 v[236:239], v175 offset0:4 offset1:6
	v_add_u32_e32 v1, s35, v195
	v_add_u32_e32 v1, v1, v190
	s_waitcnt lgkmcnt(5)
	v_mfma_f32_32x32x16_bf16 v[64:79], v[240:243], v[80:83], v[64:79]
	ds_read2_b64 v[240:243], v253 offset0:4 offset1:6
	s_waitcnt lgkmcnt(5)
	v_mfma_f32_32x32x16_bf16 v[48:63], v[244:247], v[80:83], v[48:63]
	ds_read2_b64 v[244:247], v252 offset0:4 offset1:6
	s_waitcnt lgkmcnt(5)
	v_mfma_f32_32x32x16_bf16 v[32:47], v[248:251], v[80:83], v[32:47]
	ds_read2_b64 v[248:251], v174 offset0:8 offset1:10
	s_waitcnt lgkmcnt(5)
; #define LAS __attribute__((address_space(3)))
; __device__ __forceinline__ float bf2f(bf16_t b) { return asf((unsigned)b << 16); }
; __device__ __forceinline__ bf16_t f2bf(float f) { return (bf16_t)(pk2(f, 0.f) & 0xffffu); }
; __device__ __forceinline__ int crow(int r, int hi) { return (r & 3) + 8 * (r >> 2) + 4 * hi; }
; #define LDS_BARRIER() do { asm volatile("s_waitcnt lgkmcnt(0)" ::: "memory"); __builtin_amdgcn_s_barrier(); asm volatile("" ::: "memory"); } while (0)
; __device__ __forceinline__ void gdn_scan(const Ctx& c, const Params& p, int e) {
;     ...
;             for (int n = 0; n < 128; ++n) {
;                 LDS_BARRIER();
;                 if (c.wave < 2) {
;                 const float gt = gtn; if (n + 1 < 128) gtn = GC[(size_t)bh * 128 + n + 1];
;                 f32x16 av[2];
; #pragma unroll
;                 for (int tc = 0; tc < 2; ++tc)
; #pragma unroll
;                     for (int r = 0; r < 16; ++r) av[tc][r] = bf2f(UT[(32 * tc + crow(r, hh)) * 136 + e0 + l31]);
;                 f32x16 ao[2] = {(f32x16){}, (f32x16){}};
;                 bf16x8 fa[8], fb[8];
;     ...
;                 GDN_LDF_WQ(fa, 0);
;                 GDN_LDF_WQ(fb, 1); GDN_MMA_WQ(fa, 0);
;                 GDN_LDF_WQ(fa, 2); GDN_MMA_WQ(fb, 1);
;                 GDN_LDF_WQ(fb, 3); GDN_MMA_WQ(fa, 2);
; #pragma unroll
;                 for (int tc = 0; tc < 2; ++tc)
; #pragma unroll
;                     for (int ts = 0; ts < 2; ++ts)
; #pragma unroll
;                         for (int s_ = 0; s_ < 2; ++s_) fa[tc * 4 + ts * 2 + s_] = ldA_perm(QK + (32 * tc + l31) * 72 + 32 * ts + 16 * s_ + 4 * hh);
;                 GDN_MMA_WQ(fb, 3);
;     ...
;                 GDN_LDF_K(fb, 0);
; #pragma unroll
;                 for (int ts = 0; ts < 2; ++ts)
; #pragma unroll
;                     for (int s_ = 0; s_ < 2; ++s_)
; #pragma unroll
;                         for (int tc = 0; tc < 2; ++tc) ao[tc] = __builtin_amdgcn_mfma_f32_32x32x16_bf16(fa[tc * 4 + ts * 2 + s_], Vb[ts][s_], ao[tc], 0, 0, 0);
;                 GDN_LDF_K(fa, 1); GDN_MMA_K(fb, 0);
;                 GDN_MMA_K(fa, 1);
;     ...
;                 LAS bf16_t* ob = OTb + (n & 1) * 4608;
; #pragma unroll
;                 for (int tc = 0; tc < 2; ++tc)
; #pragma unroll
;                     for (int r = 0; r < 16; ++r) ob[(32 * tc + crow(r, hh)) * 72 + 32 * (c.wave & 1) + l31] = f2bf(ao[tc][r]);
	v_mfma_f32_32x32x16_bf16 v[16:31], v[2:5], v[80:83], v[16:31]
	ds_read2_b64 v[2:5], v175 offset0:8 offset1:10
	v_cvt_pk_bf16_f32 v88, v96, v97
	ds_write_b16 v1, v88 offset:0
	ds_write_b16_d16_hi v1, v88 offset:144
	s_waitcnt lgkmcnt(7)
	v_mfma_f32_32x32x16_bf16 v[64:79], v[232:235], v[84:87], v[64:79]
	ds_read2_b64 v[232:235], v253 offset0:8 offset1:10
	v_cvt_pk_bf16_f32 v89, v98, v99
	ds_write_b16 v1, v89 offset:288
	ds_write_b16_d16_hi v1, v89 offset:432
	s_waitcnt lgkmcnt(9)
	v_mfma_f32_32x32x16_bf16 v[48:63], v[236:239], v[84:87], v[48:63]
	ds_read2_b64 v[236:239], v252 offset0:8 offset1:10
	v_cvt_pk_bf16_f32 v90, v100, v101
	ds_write_b16 v1, v90 offset:1152
	ds_write_b16_d16_hi v1, v90 offset:1296
	s_waitcnt lgkmcnt(11)
	v_mfma_f32_32x32x16_bf16 v[32:47], v[240:243], v[84:87], v[32:47]
	ds_read2_b64 v[240:243], v174 offset0:12 offset1:14
	v_cvt_pk_bf16_f32 v91, v102, v103
	ds_write_b16 v1, v91 offset:1440
	ds_write_b16_d16_hi v1, v91 offset:1584
	s_waitcnt lgkmcnt(13)
	v_mfma_f32_32x32x16_bf16 v[16:31], v[244:247], v[84:87], v[16:31]
	ds_read2_b64 v[244:247], v175 offset0:12 offset1:14
	v_cvt_pk_bf16_f32 v88, v104, v105
	ds_write_b16 v1, v88 offset:2304
	s_waitcnt lgkmcnt(7)
	ds_write_b16_d16_hi v1, v88 offset:2448
	v_mfma_f32_32x32x16_bf16 v[64:79], v[248:251], v[112:115], v[64:79]
	ds_read2_b64 v[248:251], v253 offset0:12 offset1:14
	v_cvt_pk_bf16_f32 v89, v106, v107
	ds_write_b16 v1, v89 offset:2592
	ds_write_b16_d16_hi v1, v89 offset:2736
	v_mfma_f32_32x32x16_bf16 v[48:63], v[2:5], v[112:115], v[48:63]
	ds_read2_b64 v[2:5], v252 offset0:12 offset1:14
	v_cvt_pk_bf16_f32 v90, v108, v109
	ds_write_b16 v1, v90 offset:3456
	ds_write_b16_d16_hi v1, v90 offset:3600
	v_mfma_f32_32x32x16_bf16 v[32:47], v[232:235], v[112:115], v[32:47]
	v_cvt_pk_bf16_f32 v91, v110, v111
	ds_write_b16 v1, v91 offset:3744
	s_waitcnt lgkmcnt(7)
	ds_write_b16_d16_hi v1, v91 offset:3888
	v_cvt_pk_bf16_f32 v88, v128, v129
	ds_write_b16 v1, v88 offset:4608
	ds_write_b16_d16_hi v1, v88 offset:4752
	v_mfma_f32_32x32x16_bf16 v[16:31], v[236:239], v[112:115], v[16:31]
	v_cvt_pk_bf16_f32 v89, v130, v131
	ds_write_b16 v1, v89 offset:4896
	ds_write_b16_d16_hi v1, v89 offset:5040
	v_cvt_pk_bf16_f32 v90, v132, v133
	ds_write_b16 v1, v90 offset:5760
	ds_write_b16_d16_hi v1, v90 offset:5904
	v_mfma_f32_32x32x16_bf16 v[64:79], v[240:243], v[116:119], v[64:79]
	v_cvt_pk_bf16_f32 v91, v134, v135
	ds_write_b16 v1, v91 offset:6048
	s_waitcnt lgkmcnt(7)
	ds_write_b16_d16_hi v1, v91 offset:6192
	v_cvt_pk_bf16_f32 v88, v136, v137
	ds_write_b16 v1, v88 offset:6912
	ds_write_b16_d16_hi v1, v88 offset:7056
	v_mfma_f32_32x32x16_bf16 v[48:63], v[244:247], v[116:119], v[48:63]
	v_cvt_pk_bf16_f32 v89, v138, v139
	ds_write_b16 v1, v89 offset:7200
	ds_write_b16_d16_hi v1, v89 offset:7344
	v_cvt_pk_bf16_f32 v90, v140, v141
	ds_write_b16 v1, v90 offset:8064
	ds_write_b16_d16_hi v1, v90 offset:8208
	v_mfma_f32_32x32x16_bf16 v[32:47], v[248:251], v[116:119], v[32:47]
	v_cvt_pk_bf16_f32 v91, v142, v143
	ds_write_b16 v1, v91 offset:8352
	s_waitcnt lgkmcnt(7)
	ds_write_b16_d16_hi v1, v91 offset:8496
	v_mfma_f32_32x32x16_bf16 v[16:31], v[2:5], v[116:119], v[16:31]
	s_branch .LBB0_524
.LBB0_527:
	s_waitcnt lgkmcnt(0)
	s_barrier
	s_and_b64 vcc, exec, s[4:5]
	s_cbranch_vccnz .LBB0_529
	v_mov_b64_e32 v[252:253], s[2:3]
	v_add_u32_e32 v174, 0x4000, v186
	v_add_u32_e32 v175, 0x4000, v187
	global_load_dword v253, v[252:253], off
	v_add_u32_e32 v1, v168, v188
	ds_read2_b64 v[232:235], v14 offset0:0 offset1:2
	ds_read2_b64 v[236:239], v15 offset0:0 offset1:2
	ds_read2_b64 v[240:243], v14 offset0:4 offset1:6
	ds_read2_b64 v[244:247], v15 offset0:4 offset1:6
	ds_read2_b64 v[248:251], v174 offset0:128 offset1:130
	ds_read2_b64 v[2:5], v186 offset0:0 offset1:2
	v_add_u32_e32 v252, 0x1000, v1
	s_bitcmp1_b32 s21, 0
	s_cselect_b32 s35, 0x2400, 0
	v_cvt_pk_bf16_f32 v200, v64, v65
	v_cvt_pk_bf16_f32 v201, v66, v67
	v_cvt_pk_bf16_f32 v202, v68, v69
	v_cvt_pk_bf16_f32 v203, v70, v71
	v_cvt_pk_bf16_f32 v204, v72, v73
	v_cvt_pk_bf16_f32 v205, v74, v75
	v_cvt_pk_bf16_f32 v206, v76, v77
	v_cvt_pk_bf16_f32 v207, v78, v79
	s_waitcnt lgkmcnt(5)
	v_mfma_f32_32x32x16_bf16 v[80:95], v[232:235], v[6:9], 0
	ds_read2_b64 v[232:235], v175 offset0:128 offset1:130
	s_waitcnt lgkmcnt(5)
	v_mfma_f32_32x32x16_bf16 v[112:127], v[236:239], v[6:9], 0
	ds_read2_b64 v[236:239], v187 offset0:0 offset1:2
	s_waitcnt lgkmcnt(5)
	v_mfma_f32_32x32x16_bf16 v[80:95], v[240:243], v[10:13], v[80:95]
	ds_read2_b64 v[240:243], v174 offset0:132 offset1:134
	s_waitcnt lgkmcnt(5)
	v_mfma_f32_32x32x16_bf16 v[112:127], v[244:247], v[10:13], v[112:127]
	ds_read2_b64 v[244:247], v186 offset0:4 offset1:6
	s_waitcnt lgkmcnt(5)
	v_mfma_f32_32x32x16_bf16 v[80:95], v[248:251], v[200:203], v[80:95]
	ds_read2_b64 v[248:251], v175 offset0:132 offset1:134
	v_cvt_pk_bf16_f32 v208, v48, v49
	v_cvt_pk_bf16_f32 v209, v50, v51
	s_waitcnt lgkmcnt(5)
	v_mfma_f32_32x32x16_bf16 v[96:111], v[2:5], v[200:203], 0
	ds_read2_b64 v[2:5], v187 offset0:4 offset1:6
	v_cvt_pk_bf16_f32 v210, v52, v53
	v_cvt_pk_bf16_f32 v211, v54, v55
	s_waitcnt lgkmcnt(5)
	v_mfma_f32_32x32x16_bf16 v[112:127], v[232:235], v[200:203], v[112:127]
	ds_read2_b64 v[232:235], v174 offset0:136 offset1:138
	v_cvt_pk_bf16_f32 v212, v56, v57
	v_cvt_pk_bf16_f32 v213, v58, v59
	s_waitcnt lgkmcnt(5)
	v_mfma_f32_32x32x16_bf16 v[128:143], v[236:239], v[200:203], 0
	ds_read2_b64 v[236:239], v186 offset0:8 offset1:10
	v_cvt_pk_bf16_f32 v214, v60, v61
	v_cvt_pk_bf16_f32 v215, v62, v63
	s_waitcnt lgkmcnt(5)
	v_mfma_f32_32x32x16_bf16 v[80:95], v[240:243], v[204:207], v[80:95]
	ds_read2_b64 v[240:243], v175 offset0:136 offset1:138
	v_cvt_pk_bf16_f32 v216, v32, v33
	v_cvt_pk_bf16_f32 v217, v34, v35
	s_waitcnt lgkmcnt(5)
; __device__ __forceinline__ bf16x8 ldA_perm(const LAS bf16_t* p) { s16x4 a = *(const LAS s16x4*)p; s16x4 b = *(const LAS s16x4*)(p + 8); return (bf16x8){a[0], a[1], a[2], a[3], b[0], b[1], b[2], b[3]}; }
; #define GDN_LDF_WQ(F, td_) do { _Pragma("unroll") for (int tc = 0; tc < 2; ++tc) _Pragma("unroll") for (int s_ = 0; s_ < 2; ++s_) { const int ko_ = 32 * (td_) + 16 * s_ + 4 * hh; \
;                     F[tc * 2 + s_] = ldA_perm(WNs + (32 * tc + l31) * 136 + ko_); F[4 + tc * 2 + s_] = ldA_perm(QD + (32 * tc + l31) * 136 + ko_); } } while (0)
; #define GDN_LDF_K(F, tdp_) do { _Pragma("unroll") for (int t2_ = 0; t2_ < 2; ++t2_) _Pragma("unroll") for (int tc = 0; tc < 2; ++tc) _Pragma("unroll") for (int s_ = 0; s_ < 2; ++s_) \
;                     F[t2_ * 4 + tc * 2 + s_] = ldA_perm(KDT + (32 * (2 * (tdp_) + t2_) + l31) * 72 + 32 * tc + 16 * s_ + 4 * hh); } while (0)
; __device__ __forceinline__ void gdn_scan(const Ctx& c, const Params& p, int e) {
;     ...
;                 GDN_LDF_WQ(fa, 0);
;                 GDN_LDF_WQ(fb, 1); GDN_MMA_WQ(fa, 0);
;                 GDN_LDF_WQ(fa, 2); GDN_MMA_WQ(fb, 1);
;                 GDN_LDF_WQ(fb, 3); GDN_MMA_WQ(fa, 2);
; #pragma unroll
;                 for (int tc = 0; tc < 2; ++tc)
; #pragma unroll
;                     for (int ts = 0; ts < 2; ++ts)
; #pragma unroll
;                         for (int s_ = 0; s_ < 2; ++s_) fa[tc * 4 + ts * 2 + s_] = ldA_perm(QK + (32 * tc + l31) * 72 + 32 * ts + 16 * s_ + 4 * hh);
;                 GDN_MMA_WQ(fb, 3);
;     ...
;                 bf16x8 Vb[2][2];
; #pragma unroll
;                 for (int tc = 0; tc < 2; ++tc) { Vb[tc][0] = pkfrag(av[tc], 0); Vb[tc][1] = pkfrag(av[tc], 1); }
;     ...
;                 GDN_LDF_K(fb, 0);
; #pragma unroll
;                 for (int ts = 0; ts < 2; ++ts)
; #pragma unroll
;                     for (int s_ = 0; s_ < 2; ++s_)
; #pragma unroll
;                         for (int tc = 0; tc < 2; ++tc) ao[tc] = __builtin_amdgcn_mfma_f32_32x32x16_bf16(fa[tc * 4 + ts * 2 + s_], Vb[ts][s_], ao[tc], 0, 0, 0);
;                 GDN_LDF_K(fa, 1); GDN_MMA_K(fb, 0);
;                 GDN_MMA_K(fa, 1);
	v_mfma_f32_32x32x16_bf16 v[96:111], v[244:247], v[204:207], v[96:111]
	ds_read2_b64 v[244:247], v187 offset0:8 offset1:10
	v_cvt_pk_bf16_f32 v218, v36, v37
	v_cvt_pk_bf16_f32 v219, v38, v39
	s_waitcnt lgkmcnt(5)
	v_mfma_f32_32x32x16_bf16 v[112:127], v[248:251], v[204:207], v[112:127]
	ds_read2_b64 v[248:251], v174 offset0:140 offset1:142
	v_cvt_pk_bf16_f32 v220, v40, v41
	v_cvt_pk_bf16_f32 v221, v42, v43
	s_waitcnt lgkmcnt(5)
	v_mfma_f32_32x32x16_bf16 v[128:143], v[2:5], v[204:207], v[128:143]
	ds_read2_b64 v[2:5], v186 offset0:12 offset1:14
	v_cvt_pk_bf16_f32 v222, v44, v45
	v_cvt_pk_bf16_f32 v223, v46, v47
	s_waitcnt lgkmcnt(5)
	v_mfma_f32_32x32x16_bf16 v[80:95], v[232:235], v[208:211], v[80:95]
	ds_read2_b64 v[232:235], v175 offset0:140 offset1:142
	v_cvt_pk_bf16_f32 v224, v16, v17
	v_cvt_pk_bf16_f32 v225, v18, v19
	s_waitcnt lgkmcnt(5)
	v_mfma_f32_32x32x16_bf16 v[96:111], v[236:239], v[208:211], v[96:111]
	ds_read2_b64 v[236:239], v187 offset0:12 offset1:14
	v_cvt_pk_bf16_f32 v226, v20, v21
	v_cvt_pk_bf16_f32 v227, v22, v23
	s_waitcnt lgkmcnt(5)
	v_mfma_f32_32x32x16_bf16 v[112:127], v[240:243], v[208:211], v[112:127]
	ds_read2_b64 v[240:243], v174 offset0:144 offset1:146
	v_cvt_pk_bf16_f32 v228, v24, v25
	v_cvt_pk_bf16_f32 v229, v26, v27
	s_waitcnt lgkmcnt(5)
	v_mfma_f32_32x32x16_bf16 v[128:143], v[244:247], v[208:211], v[128:143]
	ds_read2_b64 v[244:247], v186 offset0:16 offset1:18
	v_cvt_pk_bf16_f32 v230, v28, v29
	v_cvt_pk_bf16_f32 v231, v30, v31
	s_waitcnt lgkmcnt(5)
	v_mfma_f32_32x32x16_bf16 v[80:95], v[248:251], v[212:215], v[80:95]
	ds_read2_b64 v[248:251], v175 offset0:144 offset1:146
	v_pk_mul_f32 v[64:65], v[64:65], v[150:151] op_sel_hi:[1,0]
	v_pk_mul_f32 v[66:67], v[66:67], v[150:151] op_sel_hi:[1,0]
	s_waitcnt lgkmcnt(5)
	v_mfma_f32_32x32x16_bf16 v[96:111], v[2:5], v[212:215], v[96:111]
	ds_read2_b64 v[2:5], v187 offset0:16 offset1:18
	v_pk_mul_f32 v[68:69], v[68:69], v[150:151] op_sel_hi:[1,0]
	v_pk_mul_f32 v[70:71], v[70:71], v[150:151] op_sel_hi:[1,0]
	s_waitcnt lgkmcnt(5)
	v_mfma_f32_32x32x16_bf16 v[112:127], v[232:235], v[212:215], v[112:127]
	ds_read2_b64 v[232:235], v174 offset0:148 offset1:150
	v_pk_mul_f32 v[72:73], v[72:73], v[150:151] op_sel_hi:[1,0]
	v_pk_mul_f32 v[74:75], v[74:75], v[150:151] op_sel_hi:[1,0]
	s_waitcnt lgkmcnt(5)
	v_mfma_f32_32x32x16_bf16 v[128:143], v[236:239], v[212:215], v[128:143]
	ds_read2_b64 v[236:239], v186 offset0:20 offset1:22
	v_pk_mul_f32 v[76:77], v[76:77], v[150:151] op_sel_hi:[1,0]
	v_pk_mul_f32 v[78:79], v[78:79], v[150:151] op_sel_hi:[1,0]
	s_waitcnt lgkmcnt(5)
	v_mfma_f32_32x32x16_bf16 v[80:95], v[240:243], v[216:219], v[80:95]
	ds_read2_b64 v[240:243], v175 offset0:148 offset1:150
	v_pk_mul_f32 v[48:49], v[48:49], v[150:151] op_sel_hi:[1,0]
	v_pk_mul_f32 v[50:51], v[50:51], v[150:151] op_sel_hi:[1,0]
	s_waitcnt lgkmcnt(5)
	v_mfma_f32_32x32x16_bf16 v[96:111], v[244:247], v[216:219], v[96:111]
	ds_read2_b64 v[244:247], v187 offset0:20 offset1:22
	v_pk_mul_f32 v[52:53], v[52:53], v[150:151] op_sel_hi:[1,0]
	v_pk_mul_f32 v[54:55], v[54:55], v[150:151] op_sel_hi:[1,0]
	s_waitcnt lgkmcnt(5)
	v_mfma_f32_32x32x16_bf16 v[112:127], v[248:251], v[216:219], v[112:127]
	ds_read2_b64 v[248:251], v174 offset0:152 offset1:154
	v_pk_mul_f32 v[56:57], v[56:57], v[150:151] op_sel_hi:[1,0]
	v_pk_mul_f32 v[58:59], v[58:59], v[150:151] op_sel_hi:[1,0]
	s_waitcnt lgkmcnt(5)
	v_mfma_f32_32x32x16_bf16 v[128:143], v[2:5], v[216:219], v[128:143]
	ds_read2_b64 v[2:5], v175 offset0:152 offset1:154
	v_pk_mul_f32 v[60:61], v[60:61], v[150:151] op_sel_hi:[1,0]
	v_pk_mul_f32 v[62:63], v[62:63], v[150:151] op_sel_hi:[1,0]
	s_waitcnt lgkmcnt(5)
	v_mfma_f32_32x32x16_bf16 v[80:95], v[232:235], v[220:223], v[80:95]
	ds_read2_b64 v[232:235], v174 offset0:156 offset1:158
	v_pk_mul_f32 v[32:33], v[32:33], v[150:151] op_sel_hi:[1,0]
	v_pk_mul_f32 v[34:35], v[34:35], v[150:151] op_sel_hi:[1,0]
	s_waitcnt lgkmcnt(5)
	v_mfma_f32_32x32x16_bf16 v[96:111], v[236:239], v[220:223], v[96:111]
	ds_read2_b64 v[236:239], v175 offset0:156 offset1:158
	v_pk_mul_f32 v[36:37], v[36:37], v[150:151] op_sel_hi:[1,0]
	v_pk_mul_f32 v[38:39], v[38:39], v[150:151] op_sel_hi:[1,0]
	s_waitcnt lgkmcnt(5)
	v_mfma_f32_32x32x16_bf16 v[112:127], v[240:243], v[220:223], v[112:127]
	ds_read2_b64 v[240:243], v186 offset0:24 offset1:26
	v_pk_mul_f32 v[40:41], v[40:41], v[150:151] op_sel_hi:[1,0]
	v_pk_mul_f32 v[42:43], v[42:43], v[150:151] op_sel_hi:[1,0]
	s_waitcnt lgkmcnt(5)
	v_mfma_f32_32x32x16_bf16 v[128:143], v[244:247], v[220:223], v[128:143]
	ds_read2_b64 v[244:247], v187 offset0:24 offset1:26
	v_pk_mul_f32 v[44:45], v[44:45], v[150:151] op_sel_hi:[1,0]
	v_pk_mul_f32 v[46:47], v[46:47], v[150:151] op_sel_hi:[1,0]
	s_waitcnt lgkmcnt(5)
	v_mfma_f32_32x32x16_bf16 v[80:95], v[248:251], v[224:227], v[80:95]
	ds_read2_b64 v[248:251], v186 offset0:28 offset1:30
	v_pk_mul_f32 v[16:17], v[16:17], v[150:151] op_sel_hi:[1,0]
	v_pk_mul_f32 v[18:19], v[18:19], v[150:151] op_sel_hi:[1,0]
	s_waitcnt lgkmcnt(5)
	v_mfma_f32_32x32x16_bf16 v[112:127], v[2:5], v[224:227], v[112:127]
	ds_read2_b64 v[2:5], v187 offset0:28 offset1:30
	v_pk_mul_f32 v[20:21], v[20:21], v[150:151] op_sel_hi:[1,0]
	v_pk_mul_f32 v[22:23], v[22:23], v[150:151] op_sel_hi:[1,0]
	s_waitcnt lgkmcnt(5)
	v_mfma_f32_32x32x16_bf16 v[80:95], v[232:235], v[228:231], v[80:95]
	ds_read2_b64 v[232:235], v1 offset0:0 offset1:2
	v_pk_mul_f32 v[24:25], v[24:25], v[150:151] op_sel_hi:[1,0]
	v_pk_mul_f32 v[26:27], v[26:27], v[150:151] op_sel_hi:[1,0]
	s_waitcnt lgkmcnt(5)
; #define LAS __attribute__((address_space(3)))
; __device__ __forceinline__ bf16_t f2bf(float f) { return (bf16_t)(pk2(f, 0.f) & 0xffffu); }
; __device__ __forceinline__ int crow(int r, int hi) { return (r & 3) + 8 * (r >> 2) + 4 * hi; }
; __device__ __forceinline__ bf16x8 ldA_perm(const LAS bf16_t* p) { s16x4 a = *(const LAS s16x4*)p; s16x4 b = *(const LAS s16x4*)(p + 8); return (bf16x8){a[0], a[1], a[2], a[3], b[0], b[1], b[2], b[3]}; }
; #define GDN_LDF_WQ(F, td_) do { _Pragma("unroll") for (int tc = 0; tc < 2; ++tc) _Pragma("unroll") for (int s_ = 0; s_ < 2; ++s_) { const int ko_ = 32 * (td_) + 16 * s_ + 4 * hh; \
;                     F[tc * 2 + s_] = ldA_perm(WNs + (32 * tc + l31) * 136 + ko_); F[4 + tc * 2 + s_] = ldA_perm(QD + (32 * tc + l31) * 136 + ko_); } } while (0)
; __device__ __forceinline__ void gdn_scan(const Ctx& c, const Params& p, int e) {
;     ...
;                 GDN_LDF_WQ(fa, 0);
;                 GDN_LDF_WQ(fb, 1); GDN_MMA_WQ(fa, 0);
;                 GDN_LDF_WQ(fa, 2); GDN_MMA_WQ(fb, 1);
;                 GDN_LDF_WQ(fb, 3); GDN_MMA_WQ(fa, 2);
; #pragma unroll
;                 for (int tc = 0; tc < 2; ++tc)
; #pragma unroll
;                     for (int ts = 0; ts < 2; ++ts)
; #pragma unroll
;                         for (int s_ = 0; s_ < 2; ++s_) fa[tc * 4 + ts * 2 + s_] = ldA_perm(QK + (32 * tc + l31) * 72 + 32 * ts + 16 * s_ + 4 * hh);
;                 GDN_MMA_WQ(fb, 3);
;     ...
;                 bf16x8 Vb[2][2];
; #pragma unroll
;                 for (int tc = 0; tc < 2; ++tc) { Vb[tc][0] = pkfrag(av[tc], 0); Vb[tc][1] = pkfrag(av[tc], 1); }
;     ...
;                 GDN_LDF_K(fb, 0);
; #pragma unroll
;                 for (int ts = 0; ts < 2; ++ts)
; #pragma unroll
;                     for (int s_ = 0; s_ < 2; ++s_)
; #pragma unroll
;                         for (int tc = 0; tc < 2; ++tc) ao[tc] = __builtin_amdgcn_mfma_f32_32x32x16_bf16(fa[tc * 4 + ts * 2 + s_], Vb[ts][s_], ao[tc], 0, 0, 0);
;                 GDN_LDF_K(fa, 1); GDN_MMA_K(fb, 0);
;                 GDN_MMA_K(fa, 1);
;     ...
;                 LAS bf16_t* ob = OTb + (n & 1) * 4608;
; #pragma unroll
;                 for (int tc = 0; tc < 2; ++tc)
; #pragma unroll
;                     for (int r = 0; r < 16; ++r) ob[(32 * tc + crow(r, hh)) * 72 + 32 * (c.wave & 1) + l31] = f2bf(ao[tc][r]);
	v_mfma_f32_32x32x16_bf16 v[112:127], v[236:239], v[228:231], v[112:127]
	ds_read2_b64 v[236:239], v252 offset0:64 offset1:66
	v_pk_mul_f32 v[28:29], v[28:29], v[150:151] op_sel_hi:[1,0]
	v_pk_mul_f32 v[30:31], v[30:31], v[150:151] op_sel_hi:[1,0]
	s_waitcnt lgkmcnt(5)
	v_mfma_f32_32x32x16_bf16 v[96:111], v[240:243], v[224:227], v[96:111]
	ds_read2_b64 v[240:243], v1 offset0:4 offset1:6
	s_waitcnt lgkmcnt(5)
	v_mfma_f32_32x32x16_bf16 v[128:143], v[244:247], v[224:227], v[128:143]
	ds_read2_b64 v[244:247], v252 offset0:68 offset1:70
	s_waitcnt lgkmcnt(5)
	v_mfma_f32_32x32x16_bf16 v[96:111], v[248:251], v[228:231], v[96:111]
	ds_read2_b64 v[248:251], v1 offset0:8 offset1:10
	s_waitcnt lgkmcnt(5)
	v_mfma_f32_32x32x16_bf16 v[128:143], v[2:5], v[228:231], v[128:143]
	ds_read2_b64 v[2:5], v252 offset0:72 offset1:74
	s_waitcnt vmcnt(0)
	v_mov_b32_e32 v150, v253
	s_nop 3
	v_cvt_pk_bf16_f32 v80, v80, v81
	v_cvt_pk_bf16_f32 v81, v82, v83
	v_cvt_pk_bf16_f32 v82, v84, v85
	v_cvt_pk_bf16_f32 v83, v86, v87
	v_cvt_pk_bf16_f32 v84, v88, v89
	v_cvt_pk_bf16_f32 v85, v90, v91
	v_cvt_pk_bf16_f32 v86, v92, v93
	v_cvt_pk_bf16_f32 v87, v94, v95
	v_cvt_pk_bf16_f32 v112, v112, v113
	v_cvt_pk_bf16_f32 v113, v114, v115
	v_cvt_pk_bf16_f32 v114, v116, v117
	v_cvt_pk_bf16_f32 v115, v118, v119
	v_cvt_pk_bf16_f32 v116, v120, v121
	v_cvt_pk_bf16_f32 v117, v122, v123
	v_cvt_pk_bf16_f32 v118, v124, v125
	v_cvt_pk_bf16_f32 v119, v126, v127
	v_add_u32_e32 v174, v169, v188
	v_add_u32_e32 v174, 0xcc00, v174
	v_add_u32_e32 v175, 0x1200, v174
	v_add_u32_e32 v253, 0x1200, v175
	s_waitcnt lgkmcnt(5)
	v_mfma_f32_32x32x16_bf16 v[96:111], v[232:235], v[80:83], v[96:111]
	ds_read2_b64 v[232:235], v1 offset0:12 offset1:14
	s_waitcnt lgkmcnt(5)
	v_mfma_f32_32x32x16_bf16 v[128:143], v[236:239], v[80:83], v[128:143]
	ds_read2_b64 v[236:239], v252 offset0:76 offset1:78
	v_add_u32_e32 v252, 0x1200, v253
	s_waitcnt lgkmcnt(5)
	v_mfma_f32_32x32x16_bf16 v[96:111], v[240:243], v[84:87], v[96:111]
	ds_read2_b64 v[240:243], v174 offset0:0 offset1:2
	s_waitcnt lgkmcnt(5)
	v_mfma_f32_32x32x16_bf16 v[128:143], v[244:247], v[84:87], v[128:143]
	ds_read2_b64 v[244:247], v175 offset0:0 offset1:2
	s_waitcnt lgkmcnt(5)
	v_mfma_f32_32x32x16_bf16 v[96:111], v[248:251], v[112:115], v[96:111]
	ds_read2_b64 v[248:251], v253 offset0:0 offset1:2
	s_waitcnt lgkmcnt(5)
	v_mfma_f32_32x32x16_bf16 v[128:143], v[2:5], v[112:115], v[128:143]
	ds_read2_b64 v[2:5], v252 offset0:0 offset1:2
	s_waitcnt lgkmcnt(5)
	v_mfma_f32_32x32x16_bf16 v[96:111], v[232:235], v[116:119], v[96:111]
	ds_read2_b64 v[232:235], v174 offset0:4 offset1:6
	s_waitcnt lgkmcnt(5)
	v_mfma_f32_32x32x16_bf16 v[128:143], v[236:239], v[116:119], v[128:143]
	ds_read2_b64 v[236:239], v175 offset0:4 offset1:6
	v_add_u32_e32 v1, s35, v195
	v_add_u32_e32 v1, v1, v190
	s_waitcnt lgkmcnt(5)
	v_mfma_f32_32x32x16_bf16 v[64:79], v[240:243], v[80:83], v[64:79]
	ds_read2_b64 v[240:243], v253 offset0:4 offset1:6
	s_waitcnt lgkmcnt(5)
	v_mfma_f32_32x32x16_bf16 v[48:63], v[244:247], v[80:83], v[48:63]
	ds_read2_b64 v[244:247], v252 offset0:4 offset1:6
	s_waitcnt lgkmcnt(5)
	v_mfma_f32_32x32x16_bf16 v[32:47], v[248:251], v[80:83], v[32:47]
	ds_read2_b64 v[248:251], v174 offset0:8 offset1:10
	s_waitcnt lgkmcnt(5)
	v_mfma_f32_32x32x16_bf16 v[16:31], v[2:5], v[80:83], v[16:31]
	ds_read2_b64 v[2:5], v175 offset0:8 offset1:10
	v_cvt_pk_bf16_f32 v88, v96, v97
	ds_write_b16 v1, v88 offset:0
	ds_write_b16_d16_hi v1, v88 offset:144
	s_waitcnt lgkmcnt(7)
	v_mfma_f32_32x32x16_bf16 v[64:79], v[232:235], v[84:87], v[64:79]
	ds_read2_b64 v[232:235], v253 offset0:8 offset1:10
	v_cvt_pk_bf16_f32 v89, v98, v99
	ds_write_b16 v1, v89 offset:288
	ds_write_b16_d16_hi v1, v89 offset:432
	s_waitcnt lgkmcnt(9)
	v_mfma_f32_32x32x16_bf16 v[48:63], v[236:239], v[84:87], v[48:63]
	ds_read2_b64 v[236:239], v252 offset0:8 offset1:10
	v_cvt_pk_bf16_f32 v90, v100, v101
	ds_write_b16 v1, v90 offset:1152
	ds_write_b16_d16_hi v1, v90 offset:1296
	s_waitcnt lgkmcnt(11)
	v_mfma_f32_32x32x16_bf16 v[32:47], v[240:243], v[84:87], v[32:47]
	ds_read2_b64 v[240:243], v174 offset0:12 offset1:14
	v_cvt_pk_bf16_f32 v91, v102, v103
	ds_write_b16 v1, v91 offset:1440
	ds_write_b16_d16_hi v1, v91 offset:1584
	s_waitcnt lgkmcnt(13)
	v_mfma_f32_32x32x16_bf16 v[16:31], v[244:247], v[84:87], v[16:31]
	ds_read2_b64 v[244:247], v175 offset0:12 offset1:14
	v_cvt_pk_bf16_f32 v88, v104, v105
	ds_write_b16 v1, v88 offset:2304
	s_waitcnt lgkmcnt(7)
	ds_write_b16_d16_hi v1, v88 offset:2448
	v_mfma_f32_32x32x16_bf16 v[64:79], v[248:251], v[112:115], v[64:79]
	ds_read2_b64 v[248:251], v253 offset0:12 offset1:14
	v_cvt_pk_bf16_f32 v89, v106, v107
	ds_write_b16 v1, v89 offset:2592
	ds_write_b16_d16_hi v1, v89 offset:2736
	v_mfma_f32_32x32x16_bf16 v[48:63], v[2:5], v[112:115], v[48:63]
	ds_read2_b64 v[2:5], v252 offset0:12 offset1:14
	v_cvt_pk_bf16_f32 v90, v108, v109
	ds_write_b16 v1, v90 offset:3456
	ds_write_b16_d16_hi v1, v90 offset:3600
	v_mfma_f32_32x32x16_bf16 v[32:47], v[232:235], v[112:115], v[32:47]
	v_cvt_pk_bf16_f32 v91, v110, v111
	ds_write_b16 v1, v91 offset:3744
	s_waitcnt lgkmcnt(7)
	ds_write_b16_d16_hi v1, v91 offset:3888
	v_cvt_pk_bf16_f32 v88, v128, v129
	ds_write_b16 v1, v88 offset:4608
	ds_write_b16_d16_hi v1, v88 offset:4752
	v_mfma_f32_32x32x16_bf16 v[16:31], v[236:239], v[112:115], v[16:31]
	v_cvt_pk_bf16_f32 v89, v130, v131
	ds_write_b16 v1, v89 offset:4896
	ds_write_b16_d16_hi v1, v89 offset:5040
	v_cvt_pk_bf16_f32 v90, v132, v133
	ds_write_b16 v1, v90 offset:5760
	ds_write_b16_d16_hi v1, v90 offset:5904
	v_mfma_f32_32x32x16_bf16 v[64:79], v[240:243], v[116:119], v[64:79]
	v_cvt_pk_bf16_f32 v91, v134, v135
	ds_write_b16 v1, v91 offset:6048
	s_waitcnt lgkmcnt(7)
	ds_write_b16_d16_hi v1, v91 offset:6192
	v_cvt_pk_bf16_f32 v88, v136, v137
	ds_write_b16 v1, v88 offset:6912
	ds_write_b16_d16_hi v1, v88 offset:7056
	v_mfma_f32_32x32x16_bf16 v[48:63], v[244:247], v[116:119], v[48:63]
	v_cvt_pk_bf16_f32 v89, v138, v139
	ds_write_b16 v1, v89 offset:7200
	ds_write_b16_d16_hi v1, v89 offset:7344
	v_cvt_pk_bf16_f32 v90, v140, v141
	ds_write_b16 v1, v90 offset:8064
	ds_write_b16_d16_hi v1, v90 offset:8208
	v_mfma_f32_32x32x16_bf16 v[32:47], v[248:251], v[116:119], v[32:47]
	v_cvt_pk_bf16_f32 v91, v142, v143
	ds_write_b16 v1, v91 offset:8352
	s_waitcnt lgkmcnt(7)
	ds_write_b16_d16_hi v1, v91 offset:8496
	v_mfma_f32_32x32x16_bf16 v[16:31], v[2:5], v[116:119], v[16:31]

; __device__ __forceinline__ void gdn_scan(const Ctx& c, const Params& p, int e) {
;     ...
;         if (producer) {
;             int pt_ = ptid; asm volatile("" : "+v"(pt_));
;             u32x4 tq[4], tk[4], tw[4], tu[4], tqk[2];
;             const int prow = pt_ >> 4, pc8 = (pt_ & 15) * 8;
;             const int qrow = pt_ >> 3, qc8 = (pt_ & 7) * 8;
;             GDN_LOAD_TILES(0); GDN_STORE_TILES();
.LBB0_530:
	s_and_b64 vcc, exec, s[2:3]
	s_cbranch_vccz .LBB0_521
	s_mul_hi_i32 s2, s20, 0x2aaaaaab
	s_lshr_b32 s3, s2, 31
	s_add_i32 s2, s2, s3
	s_mul_i32 s3, s2, 6
	s_sub_i32 s3, s20, s3
	s_waitcnt vmcnt(0)
	v_mov_b32_e32 v97, v165
	s_lshl_b32 s4, s2, 13
	v_ashrrev_i32_e32 v64, 4, v97
	v_lshlrev_b32_e32 v1, 3, v97
	s_lshl_b32 s2, s3, 7
	s_waitcnt lgkmcnt(0)
	v_and_b32_e32 v12, 0x78, v1
	s_ashr_i32 s5, s4, 31
	v_ashrrev_i32_e32 v65, 31, v64
	s_ashr_i32 s3, s2, 31
	v_lshl_add_u64 v[2:3], v[64:65], 0, s[4:5]
	v_or_b32_e32 v102, s2, v12
	v_mov_b32_e32 v103, s3
	s_movk_i32 s35, 0x300
	v_and_b32_e32 v66, 56, v1
	v_mad_u64_u32 v[6:7], s[20:21], v2, s35, v[102:103]
	v_add_u32_e32 v1, 0x100, v97
	v_mad_i32_i24 v7, v3, s35, v7
	v_mov_b64_e32 v[10:11], s[16:17]
	v_ashrrev_i32_e32 v106, 4, v1
	v_mad_u64_u32 v[4:5], s[20:21], v2, s69, v[10:11]
	v_lshlrev_b64 v[6:7], 1, v[6:7]
	v_ashrrev_i32_e32 v107, 31, v106
	v_mad_i32_i24 v5, v3, s69, v5
	s_lshl_b64 s[20:21], s[2:3], 1
	v_lshlrev_b32_e32 v114, 4, v97
	v_lshl_add_u64 v[68:69], s[8:9], 0, v[6:7]
	v_lshl_add_u64 v[78:79], s[6:7], 0, v[6:7]
	v_lshl_add_u64 v[6:7], v[106:107], 0, s[4:5]
	v_lshl_add_u64 v[8:9], v[4:5], 0, s[20:21]
	v_lshlrev_b32_e32 v104, 1, v12
	v_mov_b32_e32 v105, v0
	v_and_b32_e32 v4, 0x80, v114
	v_mov_b32_e32 v5, v0
	v_mad_u64_u32 v[32:33], s[2:3], v6, s69, v[10:11]
	v_lshl_add_u64 v[14:15], v[8:9], 0, v[104:105]
	v_lshl_add_u64 v[12:13], v[8:9], 0, v[4:5]
	v_lshlrev_b32_e32 v8, 1, v66
	v_mov_b32_e32 v9, v0
	v_mad_i32_i24 v33, v7, s69, v33
	v_lshl_add_u64 v[12:13], v[12:13], 0, v[8:9]
	v_lshl_add_u64 v[32:33], v[32:33], 0, s[20:21]
	global_load_dwordx4 v[16:19], v[14:15], off offset:1536
	global_load_dwordx4 v[20:23], v[12:13], off offset:3072
	v_add_co_u32_e32 v12, vcc, s47, v14
	v_lshl_add_u64 v[32:33], v[32:33], 0, v[4:5]
	s_nop 0
	v_addc_co_u32_e32 v13, vcc, 0, v15, vcc
	v_lshl_add_u64 v[36:37], v[32:33], 0, v[8:9]
	s_movk_i32 s0, 0x6000
	global_load_dwordx4 v[24:27], v[68:69], off
	global_load_dwordx4 v[28:31], v[78:79], off
	global_load_dwordx4 v[32:35], v[12:13], off offset:2048
	s_nop 0
	global_load_dwordx4 v[36:39], v[36:37], off offset:3072
	v_add_co_u32_e32 v12, vcc, s0, v68
	s_mov_b32 s39, 0x3c000
	s_nop 0
	v_addc_co_u32_e32 v13, vcc, 0, v69, vcc
	v_add_co_u32_e32 v44, vcc, s0, v78
	v_add_u32_e32 v94, 0x200, v97
	s_nop 0
	v_addc_co_u32_e32 v45, vcc, 0, v79, vcc
	v_add_co_u32_e32 v48, vcc, s39, v14
	v_add_u32_e32 v95, 0x300, v97
	s_nop 0
	v_addc_co_u32_e32 v49, vcc, 0, v15, vcc
	v_add_co_u32_e32 v56, vcc, s62, v68
	v_ashrrev_i32_e32 v108, 4, v94
	s_nop 0
	v_addc_co_u32_e32 v57, vcc, 0, v69, vcc
	v_add_co_u32_e32 v60, vcc, s62, v78
	s_mov_b32 s42, 0x5a000
	s_nop 0
	v_addc_co_u32_e32 v61, vcc, 0, v79, vcc
	v_ashrrev_i32_e32 v110, 4, v95
	v_ashrrev_i32_e32 v109, 31, v108
	v_add_co_u32_e32 v70, vcc, s42, v14
	v_ashrrev_i32_e32 v111, 31, v110
	global_load_dwordx4 v[40:43], v[12:13], off
	s_nop 0
	global_load_dwordx4 v[44:47], v[44:45], off
	v_lshl_add_u64 v[12:13], v[108:109], 0, s[4:5]
	v_addc_co_u32_e32 v71, vcc, 0, v15, vcc
	v_lshl_add_u64 v[14:15], v[110:111], 0, s[4:5]
	v_mad_u64_u32 v[50:51], s[2:3], v12, s69, v[10:11]
	v_mad_u64_u32 v[72:73], s[2:3], v14, s69, v[10:11]
	v_mad_i32_i24 v51, v13, s69, v51
	v_mad_i32_i24 v73, v15, s69, v73
	v_add_co_u32_e32 v68, vcc, s63, v68
	v_lshl_add_u64 v[50:51], v[50:51], 0, s[20:21]
	v_lshl_add_u64 v[72:73], v[72:73], 0, s[20:21]
	v_addc_co_u32_e32 v69, vcc, 0, v69, vcc
	v_lshl_add_u64 v[50:51], v[50:51], 0, v[4:5]
	v_lshl_add_u64 v[72:73], v[72:73], 0, v[4:5]
	v_add_co_u32_e32 v82, vcc, s63, v78
	v_lshl_add_u64 v[52:53], v[50:51], 0, v[8:9]
	v_lshl_add_u64 v[74:75], v[72:73], 0, v[8:9]
	v_addc_co_u32_e32 v83, vcc, 0, v79, vcc
	global_load_dwordx4 v[48:51], v[48:49], off offset:2560
	s_nop 0
	global_load_dwordx4 v[52:55], v[52:53], off offset:3072
	s_nop 0
	global_load_dwordx4 v[56:59], v[56:57], off
	s_nop 0
	global_load_dwordx4 v[60:63], v[60:61], off
	s_nop 0
	global_load_dwordx4 v[70:73], v[70:71], off offset:3072
	s_nop 0
	global_load_dwordx4 v[74:77], v[74:75], off offset:3072
	s_nop 0
	global_load_dwordx4 v[78:81], v[68:69], off
	s_nop 0
	global_load_dwordx4 v[82:85], v[82:83], off
	v_ashrrev_i32_e32 v68, 3, v97
	v_ashrrev_i32_e32 v69, 31, v68
	v_lshl_add_u64 v[112:113], v[68:69], 0, s[4:5]
	v_mad_u64_u32 v[86:87], s[2:3], v112, s69, v[10:11]
	v_mad_i32_i24 v87, v113, s69, v87
	v_lshl_add_u64 v[86:87], v[86:87], 0, s[20:21]
	v_lshl_add_u64 v[86:87], v[86:87], 0, v[8:9]
	s_movk_i32 s5, 0x1000
	v_add_co_u32_e32 v88, vcc, s5, v86
	s_mov_b32 s44, 0x3d000
	s_nop 0
	v_addc_co_u32_e32 v89, vcc, 0, v87, vcc
	v_add_co_u32_e32 v90, vcc, s44, v86
	v_mul_lo_u32 v67, v64, s36
	s_nop 0
	v_addc_co_u32_e32 v91, vcc, 0, v87, vcc
	global_load_dwordx4 v[86:89], v[88:89], off offset:512
	s_nop 0
	global_load_dwordx4 v[98:101], v[90:91], off offset:1536
	v_add3_u32 v91, s80, v104, v67
	s_waitcnt vmcnt(0) lgkmcnt(0)
; #define LDS_BARRIER() do { asm volatile("s_waitcnt lgkmcnt(0)" ::: "memory"); __builtin_amdgcn_s_barrier(); asm volatile("" ::: "memory"); } while (0)
; #define GDN_STORE_O(nn) do { const LAS bf16_t* ob_ = OTb + ((nn) & 1) * 4608; _Pragma("unroll") for (int k_ = 0; k_ < 2; ++k_) { const int vi_ = pt_ + 256 * k_, row_ = vi_ >> 3, c8_ = (vi_ & 7) * 8; \
;             *(u32x4*)(Y + (size_t)(b * T_ + 64 * (nn) + row_) * D_ + 256 + h * 128 + 64 * dvh + c8_) = *(const LAS u32x4*)(ob_ + row_ * 72 + c8_); } } while (0)
; __device__ __forceinline__ void gdn_scan(const Ctx& c, const Params& p, int e) {
;     ...
;         if (producer) {
;             int pt_ = ptid; asm volatile("" : "+v"(pt_));
;             u32x4 tq[4], tk[4], tw[4], tu[4], tqk[2];
;             const int prow = pt_ >> 4, pc8 = (pt_ & 15) * 8;
;             const int qrow = pt_ >> 3, qc8 = (pt_ & 7) * 8;
;             GDN_LOAD_TILES(0); GDN_STORE_TILES();
;             for (int n = 0; n < 128; ++n) {
;                 LDS_BARRIER();
;                 if (n + 1 < 128) GDN_LOAD_TILES(n + 1);
;                 if (n >= 1) GDN_STORE_O(n - 1);
;                 LDS_BARRIER();
;                 if (n + 1 < 128) GDN_STORE_TILES();
	ds_write_b128 v91, v[16:19]
	ds_write_b128 v91, v[24:27] offset:17408
	ds_write_b128 v91, v[28:31] offset:34816
	s_movk_i32 s2, 0x90
	v_lshrrev_b32_e32 v16, 3, v94
	v_add_u32_e32 v96, s80, v8
	v_mul_lo_u32 v16, v16, s2
	v_ashrrev_i32_e32 v1, 3, v1
	v_add_u32_e32 v94, v96, v16
	v_lshrrev_b32_e32 v16, 3, v95
	v_mul_lo_u32 v90, v68, s2
	v_mul_lo_u32 v67, v1, s2
	v_mul_lo_u32 v16, v16, s2
	s_or_b32 s2, s4, 64
	v_add_u32_e32 v95, v96, v16
	v_add_u32_e32 v16, s24, v8
	s_ashr_i32 s3, s2, 31
	v_add_u32_e32 v92, v96, v90
	v_add_u32_e32 v93, v96, v67
	v_add_u32_e32 v96, v16, v90
	v_lshl_add_u64 v[16:17], v[64:65], 0, s[2:3]
	v_mad_u64_u32 v[18:19], s[40:41], v16, s69, v[10:11]
	v_mad_u64_u32 v[24:25], s[40:41], v16, s35, v[102:103]
	v_mad_i32_i24 v19, v17, s69, v19
	v_mad_i32_i24 v25, v17, s35, v25
	v_lshl_add_u64 v[16:17], v[18:19], 0, s[20:21]
	v_lshl_add_u64 v[64:65], v[16:17], 0, v[104:105]
	ds_write_b128 v92, v[20:23] offset:52224
	ds_write_b128 v91, v[32:35] offset:4352
	ds_write_b128 v91, v[40:43] offset:21760
	ds_write_b128 v91, v[44:47] offset:39168
	v_lshlrev_b64 v[24:25], 1, v[24:25]
	v_add_co_u32_e32 v32, vcc, s47, v64
	ds_write_b128 v93, v[36:39] offset:52224
	ds_write_b128 v91, v[48:51] offset:8704
	ds_write_b128 v91, v[56:59] offset:26112
	ds_write_b128 v91, v[60:63] offset:43520
	ds_write_b128 v94, v[52:55] offset:52224
	ds_write_b128 v91, v[70:73] offset:13056
	ds_write_b128 v91, v[78:81] offset:30464
	ds_write_b128 v91, v[82:85] offset:47872
	v_lshl_add_u64 v[78:79], s[8:9], 0, v[24:25]
	v_addc_co_u32_e32 v33, vcc, 0, v65, vcc
	v_add_co_u32_e32 v40, vcc, s0, v78
	v_lshl_add_u64 v[80:81], s[6:7], 0, v[24:25]
	s_nop 0
	v_addc_co_u32_e32 v41, vcc, 0, v79, vcc
	v_add_co_u32_e32 v44, vcc, s0, v80
	v_lshl_add_u64 v[34:35], v[106:107], 0, s[2:3]
	s_nop 0
	v_addc_co_u32_e32 v45, vcc, 0, v81, vcc
	v_add_co_u32_e32 v48, vcc, s39, v64
	v_lshl_add_u64 v[50:51], v[108:109], 0, s[2:3]
	s_nop 0
	v_addc_co_u32_e32 v49, vcc, 0, v65, vcc
	v_add_co_u32_e32 v56, vcc, s62, v78
	v_lshl_add_u64 v[70:71], v[110:111], 0, s[2:3]
	v_mad_u64_u32 v[36:37], s[40:41], v34, s69, v[10:11]
	v_mad_u64_u32 v[52:53], s[40:41], v50, s69, v[10:11]
	v_addc_co_u32_e32 v57, vcc, 0, v79, vcc
	v_mad_u64_u32 v[72:73], s[40:41], v70, s69, v[10:11]
	ds_write_b128 v95, v[74:77] offset:52224
	ds_write_b128 v96, v[86:89]
	ds_write_b128 v96, v[98:101] offset:4608
	v_lshl_add_u64 v[16:17], v[16:17], 0, v[4:5]
	v_mad_i32_i24 v37, v35, s69, v37
	v_mad_i32_i24 v53, v51, s69, v53
	v_add_co_u32_e32 v60, vcc, s62, v80
	v_mad_i32_i24 v73, v71, s69, v73
	s_waitcnt lgkmcnt(0)
	s_barrier
	v_lshl_add_u64 v[20:21], v[16:17], 0, v[8:9]
	v_lshl_add_u64 v[34:35], v[36:37], 0, s[20:21]
	v_lshl_add_u64 v[50:51], v[52:53], 0, s[20:21]
	v_addc_co_u32_e32 v61, vcc, 0, v81, vcc
	v_lshl_add_u64 v[70:71], v[72:73], 0, s[20:21]
	global_load_dwordx4 v[16:19], v[64:65], off offset:1536
	s_nop 0
	global_load_dwordx4 v[20:23], v[20:21], off offset:3072
	v_lshl_add_u64 v[34:35], v[34:35], 0, v[4:5]
	v_lshl_add_u64 v[50:51], v[50:51], 0, v[4:5]
	v_add_co_u32_e32 v64, vcc, s42, v64
	v_lshl_add_u64 v[70:71], v[70:71], 0, v[4:5]
	v_lshl_add_u64 v[36:37], v[34:35], 0, v[8:9]
	v_lshl_add_u64 v[52:53], v[50:51], 0, v[8:9]
	v_addc_co_u32_e32 v65, vcc, 0, v65, vcc
	v_lshl_add_u64 v[74:75], v[70:71], 0, v[8:9]
	global_load_dwordx4 v[24:27], v[78:79], off
	global_load_dwordx4 v[28:31], v[80:81], off
	s_nop 0
	global_load_dwordx4 v[32:35], v[32:33], off offset:2048
	s_nop 0
	global_load_dwordx4 v[36:39], v[36:37], off offset:3072
	s_nop 0
	global_load_dwordx4 v[40:43], v[40:41], off
	s_nop 0
	global_load_dwordx4 v[44:47], v[44:45], off
	s_nop 0
	global_load_dwordx4 v[48:51], v[48:49], off offset:2560
	s_nop 0
	global_load_dwordx4 v[52:55], v[52:53], off offset:3072
	s_nop 0
	global_load_dwordx4 v[56:59], v[56:57], off
	s_nop 0
	global_load_dwordx4 v[60:63], v[60:61], off
	s_nop 0
	global_load_dwordx4 v[70:73], v[64:65], off offset:3072
	s_nop 0
	global_load_dwordx4 v[74:77], v[74:75], off offset:3072
	v_add_co_u32_e32 v64, vcc, s63, v78
	s_nop 1
	v_addc_co_u32_e32 v65, vcc, 0, v79, vcc
	v_add_co_u32_e32 v82, vcc, s63, v80
	s_nop 1
	v_addc_co_u32_e32 v83, vcc, 0, v81, vcc
	global_load_dwordx4 v[78:81], v[64:65], off
	s_nop 0
	global_load_dwordx4 v[82:85], v[82:83], off
	v_lshl_add_u64 v[64:65], v[68:69], 0, s[2:3]
	v_mad_u64_u32 v[10:11], s[2:3], v64, s69, v[10:11]
	v_mad_i32_i24 v11, v65, s69, v11
	v_lshl_add_u64 v[10:11], v[10:11], 0, s[20:21]
	v_lshl_add_u64 v[10:11], v[10:11], 0, v[8:9]
	v_add_co_u32_e32 v64, vcc, s5, v10
	s_add_u32 s3, s74, s20
	s_nop 0
	v_addc_co_u32_e32 v65, vcc, 0, v11, vcc
	v_add_co_u32_e32 v10, vcc, s44, v10
	s_addc_u32 s5, s75, s21
	s_nop 0
	v_addc_co_u32_e32 v11, vcc, 0, v11, vcc
	global_load_dwordx4 v[86:89], v[64:65], off offset:512
	global_load_dwordx4 v[98:101], v[10:11], off offset:1536
	s_lshl_b32 s35, s34, 1
	s_add_u32 s40, s3, s35
	s_addc_u32 s41, s5, 0
	v_add_u32_e32 v69, s25, v8
	s_waitcnt lgkmcnt(0)
	s_barrier
; #define LDS_BARRIER() do { asm volatile("s_waitcnt lgkmcnt(0)" ::: "memory"); __builtin_amdgcn_s_barrier(); asm volatile("" ::: "memory"); } while (0)
; #define GDN_STORE_O(nn) do { const LAS bf16_t* ob_ = OTb + ((nn) & 1) * 4608; _Pragma("unroll") for (int k_ = 0; k_ < 2; ++k_) { const int vi_ = pt_ + 256 * k_, row_ = vi_ >> 3, c8_ = (vi_ & 7) * 8; \
;             *(u32x4*)(Y + (size_t)(b * T_ + 64 * (nn) + row_) * D_ + 256 + h * 128 + 64 * dvh + c8_) = *(const LAS u32x4*)(ob_ + row_ * 72 + c8_); } } while (0)
; __device__ __forceinline__ void gdn_scan(const Ctx& c, const Params& p, int e) {
;     ...
;         if (producer) {
;             int pt_ = ptid; asm volatile("" : "+v"(pt_));
;             u32x4 tq[4], tk[4], tw[4], tu[4], tqk[2];
;             const int prow = pt_ >> 4, pc8 = (pt_ & 15) * 8;
;             const int qrow = pt_ >> 3, qc8 = (pt_ & 7) * 8;
;             GDN_LOAD_TILES(0); GDN_STORE_TILES();
;             for (int n = 0; n < 128; ++n) {
;                 LDS_BARRIER();
;                 if (n + 1 < 128) GDN_LOAD_TILES(n + 1);
;                 if (n >= 1) GDN_STORE_O(n - 1);
;                 LDS_BARRIER();
;                 if (n + 1 < 128) GDN_STORE_TILES();
	s_waitcnt vmcnt(0) lgkmcnt(0)
	ds_write_b128 v91, v[16:19]
	ds_write_b128 v91, v[24:27] offset:17408
	ds_write_b128 v91, v[28:31] offset:34816
	ds_write_b128 v92, v[20:23] offset:52224
	ds_write_b128 v91, v[32:35] offset:4352
	ds_write_b128 v91, v[40:43] offset:21760
	ds_write_b128 v91, v[44:47] offset:39168
	ds_write_b128 v93, v[36:39] offset:52224
	ds_write_b128 v91, v[48:51] offset:8704
	ds_write_b128 v91, v[56:59] offset:26112
	ds_write_b128 v91, v[60:63] offset:43520
	ds_write_b128 v94, v[52:55] offset:52224
	ds_write_b128 v91, v[70:73] offset:13056
	ds_write_b128 v91, v[78:81] offset:30464
	ds_write_b128 v91, v[82:85] offset:47872
	ds_write_b128 v95, v[74:77] offset:52224
	ds_write_b128 v96, v[86:89]
	ds_write_b128 v96, v[98:101] offset:4608
	v_lshl_add_u64 v[70:71], s[40:41], 0, v[8:9]
	v_and_b32_e32 v8, 7, v97
	v_lshlrev_b32_e32 v8, 4, v8
	v_mad_u64_u32 v[10:11], s[40:41], v112, s69, v[8:9]
	v_mad_i32_i24 v11, v113, s69, v11
	v_lshl_add_u64 v[76:77], s[22:23], 0, v[10:11]
	v_mad_u64_u32 v[10:11], s[40:41], v14, s69, v[4:5]
	v_mad_i32_i24 v11, v15, s69, v11
	v_lshl_add_u64 v[10:11], v[10:11], 0, v[8:9]
	v_lshl_add_u64 v[78:79], s[18:19], 0, v[10:11]
	v_mad_u64_u32 v[10:11], s[40:41], v12, s69, v[4:5]
	v_mad_i32_i24 v11, v13, s69, v11
	v_lshl_add_u64 v[10:11], v[10:11], 0, v[8:9]
	v_lshl_add_u64 v[80:81], s[18:19], 0, v[10:11]
	v_mad_u64_u32 v[10:11], s[40:41], v6, s69, v[4:5]
	v_mad_i32_i24 v11, v7, s69, v11
	v_mad_u64_u32 v[4:5], s[40:41], v2, s69, v[4:5]
	v_lshl_add_u64 v[6:7], v[10:11], 0, v[8:9]
	v_mad_i32_i24 v5, v3, s69, v5
	v_lshl_add_u64 v[82:83], s[18:19], 0, v[6:7]
	v_and_b32_e32 v6, 0xf0, v114
	v_mov_b32_e32 v7, v0
	v_lshl_add_u64 v[4:5], v[4:5], 0, v[8:9]
	v_mad_u64_u32 v[10:11], s[40:41], v2, s69, v[6:7]
	v_lshl_add_u64 v[86:87], s[18:19], 0, v[4:5]
	v_mad_u64_u32 v[4:5], s[40:41], v2, s50, 0
	v_mad_i32_i24 v11, v3, s69, v11
	v_mad_i32_i24 v3, v3, s50, v5
	v_or_b32_e32 v2, v4, v6
	s_mov_b32 s2, 0
	v_add_u32_e32 v72, s4, v1
	v_add_u32_e32 v74, s4, v68
	v_lshl_add_u64 v[84:85], s[22:23], 0, v[10:11]
	v_lshl_add_u64 v[88:89], s[22:23], 0, v[2:3]
; #define LDS_BARRIER() do { asm volatile("s_waitcnt lgkmcnt(0)" ::: "memory"); __builtin_amdgcn_s_barrier(); asm volatile("" ::: "memory"); } while (0)
; #define GDN_STORE_O(nn) do { const LAS bf16_t* ob_ = OTb + ((nn) & 1) * 4608; _Pragma("unroll") for (int k_ = 0; k_ < 2; ++k_) { const int vi_ = pt_ + 256 * k_, row_ = vi_ >> 3, c8_ = (vi_ & 7) * 8; \
;             *(u32x4*)(Y + (size_t)(b * T_ + 64 * (nn) + row_) * D_ + 256 + h * 128 + 64 * dvh + c8_) = *(const LAS u32x4*)(ob_ + row_ * 72 + c8_); } } while (0)
; __device__ __forceinline__ void gdn_scan(const Ctx& c, const Params& p, int e) {
;     ...
;         if (producer) {
;             int pt_ = ptid; asm volatile("" : "+v"(pt_));
;             u32x4 tq[4], tk[4], tw[4], tu[4], tqk[2];
;             const int prow = pt_ >> 4, pc8 = (pt_ & 15) * 8;
;             const int qrow = pt_ >> 3, qc8 = (pt_ & 7) * 8;
;             GDN_LOAD_TILES(0); GDN_STORE_TILES();
;             for (int n = 0; n < 128; ++n) {
;                 LDS_BARRIER();
;                 if (n + 1 < 128) GDN_LOAD_TILES(n + 1);
;                 if (n >= 1) GDN_STORE_O(n - 1);
;                 LDS_BARRIER();
;                 if (n + 1 < 128) GDN_STORE_TILES();
;             }
;             LDS_BARRIER();
;             GDN_STORE_O(127);
.LBB0_532:
	v_lshl_add_u64 v[50:51], v[84:85], 0, s[20:21]
	v_add_co_u32_e32 v2, vcc, 0x81f1000, v50
	v_lshl_add_u64 v[62:63], v[88:89], 0, s[20:21]
	s_nop 0
	v_addc_co_u32_e32 v3, vcc, 0, v51, vcc
	v_add_co_u32_e32 v10, vcc, 0x1a230000, v62
	s_waitcnt lgkmcnt(0)
	s_barrier
	s_nop 0
	v_addc_co_u32_e32 v11, vcc, 0, v63, vcc
	v_add_co_u32_e32 v14, vcc, 0x17230000, v62
	global_load_dwordx4 v[2:5], v[2:3], off offset:1536
	s_nop 0
	v_addc_co_u32_e32 v15, vcc, 0, v63, vcc
	v_add_co_u32_e32 v18, vcc, 0x820f000, v50
	global_load_dwordx4 v[10:13], v[10:11], off
	s_nop 0
	v_addc_co_u32_e32 v19, vcc, 0, v51, vcc
	v_add_co_u32_e32 v26, vcc, 0x1a236000, v62
	v_lshl_add_u64 v[6:7], v[86:87], 0, s[20:21]
	s_nop 0
	v_addc_co_u32_e32 v27, vcc, 0, v63, vcc
	v_add_co_u32_e32 v30, vcc, 0x17236000, v62
	global_load_dwordx4 v[14:17], v[14:15], off
	s_nop 0
	v_addc_co_u32_e32 v31, vcc, 0, v63, vcc
	v_add_co_u32_e32 v34, vcc, 0x822d000, v50
	global_load_dwordx4 v[6:9], v[6:7], off
	s_nop 0
	v_addc_co_u32_e32 v35, vcc, 0, v51, vcc
	v_add_co_u32_e32 v42, vcc, 0x1a23c000, v62
	global_load_dwordx4 v[18:21], v[18:19], off offset:2048
	s_nop 0
	v_addc_co_u32_e32 v43, vcc, 0, v63, vcc
	global_load_dwordx4 v[26:29], v[26:27], off
	v_add_co_u32_e32 v46, vcc, 0x1723c000, v62
	v_lshl_add_u64 v[22:23], v[82:83], 0, s[20:21]
	global_load_dwordx4 v[30:33], v[30:31], off
	v_addc_co_u32_e32 v47, vcc, 0, v63, vcc
	global_load_dwordx4 v[22:25], v[22:23], off
	v_add_co_u32_e32 v50, vcc, 0x824b000, v50
	global_load_dwordx4 v[34:37], v[34:35], off offset:2560
	s_nop 0
	v_addc_co_u32_e32 v51, vcc, 0, v51, vcc
	global_load_dwordx4 v[42:45], v[42:43], off
	v_add_co_u32_e32 v58, vcc, 0x1a242000, v62
	v_lshl_add_u64 v[38:39], v[80:81], 0, s[20:21]
	global_load_dwordx4 v[46:49], v[46:47], off
	v_addc_co_u32_e32 v59, vcc, 0, v63, vcc
	global_load_dwordx4 v[38:41], v[38:39], off
	v_add_co_u32_e32 v62, vcc, 0x17242000, v62
	global_load_dwordx4 v[50:53], v[50:51], off offset:3072
	s_nop 0
	v_addc_co_u32_e32 v63, vcc, 0, v63, vcc
	v_lshl_add_u64 v[102:103], v[76:77], 0, s[20:21]
	global_load_dwordx4 v[58:61], v[58:59], off
	v_add_co_u32_e32 v98, vcc, 0x81f2000, v102
	v_lshl_add_u64 v[54:55], v[78:79], 0, s[20:21]
	global_load_dwordx4 v[62:65], v[62:63], off
	v_addc_co_u32_e32 v99, vcc, 0, v103, vcc
	global_load_dwordx4 v[54:57], v[54:55], off
	v_add_co_u32_e32 v102, vcc, 0x822e000, v102
	global_load_dwordx4 v[98:101], v[98:99], off offset:512
	s_nop 0
	v_addc_co_u32_e32 v103, vcc, 0, v103, vcc
	global_load_dwordx4 v[102:105], v[102:103], off offset:1536
	s_bitcmp1_b32 s2, 0
	s_cselect_b32 s3, 0x2400, 0
	v_add_u32_e32 v73, s3, v69
	v_add_u32_e32 v75, v73, v90
	ds_read_b128 v[106:109], v75
	v_ashrrev_i32_e32 v75, 31, v74
	v_lshlrev_b64 v[110:111], 11, v[74:75]
	v_lshl_add_u64 v[110:111], v[70:71], 0, v[110:111]
	v_add_u32_e32 v73, v73, v67
	s_waitcnt lgkmcnt(0)
	global_store_dwordx4 v[110:111], v[106:109], off offset:512
	ds_read_b128 v[106:109], v73
	v_ashrrev_i32_e32 v73, 31, v72
	v_lshlrev_b64 v[110:111], 11, v[72:73]
	v_lshl_add_u64 v[110:111], v[70:71], 0, v[110:111]
	s_add_i32 s2, s2, 1
	s_waitcnt lgkmcnt(0)
	global_store_dwordx4 v[110:111], v[106:109], off offset:512
	s_waitcnt lgkmcnt(0)
	s_barrier
	s_mov_b64 s[40:41], 0x18000
	v_add_u32_e32 v72, 64, v72
	v_add_u32_e32 v74, 64, v74
	v_lshl_add_u64 v[76:77], v[76:77], 0, s[76:77]
	v_lshl_add_u64 v[78:79], v[78:79], 0, s[76:77]
	v_lshl_add_u64 v[80:81], v[80:81], 0, s[76:77]
	v_lshl_add_u64 v[82:83], v[82:83], 0, s[76:77]
	v_lshl_add_u64 v[84:85], v[84:85], 0, s[76:77]
	v_lshl_add_u64 v[86:87], v[86:87], 0, s[76:77]
	v_lshl_add_u64 v[88:89], v[88:89], 0, s[40:41]
	s_cmpk_eq_i32 s2, 0x7e
	s_waitcnt vmcnt(0)
	ds_write_b128 v91, v[2:5]
	ds_write_b128 v91, v[10:13] offset:17408
	ds_write_b128 v91, v[14:17] offset:34816
	ds_write_b128 v92, v[6:9] offset:52224
	ds_write_b128 v91, v[18:21] offset:4352
	ds_write_b128 v91, v[26:29] offset:21760
	ds_write_b128 v91, v[30:33] offset:39168
	ds_write_b128 v93, v[22:25] offset:52224
	ds_write_b128 v91, v[34:37] offset:8704
	ds_write_b128 v91, v[42:45] offset:26112
	ds_write_b128 v91, v[46:49] offset:43520
	ds_write_b128 v94, v[38:41] offset:52224
	ds_write_b128 v91, v[50:53] offset:13056
	ds_write_b128 v91, v[58:61] offset:30464
	ds_write_b128 v91, v[62:65] offset:47872
	ds_write_b128 v95, v[54:57] offset:52224
	ds_write_b128 v96, v[98:101]
	ds_write_b128 v96, v[102:105] offset:4608
	s_cbranch_scc0 .LBB0_532
	s_or_b32 s2, s4, 0x1f80
	v_add_u32_e32 v6, s2, v68
	s_waitcnt lgkmcnt(0)
	s_barrier
	v_add_u32_e32 v2, v69, v90
	v_ashrrev_i32_e32 v7, 31, v6
	ds_read_b128 v[2:5], v2
	v_lshlrev_b64 v[6:7], 11, v[6:7]
	v_lshl_add_u64 v[6:7], s[74:75], 0, v[6:7]
	v_lshl_add_u64 v[6:7], v[6:7], 0, s[20:21]
	s_lshl_b32 s42, s34, 1
	v_lshl_add_u64 v[6:7], v[6:7], 0, s[42:43]
	v_lshlrev_b32_e32 v8, 1, v66
	v_mov_b32_e32 v9, v0
	v_lshl_add_u64 v[6:7], v[6:7], 0, v[8:9]
	s_waitcnt lgkmcnt(0)
	global_store_dwordx4 v[6:7], v[2:5], off offset:512
	v_add_u32_e32 v6, s2, v1
	v_ashrrev_i32_e32 v7, 31, v6
	v_add_u32_e32 v2, v69, v67
	ds_read_b128 v[2:5], v2
	v_lshlrev_b64 v[6:7], 11, v[6:7]
	v_lshl_add_u64 v[6:7], s[74:75], 0, v[6:7]
	v_lshl_add_u64 v[6:7], v[6:7], 0, s[20:21]
	v_lshl_add_u64 v[6:7], v[6:7], 0, s[42:43]
	v_lshl_add_u64 v[6:7], v[6:7], 0, v[8:9]
	s_waitcnt lgkmcnt(0)
	global_store_dwordx4 v[6:7], v[2:5], off offset:512
	s_or_b32 s2, s4, 0x1fc0
	s_waitcnt lgkmcnt(0)
	s_barrier
	v_add_u32_e32 v10, s26, v8
	v_add_u32_e32 v6, s2, v68
	s_waitcnt lgkmcnt(0)
	s_barrier
	v_add_u32_e32 v2, v10, v90
	v_ashrrev_i32_e32 v7, 31, v6
	ds_read_b128 v[2:5], v2
	v_lshlrev_b64 v[6:7], 11, v[6:7]
	v_lshl_add_u64 v[6:7], s[74:75], 0, v[6:7]
	v_lshl_add_u64 v[6:7], v[6:7], 0, s[20:21]
	v_lshl_add_u64 v[6:7], v[6:7], 0, s[42:43]
	v_lshl_add_u64 v[6:7], v[6:7], 0, v[8:9]
	s_waitcnt lgkmcnt(0)
	global_store_dwordx4 v[6:7], v[2:5], off offset:512
	v_add_u32_e32 v6, s2, v1
	v_ashrrev_i32_e32 v7, 31, v6
	v_add_u32_e32 v2, v10, v67
	ds_read_b128 v[2:5], v2
	v_lshlrev_b64 v[6:7], 11, v[6:7]
	v_lshl_add_u64 v[6:7], s[74:75], 0, v[6:7]
	v_lshl_add_u64 v[6:7], v[6:7], 0, s[20:21]
	v_lshl_add_u64 v[6:7], v[6:7], 0, s[42:43]
	v_lshl_add_u64 v[6:7], v[6:7], 0, v[8:9]
	v_readlane_b32 s41, v255, 14
	s_waitcnt lgkmcnt(0)
	global_store_dwordx4 v[6:7], v[2:5], off offset:512
	s_branch .LBB0_521

; __device__ __forceinline__ u32x4 pack8(const float* f) { u32x4 o; o.x = pk2(f[0], f[1]); o.y = pk2(f[2], f[3]); o.z = pk2(f[4], f[5]); o.w = pk2(f[6], f[7]); return o; }
; __device__ __forceinline__ void even_prep(const Ctx& c, const Params& p, int e) {
;     ...
;     { const long NT = (long)c.G * 512;
;       for (long it = (long)c.bid * 512 + c.tid; it < (long)M_ * 32; it += NT) { const int m = (int)(it >> 5), c8 = (int)(it & 31) * 8, t = m & (T_ - 1);
;           const bf16_t* zr = Z + (size_t)m * ZLD_E; float ab[8], acc[8];
;           unpack8(*(const u32x4*)(zr + c8), ab);
; #pragma unroll
;           for (int i = 0; i < 8; ++i) acc[i] = 0.f;
; #pragma unroll
;           for (int j = 0; j < 3; ++j) { const int dt = j - 2; if (t + dt >= 0) { const bf16_t* zc = zr + (long)dt * ZLD_E; float ac[8], ah[8];
;               unpack8(*(const u32x4*)(zc + 256 + c8), ac); unpack8(*(const u32x4*)(zc + 512 + c8), ah);
; #pragma unroll
;               for (int i = 0; i < 8; ++i) acc[i] += conv_a[j * 256 + c8 + i] * (ac[i] * ah[i]); } }
; #pragma unroll
;           for (int i = 0; i < 8; ++i) acc[i] *= ab[i];
;           *(u32x4*)(Y + (size_t)m * D_ + c8) = pack8(acc); } }
.LBB0_539:
	s_or_b64 exec, exec, s[14:15]
	s_waitcnt vmcnt(0) lgkmcnt(0)
	v_lshlrev_b32_e32 v34, 16, v10
	v_and_b32_e32 v35, 0xffff0000, v10
	v_lshlrev_b32_e32 v36, 16, v11
	v_and_b32_e32 v37, 0xffff0000, v11
	v_lshlrev_b32_e32 v38, 16, v12
	v_and_b32_e32 v39, 0xffff0000, v12
	v_lshlrev_b32_e32 v40, 16, v13
	v_and_b32_e32 v41, 0xffff0000, v13
	global_load_dwordx4 v[10:13], v[20:21], off offset:512
	s_nop 0
	global_load_dwordx4 v[20:23], v[20:21], off offset:1024
	s_nop 0
	global_load_dwordx4 v[26:29], v24, s[4:5] offset:2064
	global_load_dwordx4 v[30:33], v24, s[4:5] offset:2048
	v_mov_b32_e32 v1, v25
	v_lshl_add_u64 v[14:15], v[14:15], 0, s[8:9]
	s_mov_b64 s[14:15], 0xfffff
	v_mov_b32_e32 v19, v0
	v_cmp_lt_i64_e32 vcc, s[14:15], v[14:15]
	v_lshl_add_u64 v[16:17], v[16:17], 0, s[10:11]
	s_or_b64 s[12:13], vcc, s[12:13]
	s_waitcnt vmcnt(0) lgkmcnt(0)
	v_lshlrev_b32_e32 v24, 16, v10
	v_and_b32_e32 v25, 0xffff0000, v10
	v_lshlrev_b32_e32 v42, 16, v20
	v_and_b32_e32 v43, 0xffff0000, v20
	v_lshlrev_b32_e32 v10, 16, v11
	v_and_b32_e32 v11, 0xffff0000, v11
	v_lshlrev_b32_e32 v20, 16, v21
	v_and_b32_e32 v21, 0xffff0000, v21
	v_pk_mul_f32 v[10:11], v[10:11], v[20:21]
	v_lshlrev_b32_e32 v20, 16, v22
	v_pk_fma_f32 v[4:5], v[32:33], v[10:11], v[4:5]
	v_lshlrev_b32_e32 v10, 16, v12
	v_and_b32_e32 v11, 0xffff0000, v12
	v_and_b32_e32 v21, 0xffff0000, v22
	v_pk_mul_f32 v[24:25], v[24:25], v[42:43]
	v_pk_mul_f32 v[10:11], v[10:11], v[20:21]
	v_pk_fma_f32 v[2:3], v[30:31], v[24:25], v[2:3]
	v_pk_fma_f32 v[6:7], v[26:27], v[10:11], v[6:7]
	v_lshlrev_b32_e32 v10, 16, v13
	v_and_b32_e32 v11, 0xffff0000, v13
	v_lshlrev_b32_e32 v12, 16, v23
	v_and_b32_e32 v13, 0xffff0000, v23
	v_pk_mul_f32 v[2:3], v[2:3], v[34:35]
	v_pk_mul_f32 v[4:5], v[4:5], v[36:37]
	v_pk_mul_f32 v[6:7], v[6:7], v[38:39]
	v_pk_mul_f32 v[10:11], v[10:11], v[12:13]
	v_cvt_pk_bf16_f32 v2, v2, v3
	v_pk_fma_f32 v[8:9], v[10:11], v[28:29], v[8:9]
	v_cvt_pk_bf16_f32 v3, v4, v5
	v_cvt_pk_bf16_f32 v4, v6, v7
	v_ashrrev_i64 v[6:7], 21, v[0:1]
	v_pk_mul_f32 v[8:9], v[8:9], v[40:41]
	v_lshl_add_u64 v[6:7], s[74:75], 0, v[6:7]
	v_cvt_pk_bf16_f32 v5, v8, v9
	v_lshl_add_u64 v[6:7], v[6:7], 0, v[18:19]
	global_store_dwordx4 v[6:7], v[2:5], off
	s_andn2_b64 exec, exec, s[12:13]
	s_cbranch_execz .LBB0_544
.LBB0_540:
	v_and_b32_e32 v8, 0xf8, v16
	v_alignbit_b32 v25, v15, v14, 5
	v_mov_b64_e32 v[2:3], s[16:17]
	v_mad_i64_i32 v[22:23], s[14:15], v25, s69, v[2:3]
	v_lshlrev_b32_e32 v18, 1, v8
	v_mov_b32_e32 v19, v0
	v_lshl_add_u64 v[20:21], v[22:23], 0, v[18:19]
	global_load_dwordx4 v[10:13], v[20:21], off
	v_mov_b32_e32 v2, v0
	v_mov_b32_e32 v3, v0
	v_mov_b32_e32 v4, v0
	v_mov_b32_e32 v5, v0
	v_mov_b32_e32 v6, v0
	v_mov_b32_e32 v7, v0
	v_and_b32_e32 v19, 0x1fff, v25
	v_mov_b32_e32 v1, v0
	v_lshlrev_b32_e32 v24, 2, v8
	v_mov_b64_e32 v[8:9], v[6:7]
	v_cmp_lt_u32_e32 vcc, 1, v19
	v_mov_b64_e32 v[6:7], v[4:5]
	v_mov_b64_e32 v[4:5], v[2:3]
	v_mov_b64_e32 v[2:3], v[0:1]
	s_and_saveexec_b64 s[14:15], vcc
	s_cbranch_execz .LBB0_542
	v_add_co_u32_e32 v2, vcc, 0xffffc5c0, v20
	s_nop 1
	v_addc_co_u32_e32 v3, vcc, -1, v21, vcc
	v_add_co_u32_e32 v6, vcc, 0xffffc7c0, v20
	global_load_dwordx4 v[2:5], v[2:3], off
	s_nop 0
	v_addc_co_u32_e32 v7, vcc, -1, v21, vcc
	global_load_dwordx4 v[6:9], v[6:7], off
	s_nop 0
	global_load_dwordx4 v[26:29], v24, s[4:5] offset:16
	global_load_dwordx4 v[30:33], v24, s[4:5]
	s_waitcnt vmcnt(0) lgkmcnt(0)
	v_lshlrev_b32_e32 v38, 16, v2
	v_and_b32_e32 v39, 0xffff0000, v2
	v_lshlrev_b32_e32 v2, 16, v3
	v_lshlrev_b32_e32 v40, 16, v6
	v_and_b32_e32 v41, 0xffff0000, v6
	v_and_b32_e32 v3, 0xffff0000, v3
	v_lshlrev_b32_e32 v6, 16, v7
	v_and_b32_e32 v7, 0xffff0000, v7
	v_lshlrev_b32_e32 v34, 16, v5
	v_lshlrev_b32_e32 v36, 16, v9
	v_pk_mul_f32 v[38:39], v[38:39], v[40:41]
	v_pk_mul_f32 v[2:3], v[2:3], v[6:7]
	v_lshlrev_b32_e32 v6, 16, v4
	v_and_b32_e32 v7, 0xffff0000, v4
	v_lshlrev_b32_e32 v40, 16, v8
	v_and_b32_e32 v41, 0xffff0000, v8
	v_and_b32_e32 v37, 0xffff0000, v9
	v_and_b32_e32 v35, 0xffff0000, v5
	v_pk_mul_f32 v[6:7], v[6:7], v[40:41]
	v_pk_mul_f32 v[4:5], v[34:35], v[36:37]
	v_pk_fma_f32 v[6:7], v[6:7], v[26:27], 0 op_sel_hi:[1,1,0]
	v_pk_fma_f32 v[8:9], v[4:5], v[28:29], 0 op_sel_hi:[1,1,0]
	v_pk_fma_f32 v[4:5], v[32:33], v[2:3], 0 op_sel_hi:[1,1,0]
	v_pk_fma_f32 v[2:3], v[30:31], v[38:39], 0 op_sel_hi:[1,1,0]
.LBB0_542:
	s_or_b64 exec, exec, s[14:15]
	v_cmp_ne_u32_e32 vcc, 0, v19
	s_and_saveexec_b64 s[14:15], vcc
	s_cbranch_execz .LBB0_539
	v_mov_b32_e32 v19, v0
	v_lshl_add_u64 v[22:23], v[22:23], 0, v[18:19]
	v_add_co_u32_e32 v26, vcc, 0xffffe3e0, v22
	s_nop 1
	v_addc_co_u32_e32 v27, vcc, -1, v23, vcc
	global_load_dwordx4 v[26:29], v[26:27], off
	v_add_co_u32_e32 v22, vcc, 0xffffe5e0, v22
	s_waitcnt vmcnt(0) lgkmcnt(0)
	v_lshlrev_b32_e32 v42, 16, v26
	v_addc_co_u32_e32 v23, vcc, -1, v23, vcc
	global_load_dwordx4 v[30:33], v[22:23], off
	global_load_dwordx4 v[34:37], v24, s[4:5] offset:1040
	global_load_dwordx4 v[38:41], v24, s[4:5] offset:1024
	v_lshlrev_b32_e32 v22, 16, v29
	v_and_b32_e32 v43, 0xffff0000, v26
	v_lshlrev_b32_e32 v26, 16, v27
	v_and_b32_e32 v27, 0xffff0000, v27
	v_lshlrev_b32_e32 v44, 16, v28
	v_and_b32_e32 v45, 0xffff0000, v28
	v_and_b32_e32 v23, 0xffff0000, v29
	s_waitcnt vmcnt(0) lgkmcnt(0)
	v_lshlrev_b32_e32 v28, 16, v33
	v_lshlrev_b32_e32 v46, 16, v30
	v_and_b32_e32 v47, 0xffff0000, v30
	v_lshlrev_b32_e32 v30, 16, v31
	v_and_b32_e32 v31, 0xffff0000, v31
	v_lshlrev_b32_e32 v48, 16, v32
	v_and_b32_e32 v49, 0xffff0000, v32
	v_and_b32_e32 v29, 0xffff0000, v33
	v_pk_mul_f32 v[32:33], v[42:43], v[46:47]
	v_pk_mul_f32 v[26:27], v[26:27], v[30:31]
	v_pk_mul_f32 v[30:31], v[44:45], v[48:49]
	v_pk_mul_f32 v[22:23], v[22:23], v[28:29]
	v_pk_fma_f32 v[4:5], v[40:41], v[26:27], v[4:5]
	v_pk_fma_f32 v[8:9], v[22:23], v[36:37], v[8:9]
	v_pk_fma_f32 v[6:7], v[30:31], v[34:35], v[6:7]
	v_pk_fma_f32 v[2:3], v[38:39], v[32:33], v[2:3]
	s_branch .LBB0_539

; __device__ __forceinline__ void even_prep(const Ctx& c, const Params& p, int e) {
;     ...
;     for (int item = c.bid; item < 3072; item += c.G) {
;         int tid_i = c.tid; asm volatile("" : "+v"(tid_i)); const int lane_i = tid_i & 63;
;         const int n = item & 127, bh = item >> 7, h = bh % 6, b = bh / 6; const int m0 = b * T_ + 64 * n;
;         if (tid_i < 128) sgc[tid_i] = GCB[(size_t)item * 128 + tid_i];
;         __syncthreads();
.LBB0_546:
	v_mov_b32_e32 v18, v166
	s_movk_i32 s2, 0x80
	s_nop 0
	v_cmp_gt_i32_e64 s[4:5], s2, v18
	s_movk_i32 s2, 0x7f
	v_cmp_lt_i32_e32 vcc, s2, v18
	s_and_saveexec_b64 s[2:3], vcc
	s_xor_b64 s[2:3], exec, s[2:3]
	s_ashr_i32 s27, s26, 31
	s_or_saveexec_b64 s[2:3], s[2:3]
	v_mov_b64_e32 v[2:3], s[26:27]
	s_xor_b64 exec, exec, s[2:3]
	s_cbranch_execz .LBB0_550
	s_ashr_i32 s27, s26, 31
	s_lshl_b64 s[6:7], s[26:27], 9
	s_add_u32 s6, s36, s6
	v_readlane_b32 s0, v255, 45
	s_addc_u32 s7, s0, s7
	v_ashrrev_i32_e32 v19, 31, v18
	v_lshl_add_u64 v[2:3], v[18:19], 2, s[6:7]
	global_load_dword v2, v[2:3], off
	v_lshl_add_u32 v1, v18, 2, s49
	s_waitcnt vmcnt(0) lgkmcnt(0)
	ds_write_b32 v1, v2
	v_mov_b64_e32 v[2:3], s[26:27]

; __device__ __forceinline__ void conv4h(const bf16_t* zc, int row, const bf16_t* hp, bool has_prev, const float* cw, float* y) {
; #pragma unroll
;     for (int i = 0; i < 8; ++i) y[i] = 0.f;
; #pragma unroll
;     for (int j = 0; j < 4; ++j) { const int rr = row - 3 + j;
;         if (rr >= 0 || has_prev) { const bf16_t* src = (rr >= 0) ? zc + (size_t)rr * ZLD_E : hp + (3 + rr) * 384; float xv[8]; unpack8(*(const u32x4*)src, xv);
;             const f32x4 w0 = *(const f32x4*)(cw + j * 2304), w1 = *(const f32x4*)(cw + j * 2304 + 4);
;             y[0] += w0.x * xv[0]; y[1] += w0.y * xv[1]; y[2] += w0.z * xv[2]; y[3] += w0.w * xv[3];
;             y[4] += w1.x * xv[4]; y[5] += w1.y * xv[5]; y[6] += w1.z * xv[6]; y[7] += w1.w * xv[7]; } }
; __device__ __forceinline__ void even_prep(const Ctx& c, const Params& p, int e) {
;     ...
;         for (int rep = 0; rep < 2; ++rep) { const int vi = tid_i + 512 * rep, row = vi >> 4, c8 = (vi & 15) * 8;
;             const bf16_t* zc = Z + (size_t)m0 * ZLD_E + 768 + h * 128 + c8; const bf16_t* hp = HALO + (size_t)(bh * 128 + n) * 1152 + c8; float y[8], yd[8];
;             conv4h(zc, row, hp, n > 0, conv_qkv + h * 128 + c8, y);
.LBB0_551:
	v_add_u32_e32 v1, s6, v18
	v_ashrrev_i32_e32 v72, 4, v1
	v_cmp_lt_i32_e32 vcc, 2, v72
	v_mov_b32_e32 v1, v0
	v_add_u32_e32 v64, -3, v72
	v_cmp_gt_i32_e64 s[10:11], 3, v72
	s_or_b64 s[86:87], s[82:83], vcc
	v_mov_b64_e32 v[6:7], v[0:1]
	v_mov_b64_e32 v[8:9], v[0:1]
	v_mov_b64_e32 v[42:43], v[0:1]
	v_mov_b64_e32 v[44:45], v[0:1]
	s_and_saveexec_b64 s[6:7], s[86:87]
	s_cbranch_execz .LBB0_557
	s_and_saveexec_b64 s[8:9], s[10:11]
	s_xor_b64 s[8:9], exec, s[8:9]
	v_mul_lo_u32 v6, v72, s64
	v_ashrrev_i32_e32 v7, 31, v6
	v_lshl_add_u64 v[6:7], v[6:7], 1, v[14:15]
	s_andn2_saveexec_b64 s[8:9], s[8:9]
	v_mad_u64_u32 v[6:7], s[12:13], v64, s69, v[10:11]
	v_lshl_add_u64 v[6:7], v[6:7], 0, s[78:79]
	s_or_b64 exec, exec, s[8:9]
	global_load_dwordx4 v[42:45], v[6:7], off
	global_load_dwordx4 v[46:49], v[16:17], off offset:16
	s_nop 0
	global_load_dwordx4 v[6:9], v[16:17], off
	s_waitcnt vmcnt(0) lgkmcnt(0)
	v_and_b32_e32 v51, 0xffff0000, v42
	v_lshlrev_b32_e32 v50, 16, v42
	v_pk_fma_f32 v[6:7], v[6:7], v[50:51], 0 op_sel_hi:[1,1,0]
	v_and_b32_e32 v51, 0xffff0000, v43
	v_lshlrev_b32_e32 v50, 16, v43
	v_and_b32_e32 v43, 0xffff0000, v44
	v_lshlrev_b32_e32 v42, 16, v44
	v_pk_fma_f32 v[42:43], v[46:47], v[42:43], 0 op_sel_hi:[1,1,0]
	v_and_b32_e32 v47, 0xffff0000, v45
	v_lshlrev_b32_e32 v46, 16, v45
	v_pk_fma_f32 v[8:9], v[8:9], v[50:51], 0 op_sel_hi:[1,1,0]
	v_pk_fma_f32 v[44:45], v[48:49], v[46:47], 0 op_sel_hi:[1,1,0]
.LBB0_557:
	s_or_b64 exec, exec, s[6:7]
	v_cmp_lt_i32_e32 vcc, 1, v72
	s_xor_b64 s[84:85], s[2:3], -1
	v_add_u32_e32 v74, -2, v72
	v_cmp_gt_i32_e64 s[8:9], 2, v72
	s_or_b64 s[2:3], s[82:83], vcc
	s_and_saveexec_b64 s[6:7], s[2:3]
	s_cbranch_execz .LBB0_563
	s_and_saveexec_b64 s[12:13], s[8:9]
	s_xor_b64 s[12:13], exec, s[12:13]
	v_mul_lo_u32 v46, v72, s64
	v_ashrrev_i32_e32 v47, 31, v46
	v_lshl_add_u64 v[46:47], v[46:47], 1, v[14:15]
	s_mov_b64 s[14:15], 0x300
	v_lshl_add_u64 v[46:47], v[46:47], 0, s[14:15]
	s_andn2_saveexec_b64 s[12:13], s[12:13]
	v_mad_u64_u32 v[46:47], s[14:15], v74, s69, v[10:11]
	v_lshl_add_u64 v[46:47], v[46:47], 0, s[78:79]
	s_or_b64 exec, exec, s[12:13]
	global_load_dwordx4 v[46:49], v[46:47], off
	s_nop 0
	global_load_dwordx4 v[50:53], v[24:25], off offset:16
	global_load_dwordx4 v[54:57], v[24:25], off
	s_waitcnt vmcnt(0) lgkmcnt(0)
	v_and_b32_e32 v59, 0xffff0000, v46
	v_lshlrev_b32_e32 v58, 16, v46
	v_pk_fma_f32 v[6:7], v[54:55], v[58:59], v[6:7]
	v_and_b32_e32 v55, 0xffff0000, v47
	v_lshlrev_b32_e32 v54, 16, v47
	v_and_b32_e32 v47, 0xffff0000, v48
	v_lshlrev_b32_e32 v46, 16, v48
	v_pk_fma_f32 v[42:43], v[50:51], v[46:47], v[42:43]
	v_and_b32_e32 v47, 0xffff0000, v49
	v_lshlrev_b32_e32 v46, 16, v49
	v_pk_fma_f32 v[8:9], v[56:57], v[54:55], v[8:9]
	v_pk_fma_f32 v[44:45], v[52:53], v[46:47], v[44:45]
.LBB0_563:
	s_or_b64 exec, exec, s[6:7]
	v_cmp_lt_i32_e32 vcc, 0, v72
	v_add_u32_e32 v73, -1, v72
	v_cmp_gt_i32_e64 s[6:7], 1, v72
	s_or_b64 s[14:15], s[82:83], vcc
	s_and_saveexec_b64 s[12:13], s[14:15]
	s_cbranch_execz .LBB0_569
	s_and_saveexec_b64 s[34:35], s[6:7]
	s_xor_b64 s[34:35], exec, s[34:35]
	v_mul_lo_u32 v46, v72, s64
	v_ashrrev_i32_e32 v47, 31, v46
	v_lshl_add_u64 v[46:47], v[46:47], 1, v[14:15]
	v_lshl_add_u64 v[46:47], v[46:47], 0, s[78:79]
	s_andn2_saveexec_b64 s[34:35], s[34:35]
	v_mad_u64_u32 v[46:47], s[44:45], v73, s69, v[10:11]
	v_lshl_add_u64 v[46:47], v[46:47], 0, s[78:79]
	s_or_b64 exec, exec, s[34:35]
	global_load_dwordx4 v[46:49], v[46:47], off
	s_nop 0
	global_load_dwordx4 v[50:53], v[26:27], off offset:16
	global_load_dwordx4 v[54:57], v[26:27], off
	s_waitcnt vmcnt(0) lgkmcnt(0)
	v_and_b32_e32 v59, 0xffff0000, v46
	v_lshlrev_b32_e32 v58, 16, v46
	v_pk_fma_f32 v[6:7], v[54:55], v[58:59], v[6:7]
	v_and_b32_e32 v55, 0xffff0000, v47
	v_lshlrev_b32_e32 v54, 16, v47
	v_and_b32_e32 v47, 0xffff0000, v48
	v_lshlrev_b32_e32 v46, 16, v48
	v_pk_fma_f32 v[42:43], v[50:51], v[46:47], v[42:43]
	v_and_b32_e32 v47, 0xffff0000, v49
	v_lshlrev_b32_e32 v46, 16, v49
	v_pk_fma_f32 v[8:9], v[56:57], v[54:55], v[8:9]
	v_pk_fma_f32 v[44:45], v[52:53], v[46:47], v[44:45]
.LBB0_569:
	s_or_b64 exec, exec, s[12:13]
	v_cmp_lt_i32_e64 s[12:13], -1, v72
	v_cmp_gt_i32_e32 vcc, 0, v72
	s_or_b64 s[44:45], s[82:83], s[12:13]
	s_and_saveexec_b64 s[12:13], s[44:45]
	s_cbranch_execz .LBB0_575
	s_and_saveexec_b64 s[34:35], vcc
	s_xor_b64 s[34:35], exec, s[34:35]
	v_mul_lo_u32 v46, v72, s64
	v_ashrrev_i32_e32 v47, 31, v46
	v_lshl_add_u64 v[46:47], v[46:47], 1, v[14:15]
	s_mov_b64 s[62:63], 0x900
	v_lshl_add_u64 v[46:47], v[46:47], 0, s[62:63]
	s_andn2_saveexec_b64 s[34:35], s[34:35]
	v_mad_u64_u32 v[46:47], s[62:63], v72, s69, v[10:11]
	v_lshl_add_u64 v[46:47], v[46:47], 0, s[78:79]
	s_or_b64 exec, exec, s[34:35]
	global_load_dwordx4 v[46:49], v[46:47], off
	s_nop 0
	global_load_dwordx4 v[50:53], v[28:29], off offset:16
	global_load_dwordx4 v[54:57], v[28:29], off
	s_waitcnt vmcnt(0) lgkmcnt(0)
	v_and_b32_e32 v59, 0xffff0000, v46
	v_lshlrev_b32_e32 v58, 16, v46
	v_pk_fma_f32 v[6:7], v[54:55], v[58:59], v[6:7]
	v_and_b32_e32 v55, 0xffff0000, v47
	v_lshlrev_b32_e32 v54, 16, v47
	v_and_b32_e32 v47, 0xffff0000, v48
	v_lshlrev_b32_e32 v46, 16, v48
	v_pk_fma_f32 v[42:43], v[50:51], v[46:47], v[42:43]
	v_and_b32_e32 v47, 0xffff0000, v49
	v_lshlrev_b32_e32 v46, 16, v49
	v_pk_fma_f32 v[8:9], v[56:57], v[54:55], v[8:9]
	v_pk_fma_f32 v[44:45], v[52:53], v[46:47], v[44:45]
; #define LAS __attribute__((address_space(3)))
; __device__ __forceinline__ u32x4 pack8(const float* f) { u32x4 o; o.x = pk2(f[0], f[1]); o.y = pk2(f[2], f[3]); o.z = pk2(f[4], f[5]); o.w = pk2(f[6], f[7]); return o; }
; __device__ __forceinline__ float sum16_dpp(float v) { v += dppf<0xB1>(v); v += dppf<0x4E>(v); v += dppf<0x141>(v); v += dppf<0x140>(v); return v; }
; __device__ __forceinline__ void conv4h(const bf16_t* zc, int row, const bf16_t* hp, bool has_prev, const float* cw, float* y) {
; #pragma unroll
;     for (int i = 0; i < 8; ++i) y[i] = 0.f;
; #pragma unroll
;     for (int j = 0; j < 4; ++j) { const int rr = row - 3 + j;
;         if (rr >= 0 || has_prev) { const bf16_t* src = (rr >= 0) ? zc + (size_t)rr * ZLD_E : hp + (3 + rr) * 384; float xv[8]; unpack8(*(const u32x4*)src, xv);
;             const f32x4 w0 = *(const f32x4*)(cw + j * 2304), w1 = *(const f32x4*)(cw + j * 2304 + 4);
;             y[0] += w0.x * xv[0]; y[1] += w0.y * xv[1]; y[2] += w0.z * xv[2]; y[3] += w0.w * xv[3];
;             y[4] += w1.x * xv[4]; y[5] += w1.y * xv[5]; y[6] += w1.z * xv[6]; y[7] += w1.w * xv[7]; } }
; __device__ __forceinline__ void even_prep(const Ctx& c, const Params& p, int e) {
;     ...
;             float ss = 0.f;
; #pragma unroll
;             for (int i = 0; i < 8; ++i) ss += y[i] * y[i];
;             ss = sum16_dpp(ss); float rn = rsqrtf(ss + 1e-6f) * 0.08838834764831845f;
;             const float eg = __expf(sgc[row]);
; #pragma unroll
;             for (int i = 0; i < 8; ++i) { y[i] *= rn; yd[i] = y[i] * eg; }
;             *(LAS u32x4*)(QS + row * 136 + c8) = pack8(y); { const u32x4 t_ = pack8(yd); if (rep == 0) qdp0 = t_; else qdp1 = t_; }
;             conv4h(zc + 768, row, hp + 128, n > 0, conv_qkv + 768 + h * 128 + c8, y);
.LBB0_575:
	s_or_b64 exec, exec, s[12:13]
	v_mul_f32_e32 v1, 0xbfb8aa3b, v6
	v_exp_f32_e32 v1, v1
	v_mul_f32_e32 v46, 0xbfb8aa3b, v7
	v_exp_f32_e32 v46, v46
	v_mul_f32_e32 v48, 0xbfb8aa3b, v9
	v_add_f32_e32 v1, 1.0, v1
	v_exp_f32_e32 v49, v48
	v_add_f32_e32 v47, 1.0, v46
	v_rcp_f32_e32 v46, v1
	v_mul_f32_e32 v1, 0xbfb8aa3b, v8
	v_exp_f32_e32 v1, v1
	v_mul_f32_e32 v48, 0xbfb8aa3b, v42
	v_exp_f32_e32 v50, v48
	v_mul_f32_e32 v51, 0xbfb8aa3b, v44
	v_add_f32_e32 v1, 1.0, v1
	v_rcp_f32_e32 v48, v1
	v_add_f32_e32 v1, 1.0, v49
	v_add_f32_e32 v49, 1.0, v50
	v_rcp_f32_e32 v50, v49
	v_mul_f32_e32 v49, 0xbfb8aa3b, v43
	v_exp_f32_e32 v51, v51
	v_mul_f32_e32 v52, 0xbfb8aa3b, v45
	v_exp_f32_e32 v53, v52
	v_exp_f32_e32 v49, v49
	v_add_f32_e32 v51, 1.0, v51
	v_rcp_f32_e32 v47, v47
	v_rcp_f32_e32 v52, v51
	v_add_f32_e32 v51, 1.0, v53
	v_add_f32_e32 v49, 1.0, v49
	v_rcp_f32_e32 v53, v51
	v_rcp_f32_e32 v51, v49
	v_rcp_f32_e32 v49, v1
	v_pk_mul_f32 v[6:7], v[6:7], v[46:47]
	v_pk_mul_f32 v[44:45], v[44:45], v[52:53]
	v_pk_mul_f32 v[46:47], v[6:7], v[6:7]
	v_pk_mul_f32 v[8:9], v[8:9], v[48:49]
	v_add_f32_e32 v1, v47, v46
	v_pk_mul_f32 v[48:49], v[8:9], v[8:9]
	v_pk_mul_f32 v[42:43], v[42:43], v[50:51]
	v_add_f32_e32 v1, v48, v1
	v_pk_mul_f32 v[50:51], v[42:43], v[42:43]
	v_add_f32_e32 v1, v49, v1
	v_add_f32_e32 v1, v50, v1
	v_pk_mul_f32 v[52:53], v[44:45], v[44:45]
	v_add_f32_e32 v1, v51, v1
	v_add_f32_e32 v1, v52, v1
	v_add_f32_e32 v1, v53, v1
	v_lshl_add_u32 v57, v72, 2, s49
	ds_read_b32 v58, v57
	v_add_f32_dpp v1, v1, v1 quad_perm:[1,0,3,2] row_mask:0xf bank_mask:0xf bound_ctrl:1
	s_nop 1
	v_add_f32_dpp v1, v1, v1 quad_perm:[2,3,0,1] row_mask:0xf bank_mask:0xf bound_ctrl:1
	s_nop 1
	v_add_f32_dpp v1, v1, v1 row_half_mirror row_mask:0xf bank_mask:0xf bound_ctrl:1
	s_nop 1
	v_add_f32_dpp v1, v1, v1 row_mirror row_mask:0xf bank_mask:0xf bound_ctrl:1
	v_add_f32_e32 v1, 0x358637bd, v1
	v_mul_f32_e32 v46, 0x4b800000, v1
	v_cmp_gt_f32_e64 s[12:13], s33, v1
	s_nop 1
	v_cndmask_b32_e64 v1, v1, v46, s[12:13]
	v_rsq_f32_e32 v1, v1
	s_nop 0
	v_mul_f32_e32 v46, 0x45800000, v1
	v_cndmask_b32_e64 v1, v1, v46, s[12:13]
	v_mul_f32_e32 v46, 0x3db504f3, v1
	s_movk_i32 s12, 0x88
	v_pk_mul_f32 v[6:7], v[6:7], v[46:47] op_sel_hi:[1,0]
	v_pk_mul_f32 v[8:9], v[8:9], v[46:47] op_sel_hi:[1,0]
	v_pk_mul_f32 v[42:43], v[42:43], v[46:47] op_sel_hi:[1,0]
	v_pk_mul_f32 v[44:45], v[44:45], v[46:47] op_sel_hi:[1,0]
	v_mul_lo_u32 v56, v72, s12
	v_cvt_pk_bf16_f32 v46, v6, v7
	v_cvt_pk_bf16_f32 v47, v8, v9
	v_cvt_pk_bf16_f32 v48, v42, v43
	v_cvt_pk_bf16_f32 v49, v44, v45
	v_lshl_add_u32 v1, v56, 1, v67
	ds_write_b128 v1, v[46:49]
	v_mov_b32_e32 v1, v0
	v_mov_b64_e32 v[54:55], v[0:1]
	v_mov_b64_e32 v[52:53], v[0:1]
	v_mov_b64_e32 v[50:51], v[0:1]
	v_mov_b64_e32 v[48:49], v[0:1]
	s_and_saveexec_b64 s[12:13], s[86:87]
	s_cbranch_execz .LBB0_587
	s_and_saveexec_b64 s[34:35], s[10:11]
	s_xor_b64 s[34:35], exec, s[34:35]
	v_mul_lo_u32 v46, v72, s64
	v_ashrrev_i32_e32 v47, 31, v46
	v_lshl_add_u64 v[46:47], v[46:47], 1, v[14:15]
	s_mov_b64 s[62:63], 0x100
	v_lshl_add_u64 v[46:47], v[46:47], 0, s[62:63]
	s_andn2_saveexec_b64 s[34:35], s[34:35]
	v_mad_u64_u32 v[46:47], s[62:63], v64, s69, v[10:11]
	v_lshl_add_u64 v[46:47], v[46:47], 0, s[88:89]
	s_or_b64 exec, exec, s[34:35]
	global_load_dwordx4 v[52:55], v[46:47], off
	global_load_dwordx4 v[60:63], v[16:17], off offset:3088
	global_load_dwordx4 v[48:51], v[16:17], off offset:3072
	s_waitcnt vmcnt(0) lgkmcnt(0)
	v_lshlrev_b32_e32 v46, 16, v52
	v_and_b32_e32 v47, 0xffff0000, v52
	v_pk_fma_f32 v[48:49], v[48:49], v[46:47], 0 op_sel_hi:[1,1,0]
	v_lshlrev_b32_e32 v46, 16, v53
	v_and_b32_e32 v47, 0xffff0000, v53
	v_pk_fma_f32 v[50:51], v[50:51], v[46:47], 0 op_sel_hi:[1,1,0]
	v_lshlrev_b32_e32 v46, 16, v54
	v_and_b32_e32 v47, 0xffff0000, v54
	v_pk_fma_f32 v[52:53], v[60:61], v[46:47], 0 op_sel_hi:[1,1,0]
	v_lshlrev_b32_e32 v46, 16, v55
	v_and_b32_e32 v47, 0xffff0000, v55
	v_pk_fma_f32 v[54:55], v[62:63], v[46:47], 0 op_sel_hi:[1,1,0]
	s_or_b64 exec, exec, s[12:13]
	s_and_saveexec_b64 s[12:13], s[2:3]
	s_cbranch_execnz .LBB0_588

; __device__ __forceinline__ void conv4h(const bf16_t* zc, int row, const bf16_t* hp, bool has_prev, const float* cw, float* y) {
; #pragma unroll
;     for (int i = 0; i < 8; ++i) y[i] = 0.f;
; #pragma unroll
;     for (int j = 0; j < 4; ++j) { const int rr = row - 3 + j;
;         if (rr >= 0 || has_prev) { const bf16_t* src = (rr >= 0) ? zc + (size_t)rr * ZLD_E : hp + (3 + rr) * 384; float xv[8]; unpack8(*(const u32x4*)src, xv);
;             const f32x4 w0 = *(const f32x4*)(cw + j * 2304), w1 = *(const f32x4*)(cw + j * 2304 + 4);
;             y[0] += w0.x * xv[0]; y[1] += w0.y * xv[1]; y[2] += w0.z * xv[2]; y[3] += w0.w * xv[3];
;             y[4] += w1.x * xv[4]; y[5] += w1.y * xv[5]; y[6] += w1.z * xv[6]; y[7] += w1.w * xv[7]; } }
.LBB0_582:
	s_and_saveexec_b64 s[34:35], s[6:7]
	s_xor_b64 s[34:35], exec, s[34:35]
	v_mul_lo_u32 v46, v72, s64
	v_ashrrev_i32_e32 v47, 31, v46
	v_lshl_add_u64 v[46:47], v[46:47], 1, v[14:15]
	s_mov_b64 s[62:63], 0x700
	v_lshl_add_u64 v[46:47], v[46:47], 0, s[62:63]
	s_andn2_saveexec_b64 s[34:35], s[34:35]
	v_mad_u64_u32 v[46:47], s[62:63], v73, s69, v[10:11]
	v_lshl_add_u64 v[46:47], v[46:47], 0, s[88:89]
	s_or_b64 exec, exec, s[34:35]
	global_load_dwordx4 v[60:63], v[46:47], off
	global_load_dwordx4 v[76:79], v[32:33], off offset:16
	global_load_dwordx4 v[80:83], v[32:33], off
	s_waitcnt vmcnt(0) lgkmcnt(0)
	v_lshlrev_b32_e32 v46, 16, v60
	v_and_b32_e32 v47, 0xffff0000, v60
	v_pk_fma_f32 v[48:49], v[80:81], v[46:47], v[48:49]
	v_lshlrev_b32_e32 v46, 16, v61
	v_and_b32_e32 v47, 0xffff0000, v61
	v_pk_fma_f32 v[50:51], v[82:83], v[46:47], v[50:51]
	v_lshlrev_b32_e32 v46, 16, v62
	v_and_b32_e32 v47, 0xffff0000, v62
	v_pk_fma_f32 v[52:53], v[76:77], v[46:47], v[52:53]
	v_lshlrev_b32_e32 v46, 16, v63
	v_and_b32_e32 v47, 0xffff0000, v63
	v_pk_fma_f32 v[54:55], v[78:79], v[46:47], v[54:55]
	s_or_b64 exec, exec, s[12:13]
	s_and_saveexec_b64 s[12:13], s[44:45]
	s_cbranch_execz .LBB0_599
	s_branch .LBB0_594

; __device__ __forceinline__ void conv4h(const bf16_t* zc, int row, const bf16_t* hp, bool has_prev, const float* cw, float* y) {
; #pragma unroll
;     for (int i = 0; i < 8; ++i) y[i] = 0.f;
; #pragma unroll
;     for (int j = 0; j < 4; ++j) { const int rr = row - 3 + j;
;         if (rr >= 0 || has_prev) { const bf16_t* src = (rr >= 0) ? zc + (size_t)rr * ZLD_E : hp + (3 + rr) * 384; float xv[8]; unpack8(*(const u32x4*)src, xv);
;             const f32x4 w0 = *(const f32x4*)(cw + j * 2304), w1 = *(const f32x4*)(cw + j * 2304 + 4);
;             y[0] += w0.x * xv[0]; y[1] += w0.y * xv[1]; y[2] += w0.z * xv[2]; y[3] += w0.w * xv[3];
;             y[4] += w1.x * xv[4]; y[5] += w1.y * xv[5]; y[6] += w1.z * xv[6]; y[7] += w1.w * xv[7]; } }
.LBB0_588:
	s_and_saveexec_b64 s[34:35], s[8:9]
	s_xor_b64 s[34:35], exec, s[34:35]
	v_mul_lo_u32 v46, v72, s64
	v_ashrrev_i32_e32 v47, 31, v46
	v_lshl_add_u64 v[46:47], v[46:47], 1, v[14:15]
	v_lshl_add_u64 v[46:47], v[46:47], 0, s[90:91]
	s_andn2_saveexec_b64 s[34:35], s[34:35]
	v_mad_u64_u32 v[46:47], s[62:63], v74, s69, v[10:11]
	v_lshl_add_u64 v[46:47], v[46:47], 0, s[88:89]
	s_or_b64 exec, exec, s[34:35]
	global_load_dwordx4 v[60:63], v[46:47], off
	s_waitcnt vmcnt(0) lgkmcnt(0)
	v_lshlrev_b32_e32 v46, 16, v60
	v_and_b32_e32 v47, 0xffff0000, v60
	v_lshlrev_b32_e32 v80, 16, v61
	v_and_b32_e32 v81, 0xffff0000, v61
	v_lshlrev_b32_e32 v82, 16, v62
	v_and_b32_e32 v83, 0xffff0000, v62
	v_lshlrev_b32_e32 v84, 16, v63
	v_and_b32_e32 v85, 0xffff0000, v63
	global_load_dwordx4 v[60:63], v[30:31], off offset:16
	global_load_dwordx4 v[76:79], v[30:31], off
	s_waitcnt vmcnt(1)
	v_pk_fma_f32 v[52:53], v[60:61], v[82:83], v[52:53]
	s_waitcnt vmcnt(0)
	v_pk_fma_f32 v[48:49], v[76:77], v[46:47], v[48:49]
	v_pk_fma_f32 v[50:51], v[78:79], v[80:81], v[50:51]
	v_pk_fma_f32 v[54:55], v[62:63], v[84:85], v[54:55]
	s_or_b64 exec, exec, s[12:13]
	s_and_saveexec_b64 s[12:13], s[14:15]
	s_cbranch_execnz .LBB0_582

; #define LAS __attribute__((address_space(3)))
; __device__ __forceinline__ u32x4 pack8(const float* f) { u32x4 o; o.x = pk2(f[0], f[1]); o.y = pk2(f[2], f[3]); o.z = pk2(f[4], f[5]); o.w = pk2(f[6], f[7]); return o; }
; __device__ __forceinline__ float sum16_dpp(float v) { v += dppf<0xB1>(v); v += dppf<0x4E>(v); v += dppf<0x141>(v); v += dppf<0x140>(v); return v; }
; __device__ __forceinline__ void conv4h(const bf16_t* zc, int row, const bf16_t* hp, bool has_prev, const float* cw, float* y) {
; #pragma unroll
;     for (int i = 0; i < 8; ++i) y[i] = 0.f;
; #pragma unroll
;     for (int j = 0; j < 4; ++j) { const int rr = row - 3 + j;
;         if (rr >= 0 || has_prev) { const bf16_t* src = (rr >= 0) ? zc + (size_t)rr * ZLD_E : hp + (3 + rr) * 384; float xv[8]; unpack8(*(const u32x4*)src, xv);
;             const f32x4 w0 = *(const f32x4*)(cw + j * 2304), w1 = *(const f32x4*)(cw + j * 2304 + 4);
;             y[0] += w0.x * xv[0]; y[1] += w0.y * xv[1]; y[2] += w0.z * xv[2]; y[3] += w0.w * xv[3];
;             y[4] += w1.x * xv[4]; y[5] += w1.y * xv[5]; y[6] += w1.z * xv[6]; y[7] += w1.w * xv[7]; } }
; __device__ __forceinline__ void even_prep(const Ctx& c, const Params& p, int e) {
;     ...
;             conv4h(zc + 768, row, hp + 128, n > 0, conv_qkv + 768 + h * 128 + c8, y);
;             ss = 0.f;
; #pragma unroll
;             for (int i = 0; i < 8; ++i) ss += y[i] * y[i];
;             ss = sum16_dpp(ss); rn = rsqrtf(ss + 1e-6f);
;             const float bg = sbeta[row] * eg; const float ek = __expf(glast - sgc[row]);
; #pragma unroll
;             for (int i = 0; i < 8; ++i) { y[i] *= rn; KBG[row * 128 + c8 + i] = y[i] * bg; yd[i] = y[i] * ek; }
;             *(LAS u32x4*)(KN + row * 136 + c8) = pack8(y); { const u32x4 t_ = pack8(yd); if (rep == 0) kdp0 = t_; else kdp1 = t_; }
;             conv4h(zc + 1536, row, hp + 256, n > 0, conv_qkv + 1536 + h * 128 + c8, y);
;             const float be = sbeta[row];
; #pragma unroll
;             for (int i = 0; i < 8; ++i) VB[row * 128 + c8 + i] = y[i] * be; }
.LBB0_594:
	s_and_saveexec_b64 s[34:35], vcc
	s_xor_b64 s[34:35], exec, s[34:35]
	v_mul_lo_u32 v46, v72, s64
	v_ashrrev_i32_e32 v47, 31, v46
	v_lshl_add_u64 v[46:47], v[46:47], 1, v[14:15]
	s_mov_b64 s[62:63], 0xa00
	v_lshl_add_u64 v[46:47], v[46:47], 0, s[62:63]
	s_andn2_saveexec_b64 s[34:35], s[34:35]
	v_mad_u64_u32 v[46:47], s[62:63], v72, s69, v[10:11]
	v_lshl_add_u64 v[46:47], v[46:47], 0, s[88:89]
	s_or_b64 exec, exec, s[34:35]
	global_load_dwordx4 v[60:63], v[46:47], off
	global_load_dwordx4 v[76:79], v[34:35], off offset:16
	global_load_dwordx4 v[80:83], v[34:35], off
	s_waitcnt vmcnt(0) lgkmcnt(0)
	v_lshlrev_b32_e32 v46, 16, v60
	v_and_b32_e32 v47, 0xffff0000, v60
	v_pk_fma_f32 v[48:49], v[80:81], v[46:47], v[48:49]
	v_lshlrev_b32_e32 v46, 16, v61
	v_and_b32_e32 v47, 0xffff0000, v61
	v_pk_fma_f32 v[50:51], v[82:83], v[46:47], v[50:51]
	v_lshlrev_b32_e32 v46, 16, v62
	v_and_b32_e32 v47, 0xffff0000, v62
	v_pk_fma_f32 v[52:53], v[76:77], v[46:47], v[52:53]
	v_lshlrev_b32_e32 v46, 16, v63
	v_and_b32_e32 v47, 0xffff0000, v63
	v_pk_fma_f32 v[54:55], v[78:79], v[46:47], v[54:55]
.LBB0_599:
	s_or_b64 exec, exec, s[12:13]
	v_mul_f32_e32 v1, 0xbfb8aa3b, v48
	v_exp_f32_e32 v1, v1
	v_mul_f32_e32 v47, 0xbfb8aa3b, v49
	v_exp_f32_e32 v47, v47
	s_waitcnt lgkmcnt(0)
	v_mul_f32_e32 v46, 0x3fb8aa3b, v58
	v_add_f32_e32 v1, 1.0, v1
	v_mul_f32_e32 v58, 0xbfb8aa3b, v50
	v_exp_f32_e32 v60, v58
	v_rcp_f32_e32 v58, v1
	v_add_f32_e32 v1, 1.0, v47
	v_mul_f32_e32 v47, 0xbfb8aa3b, v51
	v_exp_f32_e32 v47, v47
	v_rcp_f32_e32 v59, v1
	v_add_f32_e32 v1, 1.0, v60
	v_mul_f32_e32 v60, 0xbfb8aa3b, v52
	v_exp_f32_e32 v62, v60
	v_rcp_f32_e32 v60, v1
	v_add_f32_e32 v1, 1.0, v47
	v_mul_f32_e32 v47, 0xbfb8aa3b, v53
	v_exp_f32_e32 v47, v47
	v_rcp_f32_e32 v61, v1
	v_add_f32_e32 v1, 1.0, v62
	v_mul_f32_e32 v62, 0xbfb8aa3b, v54
	v_exp_f32_e32 v65, v62
	v_rcp_f32_e32 v62, v1
	v_add_f32_e32 v1, 1.0, v47
	v_mul_f32_e32 v47, 0xbfb8aa3b, v55
	v_exp_f32_e32 v47, v47
	v_rcp_f32_e32 v63, v1
	v_add_f32_e32 v1, 1.0, v65
	v_rcp_f32_e32 v78, v1
	v_add_f32_e32 v1, 1.0, v47
	v_pk_mul_f32 v[48:49], v[48:49], v[58:59]
	v_lshl_add_u32 v75, v72, 2, s58
	v_rcp_f32_e32 v79, v1
	v_pk_mul_f32 v[58:59], v[48:49], v[48:49]
	v_pk_mul_f32 v[50:51], v[50:51], v[60:61]
	ds_read_b32 v65, v75
	ds_read_b32 v76, v57
	v_pk_mul_f32 v[60:61], v[50:51], v[50:51]
	v_add_f32_e32 v57, v59, v58
	v_pk_mul_f32 v[52:53], v[52:53], v[62:63]
	v_add_f32_e32 v57, v60, v57
	v_pk_mul_f32 v[62:63], v[52:53], v[52:53]
	v_add_f32_e32 v57, v61, v57
	v_pk_mul_f32 v[54:55], v[54:55], v[78:79]
	v_add_f32_e32 v57, v62, v57
	v_pk_mul_f32 v[78:79], v[54:55], v[54:55]
	v_add_f32_e32 v57, v63, v57
	v_add_f32_e32 v57, v78, v57
	v_add_f32_e32 v57, v79, v57
	v_exp_f32_e32 v46, v46
	v_lshlrev_b32_e32 v1, 9, v72
	v_add_f32_dpp v57, v57, v57 quad_perm:[1,0,3,2] row_mask:0xf bank_mask:0xf bound_ctrl:1
	v_add_u32_e32 v47, v68, v1
	v_add_u32_e32 v59, 0xc408, v47
	v_add_f32_dpp v57, v57, v57 quad_perm:[2,3,0,1] row_mask:0xf bank_mask:0xf bound_ctrl:1
	s_waitcnt lgkmcnt(0)
	v_mul_f32_e32 v80, v46, v65
	v_add_u32_e32 v1, 0xc400, v47
	v_add_f32_dpp v57, v57, v57 row_half_mirror row_mask:0xf bank_mask:0xf bound_ctrl:1
	v_add_u32_e32 v62, 0xc410, v47
	v_add_u32_e32 v63, 0xc418, v47
	v_add_f32_dpp v57, v57, v57 row_mirror row_mask:0xf bank_mask:0xf bound_ctrl:1
	v_add_f32_e32 v57, 0x358637bd, v57
	v_mul_f32_e32 v58, 0x4b800000, v57
	v_cmp_gt_f32_e64 s[12:13], s33, v57
	s_nop 1
	v_cndmask_b32_e64 v57, v57, v58, s[12:13]
	v_rsq_f32_e32 v57, v57
	s_nop 0
	v_mul_f32_e32 v58, 0x45800000, v57
	v_cndmask_b32_e64 v58, v57, v58, s[12:13]
	v_pk_mul_f32 v[48:49], v[48:49], v[58:59] op_sel_hi:[1,0]
	v_pk_mul_f32 v[50:51], v[50:51], v[58:59] op_sel_hi:[1,0]
	v_pk_mul_f32 v[60:61], v[80:81], v[48:49] op_sel_hi:[0,1]
	ds_write2_b32 v1, v60, v61 offset1:1
	v_pk_mul_f32 v[60:61], v[80:81], v[50:51] op_sel_hi:[0,1]
	v_pk_mul_f32 v[52:53], v[52:53], v[58:59] op_sel_hi:[1,0]
	v_pk_mul_f32 v[54:55], v[54:55], v[58:59] op_sel_hi:[1,0]
	ds_write2_b32 v59, v60, v61 offset1:1
	v_pk_mul_f32 v[60:61], v[80:81], v[52:53] op_sel_hi:[0,1]
	v_pk_mul_f32 v[58:59], v[80:81], v[54:55] op_sel_hi:[0,1]
	ds_write2_b32 v62, v60, v61 offset1:1
	ds_write2_b32 v63, v58, v59 offset1:1
	v_cvt_pk_bf16_f32 v58, v48, v49
	v_cvt_pk_bf16_f32 v59, v50, v51
	v_cvt_pk_bf16_f32 v60, v52, v53
	v_cvt_pk_bf16_f32 v61, v54, v55
	v_lshl_add_u32 v1, v56, 1, v69
	ds_write_b128 v1, v[58:61]
	v_mov_b32_e32 v1, v0
	v_mov_b64_e32 v[56:57], v[0:1]
	v_mov_b64_e32 v[58:59], v[0:1]
	v_mov_b64_e32 v[60:61], v[0:1]
	v_mov_b64_e32 v[62:63], v[0:1]
	s_and_saveexec_b64 s[12:13], s[86:87]
	s_cbranch_execz .LBB0_611
	s_and_saveexec_b64 s[34:35], s[10:11]
	s_xor_b64 s[10:11], exec, s[34:35]
	v_mul_lo_u32 v56, v72, s64
	v_ashrrev_i32_e32 v57, 31, v56
	v_lshl_add_u64 v[56:57], v[56:57], 1, v[14:15]
	s_mov_b64 s[34:35], 0x200
	v_lshl_add_u64 v[56:57], v[56:57], 0, s[34:35]
	s_andn2_saveexec_b64 s[10:11], s[10:11]
	v_mad_u64_u32 v[56:57], s[34:35], v64, s69, v[12:13]
	v_lshl_add_u64 v[56:57], v[56:57], 0, s[88:89]
	s_or_b64 exec, exec, s[10:11]
	global_load_dwordx4 v[56:59], v[56:57], off
	s_waitcnt vmcnt(0) lgkmcnt(0)
	v_lshlrev_b32_e32 v60, 16, v56
	v_and_b32_e32 v61, 0xffff0000, v56
	v_lshlrev_b32_e32 v64, 16, v57
	v_and_b32_e32 v65, 0xffff0000, v57
	v_lshlrev_b32_e32 v82, 16, v58
	v_and_b32_e32 v83, 0xffff0000, v58
	v_lshlrev_b32_e32 v84, 16, v59
	v_and_b32_e32 v85, 0xffff0000, v59
	global_load_dwordx4 v[78:81], v[22:23], off offset:16
	global_load_dwordx4 v[56:59], v[22:23], off
	s_waitcnt vmcnt(0)
	v_pk_fma_f32 v[62:63], v[56:57], v[60:61], 0 op_sel_hi:[1,1,0]
	v_pk_fma_f32 v[60:61], v[58:59], v[64:65], 0 op_sel_hi:[1,1,0]
	v_pk_fma_f32 v[58:59], v[78:79], v[82:83], 0 op_sel_hi:[1,1,0]
	v_pk_fma_f32 v[56:57], v[80:81], v[84:85], 0 op_sel_hi:[1,1,0]
	s_or_b64 exec, exec, s[12:13]
	s_and_saveexec_b64 s[10:11], s[2:3]
	s_cbranch_execnz .LBB0_612

; __device__ __forceinline__ void conv4h(const bf16_t* zc, int row, const bf16_t* hp, bool has_prev, const float* cw, float* y) {
; #pragma unroll
;     for (int i = 0; i < 8; ++i) y[i] = 0.f;
; #pragma unroll
;     for (int j = 0; j < 4; ++j) { const int rr = row - 3 + j;
;         if (rr >= 0 || has_prev) { const bf16_t* src = (rr >= 0) ? zc + (size_t)rr * ZLD_E : hp + (3 + rr) * 384; float xv[8]; unpack8(*(const u32x4*)src, xv);
;             const f32x4 w0 = *(const f32x4*)(cw + j * 2304), w1 = *(const f32x4*)(cw + j * 2304 + 4);
;             y[0] += w0.x * xv[0]; y[1] += w0.y * xv[1]; y[2] += w0.z * xv[2]; y[3] += w0.w * xv[3];
;             y[4] += w1.x * xv[4]; y[5] += w1.y * xv[5]; y[6] += w1.z * xv[6]; y[7] += w1.w * xv[7]; } }
.LBB0_606:
	s_and_saveexec_b64 s[8:9], s[6:7]
	s_xor_b64 s[6:7], exec, s[8:9]
	v_mul_lo_u32 v64, v72, s64
	v_ashrrev_i32_e32 v65, 31, v64
	v_lshl_add_u64 v[64:65], v[64:65], 1, v[14:15]
	s_mov_b64 s[8:9], 0x800
	v_lshl_add_u64 v[64:65], v[64:65], 0, s[8:9]
	s_andn2_saveexec_b64 s[6:7], s[6:7]
	v_mad_u64_u32 v[64:65], s[8:9], v73, s69, v[12:13]
	v_lshl_add_u64 v[64:65], v[64:65], 0, s[88:89]
	s_or_b64 exec, exec, s[6:7]
	global_load_dwordx4 v[78:81], v[64:65], off
	global_load_dwordx4 v[82:85], v[38:39], off offset:16
	global_load_dwordx4 v[86:89], v[38:39], off
	s_waitcnt vmcnt(0) lgkmcnt(0)
	v_lshlrev_b32_e32 v64, 16, v78
	v_and_b32_e32 v65, 0xffff0000, v78
	v_pk_fma_f32 v[62:63], v[86:87], v[64:65], v[62:63]
	v_lshlrev_b32_e32 v64, 16, v79
	v_and_b32_e32 v65, 0xffff0000, v79
	v_pk_fma_f32 v[60:61], v[88:89], v[64:65], v[60:61]
	v_lshlrev_b32_e32 v64, 16, v80
	v_and_b32_e32 v65, 0xffff0000, v80
	v_pk_fma_f32 v[58:59], v[82:83], v[64:65], v[58:59]
	v_lshlrev_b32_e32 v64, 16, v81
	v_and_b32_e32 v65, 0xffff0000, v81
	v_pk_fma_f32 v[56:57], v[84:85], v[64:65], v[56:57]
	s_or_b64 exec, exec, s[2:3]
	s_and_saveexec_b64 s[2:3], s[44:45]
	s_cbranch_execz .LBB0_623
	s_branch .LBB0_618

; __device__ __forceinline__ void conv4h(const bf16_t* zc, int row, const bf16_t* hp, bool has_prev, const float* cw, float* y) {
; #pragma unroll
;     for (int i = 0; i < 8; ++i) y[i] = 0.f;
; #pragma unroll
;     for (int j = 0; j < 4; ++j) { const int rr = row - 3 + j;
;         if (rr >= 0 || has_prev) { const bf16_t* src = (rr >= 0) ? zc + (size_t)rr * ZLD_E : hp + (3 + rr) * 384; float xv[8]; unpack8(*(const u32x4*)src, xv);
;             const f32x4 w0 = *(const f32x4*)(cw + j * 2304), w1 = *(const f32x4*)(cw + j * 2304 + 4);
;             y[0] += w0.x * xv[0]; y[1] += w0.y * xv[1]; y[2] += w0.z * xv[2]; y[3] += w0.w * xv[3];
;             y[4] += w1.x * xv[4]; y[5] += w1.y * xv[5]; y[6] += w1.z * xv[6]; y[7] += w1.w * xv[7]; } }
.LBB0_612:
	s_and_saveexec_b64 s[2:3], s[8:9]
	s_xor_b64 s[2:3], exec, s[2:3]
	v_mul_lo_u32 v64, v72, s64
	v_ashrrev_i32_e32 v65, 31, v64
	v_lshl_add_u64 v[64:65], v[64:65], 1, v[14:15]
	s_mov_b64 s[8:9], 0x500
	v_lshl_add_u64 v[64:65], v[64:65], 0, s[8:9]
	s_andn2_saveexec_b64 s[2:3], s[2:3]
	v_mad_u64_u32 v[64:65], s[8:9], v74, s69, v[12:13]
	v_lshl_add_u64 v[64:65], v[64:65], 0, s[88:89]
	s_or_b64 exec, exec, s[2:3]
	global_load_dwordx4 v[78:81], v[64:65], off
	s_waitcnt vmcnt(0) lgkmcnt(0)
	v_lshlrev_b32_e32 v64, 16, v78
	v_and_b32_e32 v65, 0xffff0000, v78
	v_lshlrev_b32_e32 v86, 16, v79
	v_and_b32_e32 v87, 0xffff0000, v79
	v_lshlrev_b32_e32 v88, 16, v80
	v_and_b32_e32 v89, 0xffff0000, v80
	v_lshlrev_b32_e32 v90, 16, v81
	v_and_b32_e32 v91, 0xffff0000, v81
	global_load_dwordx4 v[78:81], v[36:37], off offset:16
	global_load_dwordx4 v[82:85], v[36:37], off
	s_waitcnt vmcnt(1)
	v_pk_fma_f32 v[58:59], v[78:79], v[88:89], v[58:59]
	s_waitcnt vmcnt(0)
	v_pk_fma_f32 v[62:63], v[82:83], v[64:65], v[62:63]
	v_pk_fma_f32 v[60:61], v[84:85], v[86:87], v[60:61]
	v_pk_fma_f32 v[56:57], v[80:81], v[90:91], v[56:57]
	s_or_b64 exec, exec, s[10:11]
	s_and_saveexec_b64 s[2:3], s[14:15]
	s_cbranch_execnz .LBB0_606

; __device__ __forceinline__ void conv4h(const bf16_t* zc, int row, const bf16_t* hp, bool has_prev, const float* cw, float* y) {
; #pragma unroll
;     for (int i = 0; i < 8; ++i) y[i] = 0.f;
; #pragma unroll
;     for (int j = 0; j < 4; ++j) { const int rr = row - 3 + j;
;         if (rr >= 0 || has_prev) { const bf16_t* src = (rr >= 0) ? zc + (size_t)rr * ZLD_E : hp + (3 + rr) * 384; float xv[8]; unpack8(*(const u32x4*)src, xv);
;             const f32x4 w0 = *(const f32x4*)(cw + j * 2304), w1 = *(const f32x4*)(cw + j * 2304 + 4);
;             y[0] += w0.x * xv[0]; y[1] += w0.y * xv[1]; y[2] += w0.z * xv[2]; y[3] += w0.w * xv[3];
;             y[4] += w1.x * xv[4]; y[5] += w1.y * xv[5]; y[6] += w1.z * xv[6]; y[7] += w1.w * xv[7]; } }
.LBB0_618:
	s_and_saveexec_b64 s[6:7], vcc
	s_xor_b64 s[6:7], exec, s[6:7]
	v_mul_lo_u32 v64, v72, s64
	v_ashrrev_i32_e32 v65, 31, v64
	v_lshl_add_u64 v[64:65], v[64:65], 1, v[14:15]
	s_mov_b64 s[8:9], 0xb00
	v_lshl_add_u64 v[64:65], v[64:65], 0, s[8:9]
	s_andn2_saveexec_b64 s[6:7], s[6:7]
	v_mad_u64_u32 v[64:65], s[8:9], v72, s69, v[12:13]
	v_lshl_add_u64 v[64:65], v[64:65], 0, s[88:89]
	s_or_b64 exec, exec, s[6:7]
	global_load_dwordx4 v[78:81], v[64:65], off
	global_load_dwordx4 v[82:85], v[40:41], off offset:16
	global_load_dwordx4 v[86:89], v[40:41], off
	s_waitcnt vmcnt(0) lgkmcnt(0)
	v_lshlrev_b32_e32 v64, 16, v78
	v_and_b32_e32 v65, 0xffff0000, v78
	v_pk_fma_f32 v[62:63], v[86:87], v[64:65], v[62:63]
	v_lshlrev_b32_e32 v64, 16, v79
	v_and_b32_e32 v65, 0xffff0000, v79
	v_pk_fma_f32 v[60:61], v[88:89], v[64:65], v[60:61]
	v_lshlrev_b32_e32 v64, 16, v80
	v_and_b32_e32 v65, 0xffff0000, v80
	v_pk_fma_f32 v[58:59], v[82:83], v[64:65], v[58:59]
	v_lshlrev_b32_e32 v64, 16, v81
	v_and_b32_e32 v65, 0xffff0000, v81
	v_pk_fma_f32 v[56:57], v[84:85], v[64:65], v[56:57]

; #define LAS __attribute__((address_space(3)))
; __device__ __forceinline__ bf16_t f2bf(float f) { return (bf16_t)(pk2(f, 0.f) & 0xffffu); }
; __device__ __forceinline__ int crow(int r, int hi) { return (r & 3) + 8 * (r >> 2) + 4 * hi; }
; __device__ __forceinline__ void even_prep(const Ctx& c, const Params& p, int e) {
;     ...
;         for (int rep = 0; rep < 2; ++rep) { const int vi = tid_i + 512 * rep, row = vi >> 4, c8 = (vi & 15) * 8;
;             bf16_t* zc = Zw + (size_t)(m0 + row) * ZLD_E + 768 + h * 128 + c8; *(u32x4*)zc = rep ? qdp1 : qdp0;
;             const u32x4 kd_ = rep ? kdp1 : kdp0; bf16_t* kt_ = Zw + (size_t)(m0 + (c8 >> 1)) * ZLD_E + 768 + 768 + h * 128 + row;
;             kt_[0] = (bf16_t)(kd_.x & 0xffffu); kt_[64] = (bf16_t)(kd_.x >> 16); kt_[ZLD_E] = (bf16_t)(kd_.y & 0xffffu); kt_[ZLD_E + 64] = (bf16_t)(kd_.y >> 16);
;             kt_[2 * ZLD_E] = (bf16_t)(kd_.z & 0xffffu); kt_[2 * ZLD_E + 64] = (bf16_t)(kd_.z >> 16); kt_[3 * ZLD_E] = (bf16_t)(kd_.w & 0xffffu); kt_[3 * ZLD_E + 64] = (bf16_t)(kd_.w >> 16); }
;         { const int l31 = lane_i & 31, hh = lane_i >> 5; const int w = c.wave & 3; const int ti = (w == 0 || w == 3) ? 0 : 1, tj = (w >= 2) ? 1 : 0; const bool isq = c.wave >= 4;
;             bf16_t* qko = Zw + (size_t)m0 * ZLD_E + 768 + 1536 + h * 128;
;             if (w == 3) {
; #pragma unroll
;                 for (int r = 0; r < 16; ++r) { const int i = 32 * ti + crow(r, hh), j = 32 * tj + l31; if (isq) qko[(size_t)i * ZLD_E + j] = 0; else Lm[i * 64 + j] = 0.f; }
;             } else { f32x16 acc = {}; const LAS bf16_t* Am = isq ? QS : KN;
; #pragma unroll
;                 for (int ks = 0; ks < 8; ++ks) { const bf16x8 a = *(const LAS bf16x8*)(Am + (32 * ti + l31) * 136 + 16 * ks + 8 * hh); const bf16x8 bb = *(const LAS bf16x8*)(KN + (32 * tj + l31) * 136 + 16 * ks + 8 * hh);
;                     acc = __builtin_amdgcn_mfma_f32_32x32x16_bf16(a, bb, acc, 0, 0, 0); }
;                 const int j = 32 * tj + l31; const float gj = sgc[j];
; #pragma unroll
;                 for (int r = 0; r < 16; ++r) { const int i = 32 * ti + crow(r, hh); const float dec = __expf(fminf(sgc[i] - gj, 0.f));
;                     if (isq) qko[(size_t)i * ZLD_E + j] = (i >= j) ? f2bf(acc[r] * dec) : (bf16_t)0;
;                     else Lm[i * 64 + j] = (i > j) ? sbeta[i] * acc[r] * dec : 0.f; } } }
.LBB0_625:
	v_lshrrev_b32_e32 v10, 1, v20
	v_ashrrev_i32_e32 v14, 4, v18
	v_or_b32_e32 v12, s27, v10
	v_mov_b64_e32 v[10:11], s[16:17]
	v_add_u32_e32 v15, s27, v14
	v_mad_i64_i32 v[16:17], s[2:3], v15, s69, v[10:11]
	v_mad_i64_i32 v[12:13], s[2:3], v12, s69, v[10:11]
	v_lshl_add_u64 v[16:17], v[16:17], 0, s[80:81]
	v_lshlrev_b32_e32 v22, 1, v20
	v_mov_b32_e32 v23, v0
	v_lshl_add_u64 v[12:13], v[12:13], 0, s[80:81]
	v_lshl_add_u64 v[16:17], v[16:17], 0, v[22:23]
	v_ashrrev_i32_e32 v15, 31, v14
	s_waitcnt lgkmcnt(0)
	s_barrier
	global_store_dwordx4 v[16:17], v[2:5], off offset:1536
	s_movk_i32 s0, 0x4000
	s_movk_i32 s6, 0x6000
	v_lshl_add_u64 v[2:3], v[14:15], 1, v[12:13]
	v_add_co_u32_e32 v4, vcc, s1, v2
	global_store_short v[2:3], v71, off offset:3072
	global_store_short_d16_hi v[2:3], v71, off offset:3200
	v_addc_co_u32_e32 v5, vcc, 0, v3, vcc
	global_store_short v[4:5], v70, off offset:2592
	global_store_short_d16_hi v[4:5], v70, off offset:2720
	v_add_co_u32_e32 v4, vcc, s0, v2
	v_and_b32_e32 v19, 31, v18
	s_nop 0
	v_addc_co_u32_e32 v5, vcc, 0, v3, vcc
	v_add_co_u32_e32 v2, vcc, s6, v2
	global_store_short v[4:5], v66, off offset:2112
	global_store_short_d16_hi v[4:5], v66, off offset:2240
	v_addc_co_u32_e32 v3, vcc, 0, v3, vcc
	global_store_short v[2:3], v21, off offset:1632
	global_store_short_d16_hi v[2:3], v21, off offset:1760
	v_add_u32_e32 v2, 0x200, v18
	v_ashrrev_i32_e32 v2, 4, v2
	v_add_u32_e32 v3, s27, v2
	v_mad_i64_i32 v[4:5], s[2:3], v3, s69, v[10:11]
	v_lshl_add_u64 v[4:5], v[4:5], 0, s[80:81]
	v_ashrrev_i32_e32 v3, 31, v2
	v_lshl_add_u64 v[4:5], v[4:5], 0, v[22:23]
	v_lshl_add_u64 v[2:3], v[2:3], 1, v[12:13]
	global_store_dwordx4 v[4:5], v[6:9], off offset:1536
	v_add_co_u32_e32 v4, vcc, s1, v2
	global_store_short v[2:3], v50, off offset:3072
	global_store_short_d16_hi v[2:3], v50, off offset:3200
	v_addc_co_u32_e32 v5, vcc, 0, v3, vcc
	global_store_short v[4:5], v49, off offset:2592
	global_store_short_d16_hi v[4:5], v49, off offset:2720
	v_add_co_u32_e32 v4, vcc, s0, v2
	s_add_u32 s2, s29, s80
	s_nop 0
	v_addc_co_u32_e32 v5, vcc, 0, v3, vcc
	v_add_co_u32_e32 v2, vcc, s6, v2
	s_addc_u32 s3, s40, s81
	s_nop 0
	v_addc_co_u32_e32 v3, vcc, 0, v3, vcc
	s_add_u32 s2, s2, 0x1200
	global_store_short v[4:5], v48, off offset:2112
	global_store_short_d16_hi v[4:5], v48, off offset:2240
	global_store_short v[2:3], v1, off offset:1632
	global_store_short_d16_hi v[2:3], v1, off offset:1760
	v_bfe_u32 v1, v18, 5, 1
	s_addc_u32 s3, s3, 0
	s_mov_b64 s[6:7], -1
	s_and_b64 vcc, exec, s[20:21]
	s_mov_b32 s62, 0xc000
	s_mov_b32 s63, 0x12000
	s_mov_b32 s86, 0x30000
	v_readlane_b32 s80, v255, 41
	s_cbranch_vccz .LBB0_723
	v_or_b32_e32 v2, s31, v19
	v_mul_u32_u24_e32 v2, 0x110, v2
	v_lshlrev_b32_e32 v6, 4, v1
	v_readlane_b32 s0, v255, 49
	v_lshl_or_b32 v23, v1, 2, s31
	v_lshl_add_u32 v38, v23, 2, s49
	v_add3_u32 v32, s0, v2, v6
	ds_read_b128 v[2:5], v32
	v_readlane_b32 s0, v255, 51
	s_and_b64 vcc, exec, s[24:25]
	s_nop 0
	v_or_b32_e32 v21, s0, v19
	v_mul_u32_u24_e32 v7, 0x110, v21
	v_add3_u32 v36, s80, v7, v6
	ds_read_b128 v[6:9], v36
	s_waitcnt lgkmcnt(0)
	v_mfma_f32_32x32x16_bf16 v[2:17], v[2:5], v[6:9], 0
	ds_read_b128 v[24:27], v32 offset:32
	ds_read_b128 v[28:31], v36 offset:32
	v_lshlrev_b32_e32 v37, 2, v21
	s_waitcnt lgkmcnt(0)
	v_mfma_f32_32x32x16_bf16 v[2:17], v[24:27], v[28:31], v[2:17]
	ds_read_b128 v[24:27], v32 offset:64
	ds_read_b128 v[28:31], v36 offset:64
	s_waitcnt lgkmcnt(0)
	v_mfma_f32_32x32x16_bf16 v[2:17], v[24:27], v[28:31], v[2:17]
	ds_read_b128 v[24:27], v32 offset:96
	ds_read_b128 v[28:31], v36 offset:96
	s_waitcnt lgkmcnt(0)
	v_mfma_f32_32x32x16_bf16 v[2:17], v[24:27], v[28:31], v[2:17]
	ds_read_b128 v[24:27], v32 offset:128
	ds_read_b128 v[28:31], v36 offset:128
	s_waitcnt lgkmcnt(0)
	v_mfma_f32_32x32x16_bf16 v[2:17], v[24:27], v[28:31], v[2:17]
	ds_read_b128 v[24:27], v32 offset:160
	ds_read_b128 v[28:31], v36 offset:160
	s_waitcnt lgkmcnt(0)
	v_mfma_f32_32x32x16_bf16 v[2:17], v[24:27], v[28:31], v[2:17]
	ds_read_b128 v[24:27], v32 offset:192
	ds_read_b128 v[28:31], v36 offset:192
	ds_read_b128 v[32:35], v32 offset:224
	s_waitcnt lgkmcnt(0)
	v_mfma_f32_32x32x16_bf16 v[2:17], v[24:27], v[28:31], v[2:17]
	v_add_u32_e32 v24, s49, v37
	ds_read_b32 v25, v38
	ds_read_b128 v[28:31], v36 offset:224
	ds_read_b32 v27, v24
	v_add_u32_e32 v26, s48, v37
	s_waitcnt lgkmcnt(0)
	v_sub_f32_e32 v24, v25, v27
	v_mfma_f32_32x32x16_bf16 v[2:17], v[32:35], v[28:31], v[2:17]
	v_min_f32_e32 v24, 0, v24
	v_mul_f32_e32 v24, 0x3fb8aa3b, v24
	v_exp_f32_e32 v28, v24
	s_cbranch_vccz .LBB0_630
	v_cmp_gt_u32_e32 vcc, v23, v21
	v_mov_b32_e32 v24, 0
	s_and_saveexec_b64 s[6:7], vcc
	s_cbranch_execz .LBB0_629
	v_lshl_add_u32 v24, v23, 2, s58
	ds_read_b32 v24, v24
	s_waitcnt lgkmcnt(0)
	s_nop 0
	v_mul_f32_e32 v24, v2, v24
	v_mul_f32_e32 v24, v28, v24

; __device__ __forceinline__ bf16_t f2bf(float f) { return (bf16_t)(pk2(f, 0.f) & 0xffffu); }
; __device__ __forceinline__ int crow(int r, int hi) { return (r & 3) + 8 * (r >> 2) + 4 * hi; }
; __device__ __forceinline__ void even_prep(const Ctx& c, const Params& p, int e) {
;     ...
;                 const int j = 32 * tj + l31; const float gj = sgc[j];
; #pragma unroll
;                 for (int r = 0; r < 16; ++r) { const int i = 32 * ti + crow(r, hh); const float dec = __expf(fminf(sgc[i] - gj, 0.f));
;                     if (isq) qko[(size_t)i * ZLD_E + j] = (i >= j) ? f2bf(acc[r] * dec) : (bf16_t)0;
.LBB0_630:
	v_lshlrev_b32_e32 v24, 1, v21
	v_mov_b32_e32 v25, v0
	v_lshl_add_u64 v[24:25], s[2:3], 0, v[24:25]
	s_and_b64 vcc, exec, s[6:7]
	v_cmp_ge_u32_e64 s[6:7], v23, v21
	s_cbranch_vccz .LBB0_632
	s_nop 1
	v_mul_f32_e32 v2, v2, v28
	v_cvt_pk_bf16_f32 v2, v2, s0
	v_mul_u32_u24_e32 v28, 0x1e20, v23
	v_mov_b32_e32 v29, v0
	v_cndmask_b32_e64 v2, 0, v2, s[6:7]
	v_lshl_add_u64 v[28:29], v[24:25], 0, v[28:29]
	global_store_short v[28:29], v2, off

; __device__ __forceinline__ bf16_t f2bf(float f) { return (bf16_t)(pk2(f, 0.f) & 0xffffu); }
; __device__ __forceinline__ int crow(int r, int hi) { return (r & 3) + 8 * (r >> 2) + 4 * hi; }
; __device__ __forceinline__ void even_prep(const Ctx& c, const Params& p, int e) {
;     ...
;                 for (int r = 0; r < 16; ++r) { const int i = 32 * ti + crow(r, hh); const float dec = __expf(fminf(sgc[i] - gj, 0.f));
;                     if (isq) qko[(size_t)i * ZLD_E + j] = (i >= j) ? f2bf(acc[r] * dec) : (bf16_t)0;
.LBB0_636:
	s_and_b64 vcc, exec, s[8:9]
	s_cbranch_vccz .LBB0_638
	v_mul_f32_e32 v3, v3, v28
	v_cvt_pk_bf16_f32 v3, v3, s0
	v_cmp_ge_u32_e32 vcc, v2, v21
	v_mul_u32_u24_e32 v2, 0x1e20, v2
	s_nop 0
	v_cndmask_b32_e32 v28, 0, v3, vcc
	v_mov_b32_e32 v3, v0
	v_lshl_add_u64 v[2:3], v[24:25], 0, v[2:3]
	global_store_short v[2:3], v28, off

; __device__ __forceinline__ bf16_t f2bf(float f) { return (bf16_t)(pk2(f, 0.f) & 0xffffu); }
; __device__ __forceinline__ int crow(int r, int hi) { return (r & 3) + 8 * (r >> 2) + 4 * hi; }
; __device__ __forceinline__ void even_prep(const Ctx& c, const Params& p, int e) {
;     ...
;                 for (int r = 0; r < 16; ++r) { const int i = 32 * ti + crow(r, hh); const float dec = __expf(fminf(sgc[i] - gj, 0.f));
;                     if (isq) qko[(size_t)i * ZLD_E + j] = (i >= j) ? f2bf(acc[r] * dec) : (bf16_t)0;
.LBB0_642:
	s_and_b64 vcc, exec, s[8:9]
	s_cbranch_vccz .LBB0_644
	v_mul_f32_e32 v3, v4, v3
	v_cvt_pk_bf16_f32 v3, v3, s0
	v_cmp_ge_u32_e32 vcc, v2, v21
	v_mul_u32_u24_e32 v2, 0x1e20, v2
	s_nop 0
	v_cndmask_b32_e32 v4, 0, v3, vcc
	v_mov_b32_e32 v3, v0
	v_lshl_add_u64 v[2:3], v[24:25], 0, v[2:3]
	global_store_short v[2:3], v4, off

; __device__ __forceinline__ bf16_t f2bf(float f) { return (bf16_t)(pk2(f, 0.f) & 0xffffu); }
; __device__ __forceinline__ int crow(int r, int hi) { return (r & 3) + 8 * (r >> 2) + 4 * hi; }
; __device__ __forceinline__ void even_prep(const Ctx& c, const Params& p, int e) {
;     ...
;                 for (int r = 0; r < 16; ++r) { const int i = 32 * ti + crow(r, hh); const float dec = __expf(fminf(sgc[i] - gj, 0.f));
;                     if (isq) qko[(size_t)i * ZLD_E + j] = (i >= j) ? f2bf(acc[r] * dec) : (bf16_t)0;
.LBB0_648:
	s_and_b64 vcc, exec, s[8:9]
	s_cbranch_vccz .LBB0_650
	v_mul_f32_e32 v3, v5, v3
	v_cvt_pk_bf16_f32 v3, v3, s0
	v_cmp_ge_u32_e32 vcc, v2, v21
	v_mul_u32_u24_e32 v2, 0x1e20, v2
	s_nop 0
	v_cndmask_b32_e32 v4, 0, v3, vcc
	v_mov_b32_e32 v3, v0
	v_lshl_add_u64 v[2:3], v[24:25], 0, v[2:3]
	global_store_short v[2:3], v4, off

; __device__ __forceinline__ bf16_t f2bf(float f) { return (bf16_t)(pk2(f, 0.f) & 0xffffu); }
; __device__ __forceinline__ int crow(int r, int hi) { return (r & 3) + 8 * (r >> 2) + 4 * hi; }
; __device__ __forceinline__ void even_prep(const Ctx& c, const Params& p, int e) {
;     ...
;                 for (int r = 0; r < 16; ++r) { const int i = 32 * ti + crow(r, hh); const float dec = __expf(fminf(sgc[i] - gj, 0.f));
;                     if (isq) qko[(size_t)i * ZLD_E + j] = (i >= j) ? f2bf(acc[r] * dec) : (bf16_t)0;
.LBB0_654:
	s_and_b64 vcc, exec, s[8:9]
	s_cbranch_vccz .LBB0_656
	v_mul_f32_e32 v3, v6, v3
	v_cvt_pk_bf16_f32 v3, v3, s0
	v_cmp_ge_u32_e32 vcc, v2, v21
	v_mul_u32_u24_e32 v2, 0x1e20, v2
	s_nop 0
	v_cndmask_b32_e32 v4, 0, v3, vcc
	v_mov_b32_e32 v3, v0
	v_lshl_add_u64 v[2:3], v[24:25], 0, v[2:3]
	global_store_short v[2:3], v4, off

; __device__ __forceinline__ bf16_t f2bf(float f) { return (bf16_t)(pk2(f, 0.f) & 0xffffu); }
; __device__ __forceinline__ int crow(int r, int hi) { return (r & 3) + 8 * (r >> 2) + 4 * hi; }
; __device__ __forceinline__ void even_prep(const Ctx& c, const Params& p, int e) {
;     ...
;                 for (int r = 0; r < 16; ++r) { const int i = 32 * ti + crow(r, hh); const float dec = __expf(fminf(sgc[i] - gj, 0.f));
;                     if (isq) qko[(size_t)i * ZLD_E + j] = (i >= j) ? f2bf(acc[r] * dec) : (bf16_t)0;
.LBB0_660:
	s_and_b64 vcc, exec, s[8:9]
	s_cbranch_vccz .LBB0_662
	v_mul_f32_e32 v3, v7, v3
	v_cvt_pk_bf16_f32 v3, v3, s0
	v_cmp_ge_u32_e32 vcc, v2, v21
	v_mul_u32_u24_e32 v2, 0x1e20, v2
	s_nop 0
	v_cndmask_b32_e32 v4, 0, v3, vcc
	v_mov_b32_e32 v3, v0
	v_lshl_add_u64 v[2:3], v[24:25], 0, v[2:3]
	global_store_short v[2:3], v4, off

; __device__ __forceinline__ bf16_t f2bf(float f) { return (bf16_t)(pk2(f, 0.f) & 0xffffu); }
; __device__ __forceinline__ int crow(int r, int hi) { return (r & 3) + 8 * (r >> 2) + 4 * hi; }
; __device__ __forceinline__ void even_prep(const Ctx& c, const Params& p, int e) {
;     ...
;                 for (int r = 0; r < 16; ++r) { const int i = 32 * ti + crow(r, hh); const float dec = __expf(fminf(sgc[i] - gj, 0.f));
;                     if (isq) qko[(size_t)i * ZLD_E + j] = (i >= j) ? f2bf(acc[r] * dec) : (bf16_t)0;
.LBB0_666:
	s_and_b64 vcc, exec, s[8:9]
	s_cbranch_vccz .LBB0_668
	v_mul_f32_e32 v3, v8, v3
	v_cvt_pk_bf16_f32 v3, v3, s0
	v_cmp_ge_u32_e32 vcc, v2, v21
	v_mul_u32_u24_e32 v2, 0x1e20, v2
	s_nop 0
	v_cndmask_b32_e32 v4, 0, v3, vcc
	v_mov_b32_e32 v3, v0
	v_lshl_add_u64 v[2:3], v[24:25], 0, v[2:3]
	global_store_short v[2:3], v4, off

; __device__ __forceinline__ bf16_t f2bf(float f) { return (bf16_t)(pk2(f, 0.f) & 0xffffu); }
; __device__ __forceinline__ int crow(int r, int hi) { return (r & 3) + 8 * (r >> 2) + 4 * hi; }
; __device__ __forceinline__ void even_prep(const Ctx& c, const Params& p, int e) {
;     ...
;                 for (int r = 0; r < 16; ++r) { const int i = 32 * ti + crow(r, hh); const float dec = __expf(fminf(sgc[i] - gj, 0.f));
;                     if (isq) qko[(size_t)i * ZLD_E + j] = (i >= j) ? f2bf(acc[r] * dec) : (bf16_t)0;
.LBB0_672:
	s_and_b64 vcc, exec, s[8:9]
	s_cbranch_vccz .LBB0_674
	v_mul_f32_e32 v3, v9, v3
	v_cvt_pk_bf16_f32 v3, v3, s0
	v_cmp_ge_u32_e32 vcc, v2, v21
	v_mul_u32_u24_e32 v2, 0x1e20, v2
	s_nop 0
	v_cndmask_b32_e32 v4, 0, v3, vcc
	v_mov_b32_e32 v3, v0
	v_lshl_add_u64 v[2:3], v[24:25], 0, v[2:3]
	global_store_short v[2:3], v4, off

; __device__ __forceinline__ bf16_t f2bf(float f) { return (bf16_t)(pk2(f, 0.f) & 0xffffu); }
; __device__ __forceinline__ int crow(int r, int hi) { return (r & 3) + 8 * (r >> 2) + 4 * hi; }
; __device__ __forceinline__ void even_prep(const Ctx& c, const Params& p, int e) {
;     ...
;                 for (int r = 0; r < 16; ++r) { const int i = 32 * ti + crow(r, hh); const float dec = __expf(fminf(sgc[i] - gj, 0.f));
;                     if (isq) qko[(size_t)i * ZLD_E + j] = (i >= j) ? f2bf(acc[r] * dec) : (bf16_t)0;
.LBB0_678:
	s_and_b64 vcc, exec, s[8:9]
	s_cbranch_vccz .LBB0_680
	v_mul_f32_e32 v3, v10, v3
	v_cvt_pk_bf16_f32 v3, v3, s0
	v_cmp_ge_u32_e32 vcc, v2, v21
	v_mul_u32_u24_e32 v2, 0x1e20, v2
	s_nop 0
	v_cndmask_b32_e32 v4, 0, v3, vcc
	v_mov_b32_e32 v3, v0
	v_lshl_add_u64 v[2:3], v[24:25], 0, v[2:3]
	global_store_short v[2:3], v4, off

; __device__ __forceinline__ bf16_t f2bf(float f) { return (bf16_t)(pk2(f, 0.f) & 0xffffu); }
; __device__ __forceinline__ int crow(int r, int hi) { return (r & 3) + 8 * (r >> 2) + 4 * hi; }
; __device__ __forceinline__ void even_prep(const Ctx& c, const Params& p, int e) {
;     ...
;                 for (int r = 0; r < 16; ++r) { const int i = 32 * ti + crow(r, hh); const float dec = __expf(fminf(sgc[i] - gj, 0.f));
;                     if (isq) qko[(size_t)i * ZLD_E + j] = (i >= j) ? f2bf(acc[r] * dec) : (bf16_t)0;
.LBB0_684:
	s_and_b64 vcc, exec, s[8:9]
	s_cbranch_vccz .LBB0_686
	v_mul_f32_e32 v3, v11, v3
	v_cvt_pk_bf16_f32 v3, v3, s0
	v_cmp_ge_u32_e32 vcc, v2, v21
	v_mul_u32_u24_e32 v2, 0x1e20, v2
	s_nop 0
	v_cndmask_b32_e32 v4, 0, v3, vcc
	v_mov_b32_e32 v3, v0
	v_lshl_add_u64 v[2:3], v[24:25], 0, v[2:3]
	global_store_short v[2:3], v4, off

; __device__ __forceinline__ bf16_t f2bf(float f) { return (bf16_t)(pk2(f, 0.f) & 0xffffu); }
; __device__ __forceinline__ int crow(int r, int hi) { return (r & 3) + 8 * (r >> 2) + 4 * hi; }
; __device__ __forceinline__ void even_prep(const Ctx& c, const Params& p, int e) {
;     ...
;                 for (int r = 0; r < 16; ++r) { const int i = 32 * ti + crow(r, hh); const float dec = __expf(fminf(sgc[i] - gj, 0.f));
;                     if (isq) qko[(size_t)i * ZLD_E + j] = (i >= j) ? f2bf(acc[r] * dec) : (bf16_t)0;
.LBB0_690:
	s_and_b64 vcc, exec, s[8:9]
	s_cbranch_vccz .LBB0_692
	v_mul_f32_e32 v3, v12, v3
	v_cvt_pk_bf16_f32 v3, v3, s0
	v_cmp_ge_u32_e32 vcc, v2, v21
	v_mul_u32_u24_e32 v2, 0x1e20, v2
	s_nop 0
	v_cndmask_b32_e32 v4, 0, v3, vcc
	v_mov_b32_e32 v3, v0
	v_lshl_add_u64 v[2:3], v[24:25], 0, v[2:3]
	global_store_short v[2:3], v4, off

; __device__ __forceinline__ bf16_t f2bf(float f) { return (bf16_t)(pk2(f, 0.f) & 0xffffu); }
; __device__ __forceinline__ int crow(int r, int hi) { return (r & 3) + 8 * (r >> 2) + 4 * hi; }
; __device__ __forceinline__ void even_prep(const Ctx& c, const Params& p, int e) {
;     ...
;                 for (int r = 0; r < 16; ++r) { const int i = 32 * ti + crow(r, hh); const float dec = __expf(fminf(sgc[i] - gj, 0.f));
;                     if (isq) qko[(size_t)i * ZLD_E + j] = (i >= j) ? f2bf(acc[r] * dec) : (bf16_t)0;
.LBB0_696:
	s_and_b64 vcc, exec, s[8:9]
	s_cbranch_vccz .LBB0_698
	v_mul_f32_e32 v3, v13, v3
	v_cvt_pk_bf16_f32 v3, v3, s0
	v_cmp_ge_u32_e32 vcc, v2, v21
	v_mul_u32_u24_e32 v2, 0x1e20, v2
	s_nop 0
	v_cndmask_b32_e32 v4, 0, v3, vcc
	v_mov_b32_e32 v3, v0
	v_lshl_add_u64 v[2:3], v[24:25], 0, v[2:3]
	global_store_short v[2:3], v4, off

; __device__ __forceinline__ bf16_t f2bf(float f) { return (bf16_t)(pk2(f, 0.f) & 0xffffu); }
; __device__ __forceinline__ int crow(int r, int hi) { return (r & 3) + 8 * (r >> 2) + 4 * hi; }
; __device__ __forceinline__ void even_prep(const Ctx& c, const Params& p, int e) {
;     ...
;                 for (int r = 0; r < 16; ++r) { const int i = 32 * ti + crow(r, hh); const float dec = __expf(fminf(sgc[i] - gj, 0.f));
;                     if (isq) qko[(size_t)i * ZLD_E + j] = (i >= j) ? f2bf(acc[r] * dec) : (bf16_t)0;
.LBB0_702:
	s_and_b64 vcc, exec, s[8:9]
	s_cbranch_vccz .LBB0_704
	v_mul_f32_e32 v3, v14, v3
	v_cvt_pk_bf16_f32 v3, v3, s0
	v_cmp_ge_u32_e32 vcc, v2, v21
	v_mul_u32_u24_e32 v2, 0x1e20, v2
	s_nop 0
	v_cndmask_b32_e32 v4, 0, v3, vcc
	v_mov_b32_e32 v3, v0
	v_lshl_add_u64 v[2:3], v[24:25], 0, v[2:3]
	global_store_short v[2:3], v4, off

; __device__ __forceinline__ bf16_t f2bf(float f) { return (bf16_t)(pk2(f, 0.f) & 0xffffu); }
; __device__ __forceinline__ int crow(int r, int hi) { return (r & 3) + 8 * (r >> 2) + 4 * hi; }
; __device__ __forceinline__ void even_prep(const Ctx& c, const Params& p, int e) {
;     ...
;                 for (int r = 0; r < 16; ++r) { const int i = 32 * ti + crow(r, hh); const float dec = __expf(fminf(sgc[i] - gj, 0.f));
;                     if (isq) qko[(size_t)i * ZLD_E + j] = (i >= j) ? f2bf(acc[r] * dec) : (bf16_t)0;
.LBB0_708:
	s_and_b64 vcc, exec, s[8:9]
	s_cbranch_vccz .LBB0_710
	v_mul_f32_e32 v3, v15, v3
	v_cvt_pk_bf16_f32 v3, v3, s0
	v_cmp_ge_u32_e32 vcc, v2, v21
	v_mul_u32_u24_e32 v2, 0x1e20, v2
	s_nop 0
	v_cndmask_b32_e32 v4, 0, v3, vcc
	v_mov_b32_e32 v3, v0
	v_lshl_add_u64 v[2:3], v[24:25], 0, v[2:3]
	global_store_short v[2:3], v4, off

; __device__ __forceinline__ bf16_t f2bf(float f) { return (bf16_t)(pk2(f, 0.f) & 0xffffu); }
; __device__ __forceinline__ int crow(int r, int hi) { return (r & 3) + 8 * (r >> 2) + 4 * hi; }
; __device__ __forceinline__ void even_prep(const Ctx& c, const Params& p, int e) {
;     ...
;                 for (int r = 0; r < 16; ++r) { const int i = 32 * ti + crow(r, hh); const float dec = __expf(fminf(sgc[i] - gj, 0.f));
;                     if (isq) qko[(size_t)i * ZLD_E + j] = (i >= j) ? f2bf(acc[r] * dec) : (bf16_t)0;
.LBB0_714:
	s_and_b64 vcc, exec, s[8:9]
	s_cbranch_vccz .LBB0_716
	v_mul_f32_e32 v3, v16, v3
	v_cvt_pk_bf16_f32 v3, v3, s0
	v_cmp_ge_u32_e32 vcc, v2, v21
	v_mul_u32_u24_e32 v2, 0x1e20, v2
	s_nop 0
	v_cndmask_b32_e32 v4, 0, v3, vcc
	v_mov_b32_e32 v3, v0
	v_lshl_add_u64 v[2:3], v[24:25], 0, v[2:3]
	global_store_short v[2:3], v4, off

; __device__ __forceinline__ bf16_t f2bf(float f) { return (bf16_t)(pk2(f, 0.f) & 0xffffu); }
; __device__ __forceinline__ int crow(int r, int hi) { return (r & 3) + 8 * (r >> 2) + 4 * hi; }
; __device__ __forceinline__ void even_prep(const Ctx& c, const Params& p, int e) {
;     ...
;                 for (int r = 0; r < 16; ++r) { const int i = 32 * ti + crow(r, hh); const float dec = __expf(fminf(sgc[i] - gj, 0.f));
;                     if (isq) qko[(size_t)i * ZLD_E + j] = (i >= j) ? f2bf(acc[r] * dec) : (bf16_t)0;
.LBB0_720:
	s_and_b64 vcc, exec, s[6:7]
	s_cbranch_vccz .LBB0_722
	v_mul_f32_e32 v3, v17, v3
	v_cvt_pk_bf16_f32 v3, v3, s0
	v_cmp_ge_u32_e32 vcc, v2, v21
	v_mul_u32_u24_e32 v2, 0x1e20, v2
	s_nop 0
	v_cndmask_b32_e32 v4, 0, v3, vcc
	v_mov_b32_e32 v3, v0
	v_lshl_add_u64 v[2:3], v[24:25], 0, v[2:3]
	global_store_short v[2:3], v4, off

; __device__ __forceinline__ int crow(int r, int hi) { return (r & 3) + 8 * (r >> 2) + 4 * hi; }
; __device__ __forceinline__ void even_prep(const Ctx& c, const Params& p, int e) {
;     ...
;             if (w == 3) {
; #pragma unroll
;                 for (int r = 0; r < 16; ++r) { const int i = 32 * ti + crow(r, hh), j = 32 * tj + l31; if (isq) qko[(size_t)i * ZLD_E + j] = 0; else Lm[i * 64 + j] = 0.f; }
.LBB0_726:
	v_lshlrev_b32_e32 v2, 1, v19
	v_mov_b32_e32 v3, v0
	s_andn2_b64 vcc, exec, s[6:7]
	v_lshl_add_u64 v[2:3], s[2:3], 0, v[2:3]
	s_cbranch_vccnz .LBB0_728
	v_mul_u32_u24_e32 v6, 0x7880, v1
	v_mov_b32_e32 v7, v0
	v_lshl_add_u64 v[6:7], v[2:3], 0, v[6:7]
	global_store_short v[6:7], v0, off offset:64

; __device__ __forceinline__ int crow(int r, int hi) { return (r & 3) + 8 * (r >> 2) + 4 * hi; }
; __device__ __forceinline__ void even_prep(const Ctx& c, const Params& p, int e) {
;     ...
;             if (w == 3) {
; #pragma unroll
;                 for (int r = 0; r < 16; ++r) { const int i = 32 * ti + crow(r, hh), j = 32 * tj + l31; if (isq) qko[(size_t)i * ZLD_E + j] = 0; else Lm[i * 64 + j] = 0.f; }
.LBB0_759:
	v_mul_u32_u24_e32 v6, 0x1e20, v5
	v_mov_b32_e32 v7, v0
	v_lshl_add_u64 v[6:7], v[2:3], 0, v[6:7]
	global_store_short v[6:7], v0, off offset:64
	v_or_b32_e32 v5, 2, v1
	s_and_b64 vcc, exec, s[6:7]
	s_mov_b64 s[2:3], -1
	s_cbranch_vccz .LBB0_731

; __device__ __forceinline__ int crow(int r, int hi) { return (r & 3) + 8 * (r >> 2) + 4 * hi; }
; __device__ __forceinline__ void even_prep(const Ctx& c, const Params& p, int e) {
;     ...
;             if (w == 3) {
; #pragma unroll
;                 for (int r = 0; r < 16; ++r) { const int i = 32 * ti + crow(r, hh), j = 32 * tj + l31; if (isq) qko[(size_t)i * ZLD_E + j] = 0; else Lm[i * 64 + j] = 0.f; }
.LBB0_761:
	v_mul_u32_u24_e32 v6, 0x1e20, v5
	v_mov_b32_e32 v7, v0
	v_lshl_add_u64 v[6:7], v[2:3], 0, v[6:7]
	global_store_short v[6:7], v0, off offset:64
	v_or_b32_e32 v5, 3, v1
	s_and_b64 vcc, exec, s[6:7]
	s_mov_b64 s[2:3], -1
	s_cbranch_vccz .LBB0_733

; __device__ __forceinline__ int crow(int r, int hi) { return (r & 3) + 8 * (r >> 2) + 4 * hi; }
; __device__ __forceinline__ void even_prep(const Ctx& c, const Params& p, int e) {
;     ...
;             if (w == 3) {
; #pragma unroll
;                 for (int r = 0; r < 16; ++r) { const int i = 32 * ti + crow(r, hh), j = 32 * tj + l31; if (isq) qko[(size_t)i * ZLD_E + j] = 0; else Lm[i * 64 + j] = 0.f; }
.LBB0_763:
	v_mul_u32_u24_e32 v6, 0x1e20, v5
	v_mov_b32_e32 v7, v0
	v_lshl_add_u64 v[6:7], v[2:3], 0, v[6:7]
	global_store_short v[6:7], v0, off offset:64
	v_or_b32_e32 v5, 8, v1
	s_and_b64 vcc, exec, s[6:7]
	s_mov_b64 s[2:3], -1
	s_cbranch_vccz .LBB0_735

; __device__ __forceinline__ int crow(int r, int hi) { return (r & 3) + 8 * (r >> 2) + 4 * hi; }
; __device__ __forceinline__ void even_prep(const Ctx& c, const Params& p, int e) {
;     ...
;             if (w == 3) {
; #pragma unroll
;                 for (int r = 0; r < 16; ++r) { const int i = 32 * ti + crow(r, hh), j = 32 * tj + l31; if (isq) qko[(size_t)i * ZLD_E + j] = 0; else Lm[i * 64 + j] = 0.f; }
.LBB0_765:
	v_mul_u32_u24_e32 v6, 0x1e20, v5
	v_mov_b32_e32 v7, v0
	v_lshl_add_u64 v[6:7], v[2:3], 0, v[6:7]
	global_store_short v[6:7], v0, off offset:64
	v_or_b32_e32 v5, 9, v1
	s_and_b64 vcc, exec, s[6:7]
	s_mov_b64 s[2:3], -1
	s_cbranch_vccz .LBB0_737

; __device__ __forceinline__ int crow(int r, int hi) { return (r & 3) + 8 * (r >> 2) + 4 * hi; }
; __device__ __forceinline__ void even_prep(const Ctx& c, const Params& p, int e) {
;     ...
;             if (w == 3) {
; #pragma unroll
;                 for (int r = 0; r < 16; ++r) { const int i = 32 * ti + crow(r, hh), j = 32 * tj + l31; if (isq) qko[(size_t)i * ZLD_E + j] = 0; else Lm[i * 64 + j] = 0.f; }
.LBB0_767:
	v_mul_u32_u24_e32 v6, 0x1e20, v5
	v_mov_b32_e32 v7, v0
	v_lshl_add_u64 v[6:7], v[2:3], 0, v[6:7]
	global_store_short v[6:7], v0, off offset:64
	v_or_b32_e32 v5, 10, v1
	s_and_b64 vcc, exec, s[6:7]
	s_mov_b64 s[2:3], -1
	s_cbranch_vccz .LBB0_739

; __device__ __forceinline__ int crow(int r, int hi) { return (r & 3) + 8 * (r >> 2) + 4 * hi; }
; __device__ __forceinline__ void even_prep(const Ctx& c, const Params& p, int e) {
;     ...
;             if (w == 3) {
; #pragma unroll
;                 for (int r = 0; r < 16; ++r) { const int i = 32 * ti + crow(r, hh), j = 32 * tj + l31; if (isq) qko[(size_t)i * ZLD_E + j] = 0; else Lm[i * 64 + j] = 0.f; }
.LBB0_769:
	v_mul_u32_u24_e32 v6, 0x1e20, v5
	v_mov_b32_e32 v7, v0
	v_lshl_add_u64 v[6:7], v[2:3], 0, v[6:7]
	global_store_short v[6:7], v0, off offset:64
	v_or_b32_e32 v5, 11, v1
	s_and_b64 vcc, exec, s[6:7]
	s_mov_b64 s[2:3], -1
	s_cbranch_vccz .LBB0_741

; __device__ __forceinline__ int crow(int r, int hi) { return (r & 3) + 8 * (r >> 2) + 4 * hi; }
; __device__ __forceinline__ void even_prep(const Ctx& c, const Params& p, int e) {
;     ...
;             if (w == 3) {
; #pragma unroll
;                 for (int r = 0; r < 16; ++r) { const int i = 32 * ti + crow(r, hh), j = 32 * tj + l31; if (isq) qko[(size_t)i * ZLD_E + j] = 0; else Lm[i * 64 + j] = 0.f; }
.LBB0_771:
	v_mul_u32_u24_e32 v6, 0x1e20, v5
	v_mov_b32_e32 v7, v0
	v_lshl_add_u64 v[6:7], v[2:3], 0, v[6:7]
	global_store_short v[6:7], v0, off offset:64
	v_or_b32_e32 v5, 16, v1
	s_and_b64 vcc, exec, s[6:7]
	s_mov_b64 s[2:3], -1
	s_cbranch_vccz .LBB0_743

; __device__ __forceinline__ int crow(int r, int hi) { return (r & 3) + 8 * (r >> 2) + 4 * hi; }
; __device__ __forceinline__ void even_prep(const Ctx& c, const Params& p, int e) {
;     ...
;             if (w == 3) {
; #pragma unroll
;                 for (int r = 0; r < 16; ++r) { const int i = 32 * ti + crow(r, hh), j = 32 * tj + l31; if (isq) qko[(size_t)i * ZLD_E + j] = 0; else Lm[i * 64 + j] = 0.f; }
.LBB0_773:
	v_mul_u32_u24_e32 v6, 0x1e20, v5
	v_mov_b32_e32 v7, v0
	v_lshl_add_u64 v[6:7], v[2:3], 0, v[6:7]
	global_store_short v[6:7], v0, off offset:64
	v_or_b32_e32 v5, 17, v1
	s_and_b64 vcc, exec, s[6:7]
	s_mov_b64 s[2:3], -1
	s_cbranch_vccz .LBB0_745

; __device__ __forceinline__ int crow(int r, int hi) { return (r & 3) + 8 * (r >> 2) + 4 * hi; }
; __device__ __forceinline__ void even_prep(const Ctx& c, const Params& p, int e) {
;     ...
;             if (w == 3) {
; #pragma unroll
;                 for (int r = 0; r < 16; ++r) { const int i = 32 * ti + crow(r, hh), j = 32 * tj + l31; if (isq) qko[(size_t)i * ZLD_E + j] = 0; else Lm[i * 64 + j] = 0.f; }
.LBB0_775:
	v_mul_u32_u24_e32 v6, 0x1e20, v5
	v_mov_b32_e32 v7, v0
	v_lshl_add_u64 v[6:7], v[2:3], 0, v[6:7]
	global_store_short v[6:7], v0, off offset:64
	v_or_b32_e32 v5, 18, v1
	s_and_b64 vcc, exec, s[6:7]
	s_mov_b64 s[2:3], -1
	s_cbranch_vccz .LBB0_747

; __device__ __forceinline__ int crow(int r, int hi) { return (r & 3) + 8 * (r >> 2) + 4 * hi; }
; __device__ __forceinline__ void even_prep(const Ctx& c, const Params& p, int e) {
;     ...
;             if (w == 3) {
; #pragma unroll
;                 for (int r = 0; r < 16; ++r) { const int i = 32 * ti + crow(r, hh), j = 32 * tj + l31; if (isq) qko[(size_t)i * ZLD_E + j] = 0; else Lm[i * 64 + j] = 0.f; }
.LBB0_777:
	v_mul_u32_u24_e32 v6, 0x1e20, v5
	v_mov_b32_e32 v7, v0
	v_lshl_add_u64 v[6:7], v[2:3], 0, v[6:7]
	global_store_short v[6:7], v0, off offset:64
	v_or_b32_e32 v5, 19, v1
	s_and_b64 vcc, exec, s[6:7]
	s_mov_b64 s[2:3], -1
	s_cbranch_vccz .LBB0_749

; __device__ __forceinline__ int crow(int r, int hi) { return (r & 3) + 8 * (r >> 2) + 4 * hi; }
; __device__ __forceinline__ void even_prep(const Ctx& c, const Params& p, int e) {
;     ...
;             if (w == 3) {
; #pragma unroll
;                 for (int r = 0; r < 16; ++r) { const int i = 32 * ti + crow(r, hh), j = 32 * tj + l31; if (isq) qko[(size_t)i * ZLD_E + j] = 0; else Lm[i * 64 + j] = 0.f; }
.LBB0_779:
	v_mul_u32_u24_e32 v6, 0x1e20, v5
	v_mov_b32_e32 v7, v0
	v_lshl_add_u64 v[6:7], v[2:3], 0, v[6:7]
	global_store_short v[6:7], v0, off offset:64
	v_or_b32_e32 v5, 24, v1
	s_and_b64 vcc, exec, s[6:7]
	s_mov_b64 s[2:3], -1
	s_cbranch_vccz .LBB0_751

; __device__ __forceinline__ int crow(int r, int hi) { return (r & 3) + 8 * (r >> 2) + 4 * hi; }
; __device__ __forceinline__ void even_prep(const Ctx& c, const Params& p, int e) {
;     ...
;             if (w == 3) {
; #pragma unroll
;                 for (int r = 0; r < 16; ++r) { const int i = 32 * ti + crow(r, hh), j = 32 * tj + l31; if (isq) qko[(size_t)i * ZLD_E + j] = 0; else Lm[i * 64 + j] = 0.f; }
.LBB0_781:
	v_mul_u32_u24_e32 v6, 0x1e20, v5
	v_mov_b32_e32 v7, v0
	v_lshl_add_u64 v[6:7], v[2:3], 0, v[6:7]
	global_store_short v[6:7], v0, off offset:64
	v_or_b32_e32 v5, 25, v1
	s_and_b64 vcc, exec, s[6:7]
	s_mov_b64 s[2:3], -1
	s_cbranch_vccz .LBB0_753

; __device__ __forceinline__ int crow(int r, int hi) { return (r & 3) + 8 * (r >> 2) + 4 * hi; }
; __device__ __forceinline__ void even_prep(const Ctx& c, const Params& p, int e) {
;     ...
;             if (w == 3) {
; #pragma unroll
;                 for (int r = 0; r < 16; ++r) { const int i = 32 * ti + crow(r, hh), j = 32 * tj + l31; if (isq) qko[(size_t)i * ZLD_E + j] = 0; else Lm[i * 64 + j] = 0.f; }
.LBB0_783:
	v_mul_u32_u24_e32 v6, 0x1e20, v5
	v_mov_b32_e32 v7, v0
	v_lshl_add_u64 v[6:7], v[2:3], 0, v[6:7]
	global_store_short v[6:7], v0, off offset:64
	v_or_b32_e32 v5, 26, v1
	s_and_b64 vcc, exec, s[6:7]
	s_mov_b64 s[2:3], -1
	s_cbranch_vccz .LBB0_755

; __device__ __forceinline__ int crow(int r, int hi) { return (r & 3) + 8 * (r >> 2) + 4 * hi; }
; __device__ __forceinline__ void even_prep(const Ctx& c, const Params& p, int e) {
;     ...
;             if (w == 3) {
; #pragma unroll
;                 for (int r = 0; r < 16; ++r) { const int i = 32 * ti + crow(r, hh), j = 32 * tj + l31; if (isq) qko[(size_t)i * ZLD_E + j] = 0; else Lm[i * 64 + j] = 0.f; }
.LBB0_785:
	v_mul_u32_u24_e32 v6, 0x1e20, v5
	v_mov_b32_e32 v7, v0
	v_lshl_add_u64 v[6:7], v[2:3], 0, v[6:7]
	global_store_short v[6:7], v0, off offset:64
	v_or_b32_e32 v1, 27, v1
	s_and_b64 vcc, exec, s[6:7]
	s_mov_b64 s[2:3], -1
	s_cbranch_vccz .LBB0_757

; __device__ __forceinline__ int crow(int r, int hi) { return (r & 3) + 8 * (r >> 2) + 4 * hi; }
; __device__ __forceinline__ void even_prep(const Ctx& c, const Params& p, int e) {
;     ...
;             if (w == 3) {
; #pragma unroll
;                 for (int r = 0; r < 16; ++r) { const int i = 32 * ti + crow(r, hh), j = 32 * tj + l31; if (isq) qko[(size_t)i * ZLD_E + j] = 0; else Lm[i * 64 + j] = 0.f; }
.LBB0_787:
	v_mul_u32_u24_e32 v4, 0x1e20, v1
	v_mov_b32_e32 v5, v0
	v_lshl_add_u64 v[2:3], v[2:3], 0, v[4:5]
	global_store_short v[2:3], v0, off offset:64

; #define LAS __attribute__((address_space(3)))
; __device__ __forceinline__ u32x4 pack8(const float* f) { u32x4 o; o.x = pk2(f[0], f[1]); o.y = pk2(f[2], f[3]); o.z = pk2(f[4], f[5]); o.w = pk2(f[6], f[7]); return o; }
; __device__ __forceinline__ void even_prep(const Ctx& c, const Params& p, int e) {
;     ...
; #pragma unroll 1
;         for (int rep = 0; rep < 4; ++rep) { const int vi = tid_i + 512 * rep, row = vi >> 5, which = (vi >> 4) & 1, c8 = (vi & 15) * 8;
;             const LAS float* sp = (which ? KBG : VB) + row * 128 + c8; float f[8];
; #pragma unroll
;             for (int i = 0; i < 8; ++i) f[i] = sp[i];
;             bf16_t* dp = (which ? WN : U) + (size_t)(m0 + row) * 768 + h * 128 + c8;
;             *(u32x4*)dp = pack8(f); }
;         __syncthreads();
.LBB0_791:
	s_nop 0
	v_add_u32_e32 v4, s2, v18
	v_ashrrev_i32_e32 v4, 5, v4
	v_lshl_add_u32 v10, v4, 9, v1
	v_add_u32_e32 v12, s27, v4
	ds_read2_b32 v[4:5], v10 offset1:1
	ds_read2_b32 v[6:7], v10 offset0:2 offset1:3
	ds_read2_b32 v[8:9], v10 offset0:4 offset1:5
	ds_read2_b32 v[10:11], v10 offset0:6 offset1:7
	s_addk_i32 s2, 0x200
	s_cmpk_eq_i32 s2, 0x800
	v_mad_i64_i32 v[12:13], s[4:5], v12, s50, v[2:3]
	s_waitcnt lgkmcnt(0)
	v_cvt_pk_bf16_f32 v4, v4, v5
	v_cvt_pk_bf16_f32 v5, v6, v7
	v_cvt_pk_bf16_f32 v6, v8, v9
	v_cvt_pk_bf16_f32 v7, v10, v11
	global_store_dwordx4 v[12:13], v[4:7], off
	s_cbranch_scc0 .LBB0_791
	s_add_i32 s26, s26, s38
	s_cmpk_gt_i32 s26, 0xbff
	s_waitcnt lgkmcnt(0)
	s_barrier
	s_cbranch_scc0 .LBB0_546

; __device__ __forceinline__ void halo_copy(const Ctx& c, const Params& p, int e) {
;     ...
;     for (int it = c.bid * 512 + c.tid; it < total; it += NT) { const int c8 = (it & 15) * 8; int r_ = it >> 4; const int part = r_ % 3; r_ /= 3; const int r = r_ % 3; r_ /= 3; const int n = r_ & 127, bh = r_ >> 7;
;         if (n == 0) continue; const int h = bh % 6, b = bh / 6;
;         *(u32x4*)(HALO + ((size_t)(bh * 128 + n) * 3 + r) * 384 + part * 128 + c8) = *(const u32x4*)(Z + (size_t)(b * T_ + 64 * n - 3 + r) * ZLD_E + 768 + part * 768 + h * 128 + c8); }
.LBB0_799:
	v_ashrrev_i32_e32 v5, 4, v1
	s_mov_b32 s8, 0x38e38e39
	v_mul_hi_i32 v3, v5, s8
	v_lshrrev_b32_e32 v4, 31, v3
	v_ashrrev_i32_e32 v3, 1, v3
	v_add_u32_e32 v3, v3, v4
	v_and_b32_e32 v4, 0x7f, v3
	v_cmp_ne_u32_e32 vcc, 0, v4
	s_and_saveexec_b64 s[8:9], vcc
	s_cbranch_execz .LBB0_798
	s_mov_b32 s0, 0x55555556
	v_mul_hi_i32 v7, v5, s0
	v_lshrrev_b32_e32 v8, 31, v7
	v_add_u32_e32 v7, v7, v8
	v_mul_hi_i32 v8, v7, s0
	v_lshrrev_b32_e32 v9, 31, v8
	v_add_u32_e32 v8, v8, v9
	v_lshl_add_u32 v8, v8, 1, v8
	v_ashrrev_i32_e32 v6, 7, v3
	v_sub_u32_e32 v8, v7, v8
	v_lshl_add_u32 v7, v7, 1, v7
	s_mov_b32 s0, 0x2aaaaaab
	s_waitcnt vmcnt(0) lgkmcnt(0)
	v_sub_u32_e32 v14, v5, v7
	v_mul_hi_i32 v5, v6, s0
	v_lshrrev_b32_e32 v7, 31, v5
	v_add_u32_e32 v5, v5, v7
	v_mul_lo_u32 v7, v5, 6
	v_lshlrev_b32_e32 v5, 13, v5
	v_lshl_add_u32 v4, v4, 6, v8
	v_sub_u32_e32 v10, v6, v7
	v_add3_u32 v6, v4, v5, -3
	v_mov_b64_e32 v[4:5], s[16:17]
	s_movk_i32 s0, 0x300
	v_mad_i64_i32 v[4:5], s[12:13], v6, s69, v[4:5]
	v_mul_lo_u32 v6, v14, s0
	v_ashrrev_i32_e32 v7, 31, v6
	v_lshl_add_u64 v[4:5], v[6:7], 1, v[4:5]
	v_lshlrev_b32_e32 v6, 7, v10
	v_and_b32_e32 v9, 0x78, v2
	v_ashrrev_i32_e32 v7, 31, v6
	v_lshl_add_u64 v[4:5], v[6:7], 1, v[4:5]
	v_lshlrev_b32_e32 v10, 1, v9
	v_mov_b32_e32 v11, v0
	v_lshl_add_u64 v[4:5], v[4:5], 0, v[10:11]
	global_load_dwordx4 v[4:7], v[4:5], off offset:1536
	v_mad_u64_u32 v[8:9], s[12:13], v3, 3, v[8:9]
	v_mov_b64_e32 v[12:13], s[4:5]
	v_mad_i64_i32 v[8:9], s[12:13], v8, s0, v[12:13]
	v_lshlrev_b32_e32 v12, 7, v14
	v_ashrrev_i32_e32 v13, 31, v12
	v_lshl_add_u64 v[8:9], v[12:13], 1, v[8:9]
	v_lshl_add_u64 v[8:9], v[8:9], 0, v[10:11]
	s_waitcnt vmcnt(0) lgkmcnt(0)
	global_store_dwordx4 v[8:9], v[4:7], off
	s_branch .LBB0_798

; __device__ __forceinline__ float bf2f(bf16_t b) { return asf((unsigned)b << 16); }
; __device__ __forceinline__ float sigmoidf_(float x) { return __builtin_amdgcn_rcpf(1.f + __expf(-x)); }
; __device__ __forceinline__ float softplusf_(float x) { return fmaxf(x, 0.f) + __logf(1.f + __expf(-fabsf(x))); }
; __device__ __forceinline__ void halo_copy(const Ctx& c, const Params& p, int e) {
;     ...
;     for (int item = c.gw; item < 3072; item += c.ngw) { const int n = item & 127, bh = item >> 7, h = bh % 6, b = bh / 6, t = c.lane;
;         const bf16_t* zr = Z + (size_t)(b * T_ + 64 * n + t) * ZLD_E;
;         const float braw = bf2f(zr[3840 + h]), araw = bf2f(zr[3846 + h]);
;         const float beta = sigmoidf_(braw);
;         float g = -__expf(p.in[c.zo + 9][e * 6 + h]) * softplusf_(araw + p.in[c.zo + 10][e * 6 + h]);
; #pragma unroll
;         for (int o = 1; o < 64; o <<= 1) { const float u = __shfl_up(g, o); if (t >= o) g += u; }
;         GCB[(size_t)item * 128 + t] = g; GCB[(size_t)item * 128 + 64 + t] = beta; if (t == 63) GC[(size_t)bh * 128 + n] = __expf(g); }
.LBB0_804:
	s_ashr_i32 s34, s29, 7
	s_mul_hi_i32 s18, s34, 0x2aaaaaab
	s_lshr_b32 s19, s18, 31
	s_add_i32 s18, s18, s19
	s_and_b32 s31, s29, 0x7f
	s_mul_i32 s19, s18, 6
	s_sub_i32 s20, s34, s19
	s_lshl_b32 s18, s18, 13
	s_lshl_b32 s19, s31, 6
	s_or_b32 s18, s18, s19
	v_add_u32_e32 v9, s18, v164
	s_waitcnt vmcnt(0) lgkmcnt(0)
	v_mov_b64_e32 v[10:11], s[16:17]
	v_mad_i64_i32 v[10:11], s[18:19], v9, s69, v[10:11]
	s_ashr_i32 s21, s20, 31
	v_lshl_add_u64 v[10:11], s[20:21], 1, v[10:11]
	s_movk_i32 s0, 0x1000
	v_add_co_u32_e64 v10, s[18:19], s0, v10
	s_nop 1
	v_addc_co_u32_e64 v11, s[18:19], 0, v11, s[18:19]
	global_load_ushort v9, v[10:11], off offset:3584
	v_readlane_b32 s18, v255, 39
	s_mul_i32 s18, s18, 6
	v_readlane_b32 s19, v255, 40
	s_add_i32 s18, s20, s18
	s_ashr_i32 s19, s18, 31
	s_lshl_b64 s[18:19], s[18:19], 2
	s_add_u32 s20, s24, s18
	s_addc_u32 s21, s25, s19
	s_add_u32 s18, s26, s18
	global_load_ushort v10, v[10:11], off offset:3596
	s_addc_u32 s19, s27, s19
	global_load_dword v12, v0, s[18:19]
	s_mov_b32 s18, 0xbfb8aa3b
	s_waitcnt vmcnt(0) lgkmcnt(0)
	v_lshlrev_b32_e32 v9, 16, v9
	v_mul_f32_e32 v9, 0xbfb8aa3b, v9
	v_exp_f32_e32 v9, v9
	v_lshlrev_b32_e32 v10, 16, v10
	v_add_f32_e32 v11, 1.0, v9
	global_load_dword v9, v0, s[20:21]
	s_mov_b32 s20, 0x3f317217
	v_rcp_f32_e32 v11, v11
	v_add_f32_e32 v10, v12, v10
	v_max_f32_e32 v12, 0, v10
	v_mul_f32_e64 v10, |v10|, s18
	v_exp_f32_e32 v10, v10
	s_waitcnt vmcnt(0)
	v_mul_f32_e32 v9, 0x3fb8aa3b, v9
	v_add_f32_e32 v10, 1.0, v10
	v_cmp_gt_f32_e64 s[18:19], s33, v10
	v_exp_f32_e32 v9, v9
	s_nop 0
	v_cndmask_b32_e64 v13, 0, 32, s[18:19]
	v_ldexp_f32 v10, v10, v13
	v_log_f32_e32 v10, v10
	s_nop 0
	v_mul_f32_e32 v13, 0x3f317217, v10
	v_fma_f32 v13, v10, s20, -v13
	v_fmac_f32_e32 v13, 0x3377d1cf, v10
	s_mov_b32 s20, 0x7f800000
	v_fmac_f32_e32 v13, 0x3f317217, v10
	v_cmp_lt_f32_e64 s[20:21], |v10|, s20
	s_nop 1
	v_cndmask_b32_e64 v10, v10, v13, s[20:21]
	v_cndmask_b32_e64 v13, 0, v182, s[18:19]
	v_sub_f32_e32 v10, v10, v13
	v_add_f32_e32 v10, v12, v10
	v_mul_f32_e64 v12, v10, -v9
	ds_bpermute_b32 v13, v1, v12
	s_waitcnt lgkmcnt(0)
	v_fma_f32 v9, v10, -v9, v13
	v_cndmask_b32_e64 v9, v9, v12, s[4:5]
	ds_bpermute_b32 v10, v4, v9
	s_waitcnt lgkmcnt(0)
	v_add_f32_e32 v10, v9, v10
	v_cndmask_b32_e64 v9, v10, v9, s[6:7]
	ds_bpermute_b32 v10, v5, v9
	s_waitcnt lgkmcnt(0)
	v_add_f32_e32 v10, v9, v10
	v_cndmask_b32_e64 v9, v10, v9, s[8:9]
	ds_bpermute_b32 v10, v6, v9
	s_waitcnt lgkmcnt(0)
	v_add_f32_e32 v10, v9, v10
	v_cndmask_b32_e64 v9, v10, v9, s[10:11]
	ds_bpermute_b32 v10, v7, v9
	s_waitcnt lgkmcnt(0)
	v_add_f32_e32 v10, v9, v10
	v_cndmask_b32_e64 v10, v10, v9, s[12:13]
	ds_bpermute_b32 v9, v8, v10
	s_waitcnt lgkmcnt(0)
	v_add_f32_e32 v9, v10, v9
	v_cndmask_b32_e64 v10, v9, v10, s[14:15]
	global_store_dword v[2:3], v10, off
	global_store_dword v[2:3], v11, off offset:256
	s_and_saveexec_b64 s[18:19], vcc
	s_cbranch_execz .LBB0_803
	s_ashr_i32 s35, s34, 31
	s_lshl_b64 s[20:21], s[34:35], 9
	v_mul_f32_e32 v9, 0x3fb8aa3b, v9
	s_add_u32 s20, s36, s20
	v_exp_f32_e32 v9, v9
	s_addc_u32 s21, s39, s21
	s_lshl_b32 s31, s31, 2
	s_add_u32 s20, s20, s31
	s_addc_u32 s21, s21, 0
	v_mov_b64_e32 v[10:11], s[20:21]
	global_store_dword v[10:11], v9, off
	s_branch .LBB0_803

; __device__ __forceinline__ u32x4 pack8(const float* f) { u32x4 o; o.x = pk2(f[0], f[1]); o.y = pk2(f[2], f[3]); o.z = pk2(f[4], f[5]); o.w = pk2(f[6], f[7]); return o; }
; __device__ __forceinline__ float siluf_(float x) { return x * __builtin_amdgcn_rcpf(1.f + __expf(-x)); }
; template <int CTRL> __device__ __forceinline__ float dppf(float v) { return __builtin_bit_cast(float, __builtin_amdgcn_update_dpp(0, __builtin_bit_cast(int, v), CTRL, 0xF, 0xF, true)); }
; __device__ __forceinline__ void gdn_post(const Ctx& c, const Params& p, int e) {
;     ...
;     for (int it = c.bid * 512 + c.tid; it < total; it += NT) { const int part = it & 3, h = (it >> 2) % 6, m = (it >> 2) / 6;
;         bf16_t* yo = Y + (size_t)m * D_ + 256 + h * 128 + 32 * part; const bf16_t* zg = Z + (size_t)m * ZLD_E + 3072 + h * 128 + 32 * part; const float* on = onorm + 32 * part;
;         float ov[32]; float ss = 0.f;
; #pragma unroll
;         for (int k = 0; k < 4; ++k) unpack8(*(const u32x4*)(yo + 8 * k), ov + 8 * k);
; #pragma unroll
;         for (int k = 0; k < 32; ++k) ss += ov[k] * ov[k];
;         ss += dppf<0xB1>(ss); ss += dppf<0x4E>(ss);
;         const float rn = rsqrtf(ss * (1.f / 128.f) + 1e-6f);
; #pragma unroll
;         for (int k = 0; k < 4; ++k) { float gz[8], out[8]; unpack8(*(const u32x4*)(zg + 8 * k), gz);
; #pragma unroll
;             for (int i = 0; i < 8; ++i) out[i] = ov[8 * k + i] * rn * on[8 * k + i] * siluf_(gz[i]);
;             *(u32x4*)(yo + 8 * k) = pack8(out); } }
.LBB0_812:
	v_ashrrev_i32_e32 v14, 2, v1
	v_mul_hi_i32 v12, v14, s12
	v_lshrrev_b32_e32 v13, 31, v12
	v_add_u32_e32 v12, v12, v13
	v_mul_lo_u32 v15, v12, 6
	v_sub_u32_e32 v16, v14, v15
	v_ashrrev_i32_e32 v13, 31, v12
	v_lshlrev_b32_e32 v16, 7, v16
	v_lshlrev_b64 v[14:15], 11, v[12:13]
	v_ashrrev_i32_e32 v17, 31, v16
	v_and_b32_e32 v2, 0x60, v33
	v_lshl_add_u64 v[14:15], s[22:23], 0, v[14:15]
	s_movk_i32 s10, 0x1620
	v_lshlrev_b64 v[16:17], 1, v[16:17]
	v_mov_b32_e32 v11, v0
	v_lshlrev_b32_e32 v10, 1, v2
	v_mad_i64_i32 v[12:13], s[10:11], v12, s10, v[14:15]
	v_lshl_add_u64 v[14:15], v[14:15], 0, v[16:17]
	v_lshl_add_u64 v[12:13], v[12:13], 0, v[16:17]
	v_lshl_add_u64 v[16:17], v[14:15], 0, v[10:11]
	s_mov_b64 s[10:11], 0x2100200
	v_lshl_add_u64 v[10:11], v[12:13], 0, v[10:11]
	v_lshl_add_u64 v[14:15], v[16:17], 0, s[10:11]
	s_mov_b64 s[10:11], 0x8101800
	v_add_co_u32_e32 v28, vcc, s13, v16
	v_lshl_add_u64 v[20:21], v[10:11], 0, s[10:11]
	s_nop 0
	v_addc_co_u32_e32 v29, vcc, 0, v17, vcc
	s_mov_b32 s10, 0x8101000
	v_add_co_u32_e32 v10, vcc, s10, v10
	v_lshlrev_b32_e32 v54, 2, v2
	s_nop 0
	v_addc_co_u32_e32 v11, vcc, 0, v11, vcc
	global_load_dwordx4 v[2:5], v54, s[4:5] offset:16
	global_load_dwordx4 v[6:9], v54, s[4:5]
	global_load_dwordx4 v[56:59], v[14:15], off offset:48
	global_load_dwordx4 v[22:25], v[28:29], off offset:512
	global_load_dwordx4 v[34:37], v[10:11], off offset:2048
	global_load_dwordx4 v[60:63], v[14:15], off offset:16
	global_load_dwordx4 v[64:67], v[14:15], off offset:32
	s_nop 0
	global_load_dwordx4 v[10:13], v[20:21], off offset:16
	v_add_u32_e32 v1, s8, v1
	s_mov_b32 s10, 0xbffff
	s_waitcnt vmcnt(0) lgkmcnt(0)
	v_and_b32_e32 v16, 0xffff0000, v58
	v_lshlrev_b32_e32 v52, 16, v22
	v_lshlrev_b32_e32 v68, 16, v36
	v_and_b32_e32 v53, 0xffff0000, v22
	v_lshlrev_b32_e32 v72, 16, v34
	v_lshlrev_b32_e32 v50, 16, v23
	v_and_b32_e32 v51, 0xffff0000, v23
	v_mul_f32_e32 v32, 0xbfb8aa3b, v68
	v_pk_mul_f32 v[74:75], v[52:53], v[52:53]
	v_mul_f32_e32 v98, 0xbfb8aa3b, v72
	v_lshlrev_b32_e32 v26, 16, v67
	v_and_b32_e32 v27, 0xffff0000, v67
	v_lshlrev_b32_e32 v30, 16, v66
	v_and_b32_e32 v31, 0xffff0000, v66
	v_pk_mul_f32 v[66:67], v[50:51], v[50:51]
	v_exp_f32_e32 v32, v32
	v_exp_f32_e32 v98, v98
	v_add_f32_e32 v74, v74, v75
	v_lshlrev_b32_e32 v48, 16, v24
	v_and_b32_e32 v49, 0xffff0000, v24
	v_add_f32_e32 v66, v66, v74
	v_lshlrev_b32_e32 v17, 16, v58
	v_and_b32_e32 v18, 0xffff0000, v59
	v_lshlrev_b32_e32 v19, 16, v59
	v_lshlrev_b32_e32 v58, 16, v37
	v_and_b32_e32 v59, 0xffff0000, v37
	v_and_b32_e32 v69, 0xffff0000, v36
	v_lshlrev_b32_e32 v70, 16, v35
	v_and_b32_e32 v71, 0xffff0000, v35
	v_and_b32_e32 v73, 0xffff0000, v34
	v_lshlrev_b32_e32 v34, 16, v65
	v_and_b32_e32 v35, 0xffff0000, v65
	v_lshlrev_b32_e32 v36, 16, v64
	v_and_b32_e32 v37, 0xffff0000, v64
	v_pk_mul_f32 v[64:65], v[48:49], v[48:49]
	v_add_f32_e32 v66, v67, v66
	v_lshlrev_b32_e32 v46, 16, v25
	v_and_b32_e32 v47, 0xffff0000, v25
	v_add_f32_e32 v64, v64, v66
	v_lshlrev_b32_e32 v38, 16, v63
	v_and_b32_e32 v39, 0xffff0000, v63
	v_lshlrev_b32_e32 v40, 16, v62
	v_and_b32_e32 v41, 0xffff0000, v62
	v_pk_mul_f32 v[62:63], v[46:47], v[46:47]
	v_add_f32_e32 v32, 1.0, v32
	v_add_f32_e32 v74, 1.0, v98
	v_add_f32_e32 v98, v65, v64
	v_lshlrev_b32_e32 v44, 16, v60
	v_and_b32_e32 v45, 0xffff0000, v60
	v_rcp_f32_e32 v64, v32
	v_add_f32_e32 v32, v62, v98
	v_pk_mul_f32 v[82:83], v[44:45], v[44:45]
	v_add_f32_e32 v32, v63, v32
	v_lshlrev_b32_e32 v42, 16, v61
	v_and_b32_e32 v43, 0xffff0000, v61
	v_add_f32_e32 v32, v82, v32
	v_pk_mul_f32 v[80:81], v[42:43], v[42:43]
	v_add_f32_e32 v32, v83, v32
	v_add_f32_e32 v32, v80, v32
	v_pk_mul_f32 v[78:79], v[40:41], v[40:41]
	v_add_f32_e32 v32, v81, v32
	v_add_f32_e32 v32, v78, v32
	v_pk_mul_f32 v[76:77], v[38:39], v[38:39]
	v_add_f32_e32 v32, v79, v32
	v_add_f32_e32 v32, v76, v32
	v_pk_mul_f32 v[90:91], v[36:37], v[36:37]
	v_add_f32_e32 v32, v77, v32
	v_add_f32_e32 v32, v90, v32
	v_pk_mul_f32 v[88:89], v[34:35], v[34:35]
	v_add_f32_e32 v32, v91, v32
	v_add_f32_e32 v32, v88, v32
	v_pk_mul_f32 v[86:87], v[30:31], v[30:31]
	v_add_f32_e32 v32, v89, v32
	v_add_f32_e32 v32, v86, v32
	v_pk_mul_f32 v[84:85], v[26:27], v[26:27]
	v_add_f32_e32 v32, v87, v32
	v_lshlrev_b32_e32 v24, 16, v56
	v_and_b32_e32 v25, 0xffff0000, v56
	v_add_f32_e32 v32, v84, v32
	v_pk_mul_f32 v[94:95], v[24:25], v[24:25]
	v_add_f32_e32 v32, v85, v32
	v_lshlrev_b32_e32 v22, 16, v57
	v_and_b32_e32 v23, 0xffff0000, v57
	v_add_f32_e32 v32, v94, v32
	v_pk_mul_f32 v[92:93], v[22:23], v[22:23]
	v_add_f32_e32 v32, v95, v32
	v_add_f32_e32 v32, v92, v32
	v_pk_mul_f32 v[56:57], v[16:17], v[16:17]
	v_add_f32_e32 v32, v93, v32
	v_add_f32_e32 v32, v57, v32
	v_pk_mul_f32 v[60:61], v[18:19], v[18:19]
	v_mul_f32_e32 v55, 0xbfb8aa3b, v69
	v_add_f32_e32 v32, v56, v32
	v_exp_f32_e32 v55, v55
	v_add_f32_e32 v32, v61, v32
	v_add_f32_e32 v32, v60, v32
	v_mul_f32_e32 v96, 0xbfb8aa3b, v70
	v_mul_f32_e32 v97, 0xbfb8aa3b, v71
	v_add_f32_dpp v32, v32, v32 quad_perm:[1,0,3,2] row_mask:0xf bank_mask:0xf bound_ctrl:1
	v_mul_f32_e32 v99, 0xbfb8aa3b, v73
	v_mul_f32_e32 v100, 0xbfb8aa3b, v58
	v_add_f32_dpp v32, v32, v32 quad_perm:[2,3,0,1] row_mask:0xf bank_mask:0xf bound_ctrl:1
	v_mul_f32_e32 v101, 0xbfb8aa3b, v59
	v_add_f32_e32 v55, 1.0, v55
	v_fmamk_f32 v32, v32, 0x3c000000, v148
	v_exp_f32_e32 v96, v96
	v_exp_f32_e32 v97, v97
	v_exp_f32_e32 v99, v99
	v_exp_f32_e32 v100, v100
	v_exp_f32_e32 v101, v101
	v_rcp_f32_e32 v65, v55
	v_mul_f32_e32 v55, 0x4b800000, v32
	v_cmp_gt_f32_e32 vcc, s33, v32
	v_add_f32_e32 v66, 1.0, v96
	v_add_f32_e32 v67, 1.0, v97
	v_cndmask_b32_e32 v32, v32, v55, vcc
	v_rsq_f32_e32 v32, v32
; __device__ __forceinline__ u32x4 pack8(const float* f) { u32x4 o; o.x = pk2(f[0], f[1]); o.y = pk2(f[2], f[3]); o.z = pk2(f[4], f[5]); o.w = pk2(f[6], f[7]); return o; }
; __device__ __forceinline__ float siluf_(float x) { return x * __builtin_amdgcn_rcpf(1.f + __expf(-x)); }
; template <int CTRL> __device__ __forceinline__ float dppf(float v) { return __builtin_bit_cast(float, __builtin_amdgcn_update_dpp(0, __builtin_bit_cast(int, v), CTRL, 0xF, 0xF, true)); }
; __device__ __forceinline__ void gdn_post(const Ctx& c, const Params& p, int e) {
;     ...
;         for (int k = 0; k < 4; ++k) unpack8(*(const u32x4*)(yo + 8 * k), ov + 8 * k);
; #pragma unroll
;         for (int k = 0; k < 32; ++k) ss += ov[k] * ov[k];
;         ss += dppf<0xB1>(ss); ss += dppf<0x4E>(ss);
;         const float rn = rsqrtf(ss * (1.f / 128.f) + 1e-6f);
; #pragma unroll
;         for (int k = 0; k < 4; ++k) { float gz[8], out[8]; unpack8(*(const u32x4*)(zg + 8 * k), gz);
; #pragma unroll
;             for (int i = 0; i < 8; ++i) out[i] = ov[8 * k + i] * rn * on[8 * k + i] * siluf_(gz[i]);
;             *(u32x4*)(yo + 8 * k) = pack8(out); } }
	v_add_f32_e32 v75, 1.0, v99
	v_add_f32_e32 v96, 1.0, v100
	v_add_f32_e32 v97, 1.0, v101
	v_rcp_f32_e32 v66, v66
	v_rcp_f32_e32 v67, v67
	v_rcp_f32_e32 v74, v74
	v_rcp_f32_e32 v75, v75
	v_rcp_f32_e32 v96, v96
	v_rcp_f32_e32 v97, v97
	v_mul_f32_e32 v55, 0x45800000, v32
	v_cndmask_b32_e32 v32, v32, v55, vcc
	v_pk_mul_f32 v[52:53], v[32:33], v[52:53] op_sel_hi:[0,1]
	v_pk_mul_f32 v[50:51], v[32:33], v[50:51] op_sel_hi:[0,1]
	v_pk_mul_f32 v[48:49], v[32:33], v[48:49] op_sel_hi:[0,1]
	v_pk_mul_f32 v[46:47], v[32:33], v[46:47] op_sel_hi:[0,1]
	v_pk_mul_f32 v[62:63], v[64:65], v[68:69]
	v_pk_mul_f32 v[64:65], v[66:67], v[70:71]
	v_pk_mul_f32 v[66:67], v[74:75], v[72:73]
	v_pk_mul_f32 v[58:59], v[96:97], v[58:59]
	v_pk_mul_f32 v[6:7], v[6:7], v[52:53]
	v_pk_mul_f32 v[8:9], v[8:9], v[50:51]
	v_pk_mul_f32 v[2:3], v[2:3], v[48:49]
	v_pk_mul_f32 v[4:5], v[4:5], v[46:47]
	v_pk_mul_f32 v[6:7], v[66:67], v[6:7]
	v_pk_mul_f32 v[8:9], v[64:65], v[8:9]
	v_pk_mul_f32 v[46:47], v[62:63], v[2:3]
	v_pk_mul_f32 v[48:49], v[58:59], v[4:5]
	v_cvt_pk_bf16_f32 v2, v6, v7
	v_cvt_pk_bf16_f32 v3, v8, v9
	v_cvt_pk_bf16_f32 v4, v46, v47
	v_cvt_pk_bf16_f32 v5, v48, v49
	global_store_dwordx4 v[28:29], v[2:5], off offset:512
	global_load_dwordx4 v[2:5], v54, s[4:5] offset:32
	s_nop 0
	global_load_dwordx4 v[6:9], v54, s[4:5] offset:48
	global_load_dwordx4 v[46:49], v[20:21], off offset:32
	v_lshlrev_b32_e32 v28, 16, v13
	v_and_b32_e32 v29, 0xffff0000, v13
	v_lshlrev_b32_e32 v50, 16, v12
	v_and_b32_e32 v51, 0xffff0000, v12
	v_lshlrev_b32_e32 v12, 16, v11
	v_and_b32_e32 v13, 0xffff0000, v11
	v_lshlrev_b32_e32 v52, 16, v10
	v_and_b32_e32 v53, 0xffff0000, v10
	v_mul_f32_e32 v10, 0xbfb8aa3b, v50
	v_mul_f32_e32 v11, 0xbfb8aa3b, v51
	v_mul_f32_e32 v55, 0xbfb8aa3b, v12
	v_mul_f32_e32 v56, 0xbfb8aa3b, v13
	v_mul_f32_e32 v57, 0xbfb8aa3b, v52
	v_mul_f32_e32 v58, 0xbfb8aa3b, v53
	v_mul_f32_e32 v59, 0xbfb8aa3b, v28
	v_mul_f32_e32 v60, 0xbfb8aa3b, v29
	v_exp_f32_e32 v10, v10
	v_exp_f32_e32 v11, v11
	v_exp_f32_e32 v55, v55
	v_exp_f32_e32 v56, v56
	v_exp_f32_e32 v57, v57
	v_exp_f32_e32 v58, v58
	v_exp_f32_e32 v59, v59
	v_exp_f32_e32 v60, v60
	v_add_f32_e32 v10, 1.0, v10
	v_add_f32_e32 v11, 1.0, v11
	v_add_f32_e32 v55, 1.0, v55
	v_add_f32_e32 v61, 1.0, v56
	v_add_f32_e32 v62, 1.0, v57
	v_add_f32_e32 v63, 1.0, v58
	v_add_f32_e32 v64, 1.0, v59
	v_add_f32_e32 v65, 1.0, v60
	v_rcp_f32_e32 v10, v10
	v_rcp_f32_e32 v11, v11
	v_rcp_f32_e32 v56, v55
	v_rcp_f32_e32 v57, v61
	v_rcp_f32_e32 v58, v62
	v_rcp_f32_e32 v59, v63
	v_rcp_f32_e32 v60, v64
	v_rcp_f32_e32 v61, v65
	v_pk_mul_f32 v[44:45], v[32:33], v[44:45] op_sel_hi:[0,1]
	v_pk_mul_f32 v[42:43], v[32:33], v[42:43] op_sel_hi:[0,1]
	v_pk_mul_f32 v[40:41], v[32:33], v[40:41] op_sel_hi:[0,1]
	v_pk_mul_f32 v[38:39], v[32:33], v[38:39] op_sel_hi:[0,1]
	v_pk_mul_f32 v[10:11], v[10:11], v[50:51]
	v_pk_mul_f32 v[12:13], v[56:57], v[12:13]
	v_pk_mul_f32 v[50:51], v[58:59], v[52:53]
	v_pk_mul_f32 v[28:29], v[60:61], v[28:29]
	v_pk_mul_f32 v[36:37], v[32:33], v[36:37] op_sel_hi:[0,1]
	v_pk_mul_f32 v[34:35], v[32:33], v[34:35] op_sel_hi:[0,1]
	v_pk_mul_f32 v[30:31], v[32:33], v[30:31] op_sel_hi:[0,1]
	v_pk_mul_f32 v[26:27], v[32:33], v[26:27] op_sel_hi:[0,1]
	v_add_u32_e32 v33, s9, v33
	v_pk_mul_f32 v[24:25], v[32:33], v[24:25] op_sel_hi:[0,1]
	v_pk_mul_f32 v[22:23], v[32:33], v[22:23] op_sel_hi:[0,1]
	v_pk_mul_f32 v[16:17], v[32:33], v[16:17] op_sel_hi:[0,1]
	v_pk_mul_f32 v[18:19], v[32:33], v[18:19] op_sel_hi:[0,1]
	v_cmp_lt_i32_e32 vcc, s10, v1
	s_or_b64 s[6:7], vcc, s[6:7]
	s_waitcnt vmcnt(0)
	v_pk_mul_f32 v[2:3], v[2:3], v[44:45]
	v_pk_mul_f32 v[4:5], v[4:5], v[42:43]
	v_pk_mul_f32 v[6:7], v[6:7], v[40:41]
	v_pk_mul_f32 v[8:9], v[8:9], v[38:39]
	v_pk_mul_f32 v[2:3], v[50:51], v[2:3]
	v_pk_mul_f32 v[4:5], v[12:13], v[4:5]
	v_pk_mul_f32 v[6:7], v[10:11], v[6:7]
	v_pk_mul_f32 v[8:9], v[28:29], v[8:9]
	v_cvt_pk_bf16_f32 v2, v2, v3
	v_cvt_pk_bf16_f32 v3, v4, v5
	v_cvt_pk_bf16_f32 v4, v6, v7
	v_cvt_pk_bf16_f32 v5, v8, v9
	global_store_dwordx4 v[14:15], v[2:5], off offset:16
	global_load_dwordx4 v[2:5], v54, s[4:5] offset:64
	s_nop 0
	global_load_dwordx4 v[6:9], v54, s[4:5] offset:80
	global_load_dwordx4 v[10:13], v[20:21], off offset:48
	s_waitcnt lgkmcnt(0)
; __device__ __forceinline__ u32x4 pack8(const float* f) { u32x4 o; o.x = pk2(f[0], f[1]); o.y = pk2(f[2], f[3]); o.z = pk2(f[4], f[5]); o.w = pk2(f[6], f[7]); return o; }
; __device__ __forceinline__ float siluf_(float x) { return x * __builtin_amdgcn_rcpf(1.f + __expf(-x)); }
; template <int CTRL> __device__ __forceinline__ float dppf(float v) { return __builtin_bit_cast(float, __builtin_amdgcn_update_dpp(0, __builtin_bit_cast(int, v), CTRL, 0xF, 0xF, true)); }
; __device__ __forceinline__ void gdn_post(const Ctx& c, const Params& p, int e) {
;     ...
;         for (int k = 0; k < 4; ++k) unpack8(*(const u32x4*)(yo + 8 * k), ov + 8 * k);
; #pragma unroll
;         for (int k = 0; k < 32; ++k) ss += ov[k] * ov[k];
;         ss += dppf<0xB1>(ss); ss += dppf<0x4E>(ss);
;         const float rn = rsqrtf(ss * (1.f / 128.f) + 1e-6f);
; #pragma unroll
;         for (int k = 0; k < 4; ++k) { float gz[8], out[8]; unpack8(*(const u32x4*)(zg + 8 * k), gz);
; #pragma unroll
;             for (int i = 0; i < 8; ++i) out[i] = ov[8 * k + i] * rn * on[8 * k + i] * siluf_(gz[i]);
;             *(u32x4*)(yo + 8 * k) = pack8(out); } }
	v_lshlrev_b32_e32 v20, 16, v46
	v_and_b32_e32 v21, 0xffff0000, v46
	v_lshlrev_b32_e32 v28, 16, v47
	v_and_b32_e32 v29, 0xffff0000, v47
	v_lshlrev_b32_e32 v38, 16, v48
	v_and_b32_e32 v39, 0xffff0000, v48
	v_lshlrev_b32_e32 v40, 16, v49
	v_and_b32_e32 v41, 0xffff0000, v49
	v_mul_f32_e32 v42, 0xbfb8aa3b, v20
	v_mul_f32_e32 v43, 0xbfb8aa3b, v21
	v_mul_f32_e32 v44, 0xbfb8aa3b, v28
	v_mul_f32_e32 v45, 0xbfb8aa3b, v29
	v_mul_f32_e32 v46, 0xbfb8aa3b, v38
	v_mul_f32_e32 v47, 0xbfb8aa3b, v39
	v_mul_f32_e32 v48, 0xbfb8aa3b, v40
	v_mul_f32_e32 v49, 0xbfb8aa3b, v41
	v_exp_f32_e32 v42, v42
	v_exp_f32_e32 v43, v43
	v_exp_f32_e32 v44, v44
	v_exp_f32_e32 v45, v45
	v_exp_f32_e32 v46, v46
	v_exp_f32_e32 v47, v47
	v_exp_f32_e32 v48, v48
	v_exp_f32_e32 v49, v49
	v_add_f32_e32 v42, 1.0, v42
	v_add_f32_e32 v43, 1.0, v43
	v_add_f32_e32 v44, 1.0, v44
	v_add_f32_e32 v45, 1.0, v45
	v_add_f32_e32 v46, 1.0, v46
	v_add_f32_e32 v47, 1.0, v47
	v_add_f32_e32 v48, 1.0, v48
	v_add_f32_e32 v49, 1.0, v49
	v_rcp_f32_e32 v42, v42
	v_rcp_f32_e32 v43, v43
	v_rcp_f32_e32 v44, v44
	v_rcp_f32_e32 v45, v45
	v_rcp_f32_e32 v46, v46
	v_rcp_f32_e32 v47, v47
	v_rcp_f32_e32 v48, v48
	v_rcp_f32_e32 v49, v49
	v_pk_mul_f32 v[20:21], v[42:43], v[20:21]
	v_pk_mul_f32 v[28:29], v[44:45], v[28:29]
	v_pk_mul_f32 v[38:39], v[46:47], v[38:39]
	v_pk_mul_f32 v[40:41], v[48:49], v[40:41]
	s_waitcnt vmcnt(0)
	v_pk_mul_f32 v[2:3], v[2:3], v[36:37]
	v_pk_mul_f32 v[4:5], v[4:5], v[34:35]
	v_pk_mul_f32 v[6:7], v[6:7], v[30:31]
	v_pk_mul_f32 v[8:9], v[8:9], v[26:27]
	v_pk_mul_f32 v[2:3], v[20:21], v[2:3]
	v_pk_mul_f32 v[4:5], v[28:29], v[4:5]
	v_pk_mul_f32 v[6:7], v[38:39], v[6:7]
	v_pk_mul_f32 v[8:9], v[40:41], v[8:9]
	v_cvt_pk_bf16_f32 v2, v2, v3
	v_cvt_pk_bf16_f32 v3, v4, v5
	v_cvt_pk_bf16_f32 v4, v6, v7
	v_cvt_pk_bf16_f32 v5, v8, v9
	global_store_dwordx4 v[14:15], v[2:5], off offset:32
	global_load_dwordx4 v[2:5], v54, s[4:5] offset:96
	s_nop 0
	global_load_dwordx4 v[6:9], v54, s[4:5] offset:112
	v_lshlrev_b32_e32 v20, 16, v10
	v_and_b32_e32 v21, 0xffff0000, v10
	v_lshlrev_b32_e32 v10, 16, v11
	v_and_b32_e32 v11, 0xffff0000, v11
	v_lshlrev_b32_e32 v26, 16, v12
	v_and_b32_e32 v27, 0xffff0000, v12
	v_lshlrev_b32_e32 v12, 16, v13
	v_and_b32_e32 v13, 0xffff0000, v13
	v_mul_f32_e32 v28, 0xbfb8aa3b, v20
	v_mul_f32_e32 v29, 0xbfb8aa3b, v21
	v_mul_f32_e32 v30, 0xbfb8aa3b, v10
	v_mul_f32_e32 v31, 0xbfb8aa3b, v11
	v_mul_f32_e32 v34, 0xbfb8aa3b, v26
	v_mul_f32_e32 v35, 0xbfb8aa3b, v27
	v_mul_f32_e32 v36, 0xbfb8aa3b, v12
	v_mul_f32_e32 v37, 0xbfb8aa3b, v13
	v_exp_f32_e32 v28, v28
	v_exp_f32_e32 v29, v29
	v_exp_f32_e32 v30, v30
	v_exp_f32_e32 v31, v31
	v_exp_f32_e32 v34, v34
	v_exp_f32_e32 v35, v35
	v_exp_f32_e32 v36, v36
	v_exp_f32_e32 v37, v37
	v_add_f32_e32 v28, 1.0, v28
	v_add_f32_e32 v29, 1.0, v29
	v_add_f32_e32 v30, 1.0, v30
	v_add_f32_e32 v31, 1.0, v31
	v_add_f32_e32 v34, 1.0, v34
	v_add_f32_e32 v35, 1.0, v35
	v_add_f32_e32 v36, 1.0, v36
	v_add_f32_e32 v37, 1.0, v37
	v_rcp_f32_e32 v28, v28
	v_rcp_f32_e32 v29, v29
	v_rcp_f32_e32 v30, v30
	v_rcp_f32_e32 v31, v31
	v_rcp_f32_e32 v34, v34
	v_rcp_f32_e32 v35, v35
	v_rcp_f32_e32 v36, v36
	v_rcp_f32_e32 v37, v37
	v_pk_mul_f32 v[20:21], v[28:29], v[20:21]
	v_pk_mul_f32 v[10:11], v[30:31], v[10:11]
	v_pk_mul_f32 v[26:27], v[34:35], v[26:27]
	v_pk_mul_f32 v[12:13], v[36:37], v[12:13]
	s_waitcnt vmcnt(0)
	v_pk_mul_f32 v[2:3], v[2:3], v[24:25]
	v_pk_mul_f32 v[4:5], v[4:5], v[22:23]
	v_pk_mul_f32 v[6:7], v[6:7], v[16:17] op_sel:[0,1] op_sel_hi:[1,0]
	v_pk_mul_f32 v[8:9], v[8:9], v[18:19] op_sel:[0,1] op_sel_hi:[1,0]
	v_pk_mul_f32 v[2:3], v[20:21], v[2:3]
	v_pk_mul_f32 v[4:5], v[10:11], v[4:5]
	v_pk_mul_f32 v[6:7], v[26:27], v[6:7]
	v_pk_mul_f32 v[8:9], v[12:13], v[8:9]
	v_cvt_pk_bf16_f32 v2, v2, v3
	v_cvt_pk_bf16_f32 v3, v4, v5
	v_cvt_pk_bf16_f32 v4, v6, v7
	v_cvt_pk_bf16_f32 v5, v8, v9
	global_store_dwordx4 v[14:15], v[2:5], off offset:48
	s_andn2_b64 exec, exec, s[6:7]
	s_cbranch_execnz .LBB0_812

; __device__ __forceinline__ unsigned pk2(float lo, float hi) { f32x2 v = {lo, hi}; bf16x2_t b = __builtin_convertvector(v, bf16x2_t); return __builtin_bit_cast(unsigned, b); }
;     __device__ __forceinline__ void operator()(const f32x4 (&acc)[2][2][4][2], const Unit& u, int wr, int wc, int fr, int fq) const {
;     ...
;             for (int m = 0; m < 4; ++m) { bf16_t* rowp = O + (size_t)(row0 + ai * HALF + m * 16) * ldc + col0;
; #pragma unroll
;                 for (int bj = 0; bj < 2; ++bj) { if (col0 + bj * HALF < ncols) { const f32x4 v0 = acc[ai][bj][m][0], v1 = acc[ai][bj][m][1];
;                     u32x4 w; w.x = pk2(v0[0], v0[1]); w.y = pk2(v0[2], v0[3]); w.z = pk2(v1[0], v1[1]); w.w = pk2(v1[2], v1[3]);
;                     *(u32x4*)(rowp + bj * HALF) = w; } } }
.LBB0_829:
	v_lshl_add_u32 v170, s18, 8, v1
	v_lshl_or_b32 v142, s6, 8, v165
	v_mov_b64_e32 v[168:169], s[16:17]
	v_ashrrev_i32_e32 v143, 31, v142
	v_mad_i64_i32 v[168:169], s[2:3], v170, s69, v[168:169]
	s_movk_i32 s0, 0xf10
	v_lshl_add_u64 v[168:169], v[142:143], 1, v[168:169]
	v_cmp_gt_i32_e32 vcc, s0, v142
	s_and_saveexec_b64 s[2:3], vcc
	s_mov_b32 s62, 0xc000
	s_mov_b32 s63, 0x12000
	s_mov_b32 s86, 0x30000
	s_cbranch_execz .LBB0_831
	v_cvt_pk_bf16_f32 v126, v126, v127
	v_cvt_pk_bf16_f32 v127, v128, v129
	v_cvt_pk_bf16_f32 v128, v122, v123
	v_cvt_pk_bf16_f32 v129, v124, v125
	global_store_dwordx4 v[168:169], v[126:129], off

; __device__ __forceinline__ unsigned pk2(float lo, float hi) { f32x2 v = {lo, hi}; bf16x2_t b = __builtin_convertvector(v, bf16x2_t); return __builtin_bit_cast(unsigned, b); }
;     __device__ __forceinline__ void operator()(const f32x4 (&acc)[2][2][4][2], const Unit& u, int wr, int wc, int fr, int fq) const {
;     ...
;             for (int m = 0; m < 4; ++m) { bf16_t* rowp = O + (size_t)(row0 + ai * HALF + m * 16) * ldc + col0;
; #pragma unroll
;                 for (int bj = 0; bj < 2; ++bj) { if (col0 + bj * HALF < ncols) { const f32x4 v0 = acc[ai][bj][m][0], v1 = acc[ai][bj][m][1];
;                     u32x4 w; w.x = pk2(v0[0], v0[1]); w.y = pk2(v0[2], v0[3]); w.z = pk2(v1[0], v1[1]); w.w = pk2(v1[2], v1[3]);
;                     *(u32x4*)(rowp + bj * HALF) = w; } } }
.LBB0_833:
	s_or_b64 exec, exec, s[2:3]
	v_or_b32_e32 v108, 16, v170
	v_mov_b64_e32 v[106:107], s[16:17]
	v_mad_i64_i32 v[106:107], s[2:3], v108, s69, v[106:107]
	v_lshl_add_u64 v[106:107], v[142:143], 1, v[106:107]
	s_and_saveexec_b64 s[2:3], vcc
	s_cbranch_execz .LBB0_835
	v_cvt_pk_bf16_f32 v108, v118, v119
	v_cvt_pk_bf16_f32 v109, v120, v121
	v_cvt_pk_bf16_f32 v110, v110, v111
	v_cvt_pk_bf16_f32 v111, v112, v113
	global_store_dwordx4 v[106:107], v[108:111], off

; __device__ __forceinline__ unsigned pk2(float lo, float hi) { f32x2 v = {lo, hi}; bf16x2_t b = __builtin_convertvector(v, bf16x2_t); return __builtin_bit_cast(unsigned, b); }
;     __device__ __forceinline__ void operator()(const f32x4 (&acc)[2][2][4][2], const Unit& u, int wr, int wc, int fr, int fq) const {
;     ...
;             for (int m = 0; m < 4; ++m) { bf16_t* rowp = O + (size_t)(row0 + ai * HALF + m * 16) * ldc + col0;
; #pragma unroll
;                 for (int bj = 0; bj < 2; ++bj) { if (col0 + bj * HALF < ncols) { const f32x4 v0 = acc[ai][bj][m][0], v1 = acc[ai][bj][m][1];
;                     u32x4 w; w.x = pk2(v0[0], v0[1]); w.y = pk2(v0[2], v0[3]); w.z = pk2(v1[0], v1[1]); w.w = pk2(v1[2], v1[3]);
;                     *(u32x4*)(rowp + bj * HALF) = w; } } }
.LBB0_837:
	s_or_b64 exec, exec, s[2:3]
	v_or_b32_e32 v92, 32, v170
	v_mov_b64_e32 v[90:91], s[16:17]
	v_mad_i64_i32 v[90:91], s[2:3], v92, s69, v[90:91]
	v_lshl_add_u64 v[90:91], v[142:143], 1, v[90:91]
	s_and_saveexec_b64 s[2:3], vcc
	s_cbranch_execz .LBB0_839
	v_cvt_pk_bf16_f32 v92, v102, v103
	v_cvt_pk_bf16_f32 v93, v104, v105
	v_cvt_pk_bf16_f32 v94, v94, v95
	v_cvt_pk_bf16_f32 v95, v96, v97
	global_store_dwordx4 v[90:91], v[92:95], off

; __device__ __forceinline__ unsigned pk2(float lo, float hi) { f32x2 v = {lo, hi}; bf16x2_t b = __builtin_convertvector(v, bf16x2_t); return __builtin_bit_cast(unsigned, b); }
;     __device__ __forceinline__ void operator()(const f32x4 (&acc)[2][2][4][2], const Unit& u, int wr, int wc, int fr, int fq) const {
;     ...
;             for (int m = 0; m < 4; ++m) { bf16_t* rowp = O + (size_t)(row0 + ai * HALF + m * 16) * ldc + col0;
; #pragma unroll
;                 for (int bj = 0; bj < 2; ++bj) { if (col0 + bj * HALF < ncols) { const f32x4 v0 = acc[ai][bj][m][0], v1 = acc[ai][bj][m][1];
;                     u32x4 w; w.x = pk2(v0[0], v0[1]); w.y = pk2(v0[2], v0[3]); w.z = pk2(v1[0], v1[1]); w.w = pk2(v1[2], v1[3]);
;                     *(u32x4*)(rowp + bj * HALF) = w; } } }
.LBB0_841:
	s_or_b64 exec, exec, s[2:3]
	v_or_b32_e32 v76, 48, v170
	v_mov_b64_e32 v[74:75], s[16:17]
	v_mad_i64_i32 v[74:75], s[2:3], v76, s69, v[74:75]
	v_lshl_add_u64 v[74:75], v[142:143], 1, v[74:75]
	s_and_saveexec_b64 s[2:3], vcc
	s_cbranch_execz .LBB0_843
	v_cvt_pk_bf16_f32 v76, v86, v87
	v_cvt_pk_bf16_f32 v77, v88, v89
	v_cvt_pk_bf16_f32 v78, v78, v79
	v_cvt_pk_bf16_f32 v79, v80, v81
	global_store_dwordx4 v[74:75], v[76:79], off

; __device__ __forceinline__ unsigned pk2(float lo, float hi) { f32x2 v = {lo, hi}; bf16x2_t b = __builtin_convertvector(v, bf16x2_t); return __builtin_bit_cast(unsigned, b); }
;     __device__ __forceinline__ void operator()(const f32x4 (&acc)[2][2][4][2], const Unit& u, int wr, int wc, int fr, int fq) const {
;     ...
;             for (int m = 0; m < 4; ++m) { bf16_t* rowp = O + (size_t)(row0 + ai * HALF + m * 16) * ldc + col0;
; #pragma unroll
;                 for (int bj = 0; bj < 2; ++bj) { if (col0 + bj * HALF < ncols) { const f32x4 v0 = acc[ai][bj][m][0], v1 = acc[ai][bj][m][1];
;                     u32x4 w; w.x = pk2(v0[0], v0[1]); w.y = pk2(v0[2], v0[3]); w.z = pk2(v1[0], v1[1]); w.w = pk2(v1[2], v1[3]);
;                     *(u32x4*)(rowp + bj * HALF) = w; } } }
.LBB0_845:
	s_or_b64 exec, exec, s[2:3]
	v_add_u32_e32 v68, 0x80, v170
	v_mov_b64_e32 v[66:67], s[16:17]
	v_mad_i64_i32 v[66:67], s[2:3], v68, s69, v[66:67]
	v_lshl_add_u64 v[66:67], v[142:143], 1, v[66:67]
	s_and_saveexec_b64 s[2:3], vcc
	s_cbranch_execz .LBB0_847
	v_cvt_pk_bf16_f32 v62, v62, v63
	v_cvt_pk_bf16_f32 v63, v64, v65
	v_cvt_pk_bf16_f32 v64, v58, v59
	v_cvt_pk_bf16_f32 v65, v60, v61
	global_store_dwordx4 v[66:67], v[62:65], off

; __device__ __forceinline__ unsigned pk2(float lo, float hi) { f32x2 v = {lo, hi}; bf16x2_t b = __builtin_convertvector(v, bf16x2_t); return __builtin_bit_cast(unsigned, b); }
;     __device__ __forceinline__ void operator()(const f32x4 (&acc)[2][2][4][2], const Unit& u, int wr, int wc, int fr, int fq) const {
;     ...
;             for (int m = 0; m < 4; ++m) { bf16_t* rowp = O + (size_t)(row0 + ai * HALF + m * 16) * ldc + col0;
; #pragma unroll
;                 for (int bj = 0; bj < 2; ++bj) { if (col0 + bj * HALF < ncols) { const f32x4 v0 = acc[ai][bj][m][0], v1 = acc[ai][bj][m][1];
;                     u32x4 w; w.x = pk2(v0[0], v0[1]); w.y = pk2(v0[2], v0[3]); w.z = pk2(v1[0], v1[1]); w.w = pk2(v1[2], v1[3]);
;                     *(u32x4*)(rowp + bj * HALF) = w; } } }
.LBB0_849:
	s_or_b64 exec, exec, s[2:3]
	v_add_u32_e32 v44, 0x90, v170
	v_mov_b64_e32 v[42:43], s[16:17]
	v_mad_i64_i32 v[42:43], s[2:3], v44, s69, v[42:43]
	v_lshl_add_u64 v[42:43], v[142:143], 1, v[42:43]
	s_and_saveexec_b64 s[2:3], vcc
	s_cbranch_execz .LBB0_851
	v_cvt_pk_bf16_f32 v44, v54, v55
	v_cvt_pk_bf16_f32 v45, v56, v57
	v_cvt_pk_bf16_f32 v46, v46, v47
	v_cvt_pk_bf16_f32 v47, v48, v49
	global_store_dwordx4 v[42:43], v[44:47], off

; __device__ __forceinline__ unsigned pk2(float lo, float hi) { f32x2 v = {lo, hi}; bf16x2_t b = __builtin_convertvector(v, bf16x2_t); return __builtin_bit_cast(unsigned, b); }
;     __device__ __forceinline__ void operator()(const f32x4 (&acc)[2][2][4][2], const Unit& u, int wr, int wc, int fr, int fq) const {
;     ...
;             for (int m = 0; m < 4; ++m) { bf16_t* rowp = O + (size_t)(row0 + ai * HALF + m * 16) * ldc + col0;
; #pragma unroll
;                 for (int bj = 0; bj < 2; ++bj) { if (col0 + bj * HALF < ncols) { const f32x4 v0 = acc[ai][bj][m][0], v1 = acc[ai][bj][m][1];
;                     u32x4 w; w.x = pk2(v0[0], v0[1]); w.y = pk2(v0[2], v0[3]); w.z = pk2(v1[0], v1[1]); w.w = pk2(v1[2], v1[3]);
;                     *(u32x4*)(rowp + bj * HALF) = w; } } }
.LBB0_853:
	s_or_b64 exec, exec, s[2:3]
	v_add_u32_e32 v28, 0xa0, v170
	v_mov_b64_e32 v[26:27], s[16:17]
	v_mad_i64_i32 v[26:27], s[2:3], v28, s69, v[26:27]
	v_lshl_add_u64 v[26:27], v[142:143], 1, v[26:27]
	s_and_saveexec_b64 s[2:3], vcc
	s_cbranch_execz .LBB0_855
	v_cvt_pk_bf16_f32 v28, v38, v39
	v_cvt_pk_bf16_f32 v29, v40, v41
	v_cvt_pk_bf16_f32 v30, v30, v31
	v_cvt_pk_bf16_f32 v31, v32, v33
	global_store_dwordx4 v[26:27], v[28:31], off

; __device__ __forceinline__ unsigned pk2(float lo, float hi) { f32x2 v = {lo, hi}; bf16x2_t b = __builtin_convertvector(v, bf16x2_t); return __builtin_bit_cast(unsigned, b); }
;     __device__ __forceinline__ void operator()(const f32x4 (&acc)[2][2][4][2], const Unit& u, int wr, int wc, int fr, int fq) const {
;     ...
;             for (int m = 0; m < 4; ++m) { bf16_t* rowp = O + (size_t)(row0 + ai * HALF + m * 16) * ldc + col0;
; #pragma unroll
;                 for (int bj = 0; bj < 2; ++bj) { if (col0 + bj * HALF < ncols) { const f32x4 v0 = acc[ai][bj][m][0], v1 = acc[ai][bj][m][1];
;                     u32x4 w; w.x = pk2(v0[0], v0[1]); w.y = pk2(v0[2], v0[3]); w.z = pk2(v1[0], v1[1]); w.w = pk2(v1[2], v1[3]);
;                     *(u32x4*)(rowp + bj * HALF) = w; } } }
.LBB0_857:
	s_or_b64 exec, exec, s[2:3]
	v_add_u32_e32 v12, 0xb0, v170
	v_mov_b64_e32 v[10:11], s[16:17]
	v_mad_i64_i32 v[10:11], s[2:3], v12, s69, v[10:11]
	v_lshl_add_u64 v[10:11], v[142:143], 1, v[10:11]
	s_and_saveexec_b64 s[2:3], vcc
	s_cbranch_execz .LBB0_860
	v_cvt_pk_bf16_f32 v12, v22, v23
	v_cvt_pk_bf16_f32 v13, v24, v25
	v_cvt_pk_bf16_f32 v14, v14, v15
	v_cvt_pk_bf16_f32 v15, v16, v17
	global_store_dwordx4 v[10:11], v[12:15], off
	s_or_b64 exec, exec, s[2:3]
	s_and_saveexec_b64 s[2:3], s[6:7]
	s_cbranch_execnz .LBB0_861

; __device__ __forceinline__ unsigned pk2(float lo, float hi) { f32x2 v = {lo, hi}; bf16x2_t b = __builtin_convertvector(v, bf16x2_t); return __builtin_bit_cast(unsigned, b); }
;     __device__ __forceinline__ void operator()(const f32x4 (&acc)[2][2][4][2], const Unit& u, int wr, int wc, int fr, int fq) const {
;     ...
;             for (int m = 0; m < 4; ++m) { bf16_t* rowp = O + (size_t)(row0 + ai * HALF + m * 16) * ldc + col0;
; #pragma unroll
;                 for (int bj = 0; bj < 2; ++bj) { if (col0 + bj * HALF < ncols) { const f32x4 v0 = acc[ai][bj][m][0], v1 = acc[ai][bj][m][1];
;                     u32x4 w; w.x = pk2(v0[0], v0[1]); w.y = pk2(v0[2], v0[3]); w.z = pk2(v1[0], v1[1]); w.w = pk2(v1[2], v1[3]);
;                     *(u32x4*)(rowp + bj * HALF) = w; } } }
.LBB0_861:
	v_cvt_pk_bf16_f32 v6, v6, v7
	v_cvt_pk_bf16_f32 v7, v8, v9
	v_cvt_pk_bf16_f32 v8, v2, v3
	v_cvt_pk_bf16_f32 v9, v4, v5
	global_store_dwordx4 v[10:11], v[6:9], off offset:256
	s_or_b64 exec, exec, s[2:3]
	s_andn2_b64 vcc, exec, s[4:5]
	s_mov_b64 s[2:3], -1
	s_cbranch_vccnz .LBB0_822

;     __device__ __forceinline__ void operator()(const f32x4 (&acc)[2][2][4][2], const Unit& u, int wr, int wc, int fr, int fq) const {
;     ...
;             for (int m = 0; m < 4; ++m) { float* rowp = out + (size_t)(row0 + ai * HALF + m * 16) * ldc + col0;
; #pragma unroll
;                 for (int bj = 0; bj < 2; ++bj)
; #pragma unroll
;                     for (int n = 0; n < 2; ++n) { f32x4* q = (f32x4*)(rowp + bj * HALF + n * 16); *q = *q + acc[ai][bj][m][n]; }
;                 asm volatile("" ::: "memory"); }
.LBB0_887:
	v_lshl_add_u32 v140, s18, 8, v1
	v_lshl_or_b32 v138, s46, 8, v165
	v_ashrrev_i32_e32 v141, 31, v140
	v_ashrrev_i32_e32 v139, 31, v138
	v_lshlrev_b64 v[142:143], 12, v[140:141]
	v_lshl_add_u64 v[168:169], s[66:67], 0, v[142:143]
	v_lshlrev_b64 v[142:143], 2, v[138:139]
	v_lshl_add_u64 v[138:139], v[168:169], 0, v[142:143]
	global_load_dwordx4 v[168:171], v[138:139], off
	s_mov_b32 s0, 0x80000
	s_mov_b64 s[2:3], 0x80000
	s_mov_b32 s62, 0xc000
	s_mov_b32 s63, 0x12000
	s_mov_b32 s86, 0x30000
	s_waitcnt vmcnt(0) lgkmcnt(0)
	v_pk_add_f32 v[128:129], v[128:129], v[170:171]
	v_pk_add_f32 v[126:127], v[126:127], v[168:169]
	global_store_dwordx4 v[138:139], v[126:129], off
	global_load_dwordx4 v[126:129], v[138:139], off offset:64
	s_waitcnt vmcnt(0) lgkmcnt(0)
	v_pk_add_f32 v[124:125], v[124:125], v[128:129]
	v_pk_add_f32 v[122:123], v[122:123], v[126:127]
	global_store_dwordx4 v[138:139], v[122:125], off offset:64
	global_load_dwordx4 v[122:125], v[138:139], off offset:512
	s_waitcnt vmcnt(0) lgkmcnt(0)
	v_pk_add_f32 v[120:121], v[120:121], v[124:125]
	v_pk_add_f32 v[118:119], v[118:119], v[122:123]
	global_store_dwordx4 v[138:139], v[118:121], off offset:512
	global_load_dwordx4 v[118:121], v[138:139], off offset:576
	s_waitcnt vmcnt(0) lgkmcnt(0)
	v_pk_add_f32 v[116:117], v[116:117], v[120:121]
	v_pk_add_f32 v[114:115], v[114:115], v[118:119]
	global_store_dwordx4 v[138:139], v[114:117], off offset:576
	s_nop 1
	v_or_b32_e32 v114, 16, v140
	v_ashrrev_i32_e32 v115, 31, v114
	v_lshlrev_b64 v[114:115], 12, v[114:115]
	v_lshl_add_u64 v[114:115], s[66:67], 0, v[114:115]
	v_lshl_add_u64 v[118:119], v[114:115], 0, v[142:143]
	global_load_dwordx4 v[114:117], v[118:119], off
	s_waitcnt vmcnt(0) lgkmcnt(0)
	v_pk_add_f32 v[112:113], v[112:113], v[116:117]
	v_pk_add_f32 v[110:111], v[110:111], v[114:115]
	global_store_dwordx4 v[118:119], v[110:113], off
	global_load_dwordx4 v[110:113], v[118:119], off offset:64
	s_waitcnt vmcnt(0) lgkmcnt(0)
	v_pk_add_f32 v[108:109], v[108:109], v[112:113]
	v_pk_add_f32 v[106:107], v[106:107], v[110:111]
	global_store_dwordx4 v[118:119], v[106:109], off offset:64
	global_load_dwordx4 v[106:109], v[118:119], off offset:512
	s_waitcnt vmcnt(0) lgkmcnt(0)
	v_pk_add_f32 v[104:105], v[104:105], v[108:109]
	v_pk_add_f32 v[102:103], v[102:103], v[106:107]
	global_store_dwordx4 v[118:119], v[102:105], off offset:512
	global_load_dwordx4 v[102:105], v[118:119], off offset:576
	s_waitcnt vmcnt(0) lgkmcnt(0)
	v_pk_add_f32 v[100:101], v[100:101], v[104:105]
	v_pk_add_f32 v[98:99], v[98:99], v[102:103]
	global_store_dwordx4 v[118:119], v[98:101], off offset:576
	s_nop 1
	v_or_b32_e32 v98, 32, v140
	v_ashrrev_i32_e32 v99, 31, v98
	v_lshlrev_b64 v[98:99], 12, v[98:99]
	v_lshl_add_u64 v[98:99], s[66:67], 0, v[98:99]
	v_lshl_add_u64 v[102:103], v[98:99], 0, v[142:143]
	global_load_dwordx4 v[98:101], v[102:103], off
	s_waitcnt vmcnt(0) lgkmcnt(0)
	v_pk_add_f32 v[96:97], v[96:97], v[100:101]
	v_pk_add_f32 v[94:95], v[94:95], v[98:99]
	global_store_dwordx4 v[102:103], v[94:97], off
	global_load_dwordx4 v[94:97], v[102:103], off offset:64
	s_waitcnt vmcnt(0) lgkmcnt(0)
	v_pk_add_f32 v[92:93], v[92:93], v[96:97]
	v_pk_add_f32 v[90:91], v[90:91], v[94:95]
	global_store_dwordx4 v[102:103], v[90:93], off offset:64
	global_load_dwordx4 v[90:93], v[102:103], off offset:512
	s_waitcnt vmcnt(0) lgkmcnt(0)
	v_pk_add_f32 v[88:89], v[88:89], v[92:93]
	v_pk_add_f32 v[86:87], v[86:87], v[90:91]
	global_store_dwordx4 v[102:103], v[86:89], off offset:512
	global_load_dwordx4 v[86:89], v[102:103], off offset:576
	s_waitcnt vmcnt(0) lgkmcnt(0)
	v_pk_add_f32 v[84:85], v[84:85], v[88:89]
	v_pk_add_f32 v[82:83], v[82:83], v[86:87]
	global_store_dwordx4 v[102:103], v[82:85], off offset:576
	s_nop 1
	v_or_b32_e32 v82, 48, v140
	v_ashrrev_i32_e32 v83, 31, v82
	v_lshlrev_b64 v[82:83], 12, v[82:83]
	v_lshl_add_u64 v[82:83], s[66:67], 0, v[82:83]
	v_lshl_add_u64 v[86:87], v[82:83], 0, v[142:143]
	global_load_dwordx4 v[82:85], v[86:87], off
	s_waitcnt vmcnt(0) lgkmcnt(0)
	v_pk_add_f32 v[80:81], v[80:81], v[84:85]
	v_pk_add_f32 v[78:79], v[78:79], v[82:83]
	global_store_dwordx4 v[86:87], v[78:81], off
	global_load_dwordx4 v[78:81], v[86:87], off offset:64
	s_waitcnt vmcnt(0) lgkmcnt(0)
	v_pk_add_f32 v[76:77], v[76:77], v[80:81]
	v_pk_add_f32 v[74:75], v[74:75], v[78:79]
	global_store_dwordx4 v[86:87], v[74:77], off offset:64
	global_load_dwordx4 v[74:77], v[86:87], off offset:512
	s_waitcnt vmcnt(0) lgkmcnt(0)
	v_pk_add_f32 v[72:73], v[72:73], v[76:77]
	v_pk_add_f32 v[70:71], v[70:71], v[74:75]
	global_store_dwordx4 v[86:87], v[70:73], off offset:512
	global_load_dwordx4 v[70:73], v[86:87], off offset:576
	s_waitcnt vmcnt(0) lgkmcnt(0)
;     __device__ __forceinline__ void operator()(const f32x4 (&acc)[2][2][4][2], const Unit& u, int wr, int wc, int fr, int fq) const {
;     ...
;             for (int m = 0; m < 4; ++m) { float* rowp = out + (size_t)(row0 + ai * HALF + m * 16) * ldc + col0;
; #pragma unroll
;                 for (int bj = 0; bj < 2; ++bj)
; #pragma unroll
;                     for (int n = 0; n < 2; ++n) { f32x4* q = (f32x4*)(rowp + bj * HALF + n * 16); *q = *q + acc[ai][bj][m][n]; }
;                 asm volatile("" ::: "memory"); }
	v_pk_add_f32 v[68:69], v[68:69], v[72:73]
	v_pk_add_f32 v[66:67], v[66:67], v[70:71]
	global_store_dwordx4 v[86:87], v[66:69], off offset:576
	v_add_co_u32_e32 v72, vcc, s0, v138
	v_lshl_add_u64 v[70:71], v[138:139], 0, s[2:3]
	s_nop 0
	v_addc_co_u32_e32 v73, vcc, 0, v139, vcc
	global_load_dwordx4 v[66:69], v[72:73], off
	s_mov_b32 s0, 0x90000
	s_mov_b64 s[2:3], 0x90000
	s_waitcnt vmcnt(0) lgkmcnt(0)
	v_pk_add_f32 v[64:65], v[64:65], v[68:69]
	v_pk_add_f32 v[62:63], v[62:63], v[66:67]
	global_store_dwordx4 v[72:73], v[62:65], off
	global_load_dwordx4 v[62:65], v[70:71], off offset:64
	s_waitcnt vmcnt(0) lgkmcnt(0)
	v_pk_add_f32 v[60:61], v[60:61], v[64:65]
	v_pk_add_f32 v[58:59], v[58:59], v[62:63]
	global_store_dwordx4 v[70:71], v[58:61], off offset:64
	global_load_dwordx4 v[58:61], v[70:71], off offset:512
	s_waitcnt vmcnt(0) lgkmcnt(0)
	v_pk_add_f32 v[56:57], v[56:57], v[60:61]
	v_pk_add_f32 v[54:55], v[54:55], v[58:59]
	global_store_dwordx4 v[70:71], v[54:57], off offset:512
	global_load_dwordx4 v[54:57], v[70:71], off offset:576
	s_waitcnt vmcnt(0) lgkmcnt(0)
	v_pk_add_f32 v[52:53], v[52:53], v[56:57]
	v_pk_add_f32 v[50:51], v[50:51], v[54:55]
	global_store_dwordx4 v[70:71], v[50:53], off offset:576
	v_add_co_u32_e32 v56, vcc, s0, v138
	v_lshl_add_u64 v[54:55], v[138:139], 0, s[2:3]
	s_nop 0
	v_addc_co_u32_e32 v57, vcc, 0, v139, vcc
	global_load_dwordx4 v[50:53], v[56:57], off
	s_mov_b32 s0, 0xa0000
	s_mov_b64 s[2:3], 0xa0000
	s_waitcnt vmcnt(0) lgkmcnt(0)
	v_pk_add_f32 v[48:49], v[48:49], v[52:53]
	v_pk_add_f32 v[46:47], v[46:47], v[50:51]
	global_store_dwordx4 v[56:57], v[46:49], off
	global_load_dwordx4 v[46:49], v[54:55], off offset:64
	s_waitcnt vmcnt(0) lgkmcnt(0)
	v_pk_add_f32 v[44:45], v[44:45], v[48:49]
	v_pk_add_f32 v[42:43], v[42:43], v[46:47]
	global_store_dwordx4 v[54:55], v[42:45], off offset:64
	global_load_dwordx4 v[42:45], v[54:55], off offset:512
	s_waitcnt vmcnt(0) lgkmcnt(0)
	v_pk_add_f32 v[40:41], v[40:41], v[44:45]
	v_pk_add_f32 v[38:39], v[38:39], v[42:43]
	global_store_dwordx4 v[54:55], v[38:41], off offset:512
	global_load_dwordx4 v[38:41], v[54:55], off offset:576
	s_waitcnt vmcnt(0) lgkmcnt(0)
	v_pk_add_f32 v[36:37], v[36:37], v[40:41]
	v_pk_add_f32 v[34:35], v[34:35], v[38:39]
	global_store_dwordx4 v[54:55], v[34:37], off offset:576
	v_add_co_u32_e32 v40, vcc, s0, v138
	v_lshl_add_u64 v[38:39], v[138:139], 0, s[2:3]
	s_nop 0
	v_addc_co_u32_e32 v41, vcc, 0, v139, vcc
	global_load_dwordx4 v[34:37], v[40:41], off
	s_mov_b32 s0, 0xb0000
	s_mov_b64 s[2:3], 0xb0000
	s_waitcnt vmcnt(0) lgkmcnt(0)
	v_pk_add_f32 v[32:33], v[32:33], v[36:37]
	v_pk_add_f32 v[30:31], v[30:31], v[34:35]
	global_store_dwordx4 v[40:41], v[30:33], off
	global_load_dwordx4 v[30:33], v[38:39], off offset:64
	s_waitcnt vmcnt(0) lgkmcnt(0)
	v_pk_add_f32 v[28:29], v[28:29], v[32:33]
	v_pk_add_f32 v[26:27], v[26:27], v[30:31]
	global_store_dwordx4 v[38:39], v[26:29], off offset:64
	global_load_dwordx4 v[26:29], v[38:39], off offset:512
	s_waitcnt vmcnt(0) lgkmcnt(0)
	v_pk_add_f32 v[24:25], v[24:25], v[28:29]
	v_pk_add_f32 v[22:23], v[22:23], v[26:27]
	global_store_dwordx4 v[38:39], v[22:25], off offset:512
	global_load_dwordx4 v[22:25], v[38:39], off offset:576
	s_waitcnt vmcnt(0) lgkmcnt(0)
	v_pk_add_f32 v[20:21], v[20:21], v[24:25]
	v_pk_add_f32 v[18:19], v[18:19], v[22:23]
	global_store_dwordx4 v[38:39], v[18:21], off offset:576
	v_add_co_u32_e32 v24, vcc, s0, v138
	v_lshl_add_u64 v[22:23], v[138:139], 0, s[2:3]
	s_nop 0
	v_addc_co_u32_e32 v25, vcc, 0, v139, vcc
	global_load_dwordx4 v[18:21], v[24:25], off
	s_mov_b64 s[2:3], -1
	s_andn2_b64 vcc, exec, s[4:5]
	s_waitcnt vmcnt(0) lgkmcnt(0)
	v_pk_add_f32 v[16:17], v[16:17], v[20:21]
	v_pk_add_f32 v[14:15], v[14:15], v[18:19]
	global_store_dwordx4 v[24:25], v[14:17], off
	global_load_dwordx4 v[14:17], v[22:23], off offset:64
	s_waitcnt vmcnt(0) lgkmcnt(0)
	v_pk_add_f32 v[12:13], v[12:13], v[16:17]
	v_pk_add_f32 v[10:11], v[10:11], v[14:15]
	global_store_dwordx4 v[22:23], v[10:13], off offset:64
	global_load_dwordx4 v[10:13], v[22:23], off offset:512
	s_waitcnt vmcnt(0) lgkmcnt(0)
	v_pk_add_f32 v[8:9], v[8:9], v[12:13]
	v_pk_add_f32 v[6:7], v[6:7], v[10:11]
	global_store_dwordx4 v[22:23], v[6:9], off offset:512
	global_load_dwordx4 v[6:9], v[22:23], off offset:576
	s_waitcnt vmcnt(0) lgkmcnt(0)
	v_pk_add_f32 v[4:5], v[4:5], v[8:9]
	v_pk_add_f32 v[2:3], v[2:3], v[6:7]
	global_store_dwordx4 v[22:23], v[2:5], off offset:576
	s_cbranch_vccnz .LBB0_876
	s_andn2_b64 vcc, exec, s[6:7]
	s_cbranch_vccnz .LBB0_875
	s_barrier
	s_branch .LBB0_875

; __device__ __forceinline__ void tr_item(const float* src, int ld, int kv, int nv, const float* ks, bf16_t* dst, int ldd, LAS float* scr, int lane) {
;     ...
;         float tmp[32]; const float* sp = src + (size_t)(lane >> 5) * ld + n;
; #pragma unroll
;         for (int i = 0; i < 32; ++i) tmp[i] = sp[(size_t)(2 * i) * ld];
; __device__ __forceinline__ void convert_common(const Ctx& c, const Params& p, int L, const float* wout_src) {
;     ...
;       for (int it = c.gw; it < items; it += c.ngw) { const int kb = it / nnb, nb = it % nnb, k0 = 64 * kb, n0 = 32 * nb; const int t = n0 >> 8, w = n0 & 255;
;           const int sc = (w < 128) ? 128 * t + w : DFF + 128 * t + (w - 128);
;           tr_item(src + (size_t)k0 * (2 * DFF) + sc, 2 * DFF, 64, 32, nullptr, dst + (size_t)n0 * D_ + k0, D_, scr, c.lane); } }
.LBB0_900:
	s_mul_hi_i32 s4, s18, 0x2e8ba2e9
	s_lshr_b32 s5, s4, 31
	s_ashr_i32 s4, s4, 5
	s_add_i32 s5, s4, s5
	s_mul_i32 s10, s5, 0xffffea00
	s_mul_i32 s11, s5, 0xfffff500
	s_lshl_b32 s4, s5, 6
	s_mul_i32 s19, s5, 0x160000
	s_add_i32 s10, s14, s10
	s_add_i32 s5, s16, s11
	s_and_b32 s20, s10, 0xe0
	s_and_b32 s5, s5, 0xffffff80
	s_or_b32 s21, s5, s20
	s_add_i32 s5, s20, s5
	s_addk_i32 s5, 0xa80
	s_cmpk_lt_u32 s20, 0x80
	s_cselect_b32 s20, s21, s5
	s_ashr_i32 s5, s4, 31
	s_mul_hi_i32 s11, s4, 0x5800
	s_add_u32 s19, s12, s19
	s_addc_u32 s11, s13, s11
	s_ashr_i32 s21, s20, 31
	s_lshl_b64 s[20:21], s[20:21], 2
	s_add_u32 s20, s19, s20
	s_addc_u32 s21, s11, s21
	v_mov_b32_e32 v13, v0
	v_lshl_add_u64 v[18:19], s[20:21], 0, v[2:3]
	v_lshl_add_u64 v[18:19], v[18:19], 0, v[12:13]
	v_add_co_u32_e32 v20, vcc, s0, v18
	s_ashr_i32 s11, s10, 31
	s_nop 0
	v_addc_co_u32_e32 v21, vcc, 0, v19, vcc
	v_add_co_u32_e32 v22, vcc, s61, v18
	s_lshl_b64 s[10:11], s[10:11], 11
	s_nop 0
	v_addc_co_u32_e32 v23, vcc, 0, v19, vcc
	v_add_co_u32_e32 v24, vcc, s25, v18
	s_add_u32 s10, s71, s10
	s_nop 0
	v_addc_co_u32_e32 v25, vcc, 0, v19, vcc
	v_add_co_u32_e32 v26, vcc, s68, v18
	s_addc_u32 s11, s60, s11
	s_nop 0
	v_addc_co_u32_e32 v27, vcc, 0, v19, vcc
	v_add_co_u32_e32 v28, vcc, s40, v18
	s_lshl_b64 s[4:5], s[4:5], 1
	s_nop 0
	v_addc_co_u32_e32 v29, vcc, 0, v19, vcc
	v_add_co_u32_e32 v30, vcc, s29, v18
	s_add_u32 s4, s10, s4
	s_nop 0
	v_addc_co_u32_e32 v31, vcc, 0, v19, vcc
	v_add_co_u32_e32 v32, vcc, s31, v18
	v_mov_b32_e32 v15, v0
	s_nop 0
	v_addc_co_u32_e32 v33, vcc, 0, v19, vcc
	v_add_co_u32_e32 v34, vcc, s34, v18
	s_addc_u32 s5, s11, s5
	s_nop 0
	v_addc_co_u32_e32 v35, vcc, 0, v19, vcc
	v_add_co_u32_e32 v36, vcc, s35, v18
	s_add_i32 s18, s18, s30
	s_nop 0
	v_addc_co_u32_e32 v37, vcc, 0, v19, vcc
	v_add_co_u32_e32 v38, vcc, s36, v18
	s_add_i32 s14, s14, s15
	s_nop 0
	v_addc_co_u32_e32 v39, vcc, 0, v19, vcc
	v_add_co_u32_e32 v40, vcc, s42, v18
	s_add_i32 s16, s16, s17
	s_nop 0
	v_addc_co_u32_e32 v41, vcc, 0, v19, vcc
	v_add_co_u32_e32 v42, vcc, s38, v18
	s_cmpk_gt_i32 s18, 0xaff
	s_nop 0
	v_addc_co_u32_e32 v43, vcc, 0, v19, vcc
	v_add_co_u32_e32 v44, vcc, s39, v18
	s_nop 1
	v_addc_co_u32_e32 v45, vcc, 0, v19, vcc
	v_add_co_u32_e32 v46, vcc, s44, v18
	s_nop 1
	v_addc_co_u32_e32 v47, vcc, 0, v19, vcc
	v_add_co_u32_e32 v48, vcc, s45, v18
	s_nop 1
	v_addc_co_u32_e32 v49, vcc, 0, v19, vcc
	v_add_co_u32_e32 v50, vcc, s24, v18
	s_nop 1
	v_addc_co_u32_e32 v51, vcc, 0, v19, vcc
	v_add_co_u32_e32 v52, vcc, s46, v18
	s_nop 1
	v_addc_co_u32_e32 v53, vcc, 0, v19, vcc
	v_add_co_u32_e32 v54, vcc, s48, v18
	s_nop 1
	v_addc_co_u32_e32 v55, vcc, 0, v19, vcc
	v_add_co_u32_e32 v56, vcc, s49, v18
	s_nop 1
	v_addc_co_u32_e32 v57, vcc, 0, v19, vcc
	v_add_co_u32_e32 v58, vcc, s58, v18
	s_nop 1
	v_addc_co_u32_e32 v59, vcc, 0, v19, vcc
	v_add_co_u32_e32 v60, vcc, s59, v18
	s_nop 1
	v_addc_co_u32_e32 v61, vcc, 0, v19, vcc
	v_add_co_u32_e32 v62, vcc, s72, v18
	s_nop 1
	v_addc_co_u32_e32 v63, vcc, 0, v19, vcc
	v_add_co_u32_e32 v64, vcc, s73, v18
	s_nop 1
	v_addc_co_u32_e32 v65, vcc, 0, v19, vcc
	v_add_co_u32_e32 v66, vcc, s80, v18
	s_nop 1
	v_addc_co_u32_e32 v67, vcc, 0, v19, vcc
	v_add_co_u32_e32 v68, vcc, s81, v18
	s_nop 1
	v_addc_co_u32_e32 v69, vcc, 0, v19, vcc
	v_add_co_u32_e32 v70, vcc, s82, v18
	s_nop 1
	v_addc_co_u32_e32 v71, vcc, 0, v19, vcc
	v_add_co_u32_e32 v72, vcc, s83, v18
	s_nop 1
	v_addc_co_u32_e32 v73, vcc, 0, v19, vcc
	v_add_co_u32_e32 v74, vcc, s84, v18
	s_nop 1
	v_addc_co_u32_e32 v75, vcc, 0, v19, vcc
	v_add_co_u32_e32 v76, vcc, s85, v18
	s_nop 1
	v_addc_co_u32_e32 v77, vcc, 0, v19, vcc
	v_add_co_u32_e32 v78, vcc, s87, v18
	s_nop 1
	v_addc_co_u32_e32 v79, vcc, 0, v19, vcc
	v_add_co_u32_e32 v80, vcc, s92, v18
	s_nop 1
	v_addc_co_u32_e32 v81, vcc, 0, v19, vcc
	global_load_dword v13, v[18:19], off
	global_load_dword v17, v[20:21], off
	s_nop 0
	global_load_dword v18, v[22:23], off
	global_load_dword v19, v[24:25], off
	global_load_dword v20, v[26:27], off
	global_load_dword v21, v[28:29], off
	s_nop 0
	global_load_dword v30, v[30:31], off
	s_nop 0
	global_load_dword v31, v[32:33], off
	s_nop 0
	global_load_dword v32, v[34:35], off
	global_load_dword v33, v[36:37], off
	s_nop 0
	global_load_dword v34, v[38:39], off
	global_load_dword v35, v[40:41], off
	global_load_dword v36, v[42:43], off
	global_load_dword v37, v[44:45], off
	s_nop 0
	global_load_dword v38, v[46:47], off
	global_load_dword v39, v[48:49], off
	global_load_dword v40, v[50:51], off
	global_load_dword v41, v[52:53], off
	global_load_dword v42, v[54:55], off
	global_load_dword v43, v[56:57], off
	global_load_dword v44, v[58:59], off
	global_load_dword v45, v[60:61], off
	global_load_dword v46, v[62:63], off
	global_load_dword v47, v[64:65], off
	global_load_dword v48, v[66:67], off
	global_load_dword v49, v[68:69], off
	global_load_dword v50, v[70:71], off
	global_load_dword v51, v[72:73], off
	global_load_dword v52, v[74:75], off
	global_load_dword v53, v[76:77], off
	global_load_dword v54, v[78:79], off
	global_load_dword v55, v[80:81], off
	v_add_u32_e32 v56, 0x400, v16
	v_add_u32_e32 v57, 0x800, v16
	v_add_u32_e32 v58, 0xc00, v16
	v_add_u32_e32 v59, 0x1000, v16
	v_add_u32_e32 v60, 0x1400, v16
	v_add_u32_e32 v61, 0x1800, v16
	v_add_u32_e32 v62, 0x1c00, v16
	s_waitcnt vmcnt(0)
; #define LAS __attribute__((address_space(3)))
; __device__ __forceinline__ unsigned pk2(float lo, float hi) { f32x2 v = {lo, hi}; bf16x2_t b = __builtin_convertvector(v, bf16x2_t); return __builtin_bit_cast(unsigned, b); }
; #define LDS_WAIT() asm volatile("s_waitcnt lgkmcnt(0)" ::: "memory")
; __device__ __forceinline__ void tr_item(const float* src, int ld, int kv, int nv, const float* ks, bf16_t* dst, int ldd, LAS float* scr, int lane) {
;     ...
;         for (int i = 0; i < 32; ++i) scr[(2 * i + (lane >> 5)) * 33 + n] = tmp[i];
;     } else {
; #pragma unroll 4
;         for (int i = 0; i < 32; ++i) { const int kk = 2 * i + (lane >> 5); float v = 0.f; if (kk < kv && n < nv) { v = src[(size_t)kk * ld + n]; if (ks) v *= ks[kk]; } scr[kk * 33 + n] = v; }
;     }
;     LDS_WAIT(); asm volatile("" ::: "memory");
;     const int c = lane & 7;
; #pragma unroll
;     for (int j = 0; j < 4; ++j) { const int nn = (lane >> 3) + 8 * j; const LAS float* s = scr + (8 * c) * 33 + nn;
;         u32x4 o; o.x = pk2(s[0 * 33], s[1 * 33]); o.y = pk2(s[2 * 33], s[3 * 33]); o.z = pk2(s[4 * 33], s[5 * 33]); o.w = pk2(s[6 * 33], s[7 * 33]);
;         *(u32x4*)(dst + (size_t)nn * ldd + 8 * c) = o; }
;     LDS_WAIT(); asm volatile("" ::: "memory");
	ds_write2_b32 v16, v13, v17 offset1:66
	s_waitcnt vmcnt(28)
	ds_write2_b32 v16, v18, v19 offset0:132 offset1:198
	s_waitcnt vmcnt(26)
	ds_write2_b32 v56, v20, v21 offset0:8 offset1:74
	s_waitcnt vmcnt(24)
	ds_write2_b32 v56, v30, v31 offset0:140 offset1:206
	s_waitcnt vmcnt(22)
	ds_write2_b32 v57, v32, v33 offset0:16 offset1:82
	s_waitcnt vmcnt(20)
	ds_write2_b32 v57, v34, v35 offset0:148 offset1:214
	s_waitcnt vmcnt(18)
	ds_write2_b32 v58, v36, v37 offset0:24 offset1:90
	s_waitcnt vmcnt(16)
	ds_write2_b32 v58, v38, v39 offset0:156 offset1:222
	s_waitcnt vmcnt(14)
	ds_write2_b32 v59, v40, v41 offset0:32 offset1:98
	s_waitcnt vmcnt(12)
	ds_write2_b32 v59, v42, v43 offset0:164 offset1:230
	s_waitcnt vmcnt(10)
	ds_write2_b32 v60, v44, v45 offset0:40 offset1:106
	s_waitcnt vmcnt(8)
	ds_write2_b32 v60, v46, v47 offset0:172 offset1:238
	s_waitcnt vmcnt(6)
	ds_write2_b32 v61, v48, v49 offset0:48 offset1:114
	s_waitcnt vmcnt(4)
	ds_write2_b32 v61, v50, v51 offset0:180 offset1:246
	s_waitcnt vmcnt(2)
	ds_write2_b32 v62, v52, v53 offset0:56 offset1:122
	s_waitcnt vmcnt(0)
	ds_write2_b32 v62, v54, v55 offset0:188 offset1:254
	s_waitcnt lgkmcnt(0)
	v_lshl_add_u64 v[22:23], s[4:5], 0, v[14:15]
	ds_read_b32 v13, v1
	ds_read_b32 v15, v1 offset:132
	ds_read_b32 v17, v1 offset:264
	ds_read_b32 v19, v1 offset:396
	ds_read_b32 v20, v1 offset:528
	ds_read_b32 v21, v1 offset:660
	ds_read_b32 v30, v1 offset:792
	ds_read_b32 v31, v1 offset:924
	v_lshl_add_u64 v[24:25], v[22:23], 0, v[4:5]
	s_waitcnt lgkmcnt(6)
	v_cvt_pk_bf16_f32 v18, v13, v15
	s_waitcnt lgkmcnt(4)
	v_cvt_pk_bf16_f32 v19, v17, v19
	s_waitcnt lgkmcnt(2)
	v_cvt_pk_bf16_f32 v20, v20, v21
	s_waitcnt lgkmcnt(0)
	v_cvt_pk_bf16_f32 v21, v30, v31
	global_store_dwordx4 v[24:25], v[18:21], off
	ds_read_b32 v13, v1 offset:32
	ds_read_b32 v15, v1 offset:164
	ds_read_b32 v17, v1 offset:296
	ds_read_b32 v19, v1 offset:428
	ds_read_b32 v20, v1 offset:560
	ds_read_b32 v21, v1 offset:692
	ds_read_b32 v24, v1 offset:824
	ds_read_b32 v25, v1 offset:956
	v_lshl_add_u64 v[26:27], v[22:23], 0, v[6:7]
	s_waitcnt lgkmcnt(0)
	v_cvt_pk_bf16_f32 v18, v13, v15
	v_cvt_pk_bf16_f32 v19, v17, v19
	v_cvt_pk_bf16_f32 v20, v20, v21
	v_cvt_pk_bf16_f32 v21, v24, v25
	global_store_dwordx4 v[26:27], v[18:21], off
	ds_read_b32 v13, v1 offset:64
	ds_read_b32 v15, v1 offset:196
	ds_read_b32 v17, v1 offset:328
	ds_read_b32 v19, v1 offset:460
	ds_read_b32 v20, v1 offset:592
	ds_read_b32 v21, v1 offset:724
	ds_read_b32 v24, v1 offset:856
	ds_read_b32 v25, v1 offset:988
	v_lshl_add_u64 v[28:29], v[22:23], 0, v[8:9]
	s_waitcnt lgkmcnt(0)
	v_cvt_pk_bf16_f32 v18, v13, v15
	v_cvt_pk_bf16_f32 v19, v17, v19
	v_cvt_pk_bf16_f32 v20, v20, v21
	v_cvt_pk_bf16_f32 v21, v24, v25
	global_store_dwordx4 v[28:29], v[18:21], off
	ds_read_b32 v13, v1 offset:96
	ds_read_b32 v15, v1 offset:228
	ds_read_b32 v17, v1 offset:360
	ds_read_b32 v19, v1 offset:492
	ds_read_b32 v20, v1 offset:624
	ds_read_b32 v21, v1 offset:756
	ds_read_b32 v24, v1 offset:888
	ds_read_b32 v25, v1 offset:1020
	v_lshl_add_u64 v[22:23], v[22:23], 0, v[10:11]
	s_waitcnt lgkmcnt(0)
	v_cvt_pk_bf16_f32 v18, v13, v15
	v_cvt_pk_bf16_f32 v19, v17, v19
	v_cvt_pk_bf16_f32 v20, v20, v21
	v_cvt_pk_bf16_f32 v21, v24, v25
	global_store_dwordx4 v[22:23], v[18:21], off
	s_waitcnt lgkmcnt(0)
	s_cbranch_scc0 .LBB0_900

; __device__ __forceinline__ void tr_item(const float* src, int ld, int kv, int nv, const float* ks, bf16_t* dst, int ldd, LAS float* scr, int lane) {
;     ...
;         float tmp[32]; const float* sp = src + (size_t)(lane >> 5) * ld + n;
; #pragma unroll
;         for (int i = 0; i < 32; ++i) tmp[i] = sp[(size_t)(2 * i) * ld];
; __device__ __forceinline__ void tr_job(const Ctx& c, const float* src, int ld, int K, int N, const float* ks, bf16_t* dst, int ldd, int Kpad, int Npad) {
;     ...
;     for (int it = c.gw; it < items; it += c.ngw) { const int kb = it / nnb, nb = it % nnb, k0 = 64 * kb, n0 = 32 * nb;
;         tr_item(src + (size_t)k0 * ld + n0, ld, K - k0, N - n0, ks ? ks + k0 : nullptr, dst + (size_t)n0 * ldd + k0, ldd, scr, c.lane); }
.LBB0_903:
	s_ashr_i32 s4, s14, 31
	s_lshr_b32 s4, s4, 27
	s_add_i32 s4, s14, s4
	s_ashr_i32 s4, s4, 5
	s_lshl_b32 s16, s4, 6
	s_lshl_b32 s4, s4, 10
	s_sub_i32 s18, s12, s4
	s_ashr_i32 s17, s16, 31
	s_ashr_i32 s19, s18, 31
	s_mul_i32 s5, s18, 0x1600
	s_mul_hi_i32 s4, s18, 0x1600
	s_add_u32 s15, s94, s5
	s_addc_u32 s20, s82, s4
	s_lshl_b64 s[4:5], s[16:17], 1
	s_add_u32 s4, s15, s4
	s_addc_u32 s5, s20, s5
	s_lshl_b64 s[16:17], s[16:17], 12
	s_add_u32 s15, s10, s16
	s_addc_u32 s20, s11, s17
	s_lshl_b64 s[16:17], s[18:19], 2
	s_add_u32 s16, s15, s16
	s_addc_u32 s17, s20, s17
	v_mov_b32_e32 v13, v0
	v_lshl_add_u64 v[18:19], s[16:17], 0, v[2:3]
	v_lshl_add_u64 v[18:19], v[18:19], 0, v[12:13]
	v_add_co_u32_e32 v20, vcc, s1, v18
	v_mov_b32_e32 v15, v0
	s_nop 0
	v_addc_co_u32_e32 v21, vcc, 0, v19, vcc
	v_add_co_u32_e32 v22, vcc, s24, v18
	s_add_i32 s14, s14, s30
	s_nop 0
	v_addc_co_u32_e32 v23, vcc, 0, v19, vcc
	v_add_co_u32_e32 v24, vcc, s25, v18
	s_add_i32 s12, s12, s13
	s_nop 0
	v_addc_co_u32_e32 v25, vcc, 0, v19, vcc
	v_add_co_u32_e32 v26, vcc, s31, v18
	s_cmpk_lt_i32 s14, 0x580
	s_nop 0
	v_addc_co_u32_e32 v27, vcc, 0, v19, vcc
	v_add_co_u32_e32 v28, vcc, s34, v18
	s_nop 1
	v_addc_co_u32_e32 v29, vcc, 0, v19, vcc
	v_add_co_u32_e32 v30, vcc, s62, v18
	s_nop 1
	v_addc_co_u32_e32 v31, vcc, 0, v19, vcc
	v_add_co_u32_e32 v32, vcc, s36, v18
	s_nop 1
	v_addc_co_u32_e32 v33, vcc, 0, v19, vcc
	v_add_co_u32_e32 v34, vcc, s0, v18
	s_nop 1
	v_addc_co_u32_e32 v35, vcc, 0, v19, vcc
	v_add_co_u32_e32 v36, vcc, s63, v18
	s_nop 1
	v_addc_co_u32_e32 v37, vcc, 0, v19, vcc
	v_add_co_u32_e32 v38, vcc, s21, v18
	s_nop 1
	v_addc_co_u32_e32 v39, vcc, 0, v19, vcc
	v_add_co_u32_e32 v40, vcc, s61, v18
	s_nop 1
	v_addc_co_u32_e32 v41, vcc, 0, v19, vcc
	v_add_co_u32_e32 v42, vcc, s29, v18
	s_nop 1
	v_addc_co_u32_e32 v43, vcc, 0, v19, vcc
	v_add_co_u32_e32 v44, vcc, s38, v18
	s_nop 1
	v_addc_co_u32_e32 v45, vcc, 0, v19, vcc
	v_add_co_u32_e32 v46, vcc, s35, v18
	s_nop 1
	v_addc_co_u32_e32 v47, vcc, 0, v19, vcc
	v_add_co_u32_e32 v48, vcc, s47, v18
	s_nop 1
	v_addc_co_u32_e32 v49, vcc, 0, v19, vcc
	v_add_co_u32_e32 v50, vcc, s44, v18
	s_nop 1
	v_addc_co_u32_e32 v51, vcc, 0, v19, vcc
	v_add_co_u32_e32 v52, vcc, s45, v18
	s_nop 1
	v_addc_co_u32_e32 v53, vcc, 0, v19, vcc
	v_add_co_u32_e32 v54, vcc, s39, v18
	s_nop 1
	v_addc_co_u32_e32 v55, vcc, 0, v19, vcc
	v_add_co_u32_e32 v56, vcc, s46, v18
	s_nop 1
	v_addc_co_u32_e32 v57, vcc, 0, v19, vcc
	v_add_co_u32_e32 v58, vcc, s48, v18
	s_nop 1
	v_addc_co_u32_e32 v59, vcc, 0, v19, vcc
	v_add_co_u32_e32 v60, vcc, s40, v18
	s_nop 1
	v_addc_co_u32_e32 v61, vcc, 0, v19, vcc
	v_add_co_u32_e32 v62, vcc, s68, v18
	s_nop 1
	v_addc_co_u32_e32 v63, vcc, 0, v19, vcc
	v_add_co_u32_e32 v64, vcc, s49, v18
	s_nop 1
	v_addc_co_u32_e32 v65, vcc, 0, v19, vcc
	v_add_co_u32_e32 v66, vcc, s86, v18
	s_nop 1
	v_addc_co_u32_e32 v67, vcc, 0, v19, vcc
	v_add_co_u32_e32 v68, vcc, s58, v18
	s_nop 1
	v_addc_co_u32_e32 v69, vcc, 0, v19, vcc
	v_add_co_u32_e32 v70, vcc, s59, v18
	s_nop 1
	v_addc_co_u32_e32 v71, vcc, 0, v19, vcc
	v_add_co_u32_e32 v72, vcc, s72, v18
	s_nop 1
	v_addc_co_u32_e32 v73, vcc, 0, v19, vcc
	v_add_co_u32_e32 v74, vcc, s73, v18
	s_nop 1
	v_addc_co_u32_e32 v75, vcc, 0, v19, vcc
	v_add_co_u32_e32 v76, vcc, s80, v18
	s_nop 1
	v_addc_co_u32_e32 v77, vcc, 0, v19, vcc
	v_add_co_u32_e32 v78, vcc, s42, v18
	s_nop 1
	v_addc_co_u32_e32 v79, vcc, 0, v19, vcc
	v_add_co_u32_e32 v80, vcc, s81, v18
	s_nop 1
	v_addc_co_u32_e32 v81, vcc, 0, v19, vcc
	global_load_dword v13, v[18:19], off
	global_load_dword v17, v[20:21], off
	s_nop 0
	global_load_dword v20, v[22:23], off
	global_load_dword v21, v[24:25], off
	global_load_dword v82, v[26:27], off
	global_load_dword v83, v[28:29], off
	s_nop 0
	global_load_dword v30, v[30:31], off
	s_nop 0
	global_load_dword v31, v[32:33], off
	s_nop 0
	global_load_dword v32, v[34:35], off
	global_load_dword v33, v[36:37], off
	s_nop 0
	global_load_dword v34, v[38:39], off
	global_load_dword v35, v[40:41], off
	global_load_dword v36, v[42:43], off
	global_load_dword v37, v[44:45], off
	s_nop 0
	global_load_dword v38, v[46:47], off
	global_load_dword v39, v[48:49], off
	global_load_dword v40, v[50:51], off
	global_load_dword v41, v[52:53], off
	global_load_dword v42, v[54:55], off
	global_load_dword v43, v[56:57], off
	global_load_dword v44, v[58:59], off
	global_load_dword v45, v[60:61], off
	global_load_dword v46, v[62:63], off
	global_load_dword v47, v[64:65], off
	global_load_dword v48, v[66:67], off
	global_load_dword v49, v[68:69], off
	global_load_dword v50, v[70:71], off
	global_load_dword v51, v[72:73], off
	global_load_dword v52, v[74:75], off
	global_load_dword v53, v[76:77], off
	global_load_dword v54, v[78:79], off
	global_load_dword v55, v[80:81], off
	v_add_u32_e32 v56, 0x400, v16
	v_add_u32_e32 v57, 0x800, v16
	v_add_u32_e32 v58, 0xc00, v16
	v_add_u32_e32 v59, 0x1000, v16
	v_add_u32_e32 v60, 0x1400, v16
	v_add_u32_e32 v61, 0x1800, v16
	v_add_u32_e32 v62, 0x1c00, v16
	s_waitcnt vmcnt(0)
; #define LAS __attribute__((address_space(3)))
; __device__ __forceinline__ unsigned pk2(float lo, float hi) { f32x2 v = {lo, hi}; bf16x2_t b = __builtin_convertvector(v, bf16x2_t); return __builtin_bit_cast(unsigned, b); }
; #define LDS_WAIT() asm volatile("s_waitcnt lgkmcnt(0)" ::: "memory")
; __device__ __forceinline__ void tr_item(const float* src, int ld, int kv, int nv, const float* ks, bf16_t* dst, int ldd, LAS float* scr, int lane) {
;     ...
;         for (int i = 0; i < 32; ++i) scr[(2 * i + (lane >> 5)) * 33 + n] = tmp[i];
;     } else {
; #pragma unroll 4
;         for (int i = 0; i < 32; ++i) { const int kk = 2 * i + (lane >> 5); float v = 0.f; if (kk < kv && n < nv) { v = src[(size_t)kk * ld + n]; if (ks) v *= ks[kk]; } scr[kk * 33 + n] = v; }
;     }
;     LDS_WAIT(); asm volatile("" ::: "memory");
;     const int c = lane & 7;
; #pragma unroll
;     for (int j = 0; j < 4; ++j) { const int nn = (lane >> 3) + 8 * j; const LAS float* s = scr + (8 * c) * 33 + nn;
;         u32x4 o; o.x = pk2(s[0 * 33], s[1 * 33]); o.y = pk2(s[2 * 33], s[3 * 33]); o.z = pk2(s[4 * 33], s[5 * 33]); o.w = pk2(s[6 * 33], s[7 * 33]);
;         *(u32x4*)(dst + (size_t)nn * ldd + 8 * c) = o; }
;     LDS_WAIT(); asm volatile("" ::: "memory");
	ds_write2_b32 v56, v82, v83 offset0:8 offset1:74
	s_waitcnt vmcnt(24)
	ds_write2_b32 v56, v30, v31 offset0:140 offset1:206
	ds_write2_b32 v16, v13, v17 offset1:66
	ds_write2_b32 v16, v20, v21 offset0:132 offset1:198
	s_waitcnt vmcnt(22)
	ds_write2_b32 v57, v32, v33 offset0:16 offset1:82
	s_waitcnt vmcnt(20)
	ds_write2_b32 v57, v34, v35 offset0:148 offset1:214
	s_waitcnt vmcnt(18)
	ds_write2_b32 v58, v36, v37 offset0:24 offset1:90
	s_waitcnt vmcnt(16)
	ds_write2_b32 v58, v38, v39 offset0:156 offset1:222
	s_waitcnt vmcnt(14)
	ds_write2_b32 v59, v40, v41 offset0:32 offset1:98
	s_waitcnt vmcnt(12)
	ds_write2_b32 v59, v42, v43 offset0:164 offset1:230
	s_waitcnt vmcnt(10)
	ds_write2_b32 v60, v44, v45 offset0:40 offset1:106
	s_waitcnt vmcnt(8)
	ds_write2_b32 v60, v46, v47 offset0:172 offset1:238
	s_waitcnt vmcnt(6)
	ds_write2_b32 v61, v48, v49 offset0:48 offset1:114
	s_waitcnt vmcnt(4)
	ds_write2_b32 v61, v50, v51 offset0:180 offset1:246
	s_waitcnt vmcnt(2)
	ds_write2_b32 v62, v52, v53 offset0:56 offset1:122
	s_waitcnt vmcnt(0)
	ds_write2_b32 v62, v54, v55 offset0:188 offset1:254
	s_waitcnt lgkmcnt(0)
	v_lshl_add_u64 v[18:19], s[4:5], 0, v[14:15]
	v_lshl_add_u64 v[22:23], v[18:19], 0, v[4:5]
	v_lshl_add_u64 v[24:25], v[18:19], 0, v[6:7]
	v_lshl_add_u64 v[26:27], v[18:19], 0, v[8:9]
	v_lshl_add_u64 v[28:29], v[18:19], 0, v[10:11]
	ds_read_b32 v13, v1
	ds_read_b32 v15, v1 offset:132
	ds_read_b32 v17, v1 offset:264
	ds_read_b32 v19, v1 offset:396
	ds_read_b32 v20, v1 offset:528
	ds_read_b32 v21, v1 offset:660
	ds_read_b32 v30, v1 offset:792
	ds_read_b32 v31, v1 offset:924
	s_waitcnt lgkmcnt(6)
	v_cvt_pk_bf16_f32 v18, v13, v15
	s_waitcnt lgkmcnt(4)
	v_cvt_pk_bf16_f32 v19, v17, v19
	s_waitcnt lgkmcnt(2)
	v_cvt_pk_bf16_f32 v20, v20, v21
	s_waitcnt lgkmcnt(0)
	v_cvt_pk_bf16_f32 v21, v30, v31
	global_store_dwordx4 v[22:23], v[18:21], off
	ds_read_b32 v13, v1 offset:32
	ds_read_b32 v15, v1 offset:164
	ds_read_b32 v17, v1 offset:296
	ds_read_b32 v19, v1 offset:428
	ds_read_b32 v20, v1 offset:560
	ds_read_b32 v21, v1 offset:692
	ds_read_b32 v22, v1 offset:824
	ds_read_b32 v23, v1 offset:956
	s_waitcnt lgkmcnt(0)
	v_cvt_pk_bf16_f32 v18, v13, v15
	v_cvt_pk_bf16_f32 v19, v17, v19
	v_cvt_pk_bf16_f32 v20, v20, v21
	v_cvt_pk_bf16_f32 v21, v22, v23
	global_store_dwordx4 v[24:25], v[18:21], off
	ds_read_b32 v13, v1 offset:64
	ds_read_b32 v15, v1 offset:196
	ds_read_b32 v17, v1 offset:328
	ds_read_b32 v19, v1 offset:460
	ds_read_b32 v20, v1 offset:592
	ds_read_b32 v21, v1 offset:724
	ds_read_b32 v22, v1 offset:856
	ds_read_b32 v23, v1 offset:988
	s_waitcnt lgkmcnt(0)
	v_cvt_pk_bf16_f32 v18, v13, v15
	v_cvt_pk_bf16_f32 v19, v17, v19
	v_cvt_pk_bf16_f32 v20, v20, v21
	v_cvt_pk_bf16_f32 v21, v22, v23
	global_store_dwordx4 v[26:27], v[18:21], off
	ds_read_b32 v13, v1 offset:96
	ds_read_b32 v15, v1 offset:228
	ds_read_b32 v17, v1 offset:360
	ds_read_b32 v19, v1 offset:492
	ds_read_b32 v20, v1 offset:624
	ds_read_b32 v21, v1 offset:756
	ds_read_b32 v22, v1 offset:888
	ds_read_b32 v23, v1 offset:1020
	s_waitcnt lgkmcnt(0)
	v_cvt_pk_bf16_f32 v18, v13, v15
	v_cvt_pk_bf16_f32 v19, v17, v19
	v_cvt_pk_bf16_f32 v20, v20, v21
	v_cvt_pk_bf16_f32 v21, v22, v23
	global_store_dwordx4 v[28:29], v[18:21], off
	s_waitcnt lgkmcnt(0)
	s_cbranch_scc1 .LBB0_903
	s_mov_b32 s40, 0x37000
	s_mov_b32 s42, 0x79000

; __device__ __forceinline__ void tr_item(const float* src, int ld, int kv, int nv, const float* ks, bf16_t* dst, int ldd, LAS float* scr, int lane) {
;     ...
;         float tmp[32]; const float* sp = src + (size_t)(lane >> 5) * ld + n;
; #pragma unroll
;         for (int i = 0; i < 32; ++i) tmp[i] = sp[(size_t)(2 * i) * ld];
; __device__ __forceinline__ void tr_job(const Ctx& c, const float* src, int ld, int K, int N, const float* ks, bf16_t* dst, int ldd, int Kpad, int Npad) {
;     ...
;     for (int it = c.gw; it < items; it += c.ngw) { const int kb = it / nnb, nb = it % nnb, k0 = 64 * kb, n0 = 32 * nb;
;         tr_item(src + (size_t)k0 * ld + n0, ld, K - k0, N - n0, ks ? ks + k0 : nullptr, dst + (size_t)n0 * ldd + k0, ldd, scr, c.lane); }
.LBB0_907:
	s_ashr_i32 s2, s12, 31
	s_lshr_b32 s2, s2, 27
	s_add_i32 s2, s12, s2
	s_ashr_i32 s2, s2, 5
	s_lshl_b32 s14, s2, 6
	s_lshl_b32 s2, s2, 10
	s_sub_i32 s16, s10, s2
	s_ashr_i32 s17, s16, 31
	s_ashr_i32 s15, s14, 31
	s_lshl_b64 s[2:3], s[16:17], 11
	s_add_u32 s13, s52, s2
	s_addc_u32 s18, s53, s3
	s_lshl_b64 s[2:3], s[14:15], 1
	s_add_u32 s2, s13, s2
	s_addc_u32 s3, s18, s3
	s_lshl_b64 s[14:15], s[14:15], 12
	s_add_u32 s13, s4, s14
	s_addc_u32 s18, s5, s15
	s_lshl_b64 s[14:15], s[16:17], 2
	s_add_u32 s14, s13, s14
	s_addc_u32 s15, s18, s15
	v_mov_b32_e32 v13, v0
	v_lshl_add_u64 v[18:19], s[14:15], 0, v[2:3]
	v_lshl_add_u64 v[18:19], v[18:19], 0, v[12:13]
	v_add_co_u32_e32 v20, vcc, s1, v18
	v_mov_b32_e32 v15, v0
	s_nop 0
	v_addc_co_u32_e32 v21, vcc, 0, v19, vcc
	v_add_co_u32_e32 v22, vcc, s20, v18
	s_add_i32 s12, s12, s30
	s_nop 0
	v_addc_co_u32_e32 v23, vcc, 0, v19, vcc
	v_add_co_u32_e32 v24, vcc, s21, v18
	s_add_i32 s10, s10, s11
	s_nop 0
	v_addc_co_u32_e32 v25, vcc, 0, v19, vcc
	v_add_co_u32_e32 v26, vcc, s25, v18
	s_cmpk_gt_i32 s12, 0x1ff
	s_nop 0
	v_addc_co_u32_e32 v27, vcc, 0, v19, vcc
	v_add_co_u32_e32 v28, vcc, s29, v18
	s_nop 1
	v_addc_co_u32_e32 v29, vcc, 0, v19, vcc
	v_add_co_u32_e32 v30, vcc, s62, v18
	s_nop 1
	v_addc_co_u32_e32 v31, vcc, 0, v19, vcc
	v_add_co_u32_e32 v32, vcc, s34, v18
	s_nop 1
	v_addc_co_u32_e32 v33, vcc, 0, v19, vcc
	v_add_co_u32_e32 v34, vcc, s0, v18
	s_nop 1
	v_addc_co_u32_e32 v35, vcc, 0, v19, vcc
	v_add_co_u32_e32 v36, vcc, s63, v18
	s_nop 1
	v_addc_co_u32_e32 v37, vcc, 0, v19, vcc
	v_add_co_u32_e32 v38, vcc, s19, v18
	s_nop 1
	v_addc_co_u32_e32 v39, vcc, 0, v19, vcc
	v_add_co_u32_e32 v40, vcc, s61, v18
	s_nop 1
	v_addc_co_u32_e32 v41, vcc, 0, v19, vcc
	v_add_co_u32_e32 v42, vcc, s24, v18
	s_nop 1
	v_addc_co_u32_e32 v43, vcc, 0, v19, vcc
	v_add_co_u32_e32 v44, vcc, s35, v18
	s_nop 1
	v_addc_co_u32_e32 v45, vcc, 0, v19, vcc
	v_add_co_u32_e32 v46, vcc, s31, v18
	s_nop 1
	v_addc_co_u32_e32 v47, vcc, 0, v19, vcc
	v_add_co_u32_e32 v48, vcc, s47, v18
	s_nop 1
	v_addc_co_u32_e32 v49, vcc, 0, v19, vcc
	v_add_co_u32_e32 v50, vcc, s44, v18
	s_nop 1
	v_addc_co_u32_e32 v51, vcc, 0, v19, vcc
	v_add_co_u32_e32 v52, vcc, s45, v18
	s_nop 1
	v_addc_co_u32_e32 v53, vcc, 0, v19, vcc
	v_add_co_u32_e32 v54, vcc, s36, v18
	s_nop 1
	v_addc_co_u32_e32 v55, vcc, 0, v19, vcc
	v_add_co_u32_e32 v56, vcc, s46, v18
	s_nop 1
	v_addc_co_u32_e32 v57, vcc, 0, v19, vcc
	v_add_co_u32_e32 v58, vcc, s48, v18
	s_nop 1
	v_addc_co_u32_e32 v59, vcc, 0, v19, vcc
	v_add_co_u32_e32 v60, vcc, s38, v18
	s_nop 1
	v_addc_co_u32_e32 v61, vcc, 0, v19, vcc
	v_add_co_u32_e32 v62, vcc, s68, v18
	s_nop 1
	v_addc_co_u32_e32 v63, vcc, 0, v19, vcc
	v_add_co_u32_e32 v64, vcc, s49, v18
	s_nop 1
	v_addc_co_u32_e32 v65, vcc, 0, v19, vcc
	v_add_co_u32_e32 v66, vcc, s86, v18
	s_nop 1
	v_addc_co_u32_e32 v67, vcc, 0, v19, vcc
	v_add_co_u32_e32 v68, vcc, s58, v18
	s_nop 1
	v_addc_co_u32_e32 v69, vcc, 0, v19, vcc
	v_add_co_u32_e32 v70, vcc, s59, v18
	s_nop 1
	v_addc_co_u32_e32 v71, vcc, 0, v19, vcc
	v_add_co_u32_e32 v72, vcc, s72, v18
	s_nop 1
	v_addc_co_u32_e32 v73, vcc, 0, v19, vcc
	v_add_co_u32_e32 v74, vcc, s73, v18
	s_nop 1
	v_addc_co_u32_e32 v75, vcc, 0, v19, vcc
	v_add_co_u32_e32 v76, vcc, s80, v18
	s_nop 1
	v_addc_co_u32_e32 v77, vcc, 0, v19, vcc
	v_add_co_u32_e32 v78, vcc, s39, v18
	s_nop 1
	v_addc_co_u32_e32 v79, vcc, 0, v19, vcc
	v_add_co_u32_e32 v80, vcc, s81, v18
	s_nop 1
	v_addc_co_u32_e32 v81, vcc, 0, v19, vcc
	global_load_dword v13, v[18:19], off
	global_load_dword v17, v[20:21], off
	s_nop 0
	global_load_dword v20, v[22:23], off
	global_load_dword v21, v[24:25], off
	global_load_dword v82, v[26:27], off
	global_load_dword v83, v[28:29], off
	s_nop 0
	global_load_dword v30, v[30:31], off
	s_nop 0
	global_load_dword v31, v[32:33], off
	s_nop 0
	global_load_dword v32, v[34:35], off
	global_load_dword v33, v[36:37], off
	s_nop 0
	global_load_dword v34, v[38:39], off
	global_load_dword v35, v[40:41], off
	global_load_dword v36, v[42:43], off
	global_load_dword v37, v[44:45], off
	s_nop 0
	global_load_dword v38, v[46:47], off
	global_load_dword v39, v[48:49], off
	global_load_dword v40, v[50:51], off
	global_load_dword v41, v[52:53], off
	global_load_dword v42, v[54:55], off
	global_load_dword v43, v[56:57], off
	global_load_dword v44, v[58:59], off
	global_load_dword v45, v[60:61], off
	global_load_dword v46, v[62:63], off
	global_load_dword v47, v[64:65], off
	global_load_dword v48, v[66:67], off
	global_load_dword v49, v[68:69], off
	global_load_dword v50, v[70:71], off
	global_load_dword v51, v[72:73], off
	global_load_dword v52, v[74:75], off
	global_load_dword v53, v[76:77], off
	global_load_dword v54, v[78:79], off
	global_load_dword v55, v[80:81], off
	v_add_u32_e32 v56, 0x400, v16
	v_add_u32_e32 v57, 0x800, v16
	v_add_u32_e32 v58, 0xc00, v16
	v_add_u32_e32 v59, 0x1000, v16
	v_add_u32_e32 v60, 0x1400, v16
	v_add_u32_e32 v61, 0x1800, v16
	v_add_u32_e32 v62, 0x1c00, v16
	s_waitcnt vmcnt(0)
; #define LAS __attribute__((address_space(3)))
; __device__ __forceinline__ unsigned pk2(float lo, float hi) { f32x2 v = {lo, hi}; bf16x2_t b = __builtin_convertvector(v, bf16x2_t); return __builtin_bit_cast(unsigned, b); }
; #define LDS_WAIT() asm volatile("s_waitcnt lgkmcnt(0)" ::: "memory")
; __device__ __forceinline__ void tr_item(const float* src, int ld, int kv, int nv, const float* ks, bf16_t* dst, int ldd, LAS float* scr, int lane) {
;     ...
;         for (int i = 0; i < 32; ++i) scr[(2 * i + (lane >> 5)) * 33 + n] = tmp[i];
;     } else {
; #pragma unroll 4
;         for (int i = 0; i < 32; ++i) { const int kk = 2 * i + (lane >> 5); float v = 0.f; if (kk < kv && n < nv) { v = src[(size_t)kk * ld + n]; if (ks) v *= ks[kk]; } scr[kk * 33 + n] = v; }
;     }
;     LDS_WAIT(); asm volatile("" ::: "memory");
;     const int c = lane & 7;
; #pragma unroll
;     for (int j = 0; j < 4; ++j) { const int nn = (lane >> 3) + 8 * j; const LAS float* s = scr + (8 * c) * 33 + nn;
;         u32x4 o; o.x = pk2(s[0 * 33], s[1 * 33]); o.y = pk2(s[2 * 33], s[3 * 33]); o.z = pk2(s[4 * 33], s[5 * 33]); o.w = pk2(s[6 * 33], s[7 * 33]);
;         *(u32x4*)(dst + (size_t)nn * ldd + 8 * c) = o; }
;     LDS_WAIT(); asm volatile("" ::: "memory");
	ds_write2_b32 v16, v13, v17 offset1:66
	s_waitcnt vmcnt(28)
	ds_write2_b32 v16, v20, v21 offset0:132 offset1:198
	s_waitcnt vmcnt(26)
	ds_write2_b32 v56, v82, v83 offset0:8 offset1:74
	s_waitcnt vmcnt(24)
	ds_write2_b32 v56, v30, v31 offset0:140 offset1:206
	s_waitcnt vmcnt(22)
	ds_write2_b32 v57, v32, v33 offset0:16 offset1:82
	s_waitcnt vmcnt(20)
	ds_write2_b32 v57, v34, v35 offset0:148 offset1:214
	s_waitcnt vmcnt(18)
	ds_write2_b32 v58, v36, v37 offset0:24 offset1:90
	s_waitcnt vmcnt(16)
	ds_write2_b32 v58, v38, v39 offset0:156 offset1:222
	s_waitcnt vmcnt(14)
	ds_write2_b32 v59, v40, v41 offset0:32 offset1:98
	s_waitcnt vmcnt(12)
	ds_write2_b32 v59, v42, v43 offset0:164 offset1:230
	s_waitcnt vmcnt(10)
	ds_write2_b32 v60, v44, v45 offset0:40 offset1:106
	s_waitcnt vmcnt(8)
	ds_write2_b32 v60, v46, v47 offset0:172 offset1:238
	s_waitcnt vmcnt(6)
	ds_write2_b32 v61, v48, v49 offset0:48 offset1:114
	s_waitcnt vmcnt(4)
	ds_write2_b32 v61, v50, v51 offset0:180 offset1:246
	s_waitcnt vmcnt(2)
	ds_write2_b32 v62, v52, v53 offset0:56 offset1:122
	s_waitcnt vmcnt(0)
	ds_write2_b32 v62, v54, v55 offset0:188 offset1:254
	s_waitcnt lgkmcnt(0)
	v_lshl_add_u64 v[18:19], s[2:3], 0, v[14:15]
	v_lshl_add_u64 v[22:23], v[18:19], 0, v[4:5]
	v_lshl_add_u64 v[24:25], v[18:19], 0, v[6:7]
	v_lshl_add_u64 v[26:27], v[18:19], 0, v[8:9]
	v_lshl_add_u64 v[28:29], v[18:19], 0, v[10:11]
	ds_read_b32 v13, v1
	ds_read_b32 v15, v1 offset:132
	ds_read_b32 v17, v1 offset:264
	ds_read_b32 v19, v1 offset:396
	ds_read_b32 v20, v1 offset:528
	ds_read_b32 v21, v1 offset:660
	ds_read_b32 v30, v1 offset:792
	ds_read_b32 v31, v1 offset:924
	s_waitcnt lgkmcnt(6)
	v_cvt_pk_bf16_f32 v18, v13, v15
	s_waitcnt lgkmcnt(4)
	v_cvt_pk_bf16_f32 v19, v17, v19
	s_waitcnt lgkmcnt(2)
	v_cvt_pk_bf16_f32 v20, v20, v21
	s_waitcnt lgkmcnt(0)
	v_cvt_pk_bf16_f32 v21, v30, v31
	global_store_dwordx4 v[22:23], v[18:21], off
	ds_read_b32 v13, v1 offset:32
	ds_read_b32 v15, v1 offset:164
	ds_read_b32 v17, v1 offset:296
	ds_read_b32 v19, v1 offset:428
	ds_read_b32 v20, v1 offset:560
	ds_read_b32 v21, v1 offset:692
	ds_read_b32 v22, v1 offset:824
	ds_read_b32 v23, v1 offset:956
	s_waitcnt lgkmcnt(0)
	v_cvt_pk_bf16_f32 v18, v13, v15
	v_cvt_pk_bf16_f32 v19, v17, v19
	v_cvt_pk_bf16_f32 v20, v20, v21
	v_cvt_pk_bf16_f32 v21, v22, v23
	global_store_dwordx4 v[24:25], v[18:21], off
	ds_read_b32 v13, v1 offset:64
	ds_read_b32 v15, v1 offset:196
	ds_read_b32 v17, v1 offset:328
	ds_read_b32 v19, v1 offset:460
	ds_read_b32 v20, v1 offset:592
	ds_read_b32 v21, v1 offset:724
	ds_read_b32 v22, v1 offset:856
	ds_read_b32 v23, v1 offset:988
	s_waitcnt lgkmcnt(0)
	v_cvt_pk_bf16_f32 v18, v13, v15
	v_cvt_pk_bf16_f32 v19, v17, v19
	v_cvt_pk_bf16_f32 v20, v20, v21
	v_cvt_pk_bf16_f32 v21, v22, v23
	global_store_dwordx4 v[26:27], v[18:21], off
	ds_read_b32 v13, v1 offset:96
	ds_read_b32 v15, v1 offset:228
	ds_read_b32 v17, v1 offset:360
	ds_read_b32 v19, v1 offset:492
	ds_read_b32 v20, v1 offset:624
	ds_read_b32 v21, v1 offset:756
	ds_read_b32 v22, v1 offset:888
	ds_read_b32 v23, v1 offset:1020
	s_waitcnt lgkmcnt(0)
	v_cvt_pk_bf16_f32 v18, v13, v15
	v_cvt_pk_bf16_f32 v19, v17, v19
	v_cvt_pk_bf16_f32 v20, v20, v21
	v_cvt_pk_bf16_f32 v21, v22, v23
	global_store_dwordx4 v[28:29], v[18:21], off
	s_waitcnt lgkmcnt(0)
	s_cbranch_scc0 .LBB0_907

; __device__ __forceinline__ void tr_item(const float* src, int ld, int kv, int nv, const float* ks, bf16_t* dst, int ldd, LAS float* scr, int lane) {
;     ...
;         float tmp[32]; const float* sp = src + (size_t)(lane >> 5) * ld + n;
; #pragma unroll
;         for (int i = 0; i < 32; ++i) tmp[i] = sp[(size_t)(2 * i) * ld];
; __device__ __forceinline__ void tr_job(const Ctx& c, const float* src, int ld, int K, int N, const float* ks, bf16_t* dst, int ldd, int Kpad, int Npad) {
;     ...
;     for (int it = c.gw; it < items; it += c.ngw) { const int kb = it / nnb, nb = it % nnb, k0 = 64 * kb, n0 = 32 * nb;
;         tr_item(src + (size_t)k0 * ld + n0, ld, K - k0, N - n0, ks ? ks + k0 : nullptr, dst + (size_t)n0 * ldd + k0, ldd, scr, c.lane); }
.LBB0_910:
	s_mul_hi_i32 s2, s12, 0x1948b0fd
	s_lshr_b32 s3, s2, 31
	s_ashr_i32 s2, s2, 3
	s_add_i32 s3, s2, s3
	s_mul_i32 s13, s3, 0xfffff5e0
	s_add_i32 s14, s10, s13
	s_lshl_b32 s2, s3, 6
	s_ashr_i32 s15, s14, 31
	s_mul_i32 s18, s3, 0xa2000
	s_ashr_i32 s3, s2, 31
	s_lshl_b64 s[16:17], s[14:15], 11
	s_add_u32 s16, s93, s16
	s_mul_hi_i32 s13, s2, 0x2880
	s_addc_u32 s17, s37, s17
	s_lshl_b64 s[2:3], s[2:3], 1
	s_add_u32 s2, s16, s2
	s_addc_u32 s3, s17, s3
	s_add_u32 s16, s4, s18
	s_addc_u32 s13, s5, s13
	s_lshl_b64 s[14:15], s[14:15], 2
	s_add_u32 s14, s16, s14
	s_addc_u32 s15, s13, s15
	v_mov_b32_e32 v13, v0
	v_lshl_add_u64 v[16:17], s[14:15], 0, v[2:3]
	v_lshl_add_u64 v[28:29], v[16:17], 0, v[12:13]
	v_add_co_u32_e32 v16, vcc, s21, v28
	s_mov_b32 s13, 0x23000
	s_nop 0
	v_addc_co_u32_e32 v17, vcc, 0, v29, vcc
	v_add_co_u32_e32 v18, vcc, s19, v28
	v_mov_b32_e32 v15, v0
	s_nop 0
	v_addc_co_u32_e32 v19, vcc, 0, v29, vcc
	v_add_co_u32_e32 v20, vcc, s20, v28
	s_add_i32 s12, s12, s30
	s_nop 0
	v_addc_co_u32_e32 v21, vcc, 0, v29, vcc
	v_add_co_u32_e32 v22, vcc, s0, v28
	s_add_i32 s10, s10, s11
	s_nop 0
	v_addc_co_u32_e32 v23, vcc, 0, v29, vcc
	v_add_co_u32_e32 v24, vcc, s31, v28
	s_cmpk_lt_i32 s12, 0x510
	s_nop 0
	v_addc_co_u32_e32 v25, vcc, 0, v29, vcc
	v_add_co_u32_e32 v26, vcc, s47, v28
	s_nop 1
	v_addc_co_u32_e32 v27, vcc, 0, v29, vcc
	v_add_co_u32_e32 v30, vcc, s13, v28
	s_mov_b32 s13, 0x41000
	s_nop 0
	v_addc_co_u32_e32 v31, vcc, 0, v29, vcc
	v_add_co_u32_e32 v32, vcc, s25, v28
	s_nop 1
	v_addc_co_u32_e32 v33, vcc, 0, v29, vcc
	v_add_co_u32_e32 v34, vcc, s34, v28
	s_nop 1
	v_addc_co_u32_e32 v35, vcc, 0, v29, vcc
	v_add_co_u32_e32 v36, vcc, s29, v28
	s_nop 1
	v_addc_co_u32_e32 v37, vcc, 0, v29, vcc
	v_add_co_u32_e32 v38, vcc, s40, v28
	s_nop 1
	v_addc_co_u32_e32 v39, vcc, 0, v29, vcc
	v_add_co_u32_e32 v40, vcc, s24, v28
	s_nop 1
	v_addc_co_u32_e32 v41, vcc, 0, v29, vcc
	v_add_co_u32_e32 v42, vcc, s13, v28
	s_mov_b32 s13, 0x46000
	s_nop 0
	v_addc_co_u32_e32 v43, vcc, 0, v29, vcc
	v_add_co_u32_e32 v44, vcc, s13, v28
	s_mov_b32 s13, 0x51000
	s_nop 0
	v_addc_co_u32_e32 v45, vcc, 0, v29, vcc
	v_add_co_u32_e32 v46, vcc, s35, v28
	s_nop 1
	v_addc_co_u32_e32 v47, vcc, 0, v29, vcc
	v_add_co_u32_e32 v48, vcc, s13, v28
	s_mov_b32 s13, 0x56000
	s_nop 0
	v_addc_co_u32_e32 v49, vcc, 0, v29, vcc
	v_add_co_u32_e32 v50, vcc, s13, v28
	s_mov_b32 s13, 0x5b000
	s_nop 0
	v_addc_co_u32_e32 v51, vcc, 0, v29, vcc
	v_add_co_u32_e32 v52, vcc, s13, v28
	s_mov_b32 s13, 0x60000
	s_nop 0
	v_addc_co_u32_e32 v53, vcc, 0, v29, vcc
	v_add_co_u32_e32 v56, vcc, s13, v28
	s_mov_b32 s13, 0x65000
	s_nop 0
	v_addc_co_u32_e32 v57, vcc, 0, v29, vcc
	v_add_co_u32_e32 v58, vcc, s13, v28
	s_mov_b32 s13, 0x6a000
	s_nop 0
	v_addc_co_u32_e32 v59, vcc, 0, v29, vcc
	v_add_co_u32_e32 v60, vcc, s13, v28
	s_mov_b32 s13, 0x6f000
	s_nop 0
	v_addc_co_u32_e32 v61, vcc, 0, v29, vcc
	v_add_co_u32_e32 v62, vcc, s13, v28
	s_mov_b32 s13, 0x74000
	s_nop 0
	v_addc_co_u32_e32 v63, vcc, 0, v29, vcc
	v_add_co_u32_e32 v64, vcc, s13, v28
	s_mov_b32 s13, 0x7e000
	s_nop 0
	v_addc_co_u32_e32 v65, vcc, 0, v29, vcc
	v_add_co_u32_e32 v66, vcc, s42, v28
	s_nop 1
	v_addc_co_u32_e32 v67, vcc, 0, v29, vcc
	v_add_co_u32_e32 v68, vcc, s13, v28
	s_mov_b32 s13, 0x83000
	s_nop 0
	v_addc_co_u32_e32 v69, vcc, 0, v29, vcc
	v_add_co_u32_e32 v70, vcc, s13, v28
	s_mov_b32 s13, 0x88000
	s_nop 0
	v_addc_co_u32_e32 v71, vcc, 0, v29, vcc
	v_add_co_u32_e32 v72, vcc, s13, v28
	s_mov_b32 s13, 0x8d000
	s_nop 0
	v_addc_co_u32_e32 v73, vcc, 0, v29, vcc
	v_add_co_u32_e32 v74, vcc, s13, v28
	s_mov_b32 s13, 0x92000
	s_nop 0
	v_addc_co_u32_e32 v75, vcc, 0, v29, vcc
	v_add_co_u32_e32 v76, vcc, s13, v28
	s_mov_b32 s13, 0x97000
	s_nop 0
	v_addc_co_u32_e32 v77, vcc, 0, v29, vcc
	v_add_co_u32_e32 v78, vcc, s13, v28
	s_mov_b32 s13, 0x9c000
	s_nop 0
	v_addc_co_u32_e32 v79, vcc, 0, v29, vcc
	v_add_co_u32_e32 v80, vcc, s13, v28
	s_nop 1
	v_addc_co_u32_e32 v81, vcc, 0, v29, vcc
	global_load_dword v13, v[28:29], off
	s_nop 0
	global_load_dword v28, v[16:17], off offset:256
	s_nop 0
	global_load_dword v18, v[18:19], off offset:512
	s_nop 0
	global_load_dword v19, v[20:21], off offset:768
	global_load_dword v29, v[22:23], off offset:1024
	global_load_dword v55, v[24:25], off offset:1280
	global_load_dword v82, v[26:27], off offset:1536
	s_nop 0
	global_load_dword v30, v[30:31], off offset:1792
	s_nop 0
	global_load_dword v31, v[32:33], off offset:2048
	s_nop 0
	global_load_dword v32, v[34:35], off offset:2304
	global_load_dword v33, v[36:37], off offset:2560
	s_nop 0
	global_load_dword v34, v[38:39], off offset:2816
	global_load_dword v35, v[40:41], off offset:3072
	global_load_dword v36, v[42:43], off offset:3328
	global_load_dword v37, v[44:45], off offset:3584
	s_nop 0
	global_load_dword v38, v[46:47], off offset:3840
	global_load_dword v39, v[48:49], off
	global_load_dword v40, v[50:51], off offset:256
	global_load_dword v41, v[52:53], off offset:512
	global_load_dword v42, v[56:57], off offset:768
	global_load_dword v43, v[58:59], off offset:1024
	global_load_dword v44, v[60:61], off offset:1280
	global_load_dword v45, v[62:63], off offset:1536
	global_load_dword v46, v[64:65], off offset:1792
	global_load_dword v47, v[66:67], off offset:2048
	global_load_dword v48, v[68:69], off offset:2304
	global_load_dword v49, v[70:71], off offset:2560
	global_load_dword v50, v[72:73], off offset:2816
	global_load_dword v51, v[74:75], off offset:3072
	global_load_dword v52, v[76:77], off offset:3328
	global_load_dword v53, v[78:79], off offset:3584
	global_load_dword v56, v[80:81], off offset:3840
	v_add_u32_e32 v57, 0x400, v54
	v_add_u32_e32 v58, 0x800, v54
	v_add_u32_e32 v59, 0xc00, v54
	v_add_u32_e32 v60, 0x1000, v54
	v_add_u32_e32 v61, 0x1400, v54
	v_add_u32_e32 v62, 0x1800, v54
	v_add_u32_e32 v63, 0x1c00, v54
	s_waitcnt vmcnt(0)
; #define LAS __attribute__((address_space(3)))
; __device__ __forceinline__ unsigned pk2(float lo, float hi) { f32x2 v = {lo, hi}; bf16x2_t b = __builtin_convertvector(v, bf16x2_t); return __builtin_bit_cast(unsigned, b); }
; #define LDS_WAIT() asm volatile("s_waitcnt lgkmcnt(0)" ::: "memory")
; __device__ __forceinline__ void tr_item(const float* src, int ld, int kv, int nv, const float* ks, bf16_t* dst, int ldd, LAS float* scr, int lane) {
;     ...
;         for (int i = 0; i < 32; ++i) scr[(2 * i + (lane >> 5)) * 33 + n] = tmp[i];
;     } else {
; #pragma unroll 4
;         for (int i = 0; i < 32; ++i) { const int kk = 2 * i + (lane >> 5); float v = 0.f; if (kk < kv && n < nv) { v = src[(size_t)kk * ld + n]; if (ks) v *= ks[kk]; } scr[kk * 33 + n] = v; }
;     }
;     LDS_WAIT(); asm volatile("" ::: "memory");
;     const int c = lane & 7;
; #pragma unroll
;     for (int j = 0; j < 4; ++j) { const int nn = (lane >> 3) + 8 * j; const LAS float* s = scr + (8 * c) * 33 + nn;
;         u32x4 o; o.x = pk2(s[0 * 33], s[1 * 33]); o.y = pk2(s[2 * 33], s[3 * 33]); o.z = pk2(s[4 * 33], s[5 * 33]); o.w = pk2(s[6 * 33], s[7 * 33]);
;         *(u32x4*)(dst + (size_t)nn * ldd + 8 * c) = o; }
;     LDS_WAIT(); asm volatile("" ::: "memory");
	ds_write2_b32 v54, v13, v28 offset1:66
	s_waitcnt vmcnt(28)
	ds_write2_b32 v54, v18, v19 offset0:132 offset1:198
	s_waitcnt vmcnt(26)
	ds_write2_b32 v57, v29, v55 offset0:8 offset1:74
	s_waitcnt vmcnt(24)
	ds_write2_b32 v57, v82, v30 offset0:140 offset1:206
	s_waitcnt vmcnt(22)
	ds_write2_b32 v58, v31, v32 offset0:16 offset1:82
	s_waitcnt vmcnt(20)
	ds_write2_b32 v58, v33, v34 offset0:148 offset1:214
	s_waitcnt vmcnt(18)
	ds_write2_b32 v59, v35, v36 offset0:24 offset1:90
	s_waitcnt vmcnt(16)
	ds_write2_b32 v59, v37, v38 offset0:156 offset1:222
	s_waitcnt vmcnt(14)
	ds_write2_b32 v60, v39, v40 offset0:32 offset1:98
	s_waitcnt vmcnt(12)
	ds_write2_b32 v60, v41, v42 offset0:164 offset1:230
	s_waitcnt vmcnt(10)
	ds_write2_b32 v61, v43, v44 offset0:40 offset1:106
	s_waitcnt vmcnt(8)
	ds_write2_b32 v61, v45, v46 offset0:172 offset1:238
	s_waitcnt vmcnt(6)
	ds_write2_b32 v62, v47, v48 offset0:48 offset1:114
	s_waitcnt vmcnt(4)
	ds_write2_b32 v62, v49, v50 offset0:180 offset1:246
	s_waitcnt vmcnt(2)
	ds_write2_b32 v63, v51, v52 offset0:56 offset1:122
	s_waitcnt vmcnt(0)
	ds_write2_b32 v63, v53, v56 offset0:188 offset1:254
	s_waitcnt lgkmcnt(0)
	v_lshl_add_u64 v[16:17], s[2:3], 0, v[14:15]
	v_lshl_add_u64 v[20:21], v[16:17], 0, v[4:5]
	v_lshl_add_u64 v[22:23], v[16:17], 0, v[6:7]
	v_lshl_add_u64 v[24:25], v[16:17], 0, v[8:9]
	v_lshl_add_u64 v[26:27], v[16:17], 0, v[10:11]
	ds_read_b32 v13, v1
	ds_read_b32 v15, v1 offset:132
	ds_read_b32 v17, v1 offset:264
	ds_read_b32 v18, v1 offset:396
	ds_read_b32 v19, v1 offset:528
	ds_read_b32 v28, v1 offset:660
	ds_read_b32 v29, v1 offset:792
	ds_read_b32 v30, v1 offset:924
	s_waitcnt lgkmcnt(6)
	v_cvt_pk_bf16_f32 v16, v13, v15
	s_waitcnt lgkmcnt(4)
	v_cvt_pk_bf16_f32 v17, v17, v18
	s_waitcnt lgkmcnt(2)
	v_cvt_pk_bf16_f32 v18, v19, v28
	s_waitcnt lgkmcnt(0)
	v_cvt_pk_bf16_f32 v19, v29, v30
	global_store_dwordx4 v[20:21], v[16:19], off
	ds_read_b32 v13, v1 offset:32
	ds_read_b32 v15, v1 offset:164
	ds_read_b32 v17, v1 offset:296
	ds_read_b32 v18, v1 offset:428
	ds_read_b32 v19, v1 offset:560
	ds_read_b32 v20, v1 offset:692
	ds_read_b32 v21, v1 offset:824
	ds_read_b32 v28, v1 offset:956
	s_waitcnt lgkmcnt(0)
	v_cvt_pk_bf16_f32 v16, v13, v15
	v_cvt_pk_bf16_f32 v17, v17, v18
	v_cvt_pk_bf16_f32 v18, v19, v20
	v_cvt_pk_bf16_f32 v19, v21, v28
	global_store_dwordx4 v[22:23], v[16:19], off
	ds_read_b32 v13, v1 offset:64
	ds_read_b32 v15, v1 offset:196
	ds_read_b32 v17, v1 offset:328
	ds_read_b32 v18, v1 offset:460
	ds_read_b32 v19, v1 offset:592
	ds_read_b32 v20, v1 offset:724
	ds_read_b32 v21, v1 offset:856
	ds_read_b32 v22, v1 offset:988
	s_waitcnt lgkmcnt(0)
	v_cvt_pk_bf16_f32 v16, v13, v15
	v_cvt_pk_bf16_f32 v17, v17, v18
	v_cvt_pk_bf16_f32 v18, v19, v20
	v_cvt_pk_bf16_f32 v19, v21, v22
	global_store_dwordx4 v[24:25], v[16:19], off
	ds_read_b32 v13, v1 offset:96
	ds_read_b32 v15, v1 offset:228
	ds_read_b32 v17, v1 offset:360
	ds_read_b32 v18, v1 offset:492
	ds_read_b32 v19, v1 offset:624
	ds_read_b32 v20, v1 offset:756
	ds_read_b32 v21, v1 offset:888
	ds_read_b32 v22, v1 offset:1020
	s_waitcnt lgkmcnt(0)
	v_cvt_pk_bf16_f32 v16, v13, v15
	v_cvt_pk_bf16_f32 v17, v17, v18
	v_cvt_pk_bf16_f32 v18, v19, v20
	v_cvt_pk_bf16_f32 v19, v21, v22
	global_store_dwordx4 v[26:27], v[16:19], off
	s_waitcnt lgkmcnt(0)
	s_cbranch_scc1 .LBB0_910

; #define LAS __attribute__((address_space(3)))
; __device__ __forceinline__ unsigned pk2(float lo, float hi) { f32x2 v = {lo, hi}; bf16x2_t b = __builtin_convertvector(v, bf16x2_t); return __builtin_bit_cast(unsigned, b); }
; #define LDS_WAIT() asm volatile("s_waitcnt lgkmcnt(0)" ::: "memory")
; __device__ __forceinline__ void tr_item(const float* src, int ld, int kv, int nv, const float* ks, bf16_t* dst, int ldd, LAS float* scr, int lane) {
;     ...
;     LDS_WAIT(); asm volatile("" ::: "memory");
;     const int c = lane & 7;
; #pragma unroll
;     for (int j = 0; j < 4; ++j) { const int nn = (lane >> 3) + 8 * j; const LAS float* s = scr + (8 * c) * 33 + nn;
;         u32x4 o; o.x = pk2(s[0 * 33], s[1 * 33]); o.y = pk2(s[2 * 33], s[3 * 33]); o.z = pk2(s[4 * 33], s[5 * 33]); o.w = pk2(s[6 * 33], s[7 * 33]);
;         *(u32x4*)(dst + (size_t)nn * ldd + 8 * c) = o; }
;     LDS_WAIT(); asm volatile("" ::: "memory");
.LBB0_913:
	s_waitcnt lgkmcnt(0)
	ds_read_b32 v24, v21
	ds_read_b32 v25, v21 offset:132
	ds_read_b32 v26, v21 offset:264
	ds_read_b32 v27, v21 offset:396
	ds_read_b32 v30, v21 offset:528
	ds_read_b32 v31, v21 offset:660
	ds_read_b32 v32, v21 offset:792
	ds_read_b32 v33, v21 offset:924
	v_lshl_add_u64 v[28:29], s[2:3], 1, v[8:9]
	s_waitcnt lgkmcnt(0)
	v_cvt_pk_bf16_f32 v24, v24, v25
	s_waitcnt lgkmcnt(4)
	v_cvt_pk_bf16_f32 v25, v26, v27
	s_waitcnt lgkmcnt(2)
	v_cvt_pk_bf16_f32 v26, v30, v31
	s_waitcnt lgkmcnt(0)
	v_cvt_pk_bf16_f32 v27, v32, v33
	v_lshl_add_u64 v[30:31], v[28:29], 0, v[10:11]
	global_store_dwordx4 v[30:31], v[24:27], off
	ds_read_b32 v24, v21 offset:32
	ds_read_b32 v25, v21 offset:164
	ds_read_b32 v26, v21 offset:296
	ds_read_b32 v27, v21 offset:428
	ds_read_b32 v30, v21 offset:560
	ds_read_b32 v31, v21 offset:692
	ds_read_b32 v32, v21 offset:824
	ds_read_b32 v33, v21 offset:956
	s_waitcnt lgkmcnt(0)
	v_cvt_pk_bf16_f32 v24, v24, v25
	v_cvt_pk_bf16_f32 v25, v26, v27
	v_cvt_pk_bf16_f32 v26, v30, v31
	v_lshl_add_u64 v[30:31], v[28:29], 0, v[12:13]
	v_cvt_pk_bf16_f32 v27, v32, v33
	global_store_dwordx4 v[30:31], v[24:27], off
	ds_read_b32 v24, v21 offset:64
	ds_read_b32 v25, v21 offset:196
	ds_read_b32 v26, v21 offset:328
	ds_read_b32 v27, v21 offset:460
	ds_read_b32 v30, v21 offset:592
	ds_read_b32 v31, v21 offset:724
	ds_read_b32 v32, v21 offset:856
	ds_read_b32 v33, v21 offset:988
	s_waitcnt lgkmcnt(0)
	v_cvt_pk_bf16_f32 v24, v24, v25
	v_cvt_pk_bf16_f32 v25, v26, v27
	v_cvt_pk_bf16_f32 v26, v30, v31
	v_lshl_add_u64 v[30:31], v[28:29], 0, v[14:15]
	v_cvt_pk_bf16_f32 v27, v32, v33
	global_store_dwordx4 v[30:31], v[24:27], off
	ds_read_b32 v24, v21 offset:96
	ds_read_b32 v25, v21 offset:228
	ds_read_b32 v26, v21 offset:360
	ds_read_b32 v27, v21 offset:492
	ds_read_b32 v30, v21 offset:624
	ds_read_b32 v31, v21 offset:756
	ds_read_b32 v32, v21 offset:888
	ds_read_b32 v33, v21 offset:1020
	s_waitcnt lgkmcnt(0)
	v_cvt_pk_bf16_f32 v24, v24, v25
	v_cvt_pk_bf16_f32 v25, v26, v27
	v_cvt_pk_bf16_f32 v26, v30, v31
	v_lshl_add_u64 v[28:29], v[28:29], 0, v[16:17]
	v_cvt_pk_bf16_f32 v27, v32, v33
	global_store_dwordx4 v[28:29], v[24:27], off
	s_waitcnt lgkmcnt(0)
	s_add_i32 s10, s10, s30
	s_cmp_lt_i32 s10, 16
	s_cbranch_scc0 .LBB0_919

; #define LAS __attribute__((address_space(3)))
; __device__ __forceinline__ unsigned pk2(float lo, float hi) { f32x2 v = {lo, hi}; bf16x2_t b = __builtin_convertvector(v, bf16x2_t); return __builtin_bit_cast(unsigned, b); }
; #define LDS_WAIT() asm volatile("s_waitcnt lgkmcnt(0)" ::: "memory")
; __device__ __forceinline__ void tr_item(const float* src, int ld, int kv, int nv, const float* ks, bf16_t* dst, int ldd, LAS float* scr, int lane) {
;     ...
;     LDS_WAIT(); asm volatile("" ::: "memory");
;     const int c = lane & 7;
; #pragma unroll
;     for (int j = 0; j < 4; ++j) { const int nn = (lane >> 3) + 8 * j; const LAS float* s = scr + (8 * c) * 33 + nn;
;         u32x4 o; o.x = pk2(s[0 * 33], s[1 * 33]); o.y = pk2(s[2 * 33], s[3 * 33]); o.z = pk2(s[4 * 33], s[5 * 33]); o.w = pk2(s[6 * 33], s[7 * 33]);
;         *(u32x4*)(dst + (size_t)nn * ldd + 8 * c) = o; }
;     LDS_WAIT(); asm volatile("" ::: "memory");
.LBB0_922:
	s_waitcnt lgkmcnt(0)
	s_lshl_b64 s[4:5], s[12:13], 11
	s_add_u32 s12, s16, s4
	ds_read_b32 v17, v3
	ds_read_b32 v24, v3 offset:132
	ds_read_b32 v25, v3 offset:264
	ds_read_b32 v26, v3 offset:396
	ds_read_b32 v27, v3 offset:528
	ds_read_b32 v28, v3 offset:660
	ds_read_b32 v29, v3 offset:792
	ds_read_b32 v30, v3 offset:924
	s_addc_u32 s13, s17, s5
	s_lshl_b64 s[4:5], s[10:11], 1
	s_add_u32 s4, s12, s4
	s_addc_u32 s5, s13, s5
	v_mov_b32_e32 v19, v0
	v_lshl_add_u64 v[20:21], s[4:5], 0, v[18:19]
	s_waitcnt lgkmcnt(0)
	v_cvt_pk_bf16_f32 v24, v17, v24
	s_waitcnt lgkmcnt(4)
	v_cvt_pk_bf16_f32 v25, v25, v26
	s_waitcnt lgkmcnt(2)
	v_cvt_pk_bf16_f32 v26, v27, v28
	s_waitcnt lgkmcnt(0)
	v_cvt_pk_bf16_f32 v27, v29, v30
	v_lshl_add_u64 v[28:29], v[20:21], 0, v[6:7]
	global_store_dwordx4 v[28:29], v[24:27], off
	ds_read_b32 v17, v3 offset:32
	ds_read_b32 v19, v3 offset:164
	ds_read_b32 v25, v3 offset:296
	ds_read_b32 v26, v3 offset:428
	ds_read_b32 v27, v3 offset:560
	ds_read_b32 v28, v3 offset:692
	ds_read_b32 v29, v3 offset:824
	ds_read_b32 v30, v3 offset:956
	s_waitcnt lgkmcnt(0)
	v_cvt_pk_bf16_f32 v24, v17, v19
	v_cvt_pk_bf16_f32 v25, v25, v26
	v_cvt_pk_bf16_f32 v26, v27, v28
	s_add_i32 s18, s18, s30
	v_cvt_pk_bf16_f32 v27, v29, v30
	v_lshl_add_u64 v[28:29], v[20:21], 0, v[8:9]
	global_store_dwordx4 v[28:29], v[24:27], off
	ds_read_b32 v17, v3 offset:64
	ds_read_b32 v19, v3 offset:196
	ds_read_b32 v25, v3 offset:328
	ds_read_b32 v26, v3 offset:460
	ds_read_b32 v27, v3 offset:592
	ds_read_b32 v28, v3 offset:724
	ds_read_b32 v29, v3 offset:856
	ds_read_b32 v30, v3 offset:988
	s_waitcnt lgkmcnt(0)
	v_cvt_pk_bf16_f32 v24, v17, v19
	v_cvt_pk_bf16_f32 v25, v25, v26
	v_cvt_pk_bf16_f32 v26, v27, v28
	s_cmpk_lt_i32 s18, 0x60
	v_cvt_pk_bf16_f32 v27, v29, v30
	v_lshl_add_u64 v[28:29], v[20:21], 0, v[10:11]
	global_store_dwordx4 v[28:29], v[24:27], off
	ds_read_b32 v17, v3 offset:96
	ds_read_b32 v19, v3 offset:228
	ds_read_b32 v25, v3 offset:360
	ds_read_b32 v26, v3 offset:492
	ds_read_b32 v27, v3 offset:624
	ds_read_b32 v28, v3 offset:756
	ds_read_b32 v29, v3 offset:888
	ds_read_b32 v30, v3 offset:1020
	s_waitcnt lgkmcnt(0)
	v_cvt_pk_bf16_f32 v24, v17, v19
	v_cvt_pk_bf16_f32 v25, v25, v26
	v_cvt_pk_bf16_f32 v26, v27, v28
	v_lshl_add_u64 v[20:21], v[20:21], 0, v[12:13]
	v_cvt_pk_bf16_f32 v27, v29, v30
	global_store_dwordx4 v[20:21], v[24:27], off
	s_waitcnt lgkmcnt(0)
	s_cbranch_scc0 .LBB0_936

; #define LAS __attribute__((address_space(3)))
; __device__ __forceinline__ unsigned pk2(float lo, float hi) { f32x2 v = {lo, hi}; bf16x2_t b = __builtin_convertvector(v, bf16x2_t); return __builtin_bit_cast(unsigned, b); }
; __device__ __forceinline__ void tr_item(const float* src, int ld, int kv, int nv, const float* ks, bf16_t* dst, int ldd, LAS float* scr, int lane) {
;     ...
;     const int c = lane & 7;
; #pragma unroll
;     for (int j = 0; j < 4; ++j) { const int nn = (lane >> 3) + 8 * j; const LAS float* s = scr + (8 * c) * 33 + nn;
;         u32x4 o; o.x = pk2(s[0 * 33], s[1 * 33]); o.y = pk2(s[2 * 33], s[3 * 33]); o.z = pk2(s[4 * 33], s[5 * 33]); o.w = pk2(s[6 * 33], s[7 * 33]);
;         *(u32x4*)(dst + (size_t)nn * ldd + 8 * c) = o; }
; __device__ __forceinline__ void convert_odd(const Ctx& c, const Params& p, int L) {
;     ...
;       const int items = 6 * 64;
;       for (int it = c.gw; it < items; it += c.ngw) { const int kb = it / 64, nb = it % 64, n0 = 32 * nb, R = n0 >> 9, nn0 = n0 & 511;
;           const float* src = p.in[c.zo + 16]; int kv = 0, ld = 512;
;           if (R == 0 && kb == 0) { src = p.in[c.zo + 16] + (size_t)o * 64 * 512 + nn0; kv = 64; }
;           else if (R == 1 && kb == 1) { src = p.in[c.zo + 18] + (size_t)o * 64 * 512 + nn0; kv = 64; }
;           else if (R == 2 && (kb == 2 || kb == 3)) { src = p.in[c.zo + 19] + (size_t)o * 128 * 512 + (size_t)(kb - 2) * 64 * 512 + nn0; kv = 64; }
;           else if (R == 3 && kb == 4 && o > 0) { src = p.in[c.zo + 28] + (size_t)(o - 1) * 32 * 512 + nn0; kv = 32; }
;           tr_item(src, ld, kv, kv ? 32 : 0, nullptr, wl + (size_t)n0 * 384 + 64 * kb, 384, scr, c.lane); } }
.LBB0_938:
	s_mul_i32 s14, s35, 0x3000
	s_ashr_i32 s15, s14, 31
	s_lshl_b64 s[14:15], s[14:15], 1
	v_readlane_b32 s0, v255, 31
	s_add_u32 s14, s0, s14
	v_readlane_b32 s0, v255, 32
	s_waitcnt lgkmcnt(0)
	s_addc_u32 s15, s0, s15
	s_lshl_b32 s12, s12, 6
	s_ashr_i32 s13, s12, 31
	ds_read_b32 v17, v1
	ds_read_b32 v23, v1 offset:132
	ds_read_b32 v25, v1 offset:264
	ds_read_b32 v26, v1 offset:396
	ds_read_b32 v27, v1 offset:528
	ds_read_b32 v28, v1 offset:660
	ds_read_b32 v29, v1 offset:792
	ds_read_b32 v30, v1 offset:924
	s_lshl_b64 s[12:13], s[12:13], 1
	s_add_u32 s12, s14, s12
	s_addc_u32 s13, s15, s13
	v_mov_b32_e32 v19, v0
	v_lshl_add_u64 v[20:21], s[12:13], 0, v[18:19]
	s_waitcnt lgkmcnt(0)
	v_cvt_pk_bf16_f32 v24, v17, v23
	s_waitcnt lgkmcnt(4)
	v_cvt_pk_bf16_f32 v25, v25, v26
	s_waitcnt lgkmcnt(2)
	v_cvt_pk_bf16_f32 v26, v27, v28
	s_waitcnt lgkmcnt(0)
	v_cvt_pk_bf16_f32 v27, v29, v30
	v_lshl_add_u64 v[28:29], v[20:21], 0, v[6:7]
	global_store_dwordx4 v[28:29], v[24:27], off
	ds_read_b32 v17, v1 offset:32
	ds_read_b32 v19, v1 offset:164
	ds_read_b32 v23, v1 offset:296
	ds_read_b32 v25, v1 offset:428
	ds_read_b32 v26, v1 offset:560
	ds_read_b32 v27, v1 offset:692
	ds_read_b32 v28, v1 offset:824
	ds_read_b32 v29, v1 offset:956
	s_waitcnt lgkmcnt(0)
	v_cvt_pk_bf16_f32 v24, v17, v19
	v_cvt_pk_bf16_f32 v25, v23, v25
	v_cvt_pk_bf16_f32 v26, v26, v27
	s_add_i32 s34, s34, s30
	v_cvt_pk_bf16_f32 v27, v28, v29
	v_lshl_add_u64 v[28:29], v[20:21], 0, v[8:9]
	global_store_dwordx4 v[28:29], v[24:27], off
	ds_read_b32 v17, v1 offset:64
	ds_read_b32 v19, v1 offset:196
	ds_read_b32 v23, v1 offset:328
	ds_read_b32 v25, v1 offset:460
	ds_read_b32 v26, v1 offset:592
	ds_read_b32 v27, v1 offset:724
	ds_read_b32 v28, v1 offset:856
	ds_read_b32 v29, v1 offset:988
	s_waitcnt lgkmcnt(0)
	v_cvt_pk_bf16_f32 v24, v17, v19
	v_cvt_pk_bf16_f32 v25, v23, v25
	v_cvt_pk_bf16_f32 v26, v26, v27
	s_cmpk_gt_i32 s34, 0x17f
	v_cvt_pk_bf16_f32 v27, v28, v29
	v_lshl_add_u64 v[28:29], v[20:21], 0, v[10:11]
	global_store_dwordx4 v[28:29], v[24:27], off
	ds_read_b32 v17, v1 offset:96
	ds_read_b32 v19, v1 offset:228
	ds_read_b32 v23, v1 offset:360
	ds_read_b32 v25, v1 offset:492
	ds_read_b32 v26, v1 offset:624
	ds_read_b32 v27, v1 offset:756
	ds_read_b32 v28, v1 offset:888
	ds_read_b32 v29, v1 offset:1020
	s_waitcnt lgkmcnt(0)
	v_cvt_pk_bf16_f32 v24, v17, v19
	v_cvt_pk_bf16_f32 v25, v23, v25
	v_cvt_pk_bf16_f32 v26, v26, v27
	v_lshl_add_u64 v[20:21], v[20:21], 0, v[12:13]
	v_cvt_pk_bf16_f32 v27, v28, v29
	global_store_dwordx4 v[20:21], v[24:27], off
	s_waitcnt lgkmcnt(0)
	s_cbranch_scc1 .LBB0_966

; #define LAS __attribute__((address_space(3)))
; __device__ __forceinline__ unsigned pk2(float lo, float hi) { f32x2 v = {lo, hi}; bf16x2_t b = __builtin_convertvector(v, bf16x2_t); return __builtin_bit_cast(unsigned, b); }
; __device__ __forceinline__ void tr_item(const float* src, int ld, int kv, int nv, const float* ks, bf16_t* dst, int ldd, LAS float* scr, int lane) {
;     ...
;     const int c = lane & 7;
; #pragma unroll
;     for (int j = 0; j < 4; ++j) { const int nn = (lane >> 3) + 8 * j; const LAS float* s = scr + (8 * c) * 33 + nn;
;         u32x4 o; o.x = pk2(s[0 * 33], s[1 * 33]); o.y = pk2(s[2 * 33], s[3 * 33]); o.z = pk2(s[4 * 33], s[5 * 33]); o.w = pk2(s[6 * 33], s[7 * 33]);
;         *(u32x4*)(dst + (size_t)nn * ldd + 8 * c) = o; }
; __device__ __forceinline__ void convert_odd(const Ctx& c, const Params& p, int L) {
;     ...
;     tr_job(c, p.in[c.zo + 31] + (size_t)o * 512 * 768, 768, 512, 768, p.in[c.zo + 29] + (size_t)o * 512, (bf16_t*)(c.ws + WS_WB + WB_UQ), 512, 512, 768);
.LBB0_969:
	s_waitcnt lgkmcnt(0)
	s_lshl_b64 s[10:11], s[10:11], 10
	v_readlane_b32 s0, v255, 33
	s_add_u32 s10, s0, s10
	v_readlane_b32 s0, v255, 34
	ds_read_b32 v19, v1
	ds_read_b32 v22, v1 offset:132
	ds_read_b32 v23, v1 offset:264
	ds_read_b32 v24, v1 offset:396
	ds_read_b32 v25, v1 offset:528
	ds_read_b32 v29, v1 offset:660
	ds_read_b32 v30, v1 offset:792
	ds_read_b32 v31, v1 offset:924
	s_addc_u32 s11, s0, s11
	s_lshl_b64 s[4:5], s[4:5], 1
	s_add_u32 s4, s10, s4
	s_addc_u32 s5, s11, s5
	v_mov_b32_e32 v21, v0
	v_lshl_add_u64 v[26:27], s[4:5], 0, v[20:21]
	s_waitcnt lgkmcnt(0)
	v_cvt_pk_bf16_f32 v22, v19, v22
	s_waitcnt lgkmcnt(4)
	v_cvt_pk_bf16_f32 v23, v23, v24
	s_waitcnt lgkmcnt(2)
	v_cvt_pk_bf16_f32 v24, v25, v29
	s_waitcnt lgkmcnt(0)
	v_cvt_pk_bf16_f32 v25, v30, v31
	v_lshl_add_u64 v[30:31], v[26:27], 0, v[6:7]
	global_store_dwordx4 v[30:31], v[22:25], off
	ds_read_b32 v19, v1 offset:32
	ds_read_b32 v21, v1 offset:164
	ds_read_b32 v23, v1 offset:296
	ds_read_b32 v24, v1 offset:428
	ds_read_b32 v25, v1 offset:560
	ds_read_b32 v29, v1 offset:692
	ds_read_b32 v30, v1 offset:824
	ds_read_b32 v31, v1 offset:956
	s_waitcnt lgkmcnt(0)
	v_cvt_pk_bf16_f32 v22, v19, v21
	v_cvt_pk_bf16_f32 v23, v23, v24
	v_cvt_pk_bf16_f32 v24, v25, v29
	s_add_i32 s18, s18, s30
	v_cvt_pk_bf16_f32 v25, v30, v31
	v_lshl_add_u64 v[30:31], v[26:27], 0, v[8:9]
	global_store_dwordx4 v[30:31], v[22:25], off
	ds_read_b32 v19, v1 offset:64
	ds_read_b32 v21, v1 offset:196
	ds_read_b32 v23, v1 offset:328
	ds_read_b32 v24, v1 offset:460
	ds_read_b32 v25, v1 offset:592
	ds_read_b32 v29, v1 offset:724
	ds_read_b32 v30, v1 offset:856
	ds_read_b32 v31, v1 offset:988
	s_waitcnt lgkmcnt(0)
	v_cvt_pk_bf16_f32 v22, v19, v21
	v_cvt_pk_bf16_f32 v23, v23, v24
	v_cvt_pk_bf16_f32 v24, v25, v29
	s_cmpk_lt_i32 s18, 0xc0
	v_cvt_pk_bf16_f32 v25, v30, v31
	v_lshl_add_u64 v[30:31], v[26:27], 0, v[10:11]
	global_store_dwordx4 v[30:31], v[22:25], off
	ds_read_b32 v19, v1 offset:96
	ds_read_b32 v21, v1 offset:228
	ds_read_b32 v23, v1 offset:360
	ds_read_b32 v24, v1 offset:492
	ds_read_b32 v25, v1 offset:624
	ds_read_b32 v29, v1 offset:756
	ds_read_b32 v30, v1 offset:888
	ds_read_b32 v31, v1 offset:1020
	s_waitcnt lgkmcnt(0)
	v_cvt_pk_bf16_f32 v22, v19, v21
	v_cvt_pk_bf16_f32 v23, v23, v24
	v_cvt_pk_bf16_f32 v24, v25, v29
	v_lshl_add_u64 v[26:27], v[26:27], 0, v[12:13]
	v_cvt_pk_bf16_f32 v25, v30, v31
	global_store_dwordx4 v[26:27], v[22:25], off
	s_waitcnt lgkmcnt(0)
	s_cbranch_scc0 .LBB0_983

; #define LAS __attribute__((address_space(3)))
; __device__ __forceinline__ unsigned pk2(float lo, float hi) { f32x2 v = {lo, hi}; bf16x2_t b = __builtin_convertvector(v, bf16x2_t); return __builtin_bit_cast(unsigned, b); }
; __device__ __forceinline__ void tr_item(const float* src, int ld, int kv, int nv, const float* ks, bf16_t* dst, int ldd, LAS float* scr, int lane) {
;     ...
;     const int c = lane & 7;
; #pragma unroll
;     for (int j = 0; j < 4; ++j) { const int nn = (lane >> 3) + 8 * j; const LAS float* s = scr + (8 * c) * 33 + nn;
;         u32x4 o; o.x = pk2(s[0 * 33], s[1 * 33]); o.y = pk2(s[2 * 33], s[3 * 33]); o.z = pk2(s[4 * 33], s[5 * 33]); o.w = pk2(s[6 * 33], s[7 * 33]);
;         *(u32x4*)(dst + (size_t)nn * ldd + 8 * c) = o; }
; __device__ __forceinline__ void convert_odd(const Ctx& c, const Params& p, int L) {
;     ...
;     tr_job(c, p.in[c.zo + 32] + (size_t)o * 256 * 1024, 1024, 256, 1024, p.in[c.zo + 30] + (size_t)o * 256, (bf16_t*)(c.ws + WS_WB + WB_UKV), 256, 256, 1024);
.LBB0_986:
	s_waitcnt lgkmcnt(0)
	s_lshl_b64 s[10:11], s[10:11], 9
	s_add_u32 s10, s44, s10
	ds_read_b32 v19, v1
	ds_read_b32 v22, v1 offset:132
	ds_read_b32 v23, v1 offset:264
	ds_read_b32 v24, v1 offset:396
	ds_read_b32 v25, v1 offset:528
	ds_read_b32 v29, v1 offset:660
	ds_read_b32 v30, v1 offset:792
	ds_read_b32 v31, v1 offset:924
	s_addc_u32 s11, s45, s11
	s_lshl_b64 s[4:5], s[4:5], 1
	s_add_u32 s4, s10, s4
	s_addc_u32 s5, s11, s5
	v_mov_b32_e32 v21, v0
	v_lshl_add_u64 v[26:27], s[4:5], 0, v[20:21]
	s_waitcnt lgkmcnt(0)
	v_cvt_pk_bf16_f32 v22, v19, v22
	s_waitcnt lgkmcnt(4)
	v_cvt_pk_bf16_f32 v23, v23, v24
	s_waitcnt lgkmcnt(2)
	v_cvt_pk_bf16_f32 v24, v25, v29
	s_waitcnt lgkmcnt(0)
	v_cvt_pk_bf16_f32 v25, v30, v31
	v_lshl_add_u64 v[30:31], v[26:27], 0, v[6:7]
	global_store_dwordx4 v[30:31], v[22:25], off
	ds_read_b32 v19, v1 offset:32
	ds_read_b32 v21, v1 offset:164
	ds_read_b32 v23, v1 offset:296
	ds_read_b32 v24, v1 offset:428
	ds_read_b32 v25, v1 offset:560
	ds_read_b32 v29, v1 offset:692
	ds_read_b32 v30, v1 offset:824
	ds_read_b32 v31, v1 offset:956
	s_waitcnt lgkmcnt(0)
	v_cvt_pk_bf16_f32 v22, v19, v21
	v_cvt_pk_bf16_f32 v23, v23, v24
	v_cvt_pk_bf16_f32 v24, v25, v29
	s_add_i32 s20, s20, s30
	v_cvt_pk_bf16_f32 v25, v30, v31
	v_lshl_add_u64 v[30:31], v[26:27], 0, v[8:9]
	global_store_dwordx4 v[30:31], v[22:25], off
	ds_read_b32 v19, v1 offset:64
	ds_read_b32 v21, v1 offset:196
	ds_read_b32 v23, v1 offset:328
	ds_read_b32 v24, v1 offset:460
	ds_read_b32 v25, v1 offset:592
	ds_read_b32 v29, v1 offset:724
	ds_read_b32 v30, v1 offset:856
	ds_read_b32 v31, v1 offset:988
	s_waitcnt lgkmcnt(0)
	v_cvt_pk_bf16_f32 v22, v19, v21
	v_cvt_pk_bf16_f32 v23, v23, v24
	v_cvt_pk_bf16_f32 v24, v25, v29
	s_cmpk_gt_i32 s20, 0x7f
	v_cvt_pk_bf16_f32 v25, v30, v31
	v_lshl_add_u64 v[30:31], v[26:27], 0, v[10:11]
	global_store_dwordx4 v[30:31], v[22:25], off
	ds_read_b32 v19, v1 offset:96
	ds_read_b32 v21, v1 offset:228
	ds_read_b32 v23, v1 offset:360
	ds_read_b32 v24, v1 offset:492
	ds_read_b32 v25, v1 offset:624
	ds_read_b32 v29, v1 offset:756
	ds_read_b32 v30, v1 offset:888
	ds_read_b32 v31, v1 offset:1020
	s_waitcnt lgkmcnt(0)
	v_cvt_pk_bf16_f32 v22, v19, v21
	v_cvt_pk_bf16_f32 v23, v23, v24
	v_cvt_pk_bf16_f32 v24, v25, v29
	v_lshl_add_u64 v[26:27], v[26:27], 0, v[12:13]
	v_cvt_pk_bf16_f32 v25, v30, v31
	global_store_dwordx4 v[26:27], v[22:25], off
	s_waitcnt lgkmcnt(0)
	s_cbranch_scc1 .LBB0_1000

; __device__ __forceinline__ void tr_item(const float* src, int ld, int kv, int nv, const float* ks, bf16_t* dst, int ldd, LAS float* scr, int lane) {
;     ...
;         float tmp[32]; const float* sp = src + (size_t)(lane >> 5) * ld + n;
; #pragma unroll
;         for (int i = 0; i < 32; ++i) tmp[i] = sp[(size_t)(2 * i) * ld];
; #pragma unroll
;         for (int i = 0; i < 32; ++i) scr[(2 * i + (lane >> 5)) * 33 + n] = tmp[i];
; __device__ __forceinline__ void convert_common(const Ctx& c, const Params& p, int L, const float* wout_src) {
;     ...
;     { const float* src = p.in[c.zo + 4] + (size_t)L * D_ * 2 * DFF; bf16_t* dst = (bf16_t*)((unsigned char*)WB + WB_GU);
;       const int nnb = 2 * DFF / 32, items = (D_ / 64) * nnb;
;       for (int it = c.gw; it < items; it += c.ngw) { const int kb = it / nnb, nb = it % nnb, k0 = 64 * kb, n0 = 32 * nb; const int t = n0 >> 8, w = n0 & 255;
;           const int sc = (w < 128) ? 128 * t + w : DFF + 128 * t + (w - 128);
;           tr_item(src + (size_t)k0 * (2 * DFF) + sc, 2 * DFF, 64, 32, nullptr, dst + (size_t)n0 * D_ + k0, D_, scr, c.lane); } }
.LBB0_1004:
	s_mul_hi_i32 s4, s20, 0x2e8ba2e9
	s_lshr_b32 s5, s4, 31
	s_ashr_i32 s4, s4, 5
	s_add_i32 s5, s4, s5
	s_mul_i32 s10, s5, 0xffffea00
	s_mul_i32 s11, s5, 0xfffff500
	s_lshl_b32 s4, s5, 6
	s_mul_i32 s21, s5, 0x160000
	s_add_i32 s10, s16, s10
	s_add_i32 s5, s18, s11
	s_and_b32 s24, s10, 0xe0
	s_and_b32 s5, s5, 0xffffff80
	s_or_b32 s25, s5, s24
	s_add_i32 s5, s24, s5
	s_addk_i32 s5, 0xa80
	s_cmpk_lt_u32 s24, 0x80
	s_cselect_b32 s24, s25, s5
	s_ashr_i32 s5, s4, 31
	s_mul_hi_i32 s11, s4, 0x5800
	s_add_u32 s21, s14, s21
	s_addc_u32 s11, s15, s11
	s_ashr_i32 s25, s24, 31
	s_lshl_b64 s[24:25], s[24:25], 2
	s_add_u32 s24, s21, s24
	s_addc_u32 s25, s11, s25
	v_mov_b32_e32 v13, v0
	v_lshl_add_u64 v[18:19], s[24:25], 0, v[2:3]
	v_lshl_add_u64 v[18:19], v[18:19], 0, v[12:13]
	v_add_co_u32_e32 v20, vcc, s0, v18
	s_ashr_i32 s11, s10, 31
	s_nop 0
	v_addc_co_u32_e32 v21, vcc, 0, v19, vcc
	v_add_co_u32_e32 v22, vcc, s61, v18
	s_lshl_b64 s[10:11], s[10:11], 11
	s_nop 0
	v_addc_co_u32_e32 v23, vcc, 0, v19, vcc
	v_add_co_u32_e32 v24, vcc, s27, v18
	s_add_u32 s10, s71, s10
	s_nop 0
	v_addc_co_u32_e32 v25, vcc, 0, v19, vcc
	v_add_co_u32_e32 v26, vcc, s68, v18
	s_addc_u32 s11, s60, s11
	s_nop 0
	v_addc_co_u32_e32 v27, vcc, 0, v19, vcc
	v_add_co_u32_e32 v28, vcc, s29, v18
	s_lshl_b64 s[4:5], s[4:5], 1
	s_nop 0
	v_addc_co_u32_e32 v29, vcc, 0, v19, vcc
	v_add_co_u32_e32 v30, vcc, s31, v18
	s_add_u32 s4, s10, s4
	s_nop 0
	v_addc_co_u32_e32 v31, vcc, 0, v19, vcc
	v_add_co_u32_e32 v32, vcc, s34, v18
	v_mov_b32_e32 v15, v0
	s_nop 0
	v_addc_co_u32_e32 v33, vcc, 0, v19, vcc
	v_add_co_u32_e32 v34, vcc, s35, v18
	s_addc_u32 s5, s11, s5
	s_nop 0
	v_addc_co_u32_e32 v35, vcc, 0, v19, vcc
	v_add_co_u32_e32 v36, vcc, s36, v18
	s_add_i32 s20, s20, s30
	s_nop 0
	v_addc_co_u32_e32 v37, vcc, 0, v19, vcc
	v_add_co_u32_e32 v38, vcc, s38, v18
	s_add_i32 s16, s16, s17
	s_nop 0
	v_addc_co_u32_e32 v39, vcc, 0, v19, vcc
	v_add_co_u32_e32 v40, vcc, s39, v18
	s_add_i32 s18, s18, s19
	s_nop 0
	v_addc_co_u32_e32 v41, vcc, 0, v19, vcc
	v_add_co_u32_e32 v42, vcc, s40, v18
	s_cmpk_gt_i32 s20, 0xaff
	s_nop 0
	v_addc_co_u32_e32 v43, vcc, 0, v19, vcc
	v_add_co_u32_e32 v44, vcc, s42, v18
	s_nop 1
	v_addc_co_u32_e32 v45, vcc, 0, v19, vcc
	v_add_co_u32_e32 v46, vcc, s44, v18
	s_nop 1
	v_addc_co_u32_e32 v47, vcc, 0, v19, vcc
	v_add_co_u32_e32 v48, vcc, s45, v18
	s_nop 1
	v_addc_co_u32_e32 v49, vcc, 0, v19, vcc
	v_add_co_u32_e32 v50, vcc, s26, v18
	s_nop 1
	v_addc_co_u32_e32 v51, vcc, 0, v19, vcc
	v_add_co_u32_e32 v52, vcc, s46, v18
	s_nop 1
	v_addc_co_u32_e32 v53, vcc, 0, v19, vcc
	v_add_co_u32_e32 v54, vcc, s48, v18
	s_nop 1
	v_addc_co_u32_e32 v55, vcc, 0, v19, vcc
	v_add_co_u32_e32 v56, vcc, s49, v18
	s_nop 1
	v_addc_co_u32_e32 v57, vcc, 0, v19, vcc
	v_add_co_u32_e32 v58, vcc, s58, v18
	s_nop 1
	v_addc_co_u32_e32 v59, vcc, 0, v19, vcc
	v_add_co_u32_e32 v60, vcc, s59, v18
	s_nop 1
	v_addc_co_u32_e32 v61, vcc, 0, v19, vcc
	v_add_co_u32_e32 v62, vcc, s72, v18
	s_nop 1
	v_addc_co_u32_e32 v63, vcc, 0, v19, vcc
	v_add_co_u32_e32 v64, vcc, s73, v18
	s_nop 1
	v_addc_co_u32_e32 v65, vcc, 0, v19, vcc
	v_add_co_u32_e32 v66, vcc, s80, v18
	s_nop 1
	v_addc_co_u32_e32 v67, vcc, 0, v19, vcc
	v_add_co_u32_e32 v68, vcc, s81, v18
	s_nop 1
	v_addc_co_u32_e32 v69, vcc, 0, v19, vcc
	v_add_co_u32_e32 v70, vcc, s82, v18
	s_nop 1
	v_addc_co_u32_e32 v71, vcc, 0, v19, vcc
	v_add_co_u32_e32 v72, vcc, s83, v18
	s_nop 1
	v_addc_co_u32_e32 v73, vcc, 0, v19, vcc
	v_add_co_u32_e32 v74, vcc, s84, v18
	s_nop 1
	v_addc_co_u32_e32 v75, vcc, 0, v19, vcc
	v_add_co_u32_e32 v76, vcc, s85, v18
	s_nop 1
	v_addc_co_u32_e32 v77, vcc, 0, v19, vcc
	v_add_co_u32_e32 v78, vcc, s87, v18
	s_nop 1
	v_addc_co_u32_e32 v79, vcc, 0, v19, vcc
	v_add_co_u32_e32 v80, vcc, s92, v18
	s_nop 1
	v_addc_co_u32_e32 v81, vcc, 0, v19, vcc
	global_load_dword v13, v[18:19], off
	global_load_dword v17, v[20:21], off
	s_nop 0
	global_load_dword v18, v[22:23], off
	global_load_dword v19, v[24:25], off
	global_load_dword v20, v[26:27], off
	global_load_dword v21, v[28:29], off
	s_nop 0
	global_load_dword v30, v[30:31], off
	s_nop 0
	global_load_dword v31, v[32:33], off
	s_nop 0
	global_load_dword v32, v[34:35], off
	global_load_dword v33, v[36:37], off
	s_nop 0
	global_load_dword v34, v[38:39], off
	global_load_dword v35, v[40:41], off
	global_load_dword v36, v[42:43], off
	global_load_dword v37, v[44:45], off
	s_nop 0
	global_load_dword v38, v[46:47], off
	global_load_dword v39, v[48:49], off
	global_load_dword v40, v[50:51], off
	global_load_dword v41, v[52:53], off
	global_load_dword v42, v[54:55], off
	global_load_dword v43, v[56:57], off
	global_load_dword v44, v[58:59], off
	global_load_dword v45, v[60:61], off
	global_load_dword v46, v[62:63], off
	global_load_dword v47, v[64:65], off
	global_load_dword v48, v[66:67], off
	global_load_dword v49, v[68:69], off
	global_load_dword v50, v[70:71], off
	global_load_dword v51, v[72:73], off
	global_load_dword v52, v[74:75], off
	global_load_dword v53, v[76:77], off
	global_load_dword v54, v[78:79], off
	global_load_dword v55, v[80:81], off
	v_add_u32_e32 v56, 0x400, v16
	v_add_u32_e32 v57, 0x800, v16
	v_add_u32_e32 v58, 0xc00, v16
	v_add_u32_e32 v59, 0x1000, v16
	v_add_u32_e32 v60, 0x1400, v16
	v_add_u32_e32 v61, 0x1800, v16
	v_add_u32_e32 v62, 0x1c00, v16
	s_waitcnt vmcnt(0)
; #define LAS __attribute__((address_space(3)))
; __device__ __forceinline__ unsigned pk2(float lo, float hi) { f32x2 v = {lo, hi}; bf16x2_t b = __builtin_convertvector(v, bf16x2_t); return __builtin_bit_cast(unsigned, b); }
; #define LDS_WAIT() asm volatile("s_waitcnt lgkmcnt(0)" ::: "memory")
; __device__ __forceinline__ void tr_item(const float* src, int ld, int kv, int nv, const float* ks, bf16_t* dst, int ldd, LAS float* scr, int lane) {
;     ...
;         for (int i = 0; i < 32; ++i) scr[(2 * i + (lane >> 5)) * 33 + n] = tmp[i];
;     } else {
; #pragma unroll 4
;         for (int i = 0; i < 32; ++i) { const int kk = 2 * i + (lane >> 5); float v = 0.f; if (kk < kv && n < nv) { v = src[(size_t)kk * ld + n]; if (ks) v *= ks[kk]; } scr[kk * 33 + n] = v; }
;     }
;     LDS_WAIT(); asm volatile("" ::: "memory");
;     const int c = lane & 7;
; #pragma unroll
;     for (int j = 0; j < 4; ++j) { const int nn = (lane >> 3) + 8 * j; const LAS float* s = scr + (8 * c) * 33 + nn;
;         u32x4 o; o.x = pk2(s[0 * 33], s[1 * 33]); o.y = pk2(s[2 * 33], s[3 * 33]); o.z = pk2(s[4 * 33], s[5 * 33]); o.w = pk2(s[6 * 33], s[7 * 33]);
;         *(u32x4*)(dst + (size_t)nn * ldd + 8 * c) = o; }
;     LDS_WAIT(); asm volatile("" ::: "memory");
	ds_write2_b32 v16, v13, v17 offset1:66
	s_waitcnt vmcnt(28)
	ds_write2_b32 v16, v18, v19 offset0:132 offset1:198
	s_waitcnt vmcnt(26)
	ds_write2_b32 v56, v20, v21 offset0:8 offset1:74
	s_waitcnt vmcnt(24)
	ds_write2_b32 v56, v30, v31 offset0:140 offset1:206
	s_waitcnt vmcnt(22)
	ds_write2_b32 v57, v32, v33 offset0:16 offset1:82
	s_waitcnt vmcnt(20)
	ds_write2_b32 v57, v34, v35 offset0:148 offset1:214
	s_waitcnt vmcnt(18)
	ds_write2_b32 v58, v36, v37 offset0:24 offset1:90
	s_waitcnt vmcnt(16)
	ds_write2_b32 v58, v38, v39 offset0:156 offset1:222
	s_waitcnt vmcnt(14)
	ds_write2_b32 v59, v40, v41 offset0:32 offset1:98
	s_waitcnt vmcnt(12)
	ds_write2_b32 v59, v42, v43 offset0:164 offset1:230
	s_waitcnt vmcnt(10)
	ds_write2_b32 v60, v44, v45 offset0:40 offset1:106
	s_waitcnt vmcnt(8)
	ds_write2_b32 v60, v46, v47 offset0:172 offset1:238
	s_waitcnt vmcnt(6)
	ds_write2_b32 v61, v48, v49 offset0:48 offset1:114
	s_waitcnt vmcnt(4)
	ds_write2_b32 v61, v50, v51 offset0:180 offset1:246
	s_waitcnt vmcnt(2)
	ds_write2_b32 v62, v52, v53 offset0:56 offset1:122
	s_waitcnt vmcnt(0)
	ds_write2_b32 v62, v54, v55 offset0:188 offset1:254
	s_waitcnt lgkmcnt(0)
	v_lshl_add_u64 v[22:23], s[4:5], 0, v[14:15]
	ds_read_b32 v13, v1
	ds_read_b32 v15, v1 offset:132
	ds_read_b32 v17, v1 offset:264
	ds_read_b32 v19, v1 offset:396
	ds_read_b32 v20, v1 offset:528
	ds_read_b32 v21, v1 offset:660
	ds_read_b32 v30, v1 offset:792
	ds_read_b32 v31, v1 offset:924
	v_lshl_add_u64 v[24:25], v[22:23], 0, v[4:5]
	s_waitcnt lgkmcnt(6)
	v_cvt_pk_bf16_f32 v18, v13, v15
	s_waitcnt lgkmcnt(4)
	v_cvt_pk_bf16_f32 v19, v17, v19
	s_waitcnt lgkmcnt(2)
	v_cvt_pk_bf16_f32 v20, v20, v21
	s_waitcnt lgkmcnt(0)
	v_cvt_pk_bf16_f32 v21, v30, v31
	global_store_dwordx4 v[24:25], v[18:21], off
	ds_read_b32 v13, v1 offset:32
	ds_read_b32 v15, v1 offset:164
	ds_read_b32 v17, v1 offset:296
	ds_read_b32 v19, v1 offset:428
	ds_read_b32 v20, v1 offset:560
	ds_read_b32 v21, v1 offset:692
	ds_read_b32 v24, v1 offset:824
	ds_read_b32 v25, v1 offset:956
	v_lshl_add_u64 v[26:27], v[22:23], 0, v[6:7]
	s_waitcnt lgkmcnt(0)
	v_cvt_pk_bf16_f32 v18, v13, v15
	v_cvt_pk_bf16_f32 v19, v17, v19
	v_cvt_pk_bf16_f32 v20, v20, v21
	v_cvt_pk_bf16_f32 v21, v24, v25
	global_store_dwordx4 v[26:27], v[18:21], off
	ds_read_b32 v13, v1 offset:64
	ds_read_b32 v15, v1 offset:196
	ds_read_b32 v17, v1 offset:328
	ds_read_b32 v19, v1 offset:460
	ds_read_b32 v20, v1 offset:592
	ds_read_b32 v21, v1 offset:724
	ds_read_b32 v24, v1 offset:856
	ds_read_b32 v25, v1 offset:988
	v_lshl_add_u64 v[28:29], v[22:23], 0, v[8:9]
	s_waitcnt lgkmcnt(0)
	v_cvt_pk_bf16_f32 v18, v13, v15
	v_cvt_pk_bf16_f32 v19, v17, v19
	v_cvt_pk_bf16_f32 v20, v20, v21
	v_cvt_pk_bf16_f32 v21, v24, v25
	global_store_dwordx4 v[28:29], v[18:21], off
	ds_read_b32 v13, v1 offset:96
	ds_read_b32 v15, v1 offset:228
	ds_read_b32 v17, v1 offset:360
	ds_read_b32 v19, v1 offset:492
	ds_read_b32 v20, v1 offset:624
	ds_read_b32 v21, v1 offset:756
	ds_read_b32 v24, v1 offset:888
	ds_read_b32 v25, v1 offset:1020
	v_lshl_add_u64 v[22:23], v[22:23], 0, v[10:11]
	s_waitcnt lgkmcnt(0)
	v_cvt_pk_bf16_f32 v18, v13, v15
	v_cvt_pk_bf16_f32 v19, v17, v19
	v_cvt_pk_bf16_f32 v20, v20, v21
	v_cvt_pk_bf16_f32 v21, v24, v25
	global_store_dwordx4 v[22:23], v[18:21], off
	s_waitcnt lgkmcnt(0)
	s_cbranch_scc0 .LBB0_1004

; #define LAS __attribute__((address_space(3)))
; __device__ __forceinline__ void tr_item(const float* src, int ld, int kv, int nv, const float* ks, bf16_t* dst, int ldd, LAS float* scr, int lane) {
;     ...
;         float tmp[32]; const float* sp = src + (size_t)(lane >> 5) * ld + n;
; #pragma unroll
;         for (int i = 0; i < 32; ++i) tmp[i] = sp[(size_t)(2 * i) * ld];
; #pragma unroll
;         for (int i = 0; i < 32; ++i) scr[(2 * i + (lane >> 5)) * 33 + n] = tmp[i];
; __device__ __forceinline__ void tr_job(const Ctx& c, const float* src, int ld, int K, int N, const float* ks, bf16_t* dst, int ldd, int Kpad, int Npad) {
;     LAS float* scr = (LAS float*)(c.lds + c.wave * 8448);
;     const int nnb = Npad / 32, items = (Kpad / 64) * nnb;
;     for (int it = c.gw; it < items; it += c.ngw) { const int kb = it / nnb, nb = it % nnb, k0 = 64 * kb, n0 = 32 * nb;
;         tr_item(src + (size_t)k0 * ld + n0, ld, K - k0, N - n0, ks ? ks + k0 : nullptr, dst + (size_t)n0 * ldd + k0, ldd, scr, c.lane); }
.LBB0_1007:
	s_ashr_i32 s4, s16, 31
	s_lshr_b32 s4, s4, 27
	s_add_i32 s4, s16, s4
	s_ashr_i32 s4, s4, 5
	s_lshl_b32 s18, s4, 6
	s_lshl_b32 s4, s4, 10
	s_sub_i32 s20, s14, s4
	s_ashr_i32 s19, s18, 31
	s_ashr_i32 s21, s20, 31
	s_mul_i32 s5, s20, 0x1600
	s_mul_hi_i32 s4, s20, 0x1600
	s_add_u32 s17, s94, s5
	s_addc_u32 s24, s80, s4
	s_lshl_b64 s[4:5], s[18:19], 1
	s_add_u32 s4, s17, s4
	s_addc_u32 s5, s24, s5
	s_lshl_b64 s[18:19], s[18:19], 12
	s_add_u32 s17, s10, s18
	s_addc_u32 s24, s11, s19
	s_lshl_b64 s[18:19], s[20:21], 2
	s_add_u32 s18, s17, s18
	s_addc_u32 s19, s24, s19
	v_mov_b32_e32 v13, v0
	v_lshl_add_u64 v[18:19], s[18:19], 0, v[2:3]
	v_lshl_add_u64 v[18:19], v[18:19], 0, v[12:13]
	v_add_co_u32_e32 v20, vcc, s1, v18
	v_mov_b32_e32 v15, v0
	s_nop 0
	v_addc_co_u32_e32 v21, vcc, 0, v19, vcc
	v_add_co_u32_e32 v22, vcc, s26, v18
	s_add_i32 s16, s16, s30
	s_nop 0
	v_addc_co_u32_e32 v23, vcc, 0, v19, vcc
	v_add_co_u32_e32 v24, vcc, s27, v18
	s_add_i32 s14, s14, s15
	s_nop 0
	v_addc_co_u32_e32 v25, vcc, 0, v19, vcc
	v_add_co_u32_e32 v26, vcc, s31, v18
	s_cmpk_lt_i32 s16, 0x580
	s_nop 0
	v_addc_co_u32_e32 v27, vcc, 0, v19, vcc
	v_add_co_u32_e32 v28, vcc, s34, v18
	s_nop 1
	v_addc_co_u32_e32 v29, vcc, 0, v19, vcc
	v_add_co_u32_e32 v30, vcc, s62, v18
	s_nop 1
	v_addc_co_u32_e32 v31, vcc, 0, v19, vcc
	v_add_co_u32_e32 v32, vcc, s36, v18
	s_nop 1
	v_addc_co_u32_e32 v33, vcc, 0, v19, vcc
	v_add_co_u32_e32 v34, vcc, s0, v18
	s_nop 1
	v_addc_co_u32_e32 v35, vcc, 0, v19, vcc
	v_add_co_u32_e32 v36, vcc, s63, v18
	s_nop 1
	v_addc_co_u32_e32 v37, vcc, 0, v19, vcc
	v_add_co_u32_e32 v38, vcc, s25, v18
	s_nop 1
	v_addc_co_u32_e32 v39, vcc, 0, v19, vcc
	v_add_co_u32_e32 v40, vcc, s61, v18
	s_nop 1
	v_addc_co_u32_e32 v41, vcc, 0, v19, vcc
	v_add_co_u32_e32 v42, vcc, s29, v18
	s_nop 1
	v_addc_co_u32_e32 v43, vcc, 0, v19, vcc
	v_add_co_u32_e32 v44, vcc, s38, v18
	s_nop 1
	v_addc_co_u32_e32 v45, vcc, 0, v19, vcc
	v_add_co_u32_e32 v46, vcc, s35, v18
	s_nop 1
	v_addc_co_u32_e32 v47, vcc, 0, v19, vcc
	v_add_co_u32_e32 v48, vcc, s47, v18
	s_nop 1
	v_addc_co_u32_e32 v49, vcc, 0, v19, vcc
	v_add_co_u32_e32 v50, vcc, s45, v18
	s_nop 1
	v_addc_co_u32_e32 v51, vcc, 0, v19, vcc
	v_add_co_u32_e32 v52, vcc, s46, v18
	s_nop 1
	v_addc_co_u32_e32 v53, vcc, 0, v19, vcc
	v_add_co_u32_e32 v54, vcc, s39, v18
	s_nop 1
	v_addc_co_u32_e32 v55, vcc, 0, v19, vcc
	v_add_co_u32_e32 v56, vcc, s48, v18
	s_nop 1
	v_addc_co_u32_e32 v57, vcc, 0, v19, vcc
	v_add_co_u32_e32 v58, vcc, s49, v18
	s_nop 1
	v_addc_co_u32_e32 v59, vcc, 0, v19, vcc
	v_add_co_u32_e32 v60, vcc, s40, v18
	s_nop 1
	v_addc_co_u32_e32 v61, vcc, 0, v19, vcc
	v_add_co_u32_e32 v62, vcc, s68, v18
	s_nop 1
	v_addc_co_u32_e32 v63, vcc, 0, v19, vcc
	v_add_co_u32_e32 v64, vcc, s58, v18
	s_nop 1
	v_addc_co_u32_e32 v65, vcc, 0, v19, vcc
	v_add_co_u32_e32 v66, vcc, s86, v18
	s_nop 1
	v_addc_co_u32_e32 v67, vcc, 0, v19, vcc
	v_add_co_u32_e32 v68, vcc, s59, v18
	s_nop 1
	v_addc_co_u32_e32 v69, vcc, 0, v19, vcc
	v_add_co_u32_e32 v70, vcc, s60, v18
	s_nop 1
	v_addc_co_u32_e32 v71, vcc, 0, v19, vcc
	v_add_co_u32_e32 v72, vcc, s71, v18
	s_nop 1
	v_addc_co_u32_e32 v73, vcc, 0, v19, vcc
	v_add_co_u32_e32 v74, vcc, s42, v18
	s_nop 1
	v_addc_co_u32_e32 v75, vcc, 0, v19, vcc
	v_add_co_u32_e32 v76, vcc, s72, v18
	s_nop 1
	v_addc_co_u32_e32 v77, vcc, 0, v19, vcc
	v_add_co_u32_e32 v78, vcc, s44, v18
	s_nop 1
	v_addc_co_u32_e32 v79, vcc, 0, v19, vcc
	v_add_co_u32_e32 v80, vcc, s73, v18
	s_nop 1
	v_addc_co_u32_e32 v81, vcc, 0, v19, vcc
	global_load_dword v13, v[18:19], off
	global_load_dword v17, v[20:21], off
	s_nop 0
	global_load_dword v20, v[22:23], off
	global_load_dword v21, v[24:25], off
	global_load_dword v82, v[26:27], off
	global_load_dword v83, v[28:29], off
	s_nop 0
	global_load_dword v30, v[30:31], off
	s_nop 0
	global_load_dword v31, v[32:33], off
	s_nop 0
	global_load_dword v32, v[34:35], off
	global_load_dword v33, v[36:37], off
	s_nop 0
	global_load_dword v34, v[38:39], off
	global_load_dword v35, v[40:41], off
	global_load_dword v36, v[42:43], off
	global_load_dword v37, v[44:45], off
	s_nop 0
	global_load_dword v38, v[46:47], off
	global_load_dword v39, v[48:49], off
	global_load_dword v40, v[50:51], off
	global_load_dword v41, v[52:53], off
	global_load_dword v42, v[54:55], off
	global_load_dword v43, v[56:57], off
	global_load_dword v44, v[58:59], off
	global_load_dword v45, v[60:61], off
	global_load_dword v46, v[62:63], off
	global_load_dword v47, v[64:65], off
	global_load_dword v48, v[66:67], off
	global_load_dword v49, v[68:69], off
	global_load_dword v50, v[70:71], off
	global_load_dword v51, v[72:73], off
	global_load_dword v52, v[74:75], off
	global_load_dword v53, v[76:77], off
	global_load_dword v54, v[78:79], off
	global_load_dword v55, v[80:81], off
	v_add_u32_e32 v56, 0x400, v16
	v_add_u32_e32 v57, 0x800, v16
	v_add_u32_e32 v58, 0xc00, v16
	v_add_u32_e32 v59, 0x1000, v16
	v_add_u32_e32 v60, 0x1400, v16
	v_add_u32_e32 v61, 0x1800, v16
	v_add_u32_e32 v62, 0x1c00, v16
	s_waitcnt vmcnt(0)
; #define LAS __attribute__((address_space(3)))
; __device__ __forceinline__ unsigned pk2(float lo, float hi) { f32x2 v = {lo, hi}; bf16x2_t b = __builtin_convertvector(v, bf16x2_t); return __builtin_bit_cast(unsigned, b); }
; #define LDS_WAIT() asm volatile("s_waitcnt lgkmcnt(0)" ::: "memory")
; __device__ __forceinline__ void tr_item(const float* src, int ld, int kv, int nv, const float* ks, bf16_t* dst, int ldd, LAS float* scr, int lane) {
;     ...
;         for (int i = 0; i < 32; ++i) scr[(2 * i + (lane >> 5)) * 33 + n] = tmp[i];
;     } else {
; #pragma unroll 4
;         for (int i = 0; i < 32; ++i) { const int kk = 2 * i + (lane >> 5); float v = 0.f; if (kk < kv && n < nv) { v = src[(size_t)kk * ld + n]; if (ks) v *= ks[kk]; } scr[kk * 33 + n] = v; }
;     }
;     LDS_WAIT(); asm volatile("" ::: "memory");
;     const int c = lane & 7;
; #pragma unroll
;     for (int j = 0; j < 4; ++j) { const int nn = (lane >> 3) + 8 * j; const LAS float* s = scr + (8 * c) * 33 + nn;
;         u32x4 o; o.x = pk2(s[0 * 33], s[1 * 33]); o.y = pk2(s[2 * 33], s[3 * 33]); o.z = pk2(s[4 * 33], s[5 * 33]); o.w = pk2(s[6 * 33], s[7 * 33]);
;         *(u32x4*)(dst + (size_t)nn * ldd + 8 * c) = o; }
;     LDS_WAIT(); asm volatile("" ::: "memory");
	ds_write2_b32 v16, v13, v17 offset1:66
	s_waitcnt vmcnt(28)
	ds_write2_b32 v16, v20, v21 offset0:132 offset1:198
	s_waitcnt vmcnt(26)
	ds_write2_b32 v56, v82, v83 offset0:8 offset1:74
	s_waitcnt vmcnt(24)
	ds_write2_b32 v56, v30, v31 offset0:140 offset1:206
	s_waitcnt vmcnt(22)
	ds_write2_b32 v57, v32, v33 offset0:16 offset1:82
	s_waitcnt vmcnt(20)
	ds_write2_b32 v57, v34, v35 offset0:148 offset1:214
	s_waitcnt vmcnt(18)
	ds_write2_b32 v58, v36, v37 offset0:24 offset1:90
	s_waitcnt vmcnt(16)
	ds_write2_b32 v58, v38, v39 offset0:156 offset1:222
	s_waitcnt vmcnt(14)
	ds_write2_b32 v59, v40, v41 offset0:32 offset1:98
	s_waitcnt vmcnt(12)
	ds_write2_b32 v59, v42, v43 offset0:164 offset1:230
	s_waitcnt vmcnt(10)
	ds_write2_b32 v60, v44, v45 offset0:40 offset1:106
	s_waitcnt vmcnt(8)
	ds_write2_b32 v60, v46, v47 offset0:172 offset1:238
	s_waitcnt vmcnt(6)
	ds_write2_b32 v61, v48, v49 offset0:48 offset1:114
	s_waitcnt vmcnt(4)
	ds_write2_b32 v61, v50, v51 offset0:180 offset1:246
	s_waitcnt vmcnt(2)
	ds_write2_b32 v62, v52, v53 offset0:56 offset1:122
	s_waitcnt vmcnt(0)
	ds_write2_b32 v62, v54, v55 offset0:188 offset1:254
	s_waitcnt lgkmcnt(0)
	v_lshl_add_u64 v[18:19], s[4:5], 0, v[14:15]
	v_lshl_add_u64 v[22:23], v[18:19], 0, v[4:5]
	v_lshl_add_u64 v[24:25], v[18:19], 0, v[6:7]
	v_lshl_add_u64 v[26:27], v[18:19], 0, v[8:9]
	v_lshl_add_u64 v[28:29], v[18:19], 0, v[10:11]
	ds_read_b32 v13, v1
	ds_read_b32 v15, v1 offset:132
	ds_read_b32 v17, v1 offset:264
	ds_read_b32 v19, v1 offset:396
	ds_read_b32 v20, v1 offset:528
	ds_read_b32 v21, v1 offset:660
	ds_read_b32 v30, v1 offset:792
	ds_read_b32 v31, v1 offset:924
	s_waitcnt lgkmcnt(6)
	v_cvt_pk_bf16_f32 v18, v13, v15
	s_waitcnt lgkmcnt(4)
	v_cvt_pk_bf16_f32 v19, v17, v19
	s_waitcnt lgkmcnt(2)
	v_cvt_pk_bf16_f32 v20, v20, v21
	s_waitcnt lgkmcnt(0)
	v_cvt_pk_bf16_f32 v21, v30, v31
	global_store_dwordx4 v[22:23], v[18:21], off
	ds_read_b32 v13, v1 offset:32
	ds_read_b32 v15, v1 offset:164
	ds_read_b32 v17, v1 offset:296
	ds_read_b32 v19, v1 offset:428
	ds_read_b32 v20, v1 offset:560
	ds_read_b32 v21, v1 offset:692
	ds_read_b32 v22, v1 offset:824
	ds_read_b32 v23, v1 offset:956
	s_waitcnt lgkmcnt(0)
	v_cvt_pk_bf16_f32 v18, v13, v15
	v_cvt_pk_bf16_f32 v19, v17, v19
	v_cvt_pk_bf16_f32 v20, v20, v21
	v_cvt_pk_bf16_f32 v21, v22, v23
	global_store_dwordx4 v[24:25], v[18:21], off
	ds_read_b32 v13, v1 offset:64
	ds_read_b32 v15, v1 offset:196
	ds_read_b32 v17, v1 offset:328
	ds_read_b32 v19, v1 offset:460
	ds_read_b32 v20, v1 offset:592
	ds_read_b32 v21, v1 offset:724
	ds_read_b32 v22, v1 offset:856
	ds_read_b32 v23, v1 offset:988
	s_waitcnt lgkmcnt(0)
	v_cvt_pk_bf16_f32 v18, v13, v15
	v_cvt_pk_bf16_f32 v19, v17, v19
	v_cvt_pk_bf16_f32 v20, v20, v21
	v_cvt_pk_bf16_f32 v21, v22, v23
	global_store_dwordx4 v[26:27], v[18:21], off
	ds_read_b32 v13, v1 offset:96
	ds_read_b32 v15, v1 offset:228
	ds_read_b32 v17, v1 offset:360
	ds_read_b32 v19, v1 offset:492
	ds_read_b32 v20, v1 offset:624
	ds_read_b32 v21, v1 offset:756
	ds_read_b32 v22, v1 offset:888
	ds_read_b32 v23, v1 offset:1020
	s_waitcnt lgkmcnt(0)
	v_cvt_pk_bf16_f32 v18, v13, v15
	v_cvt_pk_bf16_f32 v19, v17, v19
	v_cvt_pk_bf16_f32 v20, v20, v21
	v_cvt_pk_bf16_f32 v21, v22, v23
	global_store_dwordx4 v[28:29], v[18:21], off
	s_waitcnt lgkmcnt(0)
	s_cbranch_scc1 .LBB0_1007

; #define LAS __attribute__((address_space(3)))
; __device__ __forceinline__ void tr_item(const float* src, int ld, int kv, int nv, const float* ks, bf16_t* dst, int ldd, LAS float* scr, int lane) {
;     ...
;         float tmp[32]; const float* sp = src + (size_t)(lane >> 5) * ld + n;
; #pragma unroll
;         for (int i = 0; i < 32; ++i) tmp[i] = sp[(size_t)(2 * i) * ld];
; #pragma unroll
;         for (int i = 0; i < 32; ++i) scr[(2 * i + (lane >> 5)) * 33 + n] = tmp[i];
; __device__ __forceinline__ void tr_job(const Ctx& c, const float* src, int ld, int K, int N, const float* ks, bf16_t* dst, int ldd, int Kpad, int Npad) {
;     LAS float* scr = (LAS float*)(c.lds + c.wave * 8448);
;     const int nnb = Npad / 32, items = (Kpad / 64) * nnb;
;     for (int it = c.gw; it < items; it += c.ngw) { const int kb = it / nnb, nb = it % nnb, k0 = 64 * kb, n0 = 32 * nb;
;         tr_item(src + (size_t)k0 * ld + n0, ld, K - k0, N - n0, ks ? ks + k0 : nullptr, dst + (size_t)n0 * ldd + k0, ldd, scr, c.lane); }
.LBB0_1010:
	s_ashr_i32 s2, s14, 31
	s_lshr_b32 s2, s2, 27
	s_add_i32 s2, s14, s2
	s_ashr_i32 s2, s2, 5
	s_lshl_b32 s16, s2, 6
	s_lshl_b32 s2, s2, 10
	s_sub_i32 s18, s10, s2
	s_ashr_i32 s19, s18, 31
	s_ashr_i32 s17, s16, 31
	s_lshl_b64 s[2:3], s[18:19], 11
	s_add_u32 s15, s52, s2
	s_addc_u32 s20, s53, s3
	s_lshl_b64 s[2:3], s[16:17], 1
	s_add_u32 s2, s15, s2
	s_addc_u32 s3, s20, s3
	s_lshl_b64 s[16:17], s[16:17], 12
	s_add_u32 s15, s4, s16
	s_addc_u32 s20, s5, s17
	s_lshl_b64 s[16:17], s[18:19], 2
	s_add_u32 s16, s15, s16
	s_addc_u32 s17, s20, s17
	v_mov_b32_e32 v13, v0
	v_lshl_add_u64 v[18:19], s[16:17], 0, v[2:3]
	v_lshl_add_u64 v[18:19], v[18:19], 0, v[12:13]
	v_add_co_u32_e32 v20, vcc, s1, v18
	v_mov_b32_e32 v15, v0
	s_nop 0
	v_addc_co_u32_e32 v21, vcc, 0, v19, vcc
	v_add_co_u32_e32 v22, vcc, s26, v18
	s_add_i32 s14, s14, s30
	s_nop 0
	v_addc_co_u32_e32 v23, vcc, 0, v19, vcc
	v_add_co_u32_e32 v24, vcc, s27, v18
	s_add_i32 s10, s10, s11
	s_nop 0
	v_addc_co_u32_e32 v25, vcc, 0, v19, vcc
	v_add_co_u32_e32 v26, vcc, s31, v18
	s_cmpk_gt_i32 s14, 0x1ff
	s_nop 0
	v_addc_co_u32_e32 v27, vcc, 0, v19, vcc
	v_add_co_u32_e32 v28, vcc, s34, v18
	s_nop 1
	v_addc_co_u32_e32 v29, vcc, 0, v19, vcc
	v_add_co_u32_e32 v30, vcc, s62, v18
	s_nop 1
	v_addc_co_u32_e32 v31, vcc, 0, v19, vcc
	v_add_co_u32_e32 v32, vcc, s36, v18
	s_nop 1
	v_addc_co_u32_e32 v33, vcc, 0, v19, vcc
	v_add_co_u32_e32 v34, vcc, s0, v18
	s_nop 1
	v_addc_co_u32_e32 v35, vcc, 0, v19, vcc
	v_add_co_u32_e32 v36, vcc, s63, v18
	s_nop 1
	v_addc_co_u32_e32 v37, vcc, 0, v19, vcc
	v_add_co_u32_e32 v38, vcc, s25, v18
	s_nop 1
	v_addc_co_u32_e32 v39, vcc, 0, v19, vcc
	v_add_co_u32_e32 v40, vcc, s61, v18
	s_nop 1
	v_addc_co_u32_e32 v41, vcc, 0, v19, vcc
	v_add_co_u32_e32 v42, vcc, s29, v18
	s_nop 1
	v_addc_co_u32_e32 v43, vcc, 0, v19, vcc
	v_add_co_u32_e32 v44, vcc, s38, v18
	s_nop 1
	v_addc_co_u32_e32 v45, vcc, 0, v19, vcc
	v_add_co_u32_e32 v46, vcc, s35, v18
	s_nop 1
	v_addc_co_u32_e32 v47, vcc, 0, v19, vcc
	v_add_co_u32_e32 v48, vcc, s47, v18
	s_nop 1
	v_addc_co_u32_e32 v49, vcc, 0, v19, vcc
	v_add_co_u32_e32 v50, vcc, s45, v18
	s_nop 1
	v_addc_co_u32_e32 v51, vcc, 0, v19, vcc
	v_add_co_u32_e32 v52, vcc, s46, v18
	s_nop 1
	v_addc_co_u32_e32 v53, vcc, 0, v19, vcc
	v_add_co_u32_e32 v54, vcc, s39, v18
	s_nop 1
	v_addc_co_u32_e32 v55, vcc, 0, v19, vcc
	v_add_co_u32_e32 v56, vcc, s48, v18
	s_nop 1
	v_addc_co_u32_e32 v57, vcc, 0, v19, vcc
	v_add_co_u32_e32 v58, vcc, s49, v18
	s_nop 1
	v_addc_co_u32_e32 v59, vcc, 0, v19, vcc
	v_add_co_u32_e32 v60, vcc, s40, v18
	s_nop 1
	v_addc_co_u32_e32 v61, vcc, 0, v19, vcc
	v_add_co_u32_e32 v62, vcc, s68, v18
	s_nop 1
	v_addc_co_u32_e32 v63, vcc, 0, v19, vcc
	v_add_co_u32_e32 v64, vcc, s58, v18
	s_nop 1
	v_addc_co_u32_e32 v65, vcc, 0, v19, vcc
	v_add_co_u32_e32 v66, vcc, s86, v18
	s_nop 1
	v_addc_co_u32_e32 v67, vcc, 0, v19, vcc
	v_add_co_u32_e32 v68, vcc, s59, v18
	s_nop 1
	v_addc_co_u32_e32 v69, vcc, 0, v19, vcc
	v_add_co_u32_e32 v70, vcc, s60, v18
	s_nop 1
	v_addc_co_u32_e32 v71, vcc, 0, v19, vcc
	v_add_co_u32_e32 v72, vcc, s71, v18
	s_nop 1
	v_addc_co_u32_e32 v73, vcc, 0, v19, vcc
	v_add_co_u32_e32 v74, vcc, s21, v18
	s_nop 1
	v_addc_co_u32_e32 v75, vcc, 0, v19, vcc
	v_add_co_u32_e32 v76, vcc, s24, v18
	s_nop 1
	v_addc_co_u32_e32 v77, vcc, 0, v19, vcc
	v_add_co_u32_e32 v78, vcc, s44, v18
	s_nop 1
	v_addc_co_u32_e32 v79, vcc, 0, v19, vcc
	v_add_co_u32_e32 v80, vcc, s72, v18
	s_nop 1
	v_addc_co_u32_e32 v81, vcc, 0, v19, vcc
	global_load_dword v13, v[18:19], off
	global_load_dword v17, v[20:21], off
	s_nop 0
	global_load_dword v20, v[22:23], off
	global_load_dword v21, v[24:25], off
	global_load_dword v82, v[26:27], off
	global_load_dword v83, v[28:29], off
	s_nop 0
	global_load_dword v30, v[30:31], off
	s_nop 0
	global_load_dword v31, v[32:33], off
	s_nop 0
	global_load_dword v32, v[34:35], off
	global_load_dword v33, v[36:37], off
	s_nop 0
	global_load_dword v34, v[38:39], off
	global_load_dword v35, v[40:41], off
	global_load_dword v36, v[42:43], off
	global_load_dword v37, v[44:45], off
	s_nop 0
	global_load_dword v38, v[46:47], off
	global_load_dword v39, v[48:49], off
	global_load_dword v40, v[50:51], off
	global_load_dword v41, v[52:53], off
	global_load_dword v42, v[54:55], off
	global_load_dword v43, v[56:57], off
	global_load_dword v44, v[58:59], off
	global_load_dword v45, v[60:61], off
	global_load_dword v46, v[62:63], off
	global_load_dword v47, v[64:65], off
	global_load_dword v48, v[66:67], off
	global_load_dword v49, v[68:69], off
	global_load_dword v50, v[70:71], off
	global_load_dword v51, v[72:73], off
	global_load_dword v52, v[74:75], off
	global_load_dword v53, v[76:77], off
	global_load_dword v54, v[78:79], off
	global_load_dword v55, v[80:81], off
	v_add_u32_e32 v56, 0x400, v16
	v_add_u32_e32 v57, 0x800, v16
	v_add_u32_e32 v58, 0xc00, v16
	v_add_u32_e32 v59, 0x1000, v16
	v_add_u32_e32 v60, 0x1400, v16
	v_add_u32_e32 v61, 0x1800, v16
	v_add_u32_e32 v62, 0x1c00, v16
	s_waitcnt vmcnt(0)
; #define LAS __attribute__((address_space(3)))
; __device__ __forceinline__ unsigned pk2(float lo, float hi) { f32x2 v = {lo, hi}; bf16x2_t b = __builtin_convertvector(v, bf16x2_t); return __builtin_bit_cast(unsigned, b); }
; #define LDS_WAIT() asm volatile("s_waitcnt lgkmcnt(0)" ::: "memory")
; __device__ __forceinline__ void tr_item(const float* src, int ld, int kv, int nv, const float* ks, bf16_t* dst, int ldd, LAS float* scr, int lane) {
;     ...
;         for (int i = 0; i < 32; ++i) scr[(2 * i + (lane >> 5)) * 33 + n] = tmp[i];
;     } else {
; #pragma unroll 4
;         for (int i = 0; i < 32; ++i) { const int kk = 2 * i + (lane >> 5); float v = 0.f; if (kk < kv && n < nv) { v = src[(size_t)kk * ld + n]; if (ks) v *= ks[kk]; } scr[kk * 33 + n] = v; }
;     }
;     LDS_WAIT(); asm volatile("" ::: "memory");
;     const int c = lane & 7;
; #pragma unroll
;     for (int j = 0; j < 4; ++j) { const int nn = (lane >> 3) + 8 * j; const LAS float* s = scr + (8 * c) * 33 + nn;
;         u32x4 o; o.x = pk2(s[0 * 33], s[1 * 33]); o.y = pk2(s[2 * 33], s[3 * 33]); o.z = pk2(s[4 * 33], s[5 * 33]); o.w = pk2(s[6 * 33], s[7 * 33]);
;         *(u32x4*)(dst + (size_t)nn * ldd + 8 * c) = o; }
;     LDS_WAIT(); asm volatile("" ::: "memory");
	ds_write2_b32 v16, v13, v17 offset1:66
	s_waitcnt vmcnt(28)
	ds_write2_b32 v16, v20, v21 offset0:132 offset1:198
	s_waitcnt vmcnt(26)
	ds_write2_b32 v56, v82, v83 offset0:8 offset1:74
	s_waitcnt vmcnt(24)
	ds_write2_b32 v56, v30, v31 offset0:140 offset1:206
	s_waitcnt vmcnt(22)
	ds_write2_b32 v57, v32, v33 offset0:16 offset1:82
	s_waitcnt vmcnt(20)
	ds_write2_b32 v57, v34, v35 offset0:148 offset1:214
	s_waitcnt vmcnt(18)
	ds_write2_b32 v58, v36, v37 offset0:24 offset1:90
	s_waitcnt vmcnt(16)
	ds_write2_b32 v58, v38, v39 offset0:156 offset1:222
	s_waitcnt vmcnt(14)
	ds_write2_b32 v59, v40, v41 offset0:32 offset1:98
	s_waitcnt vmcnt(12)
	ds_write2_b32 v59, v42, v43 offset0:164 offset1:230
	s_waitcnt vmcnt(10)
	ds_write2_b32 v60, v44, v45 offset0:40 offset1:106
	s_waitcnt vmcnt(8)
	ds_write2_b32 v60, v46, v47 offset0:172 offset1:238
	s_waitcnt vmcnt(6)
	ds_write2_b32 v61, v48, v49 offset0:48 offset1:114
	s_waitcnt vmcnt(4)
	ds_write2_b32 v61, v50, v51 offset0:180 offset1:246
	s_waitcnt vmcnt(2)
	ds_write2_b32 v62, v52, v53 offset0:56 offset1:122
	s_waitcnt vmcnt(0)
	ds_write2_b32 v62, v54, v55 offset0:188 offset1:254
	s_waitcnt lgkmcnt(0)
	v_lshl_add_u64 v[18:19], s[2:3], 0, v[14:15]
	v_lshl_add_u64 v[22:23], v[18:19], 0, v[4:5]
	v_lshl_add_u64 v[24:25], v[18:19], 0, v[6:7]
	v_lshl_add_u64 v[26:27], v[18:19], 0, v[8:9]
	v_lshl_add_u64 v[28:29], v[18:19], 0, v[10:11]
	ds_read_b32 v13, v1
	ds_read_b32 v15, v1 offset:132
	ds_read_b32 v17, v1 offset:264
	ds_read_b32 v19, v1 offset:396
	ds_read_b32 v20, v1 offset:528
	ds_read_b32 v21, v1 offset:660
	ds_read_b32 v30, v1 offset:792
	ds_read_b32 v31, v1 offset:924
	s_waitcnt lgkmcnt(6)
	v_cvt_pk_bf16_f32 v18, v13, v15
	s_waitcnt lgkmcnt(4)
	v_cvt_pk_bf16_f32 v19, v17, v19
	s_waitcnt lgkmcnt(2)
	v_cvt_pk_bf16_f32 v20, v20, v21
	s_waitcnt lgkmcnt(0)
	v_cvt_pk_bf16_f32 v21, v30, v31
	global_store_dwordx4 v[22:23], v[18:21], off
	ds_read_b32 v13, v1 offset:32
	ds_read_b32 v15, v1 offset:164
	ds_read_b32 v17, v1 offset:296
	ds_read_b32 v19, v1 offset:428
	ds_read_b32 v20, v1 offset:560
	ds_read_b32 v21, v1 offset:692
	ds_read_b32 v22, v1 offset:824
	ds_read_b32 v23, v1 offset:956
	s_waitcnt lgkmcnt(0)
	v_cvt_pk_bf16_f32 v18, v13, v15
	v_cvt_pk_bf16_f32 v19, v17, v19
	v_cvt_pk_bf16_f32 v20, v20, v21
	v_cvt_pk_bf16_f32 v21, v22, v23
	global_store_dwordx4 v[24:25], v[18:21], off
	ds_read_b32 v13, v1 offset:64
	ds_read_b32 v15, v1 offset:196
	ds_read_b32 v17, v1 offset:328
	ds_read_b32 v19, v1 offset:460
	ds_read_b32 v20, v1 offset:592
	ds_read_b32 v21, v1 offset:724
	ds_read_b32 v22, v1 offset:856
	ds_read_b32 v23, v1 offset:988
	s_waitcnt lgkmcnt(0)
	v_cvt_pk_bf16_f32 v18, v13, v15
	v_cvt_pk_bf16_f32 v19, v17, v19
	v_cvt_pk_bf16_f32 v20, v20, v21
	v_cvt_pk_bf16_f32 v21, v22, v23
	global_store_dwordx4 v[26:27], v[18:21], off
	ds_read_b32 v13, v1 offset:96
	ds_read_b32 v15, v1 offset:228
	ds_read_b32 v17, v1 offset:360
	ds_read_b32 v19, v1 offset:492
	ds_read_b32 v20, v1 offset:624
	ds_read_b32 v21, v1 offset:756
	ds_read_b32 v22, v1 offset:888
	ds_read_b32 v23, v1 offset:1020
	s_waitcnt lgkmcnt(0)
	v_cvt_pk_bf16_f32 v18, v13, v15
	v_cvt_pk_bf16_f32 v19, v17, v19
	v_cvt_pk_bf16_f32 v20, v20, v21
	v_cvt_pk_bf16_f32 v21, v22, v23
	global_store_dwordx4 v[28:29], v[18:21], off
	s_waitcnt lgkmcnt(0)
	s_cbranch_scc0 .LBB0_1010

; #define LAS __attribute__((address_space(3)))
; __device__ __forceinline__ unsigned pk2(float lo, float hi) { f32x2 v = {lo, hi}; bf16x2_t b = __builtin_convertvector(v, bf16x2_t); return __builtin_bit_cast(unsigned, b); }
; #define LDS_WAIT() asm volatile("s_waitcnt lgkmcnt(0)" ::: "memory")
; __device__ __forceinline__ void tr_item(const float* src, int ld, int kv, int nv, const float* ks, bf16_t* dst, int ldd, LAS float* scr, int lane) {
;     ...
;     const int c = lane & 7;
; #pragma unroll
;     for (int j = 0; j < 4; ++j) { const int nn = (lane >> 3) + 8 * j; const LAS float* s = scr + (8 * c) * 33 + nn;
;         u32x4 o; o.x = pk2(s[0 * 33], s[1 * 33]); o.y = pk2(s[2 * 33], s[3 * 33]); o.z = pk2(s[4 * 33], s[5 * 33]); o.w = pk2(s[6 * 33], s[7 * 33]);
;         *(u32x4*)(dst + (size_t)nn * ldd + 8 * c) = o; }
;     LDS_WAIT(); asm volatile("" ::: "memory");
; __device__ __forceinline__ void tr_job(const Ctx& c, const float* src, int ld, int K, int N, const float* ks, bf16_t* dst, int ldd, int Kpad, int Npad) {
;     LAS float* scr = (LAS float*)(c.lds + c.wave * 8448);
;     const int nnb = Npad / 32, items = (Kpad / 64) * nnb;
;     for (int it = c.gw; it < items; it += c.ngw) { const int kb = it / nnb, nb = it % nnb, k0 = 64 * kb, n0 = 32 * nb;
;         tr_item(src + (size_t)k0 * ld + n0, ld, K - k0, N - n0, ks ? ks + k0 : nullptr, dst + (size_t)n0 * ldd + k0, ldd, scr, c.lane); }
.LBB0_1013:
	s_waitcnt lgkmcnt(0)
	s_ashr_i32 s3, s2, 31
	s_lshl_b64 s[4:5], s[8:9], 11
	s_add_u32 s4, s93, s4
	ds_read_b32 v15, v21
	ds_read_b32 v24, v21 offset:132
	ds_read_b32 v25, v21 offset:264
	ds_read_b32 v26, v21 offset:396
	ds_read_b32 v27, v21 offset:528
	ds_read_b32 v28, v21 offset:660
	ds_read_b32 v29, v21 offset:792
	ds_read_b32 v30, v21 offset:924
	s_addc_u32 s5, s37, s5
	s_lshl_b64 s[2:3], s[2:3], 1
	s_add_u32 s2, s4, s2
	s_addc_u32 s3, s5, s3
	v_mov_b32_e32 v17, v0
	v_lshl_add_u64 v[18:19], s[2:3], 0, v[16:17]
	s_waitcnt lgkmcnt(0)
	v_cvt_pk_bf16_f32 v24, v15, v24
	s_waitcnt lgkmcnt(4)
	v_cvt_pk_bf16_f32 v25, v25, v26
	s_waitcnt lgkmcnt(2)
	v_cvt_pk_bf16_f32 v26, v27, v28
	s_waitcnt lgkmcnt(0)
	v_cvt_pk_bf16_f32 v27, v29, v30
	v_lshl_add_u64 v[28:29], v[18:19], 0, v[4:5]
	global_store_dwordx4 v[28:29], v[24:27], off
	ds_read_b32 v15, v21 offset:32
	ds_read_b32 v17, v21 offset:164
	ds_read_b32 v25, v21 offset:296
	ds_read_b32 v26, v21 offset:428
	ds_read_b32 v27, v21 offset:560
	ds_read_b32 v28, v21 offset:692
	ds_read_b32 v29, v21 offset:824
	ds_read_b32 v30, v21 offset:956
	s_waitcnt lgkmcnt(0)
	v_cvt_pk_bf16_f32 v24, v15, v17
	v_cvt_pk_bf16_f32 v25, v25, v26
	v_cvt_pk_bf16_f32 v26, v27, v28
	s_add_i32 s16, s16, s30
	v_cvt_pk_bf16_f32 v27, v29, v30
	v_lshl_add_u64 v[28:29], v[18:19], 0, v[6:7]
	global_store_dwordx4 v[28:29], v[24:27], off
	ds_read_b32 v15, v21 offset:64
	ds_read_b32 v17, v21 offset:196
	ds_read_b32 v25, v21 offset:328
	ds_read_b32 v26, v21 offset:460
	ds_read_b32 v27, v21 offset:592
	ds_read_b32 v28, v21 offset:724
	ds_read_b32 v29, v21 offset:856
	ds_read_b32 v30, v21 offset:988
	s_waitcnt lgkmcnt(0)
	v_cvt_pk_bf16_f32 v24, v15, v17
	v_cvt_pk_bf16_f32 v25, v25, v26
	v_cvt_pk_bf16_f32 v26, v27, v28
	s_cmpk_gt_i32 s16, 0x7ff
	v_cvt_pk_bf16_f32 v27, v29, v30
	v_lshl_add_u64 v[28:29], v[18:19], 0, v[8:9]
	global_store_dwordx4 v[28:29], v[24:27], off
	ds_read_b32 v15, v21 offset:96
	ds_read_b32 v17, v21 offset:228
	ds_read_b32 v25, v21 offset:360
	ds_read_b32 v26, v21 offset:492
	ds_read_b32 v27, v21 offset:624
	ds_read_b32 v28, v21 offset:756
	ds_read_b32 v29, v21 offset:888
	ds_read_b32 v30, v21 offset:1020
	s_waitcnt lgkmcnt(0)
	v_cvt_pk_bf16_f32 v24, v15, v17
	v_cvt_pk_bf16_f32 v25, v25, v26
	v_cvt_pk_bf16_f32 v26, v27, v28
	v_lshl_add_u64 v[18:19], v[18:19], 0, v[10:11]
	v_cvt_pk_bf16_f32 v27, v29, v30
	global_store_dwordx4 v[18:19], v[24:27], off
	s_waitcnt lgkmcnt(0)
	s_cbranch_scc1 .LBB0_1027

; __device__ __forceinline__ unsigned pk2(float lo, float hi) { f32x2 v = {lo, hi}; bf16x2_t b = __builtin_convertvector(v, bf16x2_t); return __builtin_bit_cast(unsigned, b); }
; __device__ __forceinline__ float wave_sum_dpp(float v) { v = half32_sum(v); auto r = __builtin_amdgcn_permlane32_swap(asu(v), asu(v), false, false); return asf(r[0]) + asf(r[1]); }
; __device__ __forceinline__ void rms_rows(const Ctx& c, const float* x, const float* gain, bf16_t* out, float* xcopy) {
;     ...
;     for (int m = c.gw; m < M_; m += c.ngw) {
;         const f32x4* xr = (const f32x4*)(x + (size_t)m * D_) + c.lane;
;         f32x4 v[4]; float s = 0.f;
; #pragma unroll
;         for (int j = 0; j < 4; ++j) { v[j] = xr[64 * j]; s += (v[j].x * v[j].x + v[j].y * v[j].y) + (v[j].z * v[j].z + v[j].w * v[j].w); }
;         if (xcopy) { f32x4* xc = (f32x4*)(xcopy + (size_t)m * D_) + c.lane;
; #pragma unroll
;             for (int j = 0; j < 4; ++j) xc[64 * j] = v[j]; }
;         const float r = rsqrtf(wave_sum_dpp(s) * (1.f / D_) + 1e-6f);
;         u32x2* o8 = (u32x2*)(out + (size_t)m * D_) + c.lane;
; #pragma unroll
;         for (int j = 0; j < 4; ++j) { u32x2 w; w.x = pk2(v[j].x * r * gv[j].x, v[j].y * r * gv[j].y); w.y = pk2(v[j].z * r * gv[j].z, v[j].w * r * gv[j].w); o8[64 * j] = w; }
;     }
.LBB0_1029:
	s_waitcnt vmcnt(0) lgkmcnt(0)
	v_mul_f32_e32 v1, v31, v31
	v_mul_f32_e32 v38, v33, v33
	v_fmac_f32_e32 v1, v30, v30
	v_fmac_f32_e32 v38, v32, v32
	v_add_f32_e32 v1, v1, v38
	v_mul_f32_e32 v38, v27, v27
	v_mul_f32_e32 v39, v29, v29
	v_fmac_f32_e32 v38, v26, v26
	v_fmac_f32_e32 v39, v28, v28
	v_add_f32_e32 v38, v38, v39
	v_add_f32_e32 v1, v1, v38
	v_mul_f32_e32 v38, v23, v23
	v_mul_f32_e32 v39, v25, v25
	v_fmac_f32_e32 v38, v22, v22
	v_fmac_f32_e32 v39, v24, v24
	v_add_f32_e32 v38, v38, v39
	v_add_f32_e32 v1, v1, v38
	v_mul_f32_e32 v38, v19, v19
	v_mul_f32_e32 v39, v21, v21
	v_fmac_f32_e32 v38, v18, v18
	v_fmac_f32_e32 v39, v20, v20
	v_add_f32_e32 v38, v38, v39
	v_add_f32_e32 v1, v1, v38
	s_add_i32 s28, s28, s30
	s_cmpk_gt_i32 s28, 0x7fff
	v_add_f32_dpp v1, v1, v1 row_ror:8 row_mask:0xf bank_mask:0xf bound_ctrl:1
	v_lshl_add_u64 v[36:37], v[36:37], 0, s[10:11]
	s_nop 0
	v_add_f32_dpp v1, v1, v1 row_ror:4 row_mask:0xf bank_mask:0xf bound_ctrl:1
	s_nop 1
	v_add_f32_dpp v1, v1, v1 row_ror:2 row_mask:0xf bank_mask:0xf bound_ctrl:1
	s_nop 1
	v_add_f32_dpp v1, v1, v1 row_ror:1 row_mask:0xf bank_mask:0xf bound_ctrl:1
	v_mov_b32_e32 v38, v1
	s_nop 1
	v_permlane16_swap_b32_e32 v1, v38
	v_add_f32_e32 v1, v1, v38
	v_mov_b32_e32 v38, v1
	s_nop 1
	v_permlane32_swap_b32_e32 v1, v38
	v_add_f32_e32 v1, v1, v38
	v_fmamk_f32 v1, v1, 0x3a800000, v148
	v_mul_f32_e32 v38, 0x4b800000, v1
	v_cmp_gt_f32_e32 vcc, s33, v1
	s_nop 1
	v_cndmask_b32_e32 v1, v1, v38, vcc
	v_rsq_f32_e32 v1, v1
	s_nop 0
	v_mul_f32_e32 v38, 0x45800000, v1
	v_cndmask_b32_e32 v38, v1, v38, vcc
	v_pk_mul_f32 v[30:31], v[30:31], v[38:39] op_sel_hi:[1,0]
	v_pk_mul_f32 v[32:33], v[32:33], v[38:39] op_sel_hi:[1,0]
	v_pk_mul_f32 v[26:27], v[26:27], v[38:39] op_sel_hi:[1,0]
	v_pk_mul_f32 v[28:29], v[28:29], v[38:39] op_sel_hi:[1,0]
	v_pk_mul_f32 v[22:23], v[22:23], v[38:39] op_sel_hi:[1,0]
	v_pk_mul_f32 v[24:25], v[24:25], v[38:39] op_sel_hi:[1,0]
	v_pk_mul_f32 v[18:19], v[18:19], v[38:39] op_sel_hi:[1,0]
	v_pk_mul_f32 v[20:21], v[20:21], v[38:39] op_sel_hi:[1,0]
	v_pk_mul_f32 v[30:31], v[14:15], v[30:31]
	v_pk_mul_f32 v[32:33], v[16:17], v[32:33]
	v_pk_mul_f32 v[26:27], v[10:11], v[26:27]
	v_pk_mul_f32 v[28:29], v[12:13], v[28:29]
	v_pk_mul_f32 v[22:23], v[6:7], v[22:23]
	v_pk_mul_f32 v[24:25], v[8:9], v[24:25]
	v_pk_mul_f32 v[18:19], v[2:3], v[18:19]
	v_pk_mul_f32 v[20:21], v[4:5], v[20:21]
	v_cvt_pk_bf16_f32 v30, v30, v31
	v_cvt_pk_bf16_f32 v31, v32, v33
	v_cvt_pk_bf16_f32 v26, v26, v27
	v_cvt_pk_bf16_f32 v27, v28, v29
	v_cvt_pk_bf16_f32 v22, v22, v23
	v_cvt_pk_bf16_f32 v23, v24, v25
	v_cvt_pk_bf16_f32 v18, v18, v19
	v_cvt_pk_bf16_f32 v19, v20, v21
	global_store_dwordx2 v[34:35], v[30:31], off
	global_store_dwordx2 v[34:35], v[26:27], off offset:512
	global_store_dwordx2 v[34:35], v[22:23], off offset:1024
	global_store_dwordx2 v[34:35], v[18:19], off offset:1536
	v_lshl_add_u64 v[34:35], v[34:35], 0, s[8:9]
	s_cbranch_scc1 .LBB0_1032
.LBB0_1030:
	v_lshl_add_u64 v[18:19], s[6:7], 0, v[36:37]
	global_load_dwordx4 v[30:33], v[18:19], off
	global_load_dwordx4 v[26:29], v[18:19], off offset:1024
	global_load_dwordx4 v[22:25], v[18:19], off offset:2048
	s_nop 0
	global_load_dwordx4 v[18:21], v[18:19], off offset:3072
	s_andn2_b64 vcc, exec, s[4:5]
	s_cbranch_vccnz .LBB0_1029
	v_lshl_add_u64 v[38:39], s[2:3], 0, v[36:37]
	s_waitcnt vmcnt(0) lgkmcnt(0)
	global_store_dwordx4 v[38:39], v[30:33], off
	global_store_dwordx4 v[38:39], v[26:29], off offset:1024
	global_store_dwordx4 v[38:39], v[22:25], off offset:2048
	global_store_dwordx4 v[38:39], v[18:21], off offset:3072
	s_branch .LBB0_1029

; __device__ __forceinline__ unsigned xb_ld(unsigned* p)              { return __hip_atomic_load(p, __ATOMIC_RELAXED, __HIP_MEMORY_SCOPE_AGENT); }
; __device__ __forceinline__ void xcd_barrier_complete(unsigned* bar, unsigned x, unsigned& nloc, unsigned& nx) {
;     const unsigned G = gridDim.x * gridDim.y * gridDim.z;
;     unsigned sum, cnt, mine, sp = 0u;
;     for (;;) {
;         sum = 0u; cnt = 0u; mine = 0u;
; #pragma unroll
;         for (unsigned j = 0; j < 16; ++j) { const unsigned c = xb_ld(&bar[XB_XCNT(j)]); sum += c; cnt += (c > 0u) ? 1u : 0u; mine = (j == x) ? c : mine; }
;         if (sum == G) break;
;         __builtin_amdgcn_s_sleep(1);
;         if ((++sp & 255u) == 0u) { if (xb_ld(&bar[XB_TMO])) break; if (sp > XB_SPIN_CAP) { atomicAdd(&bar[XB_TMO], 1u); break; } }
;     }
;     nloc = mine > 0u ? mine : 1u; nx = cnt > 0u ? cnt : 1u;
; }
.LBB0_1039:
	v_mov_b64_e32 v[12:13], s[38:39]
	s_waitcnt lgkmcnt(0)
	global_load_dword v2, v[12:13], off offset:1024 sc1
	global_load_dword v1, v[12:13], off offset:1280 sc1
	global_load_dword v3, v[12:13], off offset:1536 sc1
	s_or_b64 s[20:21], s[20:21], exec
	s_or_b64 s[18:19], s[18:19], exec
	s_waitcnt vmcnt(0) lgkmcnt(0)
	v_add_u32_e32 v4, v1, v2
	v_add_u32_e32 v5, v4, v3
	global_load_dword v4, v[12:13], off offset:1792 sc1
	s_waitcnt vmcnt(0) lgkmcnt(0)
	v_add_u32_e32 v6, v5, v4
	global_load_dword v5, v[12:13], off offset:2048 sc1
	s_waitcnt vmcnt(0) lgkmcnt(0)
	v_add_u32_e32 v7, v6, v5
	global_load_dword v6, v[12:13], off offset:2304 sc1
	s_waitcnt vmcnt(0) lgkmcnt(0)
	v_add_u32_e32 v8, v7, v6
	global_load_dword v7, v[12:13], off offset:2560 sc1
	s_waitcnt vmcnt(0) lgkmcnt(0)
	v_add_u32_e32 v9, v8, v7
	global_load_dword v8, v[12:13], off offset:2816 sc1
	s_waitcnt vmcnt(0) lgkmcnt(0)
	v_add_u32_e32 v10, v9, v8
	global_load_dword v9, v[12:13], off offset:3072 sc1
	s_waitcnt vmcnt(0) lgkmcnt(0)
	v_add_u32_e32 v11, v10, v9
	global_load_dword v10, v[12:13], off offset:3328 sc1
	s_waitcnt vmcnt(0) lgkmcnt(0)
	v_add_u32_e32 v14, v11, v10
	global_load_dword v11, v[12:13], off offset:3584 sc1
	s_waitcnt vmcnt(0) lgkmcnt(0)
	v_add_u32_e32 v14, v14, v11
	global_load_dword v12, v[12:13], off offset:3840 sc1
	s_waitcnt vmcnt(0) lgkmcnt(0)
	v_add_u32_e32 v16, v14, v12
	v_mov_b64_e32 v[14:15], s[4:5]
	global_load_dword v13, v[14:15], off sc1
	v_mov_b64_e32 v[14:15], s[6:7]
	global_load_dword v14, v[14:15], off sc1
	s_waitcnt vmcnt(0) lgkmcnt(0)
	v_add_u32_e32 v16, v16, v13
	v_add_u32_e32 v18, v16, v14
	v_mov_b64_e32 v[16:17], s[8:9]
	global_load_dword v15, v[16:17], off sc1
	v_mov_b64_e32 v[16:17], s[10:11]
	global_load_dword v16, v[16:17], off sc1
	s_waitcnt vmcnt(0) lgkmcnt(0)
	v_add_u32_e32 v18, v18, v15
	v_add_u32_e32 v17, v18, v16
	v_cmp_ne_u32_e32 vcc, s0, v17
	s_and_saveexec_b64 s[22:23], vcc
	s_cbranch_execz .LBB0_1038
	s_and_b32 s26, s34, 0xff
	s_mov_b64 s[24:25], -1
	s_cmp_eq_u32 s26, 0
	s_mov_b64 s[28:29], -1
	s_mov_b64 s[26:27], -1
	s_sleep 1
	s_cbranch_scc1 .LBB0_1042
	s_and_saveexec_b64 s[30:31], s[28:29]
	s_cbranch_execz .LBB0_1037
	s_branch .LBB0_1045
.LBB0_1042:
	v_mov_b64_e32 v[18:19], s[38:39]
	global_load_dword v17, v[18:19], off offset:512 sc1
	s_mov_b64 s[28:29], 0
	s_waitcnt vmcnt(0) lgkmcnt(0)
	v_cmp_eq_u32_e32 vcc, 0, v17
	s_and_saveexec_b64 s[30:31], vcc
	s_cmp_lt_u32 s34, 0x400001
	s_cselect_b64 s[28:29], -1, 0
	s_xor_b64 s[26:27], exec, -1
	s_and_b64 s[28:29], s[28:29], exec
	s_or_b64 exec, exec, s[30:31]
	s_and_saveexec_b64 s[30:31], s[28:29]
	s_cbranch_execz .LBB0_1037

; __device__ __forceinline__ unsigned xb_ld(unsigned* p)              { return __hip_atomic_load(p, __ATOMIC_RELAXED, __HIP_MEMORY_SCOPE_AGENT); }
; __device__ __forceinline__ unsigned xb_add(unsigned* p, unsigned v) { return __hip_atomic_fetch_add(p, v, __ATOMIC_RELAXED, __HIP_MEMORY_SCOPE_AGENT); }
; #define XB_SPIN(cond, bar) do { unsigned _sp = 0; while (cond) { __builtin_amdgcn_s_sleep(1); \
;     if ((++_sp & 255u) == 0u) { if (xb_ld(&(bar)[XB_TMO])) break; if (_sp > XB_SPIN_CAP) { atomicAdd(&(bar)[XB_TMO], 1u); break; } } } } while (0)
; __device__ __forceinline__ void xcd_barrier(const XcdBarrier& b, int wave_s) {
;     ...
;     if (wave_s == 0 && l0_ == 0) {
;         unsigned* bar = b.bar; asm volatile("" : "+s"(bar));
;         __builtin_amdgcn_s_waitcnt(0);
;         unsigned nloc = b.st[0], nx = b.st[1];
;         if (nloc == 0u) { xcd_barrier_complete(bar, b.x, nloc, nx); b.st[0] = nloc; b.st[1] = nx; }
;         const unsigned old = xb_add(&bar[XB_XSUB(b.x)], 1u);
;         const unsigned gen = old / nloc;
;         if (old + 1u == (gen + 1u) * nloc) {
;             __builtin_amdgcn_fence(__ATOMIC_RELEASE, "agent");
;             asm volatile("s_waitcnt vmcnt(0)" ::: "memory");
;             const unsigned og = xb_add(&bar[XB_TOP], 1u);
;             const unsigned tg = og / nx;
;             if (og + 1u == (tg + 1u) * nx) xb_add(&bar[XB_TOPGEN], 1u);
;             else XB_SPIN(xb_ld(&bar[XB_TOPGEN]) == tg, bar);
;             __builtin_amdgcn_fence(__ATOMIC_ACQUIRE, "agent");
;             xb_add(&bar[XB_XGEN(b.x)], 1u);
;             asm volatile("s_waitcnt vmcnt(0)" ::: "memory");
;         } else {
;             XB_SPIN(xb_ld(&bar[XB_XGEN(b.x)]) == gen, bar);
.LBB0_1050:
	s_lshl_b32 s4, s40, 8
	s_add_u32 s27, s38, s4
	s_addc_u32 s26, s39, 0
	v_mov_b32_e32 v1, s27
	v_add_co_u32_e32 v6, vcc, 0x1000, v1
	v_mov_b32_e32 v1, s26
	s_nop 0
	v_addc_co_u32_e32 v7, vcc, 0, v1, vcc
	flat_atomic_add v3, v[6:7], v149 offset:1024 sc0
	v_cvt_f32_u32_e32 v1, v4
	v_sub_u32_e32 v5, 0, v4
	v_rcp_iflag_f32_e32 v1, v1
	s_nop 0
	v_mul_f32_e32 v1, 0x4f7ffffe, v1
	v_cvt_u32_f32_e32 v1, v1
	v_mul_lo_u32 v5, v5, v1
	v_mul_hi_u32 v5, v1, v5
	v_add_u32_e32 v1, v1, v5
	s_waitcnt vmcnt(0) lgkmcnt(0)
	v_mul_hi_u32 v1, v3, v1
	v_mul_lo_u32 v5, v1, v4
	v_sub_u32_e32 v5, v3, v5
	v_cmp_ge_u32_e32 vcc, v5, v4
	v_add_u32_e32 v6, 1, v1
	v_add_u32_e32 v3, 1, v3
	v_cndmask_b32_e32 v1, v1, v6, vcc
	v_sub_u32_e32 v6, v5, v4
	v_cndmask_b32_e32 v5, v5, v6, vcc
	v_cmp_ge_u32_e32 vcc, v5, v4
	v_add_u32_e32 v5, 1, v1
	s_nop 0
	v_cndmask_b32_e32 v1, v1, v5, vcc
	v_mad_u64_u32 v[4:5], s[4:5], v4, v1, v[4:5]
	v_cmp_ne_u32_e32 vcc, v3, v4
	s_and_saveexec_b64 s[4:5], vcc
	s_xor_b64 s[4:5], exec, s[4:5]
	v_readlane_b32 s41, v255, 14
	s_cbranch_execz .LBB0_1063
	v_mov_b32_e32 v2, s27
	v_add_co_u32_e32 v2, vcc, 0x2000, v2
	v_mov_b32_e32 v3, s26
	s_nop 0
	v_addc_co_u32_e32 v3, vcc, 0, v3, vcc
	global_load_dword v2, v[2:3], off offset:1024 sc1
	s_add_u32 s8, s27, 0x2400
	s_addc_u32 s9, s26, 0
	s_waitcnt vmcnt(0) lgkmcnt(0)
	v_cmp_eq_u32_e32 vcc, v2, v1
	s_and_saveexec_b64 s[6:7], vcc
	s_cbranch_execz .LBB0_1062
	s_mov_b32 s28, 1
	s_mov_b64 s[10:11], 0
	s_branch .LBB0_1054

; __device__ __forceinline__ unsigned xb_ld(unsigned* p)              { return __hip_atomic_load(p, __ATOMIC_RELAXED, __HIP_MEMORY_SCOPE_AGENT); }
; #define XB_SPIN(cond, bar) do { unsigned _sp = 0; while (cond) { __builtin_amdgcn_s_sleep(1); \
;     if ((++_sp & 255u) == 0u) { if (xb_ld(&(bar)[XB_TMO])) break; if (_sp > XB_SPIN_CAP) { atomicAdd(&(bar)[XB_TMO], 1u); break; } } } } while (0)
; __device__ __forceinline__ void xcd_barrier(const XcdBarrier& b, int wave_s) {
;     ...
;         } else {
;             XB_SPIN(xb_ld(&bar[XB_XGEN(b.x)]) == gen, bar);
;             __builtin_amdgcn_fence(__ATOMIC_ACQUIRE, "agent");
;             asm volatile("s_waitcnt vmcnt(0)" ::: "memory");
;         }
.LBB0_1054:
	s_and_b32 s20, s28, 0xff
	s_mov_b64 s[18:19], -1
	s_cmp_lg_u32 s20, 0
	s_mov_b64 s[20:21], -1
	s_sleep 1
	s_cbranch_scc1 .LBB0_1058
	v_mov_b64_e32 v[2:3], s[38:39]
	global_load_dword v2, v[2:3], off offset:512 sc1
	s_mov_b64 s[20:21], 0
	s_mov_b64 s[22:23], -1
	s_waitcnt vmcnt(0) lgkmcnt(0)
	v_cmp_eq_u32_e32 vcc, 0, v2
	s_and_saveexec_b64 s[24:25], vcc
	s_cmp_lt_u32 s28, 0x400001
	s_cselect_b64 s[20:21], -1, 0
	s_xor_b64 s[22:23], exec, -1
	s_and_b64 s[20:21], s[20:21], exec
	s_or_b64 exec, exec, s[24:25]
.LBB0_1058:
	s_andn2_b64 s[14:15], s[14:15], exec
	s_and_b64 s[22:23], s[22:23], exec
	s_or_b64 s[14:15], s[14:15], s[22:23]
	s_and_saveexec_b64 s[22:23], s[20:21]
	s_cbranch_execz .LBB0_1053
	v_mov_b64_e32 v[2:3], s[8:9]
	global_load_dword v2, v[2:3], off sc1
	s_add_i32 s28, s28, 1
	s_or_b64 s[14:15], s[14:15], exec
	s_waitcnt vmcnt(0) lgkmcnt(0)
	v_cmp_ne_u32_e32 vcc, v2, v1
	s_orn2_b64 s[18:19], vcc, exec
	s_branch .LBB0_1053

; __device__ __forceinline__ unsigned xb_ld(unsigned* p)              { return __hip_atomic_load(p, __ATOMIC_RELAXED, __HIP_MEMORY_SCOPE_AGENT); }
; __device__ __forceinline__ unsigned xb_add(unsigned* p, unsigned v) { return __hip_atomic_fetch_add(p, v, __ATOMIC_RELAXED, __HIP_MEMORY_SCOPE_AGENT); }
; #define XB_SPIN(cond, bar) do { unsigned _sp = 0; while (cond) { __builtin_amdgcn_s_sleep(1); \
;     if ((++_sp & 255u) == 0u) { if (xb_ld(&(bar)[XB_TMO])) break; if (_sp > XB_SPIN_CAP) { atomicAdd(&(bar)[XB_TMO], 1u); break; } } } } while (0)
; __device__ __forceinline__ void xcd_barrier(const XcdBarrier& b, int wave_s) {
;     ...
;         const unsigned old = xb_add(&bar[XB_XSUB(b.x)], 1u);
;         const unsigned gen = old / nloc;
;         if (old + 1u == (gen + 1u) * nloc) {
;             __builtin_amdgcn_fence(__ATOMIC_RELEASE, "agent");
;             asm volatile("s_waitcnt vmcnt(0)" ::: "memory");
;             const unsigned og = xb_add(&bar[XB_TOP], 1u);
;             const unsigned tg = og / nx;
;             if (og + 1u == (tg + 1u) * nx) xb_add(&bar[XB_TOPGEN], 1u);
;             else XB_SPIN(xb_ld(&bar[XB_TOPGEN]) == tg, bar);
.LBB0_1063:
	s_andn2_saveexec_b64 s[4:5], s[4:5]
	s_cbranch_execz .LBB0_1079
	v_mov_b32_e32 v1, s38
	v_add_co_u32_e32 v4, vcc, 0x3000, v1
	v_mov_b32_e32 v1, s39
	buffer_wbl2 sc1
	s_waitcnt vmcnt(0)
	v_addc_co_u32_e32 v5, vcc, 0, v1, vcc
	flat_atomic_add v3, v[4:5], v149 offset:1024 sc0
	v_cvt_f32_u32_e32 v1, v2
	v_sub_u32_e32 v4, 0, v2
	s_mov_b64 s[8:9], -1
	v_rcp_iflag_f32_e32 v1, v1
	s_nop 0
	v_mul_f32_e32 v1, 0x4f7ffffe, v1
	v_cvt_u32_f32_e32 v1, v1
	v_mul_lo_u32 v4, v4, v1
	v_mul_hi_u32 v4, v1, v4
	v_add_u32_e32 v1, v1, v4
	s_waitcnt vmcnt(0) lgkmcnt(0)
	v_mul_hi_u32 v1, v3, v1
	v_mul_lo_u32 v4, v1, v2
	v_sub_u32_e32 v4, v3, v4
	v_cmp_ge_u32_e32 vcc, v4, v2
	v_add_u32_e32 v5, 1, v1
	s_nop 0
	v_cndmask_b32_e32 v1, v1, v5, vcc
	v_sub_u32_e32 v5, v4, v2
	v_cndmask_b32_e32 v4, v4, v5, vcc
	v_cmp_ge_u32_e32 vcc, v4, v2
	v_add_u32_e32 v4, 1, v1
	s_nop 0
	v_cndmask_b32_e32 v1, v1, v4, vcc
	v_add_u32_e32 v4, 1, v3
	v_mad_u64_u32 v[2:3], s[4:5], v2, v1, v[2:3]
	s_add_u32 s4, s38, 0x3500
	s_addc_u32 s5, s39, 0
	v_cmp_ne_u32_e32 vcc, v4, v2
	v_mov_b64_e32 v[2:3], s[4:5]
	s_and_saveexec_b64 s[6:7], vcc
	s_cbranch_execz .LBB0_1076
	v_mov_b64_e32 v[2:3], s[4:5]
	global_load_dword v2, v[2:3], off sc1
	s_mov_b64 s[12:13], 0
	s_waitcnt vmcnt(0) lgkmcnt(0)
	v_cmp_eq_u32_e32 vcc, v2, v1
	s_and_saveexec_b64 s[10:11], vcc
	s_cbranch_execz .LBB0_1075
	s_add_u32 s8, s38, 0x200
	s_addc_u32 s9, s39, 0
	s_mov_b32 s28, 1
	s_branch .LBB0_1068

; __device__ __forceinline__ unsigned xb_ld(unsigned* p)              { return __hip_atomic_load(p, __ATOMIC_RELAXED, __HIP_MEMORY_SCOPE_AGENT); }
; #define XB_SPIN(cond, bar) do { unsigned _sp = 0; while (cond) { __builtin_amdgcn_s_sleep(1); \
;     if ((++_sp & 255u) == 0u) { if (xb_ld(&(bar)[XB_TMO])) break; if (_sp > XB_SPIN_CAP) { atomicAdd(&(bar)[XB_TMO], 1u); break; } } } } while (0)
; __device__ __forceinline__ void xcd_barrier(const XcdBarrier& b, int wave_s) {
;     ...
;             else XB_SPIN(xb_ld(&bar[XB_TOPGEN]) == tg, bar);
.LBB0_1070:
	v_mov_b64_e32 v[2:3], s[8:9]
	global_load_dword v2, v[2:3], off sc1
	s_mov_b64 s[22:23], 0
	s_mov_b64 s[20:21], -1
	s_waitcnt vmcnt(0) lgkmcnt(0)
	v_cmp_eq_u32_e32 vcc, 0, v2
	s_and_saveexec_b64 s[24:25], vcc
	s_cmp_lt_u32 s28, 0x400001
	s_cselect_b64 s[22:23], -1, 0
	s_xor_b64 s[20:21], exec, -1
	s_and_b64 s[22:23], s[22:23], exec
	s_or_b64 exec, exec, s[24:25]
	s_and_saveexec_b64 s[24:25], s[22:23]
	s_cbranch_execz .LBB0_1067
.LBB0_1073:
	v_mov_b64_e32 v[2:3], s[4:5]
	global_load_dword v2, v[2:3], off sc1
	s_add_i32 s28, s28, 1
	s_or_b64 s[20:21], s[20:21], exec
	s_waitcnt vmcnt(0) lgkmcnt(0)
	v_cmp_ne_u32_e32 vcc, v2, v1
	s_orn2_b64 s[18:19], vcc, exec
	s_branch .LBB0_1067
